# plus FoX bias-read address trim; every packed f32 VALU op (v_pk_mul/add/fma_f32) split into two scalar ops (bit-identical)
# baseline (speedup 1.0000x reference)
.LBB0_37:
	s_and_saveexec_b64 s[84:85], s[0:1]
	s_cbranch_execz .LBB0_41
	s_add_i32 s80, s7, 0xfff7c000
	s_waitcnt vmcnt(3)
	v_mad_u64_u32 v[10:11], s[86:87], s80, v47, v[8:9]
	v_add_co_u32_e32 v2, vcc, 0x8000, v10
	s_nop 1
	v_addc_co_u32_e32 v3, vcc, 0, v11, vcc
	v_add_co_u32_e32 v12, vcc, 0x10000, v10
	s_nop 1
	v_addc_co_u32_e32 v13, vcc, 0, v11, vcc
	v_add_co_u32_e32 v14, vcc, 0x18000, v10
	s_nop 1
	v_addc_co_u32_e32 v15, vcc, 0, v11, vcc
	v_add_co_u32_e32 v16, vcc, 0x20000, v10
	s_nop 1
	v_addc_co_u32_e32 v17, vcc, 0, v11, vcc
	v_add_co_u32_e32 v18, vcc, 0x28000, v10
	s_nop 1
	v_addc_co_u32_e32 v19, vcc, 0, v11, vcc
	v_add_co_u32_e32 v20, vcc, 0x30000, v10
	s_nop 1
	v_addc_co_u32_e32 v21, vcc, 0, v11, vcc
	v_add_co_u32_e32 v22, vcc, 0x38000, v10
	s_nop 1
	v_addc_co_u32_e32 v23, vcc, 0, v11, vcc
	global_load_dword v0, v[10:11], off nt
	global_load_dword v1, v[2:3], off offset:64 nt
	s_nop 0
	global_load_dword v2, v[12:13], off offset:128 nt
	global_load_dword v3, v[14:15], off offset:192 nt
	s_nop 0
	global_load_dword v14, v[16:17], off offset:256 nt
	global_load_dword v15, v[18:19], off offset:320 nt
	s_nop 0
	global_load_dword v16, v[20:21], off offset:384 nt
	global_load_dword v17, v[22:23], off offset:448 nt
	v_add_co_u32_e32 v12, vcc, 0x40000, v10
	s_nop 1
	v_addc_co_u32_e32 v13, vcc, 0, v11, vcc
	v_add_co_u32_e32 v20, vcc, 0x48000, v10
	s_nop 1
	v_addc_co_u32_e32 v21, vcc, 0, v11, vcc
	v_add_co_u32_e32 v22, vcc, 0x50000, v10
	s_nop 1
	v_addc_co_u32_e32 v23, vcc, 0, v11, vcc
	v_add_co_u32_e32 v24, vcc, 0x58000, v10
	s_nop 1
	v_addc_co_u32_e32 v25, vcc, 0, v11, vcc
	v_add_co_u32_e32 v26, vcc, 0x60000, v10
	s_nop 1
	v_addc_co_u32_e32 v27, vcc, 0, v11, vcc
	v_add_co_u32_e32 v28, vcc, 0x68000, v10
	s_nop 1
	v_addc_co_u32_e32 v29, vcc, 0, v11, vcc
	v_add_co_u32_e32 v30, vcc, 0x70000, v10
	s_nop 1
	v_addc_co_u32_e32 v31, vcc, 0, v11, vcc
	v_add_co_u32_e32 v32, vcc, 0x78000, v10
	s_nop 1
	v_addc_co_u32_e32 v33, vcc, 0, v11, vcc
	global_load_dword v18, v[12:13], off offset:512 nt
	global_load_dword v19, v[20:21], off offset:576 nt
	s_nop 0
	global_load_dword v20, v[22:23], off offset:640 nt
	global_load_dword v21, v[24:25], off offset:704 nt
	s_nop 0
	global_load_dword v22, v[26:27], off offset:768 nt
	global_load_dword v23, v[28:29], off offset:832 nt
	global_load_dword v24, v[30:31], off offset:896 nt
	global_load_dword v25, v[32:33], off offset:960 nt
	v_add_co_u32_e32 v12, vcc, 0x80000, v10
	s_nop 1
	v_addc_co_u32_e32 v13, vcc, 0, v11, vcc
	v_add_co_u32_e32 v28, vcc, 0x88000, v10
	s_nop 1
	v_addc_co_u32_e32 v29, vcc, 0, v11, vcc
	v_add_co_u32_e32 v30, vcc, 0x90000, v10
	s_nop 1
	v_addc_co_u32_e32 v31, vcc, 0, v11, vcc
	v_add_co_u32_e32 v32, vcc, 0x98000, v10
	s_nop 1
	v_addc_co_u32_e32 v33, vcc, 0, v11, vcc
	v_add_co_u32_e32 v34, vcc, 0xa0000, v10
	s_nop 1
	v_addc_co_u32_e32 v35, vcc, 0, v11, vcc
	v_add_co_u32_e32 v36, vcc, 0xa8000, v10
	s_nop 1
	v_addc_co_u32_e32 v37, vcc, 0, v11, vcc
	v_add_co_u32_e32 v38, vcc, 0xb0000, v10
	s_nop 1
	v_addc_co_u32_e32 v39, vcc, 0, v11, vcc
	v_add_co_u32_e32 v40, vcc, 0xb8000, v10
	s_nop 1
	v_addc_co_u32_e32 v41, vcc, 0, v11, vcc
	global_load_dword v26, v[12:13], off offset:1024 nt
	global_load_dword v27, v[28:29], off offset:1088 nt
	s_nop 0
	global_load_dword v28, v[30:31], off offset:1152 nt
	global_load_dword v29, v[32:33], off offset:1216 nt
	s_nop 0
	global_load_dword v30, v[34:35], off offset:1280 nt
	global_load_dword v31, v[36:37], off offset:1344 nt
	global_load_dword v32, v[38:39], off offset:1408 nt
	global_load_dword v33, v[40:41], off offset:1472 nt
	v_add_co_u32_e32 v12, vcc, 0xc0000, v10
	s_nop 1
	v_addc_co_u32_e32 v13, vcc, 0, v11, vcc
	v_add_co_u32_e32 v36, vcc, 0xc8000, v10
	s_nop 1
	v_addc_co_u32_e32 v37, vcc, 0, v11, vcc
	v_add_co_u32_e32 v38, vcc, 0xd0000, v10
	s_nop 1
	v_addc_co_u32_e32 v39, vcc, 0, v11, vcc
	v_add_co_u32_e32 v40, vcc, 0xd8000, v10
	s_nop 1
	v_addc_co_u32_e32 v41, vcc, 0, v11, vcc
	v_add_co_u32_e32 v48, vcc, 0xe0000, v10
	s_nop 1
	v_addc_co_u32_e32 v49, vcc, 0, v11, vcc
	v_add_co_u32_e32 v50, vcc, 0xe8000, v10
	s_nop 1
	v_addc_co_u32_e32 v51, vcc, 0, v11, vcc
	v_add_co_u32_e32 v52, vcc, 0xf0000, v10
	s_nop 1
	v_addc_co_u32_e32 v53, vcc, 0, v11, vcc
	v_add_co_u32_e32 v54, vcc, 0xf8000, v10
	s_nop 1
	v_addc_co_u32_e32 v55, vcc, 0, v11, vcc
	global_load_dword v34, v[12:13], off offset:1536 nt
	global_load_dword v35, v[36:37], off offset:1600 nt
	s_nop 0
	global_load_dword v36, v[38:39], off offset:1664 nt
	global_load_dword v37, v[40:41], off offset:1728 nt
	s_nop 0
	global_load_dword v38, v[48:49], off offset:1792 nt
	global_load_dword v39, v[50:51], off offset:1856 nt
	global_load_dword v10, v[52:53], off offset:1920 nt
	global_load_dword v11, v[54:55], off offset:1984 nt
	s_andn2_b64 vcc, exec, s[76:77]
	s_cbranch_vccnz .LBB0_40
	s_lshl_b64 s[86:87], s[80:81], 2
	s_add_u32 s86, s26, s86
	s_addc_u32 s87, s27, s87
	global_load_dwordx4 v[48:51], v5, s[86:87]
	global_load_dwordx4 v[52:55], v5, s[86:87] offset:16
	global_load_dwordx4 v[56:59], v5, s[86:87] offset:32
	global_load_dwordx4 v[60:63], v5, s[86:87] offset:48
	global_load_dwordx4 v[64:67], v5, s[86:87] offset:64
	global_load_dwordx4 v[68:71], v5, s[86:87] offset:80
	global_load_dwordx4 v[72:75], v5, s[86:87] offset:96
	global_load_dwordx4 v[76:79], v5, s[86:87] offset:112
	s_waitcnt vmcnt(7)
	v_mul_f32_e64 v0, v0, v48
	v_mul_f32_e64 v1, v1, v49
	v_mul_f32_e64 v2, v2, v50
	v_mul_f32_e64 v3, v3, v51
	s_waitcnt vmcnt(6)
	v_mul_f32_e64 v14, v14, v52
	v_mul_f32_e64 v15, v15, v53
	v_mul_f32_e64 v16, v16, v54
	v_mul_f32_e64 v17, v17, v55
	s_waitcnt vmcnt(5)
	v_mul_f32_e64 v18, v18, v56
	v_mul_f32_e64 v19, v19, v57
	v_mul_f32_e64 v20, v20, v58
	v_mul_f32_e64 v21, v21, v59
	s_waitcnt vmcnt(4)
	v_mul_f32_e64 v22, v22, v60
	v_mul_f32_e64 v23, v23, v61
	v_mul_f32_e64 v24, v24, v62
	v_mul_f32_e64 v25, v25, v63
	s_waitcnt vmcnt(3)
	v_mul_f32_e64 v26, v26, v64
	v_mul_f32_e64 v27, v27, v65
	v_mul_f32_e64 v28, v28, v66
	v_mul_f32_e64 v29, v29, v67
	s_waitcnt vmcnt(2)
	v_mul_f32_e64 v30, v30, v68
	v_mul_f32_e64 v31, v31, v69
	v_mul_f32_e64 v32, v32, v70
	v_mul_f32_e64 v33, v33, v71
	s_waitcnt vmcnt(1)
	v_mul_f32_e64 v34, v34, v72
	v_mul_f32_e64 v35, v35, v73
	v_mul_f32_e64 v36, v36, v74
	v_mul_f32_e64 v37, v37, v75
	s_waitcnt vmcnt(0)
	v_mul_f32_e64 v38, v38, v76
	v_mul_f32_e64 v39, v39, v77
	v_mul_f32_e64 v10, v10, v78
	v_mul_f32_e64 v11, v11, v79

.LBB0_43:
	s_and_b32 s80, s33, 0x7fc0
	v_add_u32_e32 v4, s80, v44
	v_cmp_gt_i32_e32 vcc, s92, v4
	s_and_saveexec_b64 s[84:85], vcc
	s_cbranch_execz .LBB0_47
	s_and_b32 s80, s7, 0x7e0
	s_mul_i32 s86, s80, 0x8040
	s_add_u32 s86, s60, s86
	s_addc_u32 s87, s61, 0
	s_waitcnt vmcnt(3)
	v_lshl_add_u64 v[10:11], v[4:5], 2, s[86:87]
	v_add_co_u32_e32 v2, vcc, 0x8000, v10
	s_nop 1
	v_addc_co_u32_e32 v3, vcc, 0, v11, vcc
	v_add_co_u32_e32 v12, vcc, 0x10000, v10
	s_nop 1
	v_addc_co_u32_e32 v13, vcc, 0, v11, vcc
	v_add_co_u32_e32 v14, vcc, 0x18000, v10
	s_nop 1
	v_addc_co_u32_e32 v15, vcc, 0, v11, vcc
	v_add_co_u32_e32 v16, vcc, 0x20000, v10
	s_nop 1
	v_addc_co_u32_e32 v17, vcc, 0, v11, vcc
	v_add_co_u32_e32 v18, vcc, 0x28000, v10
	s_nop 1
	v_addc_co_u32_e32 v19, vcc, 0, v11, vcc
	v_add_co_u32_e32 v20, vcc, 0x30000, v10
	s_nop 1
	v_addc_co_u32_e32 v21, vcc, 0, v11, vcc
	v_add_co_u32_e32 v22, vcc, 0x38000, v10
	s_nop 1
	v_addc_co_u32_e32 v23, vcc, 0, v11, vcc
	global_load_dword v0, v[10:11], off nt
	global_load_dword v1, v[2:3], off offset:64 nt
	s_nop 0
	global_load_dword v2, v[12:13], off offset:128 nt
	global_load_dword v3, v[14:15], off offset:192 nt
	s_nop 0
	global_load_dword v14, v[16:17], off offset:256 nt
	global_load_dword v15, v[18:19], off offset:320 nt
	s_nop 0
	global_load_dword v16, v[20:21], off offset:384 nt
	global_load_dword v17, v[22:23], off offset:448 nt
	v_add_co_u32_e32 v12, vcc, 0x40000, v10
	s_nop 1
	v_addc_co_u32_e32 v13, vcc, 0, v11, vcc
	v_add_co_u32_e32 v20, vcc, 0x48000, v10
	s_nop 1
	v_addc_co_u32_e32 v21, vcc, 0, v11, vcc
	v_add_co_u32_e32 v22, vcc, 0x50000, v10
	s_nop 1
	v_addc_co_u32_e32 v23, vcc, 0, v11, vcc
	v_add_co_u32_e32 v24, vcc, 0x58000, v10
	s_nop 1
	v_addc_co_u32_e32 v25, vcc, 0, v11, vcc
	v_add_co_u32_e32 v26, vcc, 0x60000, v10
	s_nop 1
	v_addc_co_u32_e32 v27, vcc, 0, v11, vcc
	v_add_co_u32_e32 v28, vcc, 0x68000, v10
	s_nop 1
	v_addc_co_u32_e32 v29, vcc, 0, v11, vcc
	v_add_co_u32_e32 v30, vcc, 0x70000, v10
	s_nop 1
	v_addc_co_u32_e32 v31, vcc, 0, v11, vcc
	v_add_co_u32_e32 v32, vcc, 0x78000, v10
	s_nop 1
	v_addc_co_u32_e32 v33, vcc, 0, v11, vcc
	global_load_dword v18, v[12:13], off offset:512 nt
	global_load_dword v19, v[20:21], off offset:576 nt
	s_nop 0
	global_load_dword v20, v[22:23], off offset:640 nt
	global_load_dword v21, v[24:25], off offset:704 nt
	s_nop 0
	global_load_dword v22, v[26:27], off offset:768 nt
	global_load_dword v23, v[28:29], off offset:832 nt
	global_load_dword v24, v[30:31], off offset:896 nt
	global_load_dword v25, v[32:33], off offset:960 nt
	v_add_co_u32_e32 v12, vcc, 0x80000, v10
	s_nop 1
	v_addc_co_u32_e32 v13, vcc, 0, v11, vcc
	v_add_co_u32_e32 v28, vcc, 0x88000, v10
	s_nop 1
	v_addc_co_u32_e32 v29, vcc, 0, v11, vcc
	v_add_co_u32_e32 v30, vcc, 0x90000, v10
	s_nop 1
	v_addc_co_u32_e32 v31, vcc, 0, v11, vcc
	v_add_co_u32_e32 v32, vcc, 0x98000, v10
	s_nop 1
	v_addc_co_u32_e32 v33, vcc, 0, v11, vcc
	v_add_co_u32_e32 v34, vcc, 0xa0000, v10
	s_nop 1
	v_addc_co_u32_e32 v35, vcc, 0, v11, vcc
	v_add_co_u32_e32 v36, vcc, 0xa8000, v10
	s_nop 1
	v_addc_co_u32_e32 v37, vcc, 0, v11, vcc
	v_add_co_u32_e32 v38, vcc, 0xb0000, v10
	s_nop 1
	v_addc_co_u32_e32 v39, vcc, 0, v11, vcc
	v_add_co_u32_e32 v40, vcc, 0xb8000, v10
	s_nop 1
	v_addc_co_u32_e32 v41, vcc, 0, v11, vcc
	global_load_dword v26, v[12:13], off offset:1024 nt
	global_load_dword v27, v[28:29], off offset:1088 nt
	s_nop 0
	global_load_dword v28, v[30:31], off offset:1152 nt
	global_load_dword v29, v[32:33], off offset:1216 nt
	s_nop 0
	global_load_dword v30, v[34:35], off offset:1280 nt
	global_load_dword v31, v[36:37], off offset:1344 nt
	global_load_dword v32, v[38:39], off offset:1408 nt
	global_load_dword v33, v[40:41], off offset:1472 nt
	v_add_co_u32_e32 v12, vcc, 0xc0000, v10
	s_nop 1
	v_addc_co_u32_e32 v13, vcc, 0, v11, vcc
	v_add_co_u32_e32 v36, vcc, 0xc8000, v10
	s_nop 1
	v_addc_co_u32_e32 v37, vcc, 0, v11, vcc
	v_add_co_u32_e32 v38, vcc, 0xd0000, v10
	s_nop 1
	v_addc_co_u32_e32 v39, vcc, 0, v11, vcc
	v_add_co_u32_e32 v40, vcc, 0xd8000, v10
	s_nop 1
	v_addc_co_u32_e32 v41, vcc, 0, v11, vcc
	v_add_co_u32_e32 v48, vcc, 0xe0000, v10
	s_nop 1
	v_addc_co_u32_e32 v49, vcc, 0, v11, vcc
	v_add_co_u32_e32 v50, vcc, 0xe8000, v10
	s_nop 1
	v_addc_co_u32_e32 v51, vcc, 0, v11, vcc
	v_add_co_u32_e32 v52, vcc, 0xf0000, v10
	s_nop 1
	v_addc_co_u32_e32 v53, vcc, 0, v11, vcc
	v_add_co_u32_e32 v54, vcc, 0xf8000, v10
	s_nop 1
	v_addc_co_u32_e32 v55, vcc, 0, v11, vcc
	global_load_dword v34, v[12:13], off offset:1536 nt
	global_load_dword v35, v[36:37], off offset:1600 nt
	s_nop 0
	global_load_dword v36, v[38:39], off offset:1664 nt
	global_load_dword v37, v[40:41], off offset:1728 nt
	s_nop 0
	global_load_dword v38, v[48:49], off offset:1792 nt
	global_load_dword v39, v[50:51], off offset:1856 nt
	global_load_dword v10, v[52:53], off offset:1920 nt
	global_load_dword v11, v[54:55], off offset:1984 nt
	s_andn2_b64 vcc, exec, s[76:77]
	s_cbranch_vccnz .LBB0_46
	s_lshl_b32 s86, s80, 2
	v_mov_b32_e32 v12, s86
	global_load_dwordx4 v[48:51], v12, s[26:27]
	global_load_dwordx4 v[52:55], v12, s[26:27] offset:16
	global_load_dwordx4 v[56:59], v12, s[26:27] offset:32
	global_load_dwordx4 v[60:63], v12, s[26:27] offset:48
	global_load_dwordx4 v[64:67], v12, s[26:27] offset:64
	global_load_dwordx4 v[68:71], v12, s[26:27] offset:80
	global_load_dwordx4 v[72:75], v12, s[26:27] offset:96
	global_load_dwordx4 v[76:79], v12, s[26:27] offset:112
	s_waitcnt vmcnt(7)
	v_mul_f32_e64 v0, v0, v48
	v_mul_f32_e64 v1, v1, v49
	v_mul_f32_e64 v2, v2, v50
	v_mul_f32_e64 v3, v3, v51
	s_waitcnt vmcnt(6)
	v_mul_f32_e64 v14, v14, v52
	v_mul_f32_e64 v15, v15, v53
	v_mul_f32_e64 v16, v16, v54
	v_mul_f32_e64 v17, v17, v55
	s_waitcnt vmcnt(5)
	v_mul_f32_e64 v18, v18, v56
	v_mul_f32_e64 v19, v19, v57
	v_mul_f32_e64 v20, v20, v58
	v_mul_f32_e64 v21, v21, v59
	s_waitcnt vmcnt(4)
	v_mul_f32_e64 v22, v22, v60
	v_mul_f32_e64 v23, v23, v61
	v_mul_f32_e64 v24, v24, v62
	v_mul_f32_e64 v25, v25, v63
	s_waitcnt vmcnt(3)
	v_mul_f32_e64 v26, v26, v64
	v_mul_f32_e64 v27, v27, v65
	v_mul_f32_e64 v28, v28, v66
	v_mul_f32_e64 v29, v29, v67
	s_waitcnt vmcnt(2)
	v_mul_f32_e64 v30, v30, v68
	v_mul_f32_e64 v31, v31, v69
	v_mul_f32_e64 v32, v32, v70
	v_mul_f32_e64 v33, v33, v71
	s_waitcnt vmcnt(1)
	v_mul_f32_e64 v34, v34, v72
	v_mul_f32_e64 v35, v35, v73
	v_mul_f32_e64 v36, v36, v74
	v_mul_f32_e64 v37, v37, v75
	s_waitcnt vmcnt(0)
	v_mul_f32_e64 v38, v38, v76
	v_mul_f32_e64 v39, v39, v77
	v_mul_f32_e64 v10, v10, v78
	v_mul_f32_e64 v11, v11, v79

.LBB0_55:
	s_and_b32 s80, s33, 0xffffffc0
	v_or_b32_e32 v14, s80, v42
	v_cmp_gt_i32_e32 vcc, s97, v14
	s_and_saveexec_b64 s[84:85], vcc
	s_cbranch_execz .LBB0_59
	s_and_b32 s80, s7, 0x7e0
	s_mul_i32 s86, s80, 0x6000
	s_add_u32 s86, s40, s86
	s_addc_u32 s87, s41, 0
	v_ashrrev_i32_e32 v15, 31, v14
	s_waitcnt vmcnt(3)
	v_lshl_add_u64 v[10:11], v[14:15], 2, s[86:87]
	v_add_co_u32_e32 v2, vcc, 0x6000, v10
	s_nop 1
	v_addc_co_u32_e32 v3, vcc, 0, v11, vcc
	v_add_co_u32_e32 v12, vcc, 0xc000, v10
	s_nop 1
	v_addc_co_u32_e32 v13, vcc, 0, v11, vcc
	v_add_co_u32_e32 v16, vcc, 0x12000, v10
	s_nop 1
	v_addc_co_u32_e32 v17, vcc, 0, v11, vcc
	v_add_co_u32_e32 v18, vcc, 0x18000, v10
	s_nop 1
	v_addc_co_u32_e32 v19, vcc, 0, v11, vcc
	v_add_co_u32_e32 v20, vcc, 0x1e000, v10
	s_nop 1
	v_addc_co_u32_e32 v21, vcc, 0, v11, vcc
	v_add_co_u32_e32 v22, vcc, 0x24000, v10
	s_nop 1
	v_addc_co_u32_e32 v23, vcc, 0, v11, vcc
	v_add_co_u32_e32 v24, vcc, 0x2a000, v10
	s_nop 1
	v_addc_co_u32_e32 v25, vcc, 0, v11, vcc
	global_load_dword v0, v[10:11], off nt
	global_load_dword v1, v[2:3], off nt
	s_nop 0
	global_load_dword v2, v[12:13], off nt
	global_load_dword v3, v[16:17], off nt
	s_nop 0
	global_load_dword v16, v[18:19], off nt
	global_load_dword v17, v[20:21], off nt
	s_nop 0
	global_load_dword v18, v[22:23], off nt
	global_load_dword v19, v[24:25], off nt
	v_add_co_u32_e32 v12, vcc, 0x30000, v10
	s_nop 1
	v_addc_co_u32_e32 v13, vcc, 0, v11, vcc
	v_add_co_u32_e32 v22, vcc, 0x36000, v10
	s_nop 1
	v_addc_co_u32_e32 v23, vcc, 0, v11, vcc
	v_add_co_u32_e32 v24, vcc, 0x3c000, v10
	s_nop 1
	v_addc_co_u32_e32 v25, vcc, 0, v11, vcc
	v_add_co_u32_e32 v26, vcc, 0x42000, v10
	s_nop 1
	v_addc_co_u32_e32 v27, vcc, 0, v11, vcc
	v_add_co_u32_e32 v28, vcc, 0x48000, v10
	s_nop 1
	v_addc_co_u32_e32 v29, vcc, 0, v11, vcc
	v_add_co_u32_e32 v30, vcc, 0x4e000, v10
	s_nop 1
	v_addc_co_u32_e32 v31, vcc, 0, v11, vcc
	v_add_co_u32_e32 v32, vcc, 0x54000, v10
	s_nop 1
	v_addc_co_u32_e32 v33, vcc, 0, v11, vcc
	v_add_co_u32_e32 v34, vcc, 0x5a000, v10
	s_nop 1
	v_addc_co_u32_e32 v35, vcc, 0, v11, vcc
	global_load_dword v20, v[12:13], off nt
	global_load_dword v21, v[22:23], off nt
	s_nop 0
	global_load_dword v22, v[24:25], off nt
	global_load_dword v23, v[26:27], off nt
	s_nop 0
	global_load_dword v24, v[28:29], off nt
	global_load_dword v25, v[30:31], off nt
	global_load_dword v26, v[32:33], off nt
	global_load_dword v27, v[34:35], off nt
	v_add_co_u32_e32 v12, vcc, s93, v10
	s_nop 1
	v_addc_co_u32_e32 v13, vcc, 0, v11, vcc
	v_add_co_u32_e32 v30, vcc, 0x66000, v10
	s_nop 1
	v_addc_co_u32_e32 v31, vcc, 0, v11, vcc
	v_add_co_u32_e32 v32, vcc, 0x6c000, v10
	s_nop 1
	v_addc_co_u32_e32 v33, vcc, 0, v11, vcc
	v_add_co_u32_e32 v34, vcc, 0x72000, v10
	s_nop 1
	v_addc_co_u32_e32 v35, vcc, 0, v11, vcc
	v_add_co_u32_e32 v36, vcc, s94, v10
	s_nop 1
	v_addc_co_u32_e32 v37, vcc, 0, v11, vcc
	v_add_co_u32_e32 v38, vcc, 0x7e000, v10
	s_nop 1
	v_addc_co_u32_e32 v39, vcc, 0, v11, vcc
	v_add_co_u32_e32 v40, vcc, 0x84000, v10
	s_nop 1
	v_addc_co_u32_e32 v41, vcc, 0, v11, vcc
	v_add_co_u32_e32 v48, vcc, 0x8a000, v10
	s_nop 1
	v_addc_co_u32_e32 v49, vcc, 0, v11, vcc
	global_load_dword v28, v[12:13], off nt
	global_load_dword v29, v[30:31], off nt
	s_nop 0
	global_load_dword v30, v[32:33], off nt
	global_load_dword v31, v[34:35], off nt
	s_nop 0
	global_load_dword v32, v[36:37], off nt
	global_load_dword v33, v[38:39], off nt
	global_load_dword v34, v[40:41], off nt
	global_load_dword v35, v[48:49], off nt
	v_add_co_u32_e32 v12, vcc, s95, v10
	s_nop 1
	v_addc_co_u32_e32 v13, vcc, 0, v11, vcc
	v_add_co_u32_e32 v38, vcc, 0x96000, v10
	s_nop 1
	v_addc_co_u32_e32 v39, vcc, 0, v11, vcc
	v_add_co_u32_e32 v40, vcc, 0x9c000, v10
	s_nop 1
	v_addc_co_u32_e32 v41, vcc, 0, v11, vcc
	v_add_co_u32_e32 v48, vcc, 0xa2000, v10
	s_nop 1
	v_addc_co_u32_e32 v49, vcc, 0, v11, vcc
	v_add_co_u32_e32 v50, vcc, s96, v10
	s_nop 1
	v_addc_co_u32_e32 v51, vcc, 0, v11, vcc
	v_add_co_u32_e32 v52, vcc, 0xae000, v10
	s_nop 1
	v_addc_co_u32_e32 v53, vcc, 0, v11, vcc
	v_add_co_u32_e32 v54, vcc, 0xb4000, v10
	s_nop 1
	v_addc_co_u32_e32 v55, vcc, 0, v11, vcc
	v_add_co_u32_e32 v56, vcc, 0xba000, v10
	s_nop 1
	v_addc_co_u32_e32 v57, vcc, 0, v11, vcc
	global_load_dword v36, v[12:13], off nt
	global_load_dword v37, v[38:39], off nt
	s_nop 0
	global_load_dword v38, v[40:41], off nt
	global_load_dword v39, v[48:49], off nt
	s_nop 0
	global_load_dword v40, v[50:51], off nt
	global_load_dword v41, v[52:53], off nt
	global_load_dword v10, v[54:55], off nt
	global_load_dword v11, v[56:57], off nt
	s_andn2_b64 vcc, exec, s[78:79]
	s_cbranch_vccnz .LBB0_58
	s_lshl_b32 s86, s80, 2
	v_mov_b32_e32 v4, s86
	global_load_dwordx4 v[48:51], v4, s[38:39]
	global_load_dwordx4 v[52:55], v4, s[38:39] offset:16
	global_load_dwordx4 v[56:59], v4, s[38:39] offset:32
	global_load_dwordx4 v[60:63], v4, s[38:39] offset:48
	global_load_dwordx4 v[64:67], v4, s[38:39] offset:64
	global_load_dwordx4 v[68:71], v4, s[38:39] offset:80
	s_waitcnt vmcnt(5)
	v_mul_f32_e64 v0, v0, v48
	v_mul_f32_e64 v1, v1, v49
	v_mul_f32_e64 v2, v2, v50
	v_mul_f32_e64 v3, v3, v51
	global_load_dwordx4 v[48:51], v4, s[38:39] offset:96
	global_load_dwordx4 v[72:75], v4, s[38:39] offset:112
	s_waitcnt vmcnt(6)
	v_mul_f32_e64 v16, v16, v52
	v_mul_f32_e64 v17, v17, v53
	v_mul_f32_e64 v18, v18, v54
	v_mul_f32_e64 v19, v19, v55
	s_waitcnt vmcnt(5)
	v_mul_f32_e64 v20, v20, v56
	v_mul_f32_e64 v21, v21, v57
	v_mul_f32_e64 v22, v22, v58
	v_mul_f32_e64 v23, v23, v59
	s_waitcnt vmcnt(4)
	v_mul_f32_e64 v24, v24, v60
	v_mul_f32_e64 v25, v25, v61
	v_mul_f32_e64 v26, v26, v62
	v_mul_f32_e64 v27, v27, v63
	s_waitcnt vmcnt(3)
	v_mul_f32_e64 v28, v28, v64
	v_mul_f32_e64 v29, v29, v65
	v_mul_f32_e64 v30, v30, v66
	v_mul_f32_e64 v31, v31, v67
	s_waitcnt vmcnt(2)
	v_mul_f32_e64 v32, v32, v68
	v_mul_f32_e64 v33, v33, v69
	v_mul_f32_e64 v34, v34, v70
	v_mul_f32_e64 v35, v35, v71
	s_waitcnt vmcnt(1)
	v_mul_f32_e64 v36, v36, v48
	v_mul_f32_e64 v37, v37, v49
	v_mul_f32_e64 v38, v38, v50
	v_mul_f32_e64 v39, v39, v51
	s_waitcnt vmcnt(0)
	v_mul_f32_e64 v40, v40, v72
	v_mul_f32_e64 v41, v41, v73
	v_mul_f32_e64 v10, v10, v74
	v_mul_f32_e64 v11, v11, v75

.LBB0_155:
	v_lshl_add_u32 v144, s4, 8, v152
	v_ashrrev_i32_e32 v145, 31, v144
	v_lshl_add_u64 v[150:151], v[144:145], 2, s[54:55]
	s_nop 0
	s_cmp_lt_i32 s5, 4
	s_cselect_b64 vcc, -1, 0
	v_cndmask_b32_e32 v145, 1.0, v160, vcc
	v_mov_b64_e32 v[148:149], s[20:21]
	v_lshl_or_b32 v146, s5, 8, v154
	v_ashrrev_i32_e32 v147, 31, v146
	v_lshlrev_b64 v[146:147], 1, v[146:147]
	s_nop 0
	v_fmamk_f32 v161, v242, 0x3a000000, v158
	v_rsq_f32_e32 v252, v161
	s_nop 0
	v_mul_f32_e32 v252, v252, v145
	v_mad_i64_i32 v[162:163], s[4:5], v144, s82, v[148:149]
	v_lshl_add_u64 v[162:163], v[162:163], 0, v[146:147]
	v_mul_f32_e64 v126, v126, v252
	v_mul_f32_e64 v127, v127, v252
	v_mul_f32_e64 v124, v124, v252
	v_mul_f32_e64 v125, v125, v252
	v_mul_f32_e64 v122, v122, v252
	v_mul_f32_e64 v123, v123, v252
	v_mul_f32_e64 v120, v120, v252
	v_mul_f32_e64 v121, v121, v252
	v_mul_f32_e64 v118, v118, v252
	v_mul_f32_e64 v119, v119, v252
	v_mul_f32_e64 v116, v116, v252
	v_mul_f32_e64 v117, v117, v252
	v_mul_f32_e64 v166, v114, v252
	v_mul_f32_e64 v167, v115, v252
	v_mul_f32_e64 v164, v112, v252
	v_mul_f32_e64 v165, v113, v252
	v_cvt_pk_bf16_f32 v112, v124, v125
	v_cvt_pk_bf16_f32 v113, v126, v127
	v_cvt_pk_bf16_f32 v114, v120, v121
	v_cvt_pk_bf16_f32 v115, v122, v123
	v_cvt_pk_bf16_f32 v116, v116, v117
	v_cvt_pk_bf16_f32 v117, v118, v119
	v_cvt_pk_bf16_f32 v118, v164, v165
	v_cvt_pk_bf16_f32 v119, v166, v167
	global_store_dwordx4 v[162:163], v[112:115], off
	global_store_dwordx4 v[162:163], v[116:119], off offset:256
	s_nop 0
	s_nop 0
	v_fmamk_f32 v112, v243, 0x3a000000, v158
	v_rsq_f32_e32 v252, v112
	s_nop 0
	v_mul_f32_e32 v252, v252, v145
	v_or_b32_e32 v112, 16, v144
	v_mad_i64_i32 v[112:113], s[4:5], v112, s82, v[148:149]
	v_lshl_add_u64 v[112:113], v[112:113], 0, v[146:147]
	v_mul_f32_e64 v110, v110, v252
	v_mul_f32_e64 v111, v111, v252
	v_mul_f32_e64 v108, v108, v252
	v_mul_f32_e64 v109, v109, v252
	v_mul_f32_e64 v106, v106, v252
	v_mul_f32_e64 v107, v107, v252
	v_mul_f32_e64 v104, v104, v252
	v_mul_f32_e64 v105, v105, v252
	v_mul_f32_e64 v102, v102, v252
	v_mul_f32_e64 v103, v103, v252
	v_mul_f32_e64 v100, v100, v252
	v_mul_f32_e64 v101, v101, v252
	v_mul_f32_e64 v116, v98, v252
	v_mul_f32_e64 v117, v99, v252
	v_mul_f32_e64 v114, v96, v252
	v_mul_f32_e64 v115, v97, v252
	v_cvt_pk_bf16_f32 v96, v108, v109
	v_cvt_pk_bf16_f32 v97, v110, v111
	v_cvt_pk_bf16_f32 v98, v104, v105
	v_cvt_pk_bf16_f32 v99, v106, v107
	v_cvt_pk_bf16_f32 v100, v100, v101
	v_cvt_pk_bf16_f32 v101, v102, v103
	v_cvt_pk_bf16_f32 v102, v114, v115
	v_cvt_pk_bf16_f32 v103, v116, v117
	global_store_dwordx4 v[112:113], v[96:99], off
	global_store_dwordx4 v[112:113], v[100:103], off offset:256
	s_nop 0
	s_nop 0
	v_fmamk_f32 v96, v244, 0x3a000000, v158
	v_rsq_f32_e32 v252, v96
	s_nop 0
	v_mul_f32_e32 v252, v252, v145
	v_or_b32_e32 v96, 32, v144
	v_mad_i64_i32 v[96:97], s[4:5], v96, s82, v[148:149]
	v_lshl_add_u64 v[96:97], v[96:97], 0, v[146:147]
	v_mul_f32_e64 v94, v94, v252
	v_mul_f32_e64 v95, v95, v252
	v_mul_f32_e64 v92, v92, v252
	v_mul_f32_e64 v93, v93, v252
	v_mul_f32_e64 v90, v90, v252
	v_mul_f32_e64 v91, v91, v252
	v_mul_f32_e64 v88, v88, v252
	v_mul_f32_e64 v89, v89, v252
	v_mul_f32_e64 v86, v86, v252
	v_mul_f32_e64 v87, v87, v252
	v_mul_f32_e64 v84, v84, v252
	v_mul_f32_e64 v85, v85, v252
	v_mul_f32_e64 v100, v82, v252
	v_mul_f32_e64 v101, v83, v252
	v_mul_f32_e64 v98, v80, v252
	v_mul_f32_e64 v99, v81, v252
	v_cvt_pk_bf16_f32 v80, v92, v93
	v_cvt_pk_bf16_f32 v81, v94, v95
	v_cvt_pk_bf16_f32 v82, v88, v89
	v_cvt_pk_bf16_f32 v83, v90, v91
	v_cvt_pk_bf16_f32 v84, v84, v85
	v_cvt_pk_bf16_f32 v85, v86, v87
	v_cvt_pk_bf16_f32 v86, v98, v99
	v_cvt_pk_bf16_f32 v87, v100, v101
	global_store_dwordx4 v[96:97], v[80:83], off
	global_store_dwordx4 v[96:97], v[84:87], off offset:256
	s_nop 0
	s_nop 0
	v_fmamk_f32 v80, v245, 0x3a000000, v158
	v_rsq_f32_e32 v252, v80
	s_nop 0
	v_mul_f32_e32 v252, v252, v145
	v_or_b32_e32 v80, 48, v144
	v_mad_i64_i32 v[80:81], s[4:5], v80, s82, v[148:149]
	v_lshl_add_u64 v[80:81], v[80:81], 0, v[146:147]
	v_mul_f32_e64 v78, v78, v252
	v_mul_f32_e64 v79, v79, v252
	v_mul_f32_e64 v76, v76, v252
	v_mul_f32_e64 v77, v77, v252
	v_mul_f32_e64 v74, v74, v252
	v_mul_f32_e64 v75, v75, v252
	v_mul_f32_e64 v72, v72, v252
	v_mul_f32_e64 v73, v73, v252
	v_mul_f32_e64 v70, v70, v252
	v_mul_f32_e64 v71, v71, v252
	v_mul_f32_e64 v68, v68, v252
	v_mul_f32_e64 v69, v69, v252
	v_mul_f32_e64 v84, v66, v252
	v_mul_f32_e64 v85, v67, v252
	v_mul_f32_e64 v82, v64, v252
	v_mul_f32_e64 v83, v65, v252
	v_cvt_pk_bf16_f32 v64, v76, v77
	v_cvt_pk_bf16_f32 v65, v78, v79
	v_cvt_pk_bf16_f32 v66, v72, v73
	v_cvt_pk_bf16_f32 v67, v74, v75
	v_cvt_pk_bf16_f32 v68, v68, v69
	v_cvt_pk_bf16_f32 v69, v70, v71
	v_cvt_pk_bf16_f32 v70, v82, v83
	v_cvt_pk_bf16_f32 v71, v84, v85
	global_store_dwordx4 v[80:81], v[64:67], off
	global_store_dwordx4 v[80:81], v[68:71], off offset:256
	s_nop 0
	s_nop 0
	v_fmamk_f32 v64, v246, 0x3a000000, v158
	v_rsq_f32_e32 v252, v64
	s_nop 0
	v_mul_f32_e32 v252, v252, v145
	v_add_u32_e32 v64, 0x80, v144
	v_mad_i64_i32 v[64:65], s[4:5], v64, s82, v[148:149]
	v_lshl_add_u64 v[64:65], v[64:65], 0, v[146:147]
	v_mul_f32_e64 v62, v62, v252
	v_mul_f32_e64 v63, v63, v252
	v_mul_f32_e64 v60, v60, v252
	v_mul_f32_e64 v61, v61, v252
	v_mul_f32_e64 v58, v58, v252
	v_mul_f32_e64 v59, v59, v252
	v_mul_f32_e64 v56, v56, v252
	v_mul_f32_e64 v57, v57, v252
	v_mul_f32_e64 v54, v54, v252
	v_mul_f32_e64 v55, v55, v252
	v_mul_f32_e64 v52, v52, v252
	v_mul_f32_e64 v53, v53, v252
	v_mul_f32_e64 v68, v50, v252
	v_mul_f32_e64 v69, v51, v252
	v_mul_f32_e64 v66, v48, v252
	v_mul_f32_e64 v67, v49, v252
	v_cvt_pk_bf16_f32 v48, v60, v61
	v_cvt_pk_bf16_f32 v49, v62, v63
	v_cvt_pk_bf16_f32 v50, v56, v57
	v_cvt_pk_bf16_f32 v51, v58, v59
	v_cvt_pk_bf16_f32 v52, v52, v53
	v_cvt_pk_bf16_f32 v53, v54, v55
	v_cvt_pk_bf16_f32 v54, v66, v67
	v_cvt_pk_bf16_f32 v55, v68, v69
	global_store_dwordx4 v[64:65], v[48:51], off
	global_store_dwordx4 v[64:65], v[52:55], off offset:256
	s_nop 0
	s_nop 0
	v_fmamk_f32 v48, v247, 0x3a000000, v158
	v_rsq_f32_e32 v252, v48
	s_nop 0
	v_mul_f32_e32 v252, v252, v145
	v_add_u32_e32 v48, 0x90, v144
	v_mad_i64_i32 v[48:49], s[4:5], v48, s82, v[148:149]
	v_lshl_add_u64 v[48:49], v[48:49], 0, v[146:147]
	v_mul_f32_e64 v46, v46, v252
	v_mul_f32_e64 v47, v47, v252
	v_mul_f32_e64 v44, v44, v252
	v_mul_f32_e64 v45, v45, v252
	v_mul_f32_e64 v42, v42, v252
	v_mul_f32_e64 v43, v43, v252
	v_mul_f32_e64 v40, v40, v252
	v_mul_f32_e64 v41, v41, v252
	v_mul_f32_e64 v38, v38, v252
	v_mul_f32_e64 v39, v39, v252
	v_mul_f32_e64 v36, v36, v252
	v_mul_f32_e64 v37, v37, v252
	v_mul_f32_e64 v52, v34, v252
	v_mul_f32_e64 v53, v35, v252
	v_mul_f32_e64 v50, v32, v252
	v_mul_f32_e64 v51, v33, v252
	v_cvt_pk_bf16_f32 v32, v44, v45
	v_cvt_pk_bf16_f32 v33, v46, v47
	v_cvt_pk_bf16_f32 v34, v40, v41
	v_cvt_pk_bf16_f32 v35, v42, v43
	v_cvt_pk_bf16_f32 v36, v36, v37
	v_cvt_pk_bf16_f32 v37, v38, v39
	v_cvt_pk_bf16_f32 v38, v50, v51
	v_cvt_pk_bf16_f32 v39, v52, v53
	global_store_dwordx4 v[48:49], v[32:35], off
	global_store_dwordx4 v[48:49], v[36:39], off offset:256
	s_nop 0
	s_nop 0
	v_fmamk_f32 v32, v248, 0x3a000000, v158
	v_rsq_f32_e32 v252, v32
	s_nop 0
	v_mul_f32_e32 v252, v252, v145
	v_add_u32_e32 v32, 0xa0, v144
	v_mad_i64_i32 v[32:33], s[4:5], v32, s82, v[148:149]
	v_lshl_add_u64 v[32:33], v[32:33], 0, v[146:147]
	v_mul_f32_e64 v30, v30, v252
	v_mul_f32_e64 v31, v31, v252
	v_mul_f32_e64 v28, v28, v252
	v_mul_f32_e64 v29, v29, v252
	v_mul_f32_e64 v26, v26, v252
	v_mul_f32_e64 v27, v27, v252
	v_mul_f32_e64 v24, v24, v252
	v_mul_f32_e64 v25, v25, v252
	v_mul_f32_e64 v22, v22, v252
	v_mul_f32_e64 v23, v23, v252
	v_mul_f32_e64 v20, v20, v252
	v_mul_f32_e64 v21, v21, v252
	v_mul_f32_e64 v36, v18, v252
	v_mul_f32_e64 v37, v19, v252
	v_mul_f32_e64 v34, v16, v252
	v_mul_f32_e64 v35, v17, v252
	v_cvt_pk_bf16_f32 v16, v28, v29
	v_cvt_pk_bf16_f32 v17, v30, v31
	v_cvt_pk_bf16_f32 v18, v24, v25
	v_cvt_pk_bf16_f32 v19, v26, v27
	v_cvt_pk_bf16_f32 v20, v20, v21
	v_cvt_pk_bf16_f32 v21, v22, v23
	v_cvt_pk_bf16_f32 v22, v34, v35
	v_cvt_pk_bf16_f32 v23, v36, v37
	global_store_dwordx4 v[32:33], v[16:19], off
	global_store_dwordx4 v[32:33], v[20:23], off offset:256
	s_nop 0
	v_add_u32_e32 v17, 0xb0, v144
	s_nop 0
	v_fmamk_f32 v16, v249, 0x3a000000, v158
	v_rsq_f32_e32 v252, v16
	s_nop 0
	v_mul_f32_e32 v252, v252, v145
	v_mad_i64_i32 v[16:17], s[4:5], v17, s82, v[148:149]
	v_lshl_add_u64 v[16:17], v[16:17], 0, v[146:147]
	v_mul_f32_e64 v14, v14, v252
	v_mul_f32_e64 v15, v15, v252
	v_mul_f32_e64 v12, v12, v252
	v_mul_f32_e64 v13, v13, v252
	v_mul_f32_e64 v10, v10, v252
	v_mul_f32_e64 v11, v11, v252
	v_mul_f32_e64 v8, v8, v252
	v_mul_f32_e64 v9, v9, v252
	s_andn2_b64 vcc, exec, s[0:1]
	v_mul_f32_e64 v6, v6, v252
	v_mul_f32_e64 v7, v7, v252
	v_mul_f32_e64 v4, v4, v252
	v_mul_f32_e64 v5, v5, v252
	v_mul_f32_e64 v20, v2, v252
	v_mul_f32_e64 v21, v3, v252
	v_mul_f32_e64 v18, v0, v252
	v_mul_f32_e64 v19, v1, v252
	v_cvt_pk_bf16_f32 v0, v12, v13
	v_cvt_pk_bf16_f32 v1, v14, v15
	v_cvt_pk_bf16_f32 v2, v8, v9
	v_cvt_pk_bf16_f32 v3, v10, v11
	s_mov_b64 s[0:1], -1
	v_cvt_pk_bf16_f32 v4, v4, v5
	v_cvt_pk_bf16_f32 v5, v6, v7
	v_cvt_pk_bf16_f32 v6, v18, v19
	v_cvt_pk_bf16_f32 v7, v20, v21
	global_store_dwordx4 v[16:17], v[0:3], off
	global_store_dwordx4 v[16:17], v[4:7], off offset:256
	s_cbranch_vccnz .LBB0_148
	s_andn2_b64 vcc, exec, s[10:11]
	s_cbranch_vccnz .LBB0_147
	s_barrier
	s_branch .LBB0_147

.LBB0_216:
	v_mov_b32_e32 v32, v109
	v_and_b32_e32 v70, 63, v108
	v_nop
	v_nop
	v_permlane32_swap_b32 v109, v32
	s_lshl_b32 s6, s45, 6
	v_add_f32_e32 v71, v109, v32
	v_ashrrev_i32_e32 v32, 31, v70
	v_lshrrev_b32_e32 v32, 29, v32
	v_add_u32_e32 v32, v70, v32
	v_ashrrev_i32_e32 v72, 3, v32
	v_and_b32_e32 v32, -8, v32
	v_ashrrev_i32_e32 v73, 31, v72
	v_sub_u32_e32 v75, v70, v32
	v_lshl_add_u64 v[64:65], s[24:25], 0, v[72:73]
	v_mov_b64_e32 v[32:33], s[4:5]
	v_mad_u64_u32 v[34:35], s[26:27], v64, s44, v[32:33]
	v_mov_b32_e32 v36, v35
	v_mad_u64_u32 v[36:37], s[26:27], v65, s44, v[36:37]
	v_mov_b32_e32 v35, v36
	v_lshlrev_b32_e32 v36, 3, v75
	v_ashrrev_i32_e32 v37, 31, v36
	v_lshlrev_b64 v[66:67], 1, v[36:37]
	v_add_u32_e32 v36, 64, v70
	v_ashrrev_i32_e32 v37, 31, v36
	v_lshrrev_b32_e32 v37, 29, v37
	v_add_u32_e32 v37, v36, v37
	v_ashrrev_i32_e32 v68, 3, v37
	v_ashrrev_i32_e32 v69, 31, v68
	v_and_b32_e32 v37, -8, v37
	v_lshl_add_u64 v[58:59], s[24:25], 0, v[68:69]
	v_sub_u32_e32 v73, v36, v37
	v_mad_u64_u32 v[36:37], s[26:27], v58, s44, v[32:33]
	v_mov_b32_e32 v38, v37
	s_lshl_b32 s6, s6, 1
	v_mad_u64_u32 v[38:39], s[26:27], v59, s44, v[38:39]
	v_lshl_add_u64 v[34:35], v[34:35], 0, s[6:7]
	v_mov_b32_e32 v37, v38
	v_lshlrev_b32_e32 v38, 3, v73
	v_lshl_add_u64 v[34:35], v[34:35], 0, v[66:67]
	v_ashrrev_i32_e32 v39, 31, v38
	v_add_co_u32_e32 v34, vcc, s64, v34
	v_lshl_add_u64 v[36:37], v[36:37], 0, s[6:7]
	v_lshlrev_b64 v[60:61], 1, v[38:39]
	v_addc_co_u32_e32 v35, vcc, 0, v35, vcc
	v_lshl_add_u64 v[36:37], v[36:37], 0, v[60:61]
	v_add_co_u32_e32 v36, vcc, s64, v36
	s_mulk_i32 s69, 0x1200
	s_nop 0
	v_addc_co_u32_e32 v37, vcc, 0, v37, vcc
	global_load_dwordx4 v[44:47], v[34:35], off
	global_load_dwordx4 v[40:43], v[36:37], off
	v_add_u32_e32 v34, 0x80, v70
	v_ashrrev_i32_e32 v35, 31, v34
	v_lshrrev_b32_e32 v35, 29, v35
	v_add_u32_e32 v35, v34, v35
	v_ashrrev_i32_e32 v62, 3, v35
	v_ashrrev_i32_e32 v63, 31, v62
	v_and_b32_e32 v35, -8, v35
	v_lshl_add_u64 v[52:53], s[24:25], 0, v[62:63]
	v_sub_u32_e32 v69, v34, v35
	v_mad_u64_u32 v[34:35], s[26:27], v52, s44, v[32:33]
	v_mov_b32_e32 v36, v35
	v_mad_u64_u32 v[36:37], s[26:27], v53, s44, v[36:37]
	v_mov_b32_e32 v35, v36
	v_lshlrev_b32_e32 v36, 3, v69
	v_ashrrev_i32_e32 v37, 31, v36
	v_lshlrev_b64 v[54:55], 1, v[36:37]
	v_add_u32_e32 v36, 0xc0, v70
	v_ashrrev_i32_e32 v37, 31, v36
	v_lshrrev_b32_e32 v37, 29, v37
	v_add_u32_e32 v37, v36, v37
	v_ashrrev_i32_e32 v56, 3, v37
	v_ashrrev_i32_e32 v57, 31, v56
	v_lshl_add_u64 v[48:49], s[24:25], 0, v[56:57]
	v_and_b32_e32 v37, -8, v37
	v_mad_u64_u32 v[32:33], s[24:25], v48, s44, v[32:33]
	v_sub_u32_e32 v63, v36, v37
	v_mov_b32_e32 v36, v33
	v_mad_u64_u32 v[36:37], s[24:25], v49, s44, v[36:37]
	v_lshl_add_u64 v[34:35], v[34:35], 0, s[6:7]
	v_mov_b32_e32 v33, v36
	v_lshlrev_b32_e32 v36, 3, v63
	v_div_scale_f32 v57, s[24:25], v71, v71, 1.0
	v_lshl_add_u64 v[34:35], v[34:35], 0, v[54:55]
	v_ashrrev_i32_e32 v37, 31, v36
	v_rcp_f32_e32 v74, v57
	v_add_co_u32_e32 v34, vcc, s64, v34
	v_lshl_add_u64 v[32:33], v[32:33], 0, s[6:7]
	v_lshlrev_b64 v[50:51], 1, v[36:37]
	v_addc_co_u32_e32 v35, vcc, 0, v35, vcc
	v_lshl_add_u64 v[32:33], v[32:33], 0, v[50:51]
	v_add_co_u32_e32 v32, vcc, s64, v32
	v_fma_f32 v76, -v57, v74, 1.0
	s_nop 0
	v_addc_co_u32_e32 v33, vcc, 0, v33, vcc
	v_fmac_f32_e32 v74, v76, v74
	v_div_scale_f32 v76, vcc, 1.0, v71, 1.0
	v_mul_f32_e32 v77, v76, v74
	v_fma_f32 v78, -v57, v77, v76
	v_fmac_f32_e32 v77, v78, v74
	v_fma_f32 v57, -v57, v77, v76
	v_div_fmas_f32 v57, v57, v74, v77
	v_div_fixup_f32 v74, v57, v71, 1.0
	v_mul_f32_e64 v16, v16, v74
	v_mul_f32_e64 v17, v17, v74
	v_mul_f32_e64 v18, v18, v74
	v_mul_f32_e64 v19, v19, v74
	v_and_b32_e32 v57, 31, v70
	v_cvt_pk_bf16_f32 v16, v16, v17
	v_cvt_pk_bf16_f32 v17, v18, v19
	v_ashrrev_i32_e32 v18, 2, v70
	v_mul_f32_e64 v0, v0, v74
	v_mul_f32_e64 v1, v1, v74
	v_mul_f32_e64 v2, v2, v74
	v_mul_f32_e64 v3, v3, v74
	s_add_i32 s26, s69, 0
	v_mul_u32_u24_e32 v57, 0x90, v57
	v_and_b32_e32 v18, -8, v18
	v_cvt_pk_bf16_f32 v0, v0, v1
	v_cvt_pk_bf16_f32 v1, v2, v3
	v_mul_f32_e64 v2, v4, v74
	v_mul_f32_e64 v3, v5, v74
	v_mul_f32_e64 v4, v6, v74
	v_mul_f32_e64 v5, v7, v74
	v_add3_u32 v57, s26, v57, v18
	v_cvt_pk_bf16_f32 v2, v2, v3
	v_cvt_pk_bf16_f32 v3, v4, v5
	global_load_dwordx4 v[36:39], v[34:35], off
	s_nop 0
	global_load_dwordx4 v[32:35], v[32:33], off
	ds_write2_b64 v57, v[0:1], v[2:3] offset0:8 offset1:10
	v_mul_f32_e64 v0, v8, v74
	v_mul_f32_e64 v1, v9, v74
	v_mul_f32_e64 v2, v10, v74
	v_mul_f32_e64 v3, v11, v74
	v_mul_f32_e64 v18, v20, v74
	v_mul_f32_e64 v19, v21, v74
	v_mul_f32_e64 v20, v22, v74
	v_mul_f32_e64 v21, v23, v74
	v_cvt_pk_bf16_f32 v0, v0, v1
	v_cvt_pk_bf16_f32 v1, v2, v3
	v_mul_f32_e64 v2, v12, v74
	v_mul_f32_e64 v3, v13, v74
	v_mul_f32_e64 v4, v14, v74
	v_mul_f32_e64 v5, v15, v74
	v_cvt_pk_bf16_f32 v18, v18, v19
	v_cvt_pk_bf16_f32 v19, v20, v21
	v_cvt_pk_bf16_f32 v2, v2, v3
	v_cvt_pk_bf16_f32 v3, v4, v5
	ds_write2_b64 v57, v[16:17], v[18:19] offset1:2
	v_mul_f32_e64 v16, v24, v74
	v_mul_f32_e64 v17, v25, v74
	v_mul_f32_e64 v18, v26, v74
	v_mul_f32_e64 v19, v27, v74
	ds_write2_b64 v57, v[0:1], v[2:3] offset0:12 offset1:14
	v_mul_lo_u32 v0, v72, s60
	v_lshlrev_b32_e32 v1, 4, v75
	s_waitcnt vmcnt(3)
	v_lshlrev_b32_e32 v8, 16, v44
	v_cvt_pk_bf16_f32 v16, v16, v17
	v_cvt_pk_bf16_f32 v17, v18, v19
	v_mul_f32_e64 v18, v28, v74
	v_mul_f32_e64 v19, v29, v74
	v_mul_f32_e64 v20, v30, v74
	v_mul_f32_e64 v21, v31, v74
	v_add3_u32 v0, s26, v0, v1
	v_and_b32_e32 v11, 0xffff0000, v44
	v_mul_f32_e32 v1, 0xbfb8aa3b, v8
	v_cvt_pk_bf16_f32 v18, v18, v19
	v_cvt_pk_bf16_f32 v19, v20, v21
	v_exp_f32_e32 v4, v1
	v_mul_f32_e32 v1, 0xbfb8aa3b, v11
	ds_write2_b64 v57, v[16:17], v[18:19] offset0:4 offset1:6
	v_exp_f32_e32 v5, v1
	s_waitcnt lgkmcnt(0)
	ds_read_b128 v[0:3], v0
	v_add_f32_e32 v4, 1.0, v4
	v_rcp_f32_e32 v12, v4
	v_add_f32_e32 v4, 1.0, v5
	v_rcp_f32_e32 v13, v4
	v_mul_lo_u32 v4, v68, s60
	v_lshlrev_b32_e32 v5, 4, v73
	v_add3_u32 v4, s26, v4, v5
	ds_read_b128 v[4:7], v4
	s_waitcnt lgkmcnt(1)
	v_and_b32_e32 v9, 0xffff0000, v0
	v_lshlrev_b32_e32 v10, 16, v0
	v_mul_f32_e64 v8, v10, v8
	v_mul_f32_e64 v9, v11, v9
	v_lshlrev_b32_e32 v10, 16, v45
	v_mul_f32_e64 v8, v12, v8
	v_mul_f32_e64 v9, v13, v9
	v_and_b32_e32 v13, 0xffff0000, v45
	v_mul_f32_e32 v0, 0xbfb8aa3b, v10
	v_exp_f32_e32 v11, v0
	v_mul_f32_e32 v0, 0xbfb8aa3b, v13
	v_exp_f32_e32 v12, v0
	v_cvt_pk_bf16_f32 v0, v8, v9
	v_add_f32_e32 v8, 1.0, v11
	v_rcp_f32_e32 v8, v8
	v_add_f32_e32 v9, 1.0, v12
	v_rcp_f32_e32 v9, v9
	v_and_b32_e32 v11, 0xffff0000, v1
	v_lshlrev_b32_e32 v12, 16, v1
	v_mul_f32_e64 v10, v12, v10
	v_mul_f32_e64 v11, v13, v11
	v_and_b32_e32 v13, 0xffff0000, v46
	v_mul_f32_e64 v8, v8, v10
	v_mul_f32_e64 v9, v9, v11
	v_lshlrev_b32_e32 v10, 16, v46
	v_mul_f32_e32 v1, 0xbfb8aa3b, v10
	v_exp_f32_e32 v11, v1
	v_mul_f32_e32 v1, 0xbfb8aa3b, v13
	v_exp_f32_e32 v12, v1
	v_cvt_pk_bf16_f32 v1, v8, v9
	v_add_f32_e32 v8, 1.0, v11
	v_rcp_f32_e32 v8, v8
	v_add_f32_e32 v9, 1.0, v12
	v_rcp_f32_e32 v9, v9
	v_and_b32_e32 v11, 0xffff0000, v2
	v_lshlrev_b32_e32 v12, 16, v2
	v_mul_f32_e64 v10, v12, v10
	v_mul_f32_e64 v11, v13, v11
	v_and_b32_e32 v13, 0xffff0000, v47
	v_mul_f32_e64 v8, v8, v10
	v_mul_f32_e64 v9, v9, v11
	v_lshlrev_b32_e32 v10, 16, v47
	v_mul_f32_e32 v2, 0xbfb8aa3b, v10
	v_exp_f32_e32 v11, v2
	v_mul_f32_e32 v2, 0xbfb8aa3b, v13
	v_exp_f32_e32 v12, v2
	v_cvt_pk_bf16_f32 v2, v8, v9
	v_add_f32_e32 v8, 1.0, v11
	v_rcp_f32_e32 v8, v8
	v_add_f32_e32 v9, 1.0, v12
	v_rcp_f32_e32 v9, v9
	v_and_b32_e32 v11, 0xffff0000, v3
	v_lshlrev_b32_e32 v12, 16, v3
	v_mul_f32_e64 v10, v12, v10
	v_mul_f32_e64 v11, v13, v11
	s_waitcnt vmcnt(2)
	v_and_b32_e32 v13, 0xffff0000, v40
	v_mul_f32_e64 v8, v8, v10
	v_mul_f32_e64 v9, v9, v11
	v_lshlrev_b32_e32 v10, 16, v40
	v_mul_f32_e32 v11, 0xbfb8aa3b, v10
	v_mul_f32_e32 v12, 0xbfb8aa3b, v13
	s_add_u32 s24, s11, s6
	v_exp_f32_e32 v11, v11
	v_exp_f32_e32 v12, v12
	s_addc_u32 s25, s33, 0
	v_cvt_pk_bf16_f32 v3, v8, v9
	v_lshlrev_b64 v[8:9], 12, v[64:65]
	v_lshl_add_u64 v[8:9], s[24:25], 0, v[8:9]
	v_lshl_add_u64 v[8:9], v[8:9], 0, v[66:67]
	global_store_dwordx4 v[8:9], v[0:3], off
	v_and_b32_e32 v9, 0xffff0000, v41
	s_waitcnt lgkmcnt(0)
	v_lshlrev_b32_e32 v8, 16, v5
	v_add_f32_e32 v0, 1.0, v11
	v_add_f32_e32 v1, 1.0, v12
	v_rcp_f32_e32 v0, v0
	v_rcp_f32_e32 v1, v1
	v_and_b32_e32 v11, 0xffff0000, v4
	v_lshlrev_b32_e32 v12, 16, v4
	v_mul_f32_e64 v2, v12, v10
	v_mul_f32_e64 v3, v13, v11
	v_mul_f32_e32 v4, 0xbfb8aa3b, v9
	v_mul_f32_e64 v0, v0, v2
	v_mul_f32_e64 v1, v1, v3
	v_lshlrev_b32_e32 v2, 16, v41
	v_mul_f32_e32 v3, 0xbfb8aa3b, v2
	v_exp_f32_e32 v3, v3
	v_exp_f32_e32 v4, v4
	v_cvt_pk_bf16_f32 v0, v0, v1
	s_add_i32 s68, s68, s58
	v_add_f32_e32 v1, 1.0, v3
	v_rcp_f32_e32 v10, v1
	v_add_f32_e32 v1, 1.0, v4
	v_and_b32_e32 v3, 0xffff0000, v5
	v_lshlrev_b32_e32 v4, 16, v42
	v_rcp_f32_e32 v11, v1
	v_mul_f32_e64 v2, v8, v2
	v_mul_f32_e64 v3, v9, v3
	v_and_b32_e32 v9, 0xffff0000, v42
	v_mul_f32_e32 v1, 0xbfb8aa3b, v4
	v_exp_f32_e32 v5, v1
	v_mul_f32_e32 v1, 0xbfb8aa3b, v9
	v_exp_f32_e32 v8, v1
	v_mul_f32_e64 v2, v10, v2
	v_mul_f32_e64 v3, v11, v3
	s_add_i32 s65, s65, s58
	v_cvt_pk_bf16_f32 v1, v2, v3
	v_add_f32_e32 v2, 1.0, v5
	v_add_f32_e32 v3, 1.0, v8
	v_rcp_f32_e32 v2, v2
	v_rcp_f32_e32 v3, v3
	v_and_b32_e32 v5, 0xffff0000, v6
	v_lshlrev_b32_e32 v8, 16, v6
	v_mul_f32_e64 v4, v8, v4
	v_mul_f32_e64 v5, v9, v5
	v_and_b32_e32 v9, 0xffff0000, v43
	v_mul_f32_e64 v2, v2, v4
	v_mul_f32_e64 v3, v3, v5
	v_lshlrev_b32_e32 v4, 16, v43
	v_mul_f32_e32 v5, 0xbfb8aa3b, v4
	v_exp_f32_e32 v5, v5
	v_mul_f32_e32 v6, 0xbfb8aa3b, v9
	v_exp_f32_e32 v6, v6
	v_cvt_pk_bf16_f32 v2, v2, v3
	v_add_f32_e32 v3, 1.0, v5
	v_rcp_f32_e32 v10, v3
	v_add_f32_e32 v3, 1.0, v6
	v_rcp_f32_e32 v11, v3
	v_and_b32_e32 v5, 0xffff0000, v7
	v_lshlrev_b32_e32 v8, 16, v7
	v_mul_f32_e64 v4, v8, v4
	v_mul_f32_e64 v5, v9, v5
	s_waitcnt vmcnt(2)
	v_lshlrev_b32_e32 v8, 16, v36
	v_mul_f32_e64 v4, v10, v4
	v_mul_f32_e64 v5, v11, v5
	v_and_b32_e32 v11, 0xffff0000, v36
	v_cvt_pk_bf16_f32 v3, v4, v5
	v_lshlrev_b64 v[4:5], 12, v[58:59]
	v_lshl_add_u64 v[4:5], s[24:25], 0, v[4:5]
	v_lshl_add_u64 v[4:5], v[4:5], 0, v[60:61]
	global_store_dwordx4 v[4:5], v[0:3], off
	s_cmpk_gt_i32 s68, 0x3ff
	s_nop 0
	v_mul_lo_u32 v0, v62, s60
	v_lshlrev_b32_e32 v1, 4, v69
	v_add3_u32 v0, s26, v0, v1
	v_mul_f32_e32 v1, 0xbfb8aa3b, v8
	v_exp_f32_e32 v4, v1
	v_mul_f32_e32 v1, 0xbfb8aa3b, v11
	v_exp_f32_e32 v5, v1
	ds_read_b128 v[0:3], v0
	v_add_f32_e32 v4, 1.0, v4
	v_rcp_f32_e32 v12, v4
	v_add_f32_e32 v4, 1.0, v5
	v_rcp_f32_e32 v13, v4
	v_mul_lo_u32 v4, v56, s60
	v_lshlrev_b32_e32 v5, 4, v63
	v_add3_u32 v4, s26, v4, v5
	ds_read_b128 v[4:7], v4
	s_waitcnt lgkmcnt(1)
	v_and_b32_e32 v9, 0xffff0000, v0
	v_lshlrev_b32_e32 v10, 16, v0
	v_mul_f32_e64 v8, v10, v8
	v_mul_f32_e64 v9, v11, v9
	v_lshlrev_b32_e32 v10, 16, v37
	v_mul_f32_e64 v8, v12, v8
	v_mul_f32_e64 v9, v13, v9
	v_and_b32_e32 v13, 0xffff0000, v37
	v_mul_f32_e32 v0, 0xbfb8aa3b, v10
	v_exp_f32_e32 v11, v0
	v_mul_f32_e32 v0, 0xbfb8aa3b, v13
	v_exp_f32_e32 v12, v0
	v_cvt_pk_bf16_f32 v0, v8, v9
	v_add_f32_e32 v8, 1.0, v11
	v_rcp_f32_e32 v8, v8
	v_add_f32_e32 v9, 1.0, v12
	v_rcp_f32_e32 v9, v9
	v_and_b32_e32 v11, 0xffff0000, v1
	v_lshlrev_b32_e32 v12, 16, v1
	v_mul_f32_e64 v10, v12, v10
	v_mul_f32_e64 v11, v13, v11
	v_and_b32_e32 v13, 0xffff0000, v38
	v_mul_f32_e64 v8, v8, v10
	v_mul_f32_e64 v9, v9, v11
	v_lshlrev_b32_e32 v10, 16, v38
	v_mul_f32_e32 v1, 0xbfb8aa3b, v10
	v_exp_f32_e32 v11, v1
	v_mul_f32_e32 v1, 0xbfb8aa3b, v13
	v_exp_f32_e32 v12, v1
	v_cvt_pk_bf16_f32 v1, v8, v9
	v_add_f32_e32 v8, 1.0, v11
	v_rcp_f32_e32 v8, v8
	v_add_f32_e32 v9, 1.0, v12
	v_rcp_f32_e32 v9, v9
	v_and_b32_e32 v11, 0xffff0000, v2
	v_lshlrev_b32_e32 v12, 16, v2
	v_mul_f32_e64 v10, v12, v10
	v_mul_f32_e64 v11, v13, v11
	v_and_b32_e32 v13, 0xffff0000, v39
	v_mul_f32_e64 v8, v8, v10
	v_mul_f32_e64 v9, v9, v11
	v_lshlrev_b32_e32 v10, 16, v39
	v_mul_f32_e32 v2, 0xbfb8aa3b, v10
	v_exp_f32_e32 v11, v2
	v_mul_f32_e32 v2, 0xbfb8aa3b, v13
	v_exp_f32_e32 v12, v2
	v_cvt_pk_bf16_f32 v2, v8, v9
	v_add_f32_e32 v8, 1.0, v11
	v_rcp_f32_e32 v8, v8
	v_add_f32_e32 v9, 1.0, v12
	v_rcp_f32_e32 v9, v9
	v_and_b32_e32 v11, 0xffff0000, v3
	v_lshlrev_b32_e32 v12, 16, v3
	v_mul_f32_e64 v10, v12, v10
	v_mul_f32_e64 v11, v13, v11
	s_waitcnt vmcnt(2)
	v_and_b32_e32 v13, 0xffff0000, v32
	v_mul_f32_e64 v8, v8, v10
	v_mul_f32_e64 v9, v9, v11
	v_lshlrev_b32_e32 v10, 16, v32
	v_mul_f32_e32 v11, 0xbfb8aa3b, v10
	v_mul_f32_e32 v12, 0xbfb8aa3b, v13
	v_exp_f32_e32 v11, v11
	v_exp_f32_e32 v12, v12
	v_cvt_pk_bf16_f32 v3, v8, v9
	v_lshlrev_b64 v[8:9], 12, v[52:53]
	v_lshl_add_u64 v[8:9], s[24:25], 0, v[8:9]
	v_lshl_add_u64 v[8:9], v[8:9], 0, v[54:55]
	global_store_dwordx4 v[8:9], v[0:3], off
	v_and_b32_e32 v9, 0xffff0000, v33
	s_waitcnt lgkmcnt(0)
	v_lshlrev_b32_e32 v8, 16, v5
	v_add_f32_e32 v0, 1.0, v11
	v_add_f32_e32 v1, 1.0, v12
	v_rcp_f32_e32 v0, v0
	v_rcp_f32_e32 v1, v1
	v_and_b32_e32 v11, 0xffff0000, v4
	v_lshlrev_b32_e32 v12, 16, v4
	v_mul_f32_e64 v2, v12, v10
	v_mul_f32_e64 v3, v13, v11
	v_mul_f32_e32 v4, 0xbfb8aa3b, v9
	v_mul_f32_e64 v0, v0, v2
	v_mul_f32_e64 v1, v1, v3
	v_lshlrev_b32_e32 v2, 16, v33
	v_mul_f32_e32 v3, 0xbfb8aa3b, v2
	v_exp_f32_e32 v3, v3
	v_exp_f32_e32 v4, v4
	v_cvt_pk_bf16_f32 v0, v0, v1
	v_add_f32_e32 v1, 1.0, v3
	v_rcp_f32_e32 v10, v1
	v_add_f32_e32 v1, 1.0, v4
	v_and_b32_e32 v3, 0xffff0000, v5
	v_lshlrev_b32_e32 v4, 16, v34
	v_rcp_f32_e32 v11, v1
	v_mul_f32_e64 v2, v8, v2
	v_mul_f32_e64 v3, v9, v3
	v_and_b32_e32 v9, 0xffff0000, v34
	v_mul_f32_e32 v1, 0xbfb8aa3b, v4
	v_exp_f32_e32 v5, v1
	v_mul_f32_e32 v1, 0xbfb8aa3b, v9
	v_exp_f32_e32 v8, v1
	v_mul_f32_e64 v2, v10, v2
	v_mul_f32_e64 v3, v11, v3
	s_nop 0
	v_cvt_pk_bf16_f32 v1, v2, v3
	v_add_f32_e32 v2, 1.0, v5
	v_add_f32_e32 v3, 1.0, v8
	v_rcp_f32_e32 v2, v2
	v_rcp_f32_e32 v3, v3
	v_and_b32_e32 v5, 0xffff0000, v6
	v_lshlrev_b32_e32 v8, 16, v6
	v_mul_f32_e64 v4, v8, v4
	v_mul_f32_e64 v5, v9, v5
	v_and_b32_e32 v9, 0xffff0000, v35
	v_mul_f32_e64 v2, v2, v4
	v_mul_f32_e64 v3, v3, v5
	v_lshlrev_b32_e32 v4, 16, v35
	v_mul_f32_e32 v5, 0xbfb8aa3b, v4
	v_exp_f32_e32 v5, v5
	v_mul_f32_e32 v6, 0xbfb8aa3b, v9
	v_exp_f32_e32 v6, v6
	v_cvt_pk_bf16_f32 v2, v2, v3
	v_add_f32_e32 v3, 1.0, v5
	v_rcp_f32_e32 v10, v3
	v_add_f32_e32 v3, 1.0, v6
	v_rcp_f32_e32 v11, v3
	v_and_b32_e32 v5, 0xffff0000, v7
	v_lshlrev_b32_e32 v8, 16, v7
	v_mul_f32_e64 v4, v8, v4
	v_mul_f32_e64 v5, v9, v5
	s_nop 0
	v_mul_f32_e64 v4, v10, v4
	v_mul_f32_e64 v5, v11, v5
	s_nop 0
	v_cvt_pk_bf16_f32 v3, v4, v5
	v_lshlrev_b64 v[4:5], 12, v[48:49]
	v_lshl_add_u64 v[4:5], s[24:25], 0, v[4:5]
	v_lshl_add_u64 v[4:5], v[4:5], 0, v[50:51]
	global_store_dwordx4 v[4:5], v[0:3], off
	s_barrier
	s_cbranch_scc1 .LBB0_241

.LBB0_221:
	v_add_u32_e32 v16, s73, v8
	v_add_u32_e32 v18, s73, v9
	v_add_u32_e32 v20, s74, v8
	v_add_u32_e32 v22, s75, v9
	v_add_u32_e32 v24, s76, v8
	v_add_u32_e32 v26, s77, v9
	v_add_u32_e32 v28, s78, v8
	v_add_u32_e32 v30, s79, v9
	v_ashrrev_i32_e32 v19, 31, v18
	v_ashrrev_i32_e32 v17, 31, v16
	v_ashrrev_i32_e32 v23, 31, v22
	v_ashrrev_i32_e32 v21, 31, v20
	v_ashrrev_i32_e32 v27, 31, v26
	v_ashrrev_i32_e32 v25, 31, v24
	v_ashrrev_i32_e32 v31, 31, v30
	v_ashrrev_i32_e32 v29, 31, v28
	v_lshl_add_u64 v[16:17], v[16:17], 2, s[42:43]
	v_lshl_add_u64 v[18:19], v[18:19], 2, s[42:43]
	v_lshl_add_u64 v[20:21], v[20:21], 2, s[42:43]
	v_lshl_add_u64 v[22:23], v[22:23], 2, s[42:43]
	v_lshl_add_u64 v[24:25], v[24:25], 2, s[42:43]
	v_lshl_add_u64 v[26:27], v[26:27], 2, s[42:43]
	v_lshl_add_u64 v[28:29], v[28:29], 2, s[42:43]
	v_lshl_add_u64 v[30:31], v[30:31], 2, s[42:43]
	global_load_dword v16, v[16:17], off
	s_nop 0
	global_load_dword v17, v[18:19], off
	s_nop 0
	global_load_dword v18, v[20:21], off
	global_load_dword v19, v[22:23], off
	s_nop 0
	global_load_dword v20, v[24:25], off
	global_load_dword v21, v[26:27], off
	global_load_dword v22, v[28:29], off
	global_load_dword v23, v[30:31], off
	v_add_u32_e32 v13, -4, v13
	s_add_i32 s80, s80, 8
	v_cmp_eq_u32_e32 vcc, 0, v13
	v_add_u32_e32 v9, 0x1000, v9
	v_add_u32_e32 v8, 0x1000, v8
	v_mov_b32_e32 v15, s80
	s_or_b64 s[40:41], vcc, s[40:41]
	s_waitcnt vmcnt(6)
	v_mul_f32_e64 v16, v16, s10
	v_mul_f32_e64 v17, v17, s10
	s_waitcnt vmcnt(4)
	v_mul_f32_e64 v18, v18, s10
	v_mul_f32_e64 v19, v19, s10
	s_waitcnt vmcnt(2)
	v_mul_f32_e64 v20, v20, s10
	v_mul_f32_e64 v21, v21, s10
	s_waitcnt vmcnt(0)
	v_mul_f32_e64 v22, v22, s10
	v_mul_f32_e64 v23, v23, s10
	ds_write2st64_b32 v14, v16, v17 offset1:8
	ds_write2st64_b32 v14, v18, v19 offset0:16 offset1:24
	ds_write2st64_b32 v14, v20, v21 offset0:32 offset1:40
	ds_write2st64_b32 v14, v22, v23 offset0:48 offset1:56
	v_add_u32_e32 v14, 0x4000, v14
	s_andn2_b64 exec, exec, s[40:41]
	s_cbranch_execnz .LBB0_221
	s_or_b64 exec, exec, s[40:41]

.LBB0_225:
	v_add_u32_e32 v14, s73, v8
	v_add_u32_e32 v16, s73, v9
	v_ashrrev_i32_e32 v15, 31, v14
	v_ashrrev_i32_e32 v17, 31, v16
	v_lshl_add_u64 v[14:15], v[14:15], 2, s[42:43]
	v_lshl_add_u64 v[16:17], v[16:17], 2, s[42:43]
	global_load_dword v14, v[14:15], off
	s_nop 0
	global_load_dword v15, v[16:17], off
	v_add_u32_e32 v12, -1, v12
	v_cmp_eq_u32_e32 vcc, 0, v12
	v_add_u32_e32 v9, 0x400, v9
	v_add_u32_e32 v8, 0x400, v8
	s_or_b64 s[40:41], vcc, s[40:41]
	s_waitcnt vmcnt(0)
	v_mul_f32_e64 v14, v14, s10
	v_mul_f32_e64 v15, v15, s10
	ds_write2st64_b32 v13, v14, v15 offset1:8
	v_add_u32_e32 v13, 0x1000, v13
	s_andn2_b64 exec, exec, s[40:41]
	s_cbranch_execnz .LBB0_225

.LBB0_232:
	s_nop 2
	v_sub_f32_e32 v32, v32, v119
	v_exp_f32_e32 v94, v32
	v_sub_f32_e32 v32, v48, v119
	v_exp_f32_e32 v95, v32
	v_sub_f32_e32 v32, v33, v119
	v_exp_f32_e32 v106, v32
	v_sub_f32_e32 v32, v49, v119
	v_exp_f32_e32 v48, v32
	v_add_f32_e32 v49, v95, v94
	v_add_f32_e64 v32, v48, v106
	v_add_f32_e64 v33, v49, v107
	s_nop 0
	v_add_f32_e64 v88, v32, v32
	v_add_f32_e64 v89, v32, v33
	v_sub_f32_e32 v32, v34, v119
	v_exp_f32_e32 v49, v32
	v_sub_f32_e32 v32, v50, v119
	v_exp_f32_e32 v96, v32
	v_sub_f32_e32 v32, v35, v119
	v_exp_f32_e32 v88, v32
	v_sub_f32_e32 v32, v51, v119
	v_exp_f32_e32 v50, v32
	v_add_f32_e32 v51, v96, v49
	v_add_f32_e64 v32, v50, v88
	v_add_f32_e64 v33, v51, v89
	s_nop 0
	v_add_f32_e64 v34, v32, v32
	v_add_f32_e64 v35, v32, v33
	v_sub_f32_e32 v32, v36, v119
	v_exp_f32_e32 v51, v32
	v_sub_f32_e32 v32, v52, v119
	v_exp_f32_e32 v89, v32
	v_sub_f32_e32 v32, v37, v119
	v_exp_f32_e32 v34, v32
	v_sub_f32_e32 v32, v53, v119
	v_exp_f32_e32 v52, v32
	v_add_f32_e32 v53, v89, v51
	v_add_f32_e64 v32, v52, v34
	v_add_f32_e64 v33, v53, v35
	s_nop 0
	v_add_f32_e64 v36, v32, v32
	v_add_f32_e64 v37, v32, v33
	v_sub_f32_e32 v32, v38, v119
	v_exp_f32_e32 v35, v32
	v_sub_f32_e32 v32, v54, v119
	v_exp_f32_e32 v53, v32
	v_sub_f32_e32 v32, v39, v119
	v_exp_f32_e32 v36, v32
	v_sub_f32_e32 v32, v55, v119
	v_exp_f32_e32 v54, v32
	v_add_f32_e32 v55, v53, v35
	v_cvt_pk_bf16_f32 v34, v51, v34
	v_cvt_pk_bf16_f32 v35, v35, v36
	v_add_f32_e64 v32, v54, v36
	v_add_f32_e64 v33, v55, v37
	v_cvt_pk_bf16_f32 v36, v95, v48
	v_add_f32_e64 v90, v32, v32
	v_add_f32_e64 v91, v32, v33
	v_sub_f32_e32 v32, v40, v119
	v_exp_f32_e32 v40, v32
	v_sub_f32_e32 v32, v56, v119
	v_exp_f32_e32 v55, v32
	v_sub_f32_e32 v32, v41, v119
	v_exp_f32_e32 v90, v32
	v_sub_f32_e32 v32, v57, v119
	v_exp_f32_e32 v56, v32
	v_add_f32_e32 v57, v55, v40
	v_cvt_pk_bf16_f32 v37, v96, v50
	v_cvt_pk_bf16_f32 v38, v89, v52
	v_add_f32_e64 v32, v56, v90
	v_add_f32_e64 v33, v57, v91
	v_cvt_pk_bf16_f32 v39, v53, v54
	v_add_f32_e64 v92, v32, v32
	v_add_f32_e64 v93, v32, v33
	v_sub_f32_e32 v32, v42, v119
	v_exp_f32_e32 v41, v32
	v_sub_f32_e32 v32, v58, v119
	v_exp_f32_e32 v57, v32
	v_sub_f32_e32 v32, v43, v119
	v_exp_f32_e32 v92, v32
	v_sub_f32_e32 v32, v59, v119
	v_exp_f32_e32 v58, v32
	v_add_f32_e32 v59, v57, v41
	v_cvt_pk_bf16_f32 v40, v40, v90
	v_cvt_pk_bf16_f32 v41, v41, v92
	v_add_f32_e64 v32, v58, v92
	v_add_f32_e64 v33, v59, v93
	s_nop 0
	v_add_f32_e64 v42, v32, v32
	v_add_f32_e64 v43, v32, v33
	v_sub_f32_e32 v32, v44, v119
	v_exp_f32_e32 v59, v32
	v_sub_f32_e32 v32, v60, v119
	v_exp_f32_e32 v91, v32
	v_sub_f32_e32 v32, v45, v119
	v_exp_f32_e32 v42, v32
	v_sub_f32_e32 v32, v61, v119
	v_exp_f32_e32 v60, v32
	v_add_f32_e32 v61, v91, v59
	v_add_f32_e64 v32, v60, v42
	v_add_f32_e64 v33, v61, v43
	s_nop 0
	v_add_f32_e64 v44, v32, v32
	v_add_f32_e64 v45, v32, v33
	v_sub_f32_e32 v32, v46, v119
	v_exp_f32_e32 v43, v32
	v_sub_f32_e32 v32, v62, v119
	v_exp_f32_e32 v61, v32
	v_sub_f32_e32 v32, v47, v119
	v_exp_f32_e32 v44, v32
	v_sub_f32_e32 v32, v63, v119
	v_exp_f32_e32 v62, v32
	v_add_f32_e32 v63, v61, v43
	v_cvt_pk_bf16_f32 v42, v59, v42
	v_cvt_pk_bf16_f32 v43, v43, v44
	v_add_f32_e64 v32, v62, v44
	v_add_f32_e64 v33, v63, v45
	v_cvt_pk_bf16_f32 v44, v55, v56
	v_add_f32_e32 v93, v32, v33
	v_cvt_pk_bf16_f32 v32, v94, v106
	v_cvt_pk_bf16_f32 v33, v49, v88
	v_cvt_pk_bf16_f32 v45, v57, v58
	v_cvt_pk_bf16_f32 v46, v91, v60
	v_cvt_pk_bf16_f32 v47, v61, v62
	s_mulk_i32 s37, 0x3000
	v_add_u32_e32 v90, s37, v117
	ds_read_b64_tr_b16 v[48:49], v90 offset:18432
	ds_read_b64_tr_b16 v[50:51], v90 offset:19968
	ds_read_b64_tr_b16 v[52:53], v90 offset:21504
	ds_read_b64_tr_b16 v[54:55], v90 offset:23040
	ds_read_b64_tr_b16 v[56:57], v90 offset:24576
	ds_read_b64_tr_b16 v[58:59], v90 offset:26112
	ds_read_b64_tr_b16 v[60:61], v90 offset:27648
	ds_read_b64_tr_b16 v[62:63], v90 offset:29184
	s_waitcnt lgkmcnt(6)
	v_mfma_f32_32x32x16_bf16 v[16:31], v[48:51], v[32:35], v[16:31]
	s_waitcnt lgkmcnt(4)
	v_mfma_f32_32x32x16_bf16 v[16:31], v[52:55], v[40:43], v[16:31]
	s_waitcnt lgkmcnt(2)
	v_mfma_f32_32x32x16_bf16 v[16:31], v[56:59], v[36:39], v[16:31]
	ds_read_b64_tr_b16 v[48:49], v90 offset:18496
	ds_read_b64_tr_b16 v[50:51], v90 offset:20032
	ds_read_b64_tr_b16 v[52:53], v90 offset:21568
	ds_read_b64_tr_b16 v[54:55], v90 offset:23104
	ds_read_b64_tr_b16 v[56:57], v90 offset:24640
	ds_read_b64_tr_b16 v[58:59], v90 offset:26176
	ds_read_b64_tr_b16 v[88:89], v90 offset:27712
	ds_read_b64_tr_b16 v[90:91], v90 offset:29248
	s_waitcnt lgkmcnt(8)
	v_mfma_f32_32x32x16_bf16 v[16:31], v[60:63], v[44:47], v[16:31]
	s_waitcnt lgkmcnt(6)
	v_mfma_f32_32x32x16_bf16 v[0:15], v[48:51], v[32:35], v[0:15]
	s_waitcnt lgkmcnt(4)
	v_mfma_f32_32x32x16_bf16 v[0:15], v[52:55], v[40:43], v[0:15]
	s_waitcnt lgkmcnt(2)
	v_mfma_f32_32x32x16_bf16 v[0:15], v[56:59], v[36:39], v[0:15]
	s_waitcnt lgkmcnt(0)
	v_mfma_f32_32x32x16_bf16 v[0:15], v[88:91], v[44:47], v[0:15]
	v_add_f32_e32 v109, v109, v93

.LBB0_239:
	s_waitcnt lgkmcnt(1)
	s_nop 0
	v_mfma_f32_32x32x16_bf16 v[32:47], v[96:99], v[64:67], v[32:47]
	s_waitcnt lgkmcnt(0)
	v_mfma_f32_32x32x16_bf16 v[48:63], v[100:103], v[64:67], v[48:63]
	v_mfma_f32_32x32x16_bf16 v[32:47], v[92:95], v[68:71], v[32:47]
	ds_read_b128 v[92:95], v106 offset:64
	ds_read_b128 v[96:99], v106 offset:96
	ds_read_b128 v[100:103], v106 offset:4672
	ds_read_b128 v[120:123], v106 offset:4704
	v_mfma_f32_32x32x16_bf16 v[48:63], v[88:91], v[68:71], v[48:63]
	s_waitcnt lgkmcnt(3)
	v_mfma_f32_32x32x16_bf16 v[32:47], v[92:95], v[72:75], v[32:47]
	s_waitcnt lgkmcnt(1)
	v_mfma_f32_32x32x16_bf16 v[48:63], v[100:103], v[72:75], v[48:63]
	v_mfma_f32_32x32x16_bf16 v[32:47], v[96:99], v[76:79], v[32:47]
	s_waitcnt lgkmcnt(0)
	v_mfma_f32_32x32x16_bf16 v[48:63], v[120:123], v[76:79], v[48:63]
	s_nop 15
	s_nop 3
	v_max3_f32 v88, v32, v48, v33
	s_nop 0
	v_max3_f32 v88, v88, v49, v34
	s_nop 0
	v_max3_f32 v88, v88, v50, v35
	s_nop 0
	v_max3_f32 v88, v88, v51, v36
	s_nop 0
	v_max3_f32 v88, v88, v52, v37
	s_nop 0
	v_max3_f32 v88, v88, v53, v38
	s_nop 0
	v_max3_f32 v88, v88, v54, v39
	s_nop 0
	v_max3_f32 v88, v88, v55, v40
	s_nop 0
	v_max3_f32 v88, v88, v56, v41
	s_nop 0
	v_max3_f32 v88, v88, v57, v42
	s_nop 0
	v_max3_f32 v88, v88, v58, v43
	s_nop 0
	v_max3_f32 v88, v88, v59, v44
	s_nop 0
	v_max3_f32 v88, v88, v60, v45
	s_nop 0
	v_max3_f32 v88, v88, v61, v46
	s_nop 0
	v_max3_f32 v88, v88, v62, v47
	s_nop 0
	v_max_f32 v88, v88, v63
	s_nop 0
	v_mov_b32_e32 v89, v88
	v_nop
	v_nop
	v_permlane32_swap_b32 v88, v89
	s_nop 0
	v_max_f32_e32 v89, v89, v89
	v_max_f32_e32 v88, v88, v88
	v_max_f32_e32 v88, v88, v89
	v_add_f32_e32 v89, 0x42800000, v119
	v_cmp_gt_f32_e32 vcc, v88, v89
	s_cbranch_vccz .LBB0_232
	v_max_f32_e32 v88, v88, v88
	v_max_f32_e32 v89, v119, v119
	v_max_f32_e32 v89, v89, v88
	v_sub_f32_e32 v88, v119, v89
	v_exp_f32_e32 v88, v88
	v_mov_b32_e32 v119, v89
	v_mul_f32_e64 v14, v14, v88
	v_mul_f32_e64 v15, v15, v88
	v_mul_f32_e64 v12, v12, v88
	v_mul_f32_e64 v13, v13, v88
	v_mul_f32_e64 v10, v10, v88
	v_mul_f32_e64 v11, v11, v88
	v_mul_f32_e64 v8, v8, v88
	v_mul_f32_e64 v9, v9, v88
	v_mul_f32_e64 v6, v6, v88
	v_mul_f32_e64 v7, v7, v88
	v_mul_f32_e64 v4, v4, v88
	v_mul_f32_e64 v5, v5, v88
	v_mul_f32_e64 v2, v2, v88
	v_mul_f32_e64 v3, v3, v88
	v_mul_f32_e64 v0, v0, v88
	v_mul_f32_e64 v1, v1, v88
	v_mul_f32_e64 v30, v30, v88
	v_mul_f32_e64 v31, v31, v88
	v_mul_f32_e64 v28, v28, v88
	v_mul_f32_e64 v29, v29, v88
	v_mul_f32_e64 v26, v26, v88
	v_mul_f32_e64 v27, v27, v88
	v_mul_f32_e64 v24, v24, v88
	v_mul_f32_e64 v25, v25, v88
	v_mul_f32_e64 v22, v22, v88
	v_mul_f32_e64 v23, v23, v88
	v_mul_f32_e64 v20, v20, v88
	v_mul_f32_e64 v21, v21, v88
	v_mul_f32_e64 v18, v18, v88
	v_mul_f32_e64 v19, v19, v88
	v_mul_f32_e64 v16, v16, v88
	v_mul_f32_e64 v17, v17, v88
	v_mul_f32_e32 v109, v109, v88
	s_branch .LBB0_232

.LBB0_243:
	s_ashr_i32 s21, s37, 8
	s_and_b32 s39, s21, -2
	v_or_b32_e32 v0, s39, v240
	s_bfe_u32 s38, s37, 0x60003
	v_ashrrev_i32_e32 v1, 31, v0
	s_and_b32 s10, s25, 56
	s_lshl_b32 s21, s38, 6
	v_lshlrev_b64 v[32:33], 12, v[0:1]
	s_add_i32 s20, s10, s24
	v_or3_b32 v32, v32, s21, v228
	v_lshl_or_b32 v230, s20, 6, v226
	v_mad_u64_u32 v[34:35], s[40:41], v32, s27, v[236:237]
	s_lshl_b32 s10, s20, 5
	v_lshlrev_b64 v[2:3], 5, v[230:231]
	v_lshlrev_b64 v[4:5], 6, v[230:231]
	v_or_b32_e32 v230, 32, v230
	v_mad_i32_i24 v35, v33, s27, v35
	v_lshlrev_b64 v[16:17], 5, v[230:231]
	v_lshlrev_b64 v[18:19], 6, v[230:231]
	v_lshl_add_u64 v[32:33], v[34:35], 0, s[10:11]
	v_lshl_add_u64 v[2:3], s[6:7], 0, v[2:3]
	v_lshl_add_u64 v[12:13], v[232:233], 0, v[4:5]
	v_lshl_add_u64 v[4:5], v[234:235], 0, v[4:5]
	v_lshl_add_u64 v[16:17], s[6:7], 0, v[16:17]
	v_lshl_add_u64 v[20:21], v[232:233], 0, v[18:19]
	v_lshl_add_u64 v[28:29], v[234:235], 0, v[18:19]
	v_lshl_add_u64 v[68:69], v[32:33], 0, v[238:239]
	global_load_dwordx4 v[208:211], v[2:3], off
	s_nop 0
	global_load_dwordx4 v[0:3], v[4:5], off offset:16
	s_nop 0
	global_load_dwordx4 v[4:7], v[4:5], off
	s_nop 0
	global_load_dwordx4 v[8:11], v[12:13], off offset:16
	s_nop 0
	global_load_dwordx4 v[12:15], v[12:13], off
	s_nop 0
	global_load_dwordx4 v[212:215], v[16:17], off
	s_nop 0
	global_load_dwordx4 v[16:19], v[20:21], off offset:16
	s_nop 0
	global_load_dwordx4 v[20:23], v[20:21], off
	s_nop 0
	global_load_dwordx4 v[24:27], v[28:29], off offset:16
	s_nop 0
	global_load_dwordx4 v[28:31], v[28:29], off
	v_add_co_u32_e32 v32, vcc, s33, v68
	s_mov_b32 s21, s11
	s_nop 0
	v_addc_co_u32_e32 v33, vcc, 0, v69, vcc
	v_add_co_u32_e32 v34, vcc, s34, v68
	s_lshl_b64 s[20:21], s[20:21], 9
	s_nop 0
	v_addc_co_u32_e32 v35, vcc, 0, v69, vcc
	global_load_dwordx4 v[48:51], v[32:33], off offset:2048
	global_load_dwordx4 v[64:67], v[34:35], off offset:2048
	v_add_co_u32_e32 v128, vcc, s35, v68
	v_lshlrev_b32_e32 v230, 3, v226
	s_nop 0
	v_addc_co_u32_e32 v129, vcc, 0, v69, vcc
	v_add_co_u32_e32 v130, vcc, s36, v68
	s_add_i32 s37, s37, s58
	s_nop 0
	v_addc_co_u32_e32 v131, vcc, 0, v69, vcc
	global_load_dwordx4 v[168:171], v[128:129], off offset:2048
	global_load_dwordx4 v[222:225], v[130:131], off offset:2048
	s_add_i32 s25, s25, s26
	s_cmpk_lt_i32 s37, 0x400
	s_waitcnt vmcnt(13)
	v_mov_b32_e32 v32, v211
	s_waitcnt vmcnt(12)
	v_mul_f32_e64 v38, v210, v0
	v_mul_f32_e64 v39, v210, v1
	s_waitcnt vmcnt(11)
	v_mul_f32_e64 v34, v210, v4
	v_mul_f32_e64 v35, v210, v5
	v_mul_f32_e64 v36, v210, v6
	v_mul_f32_e64 v37, v210, v7
	v_mul_f32_e64 v40, v210, v2
	v_mul_f32_e64 v41, v210, v3
	v_mul_f32_e64 v4, v32, v4
	v_mul_f32_e64 v5, v32, v5
	v_mul_f32_e64 v6, v32, v6
	v_mul_f32_e64 v7, v32, v7
	v_mul_f32_e64 v0, v32, v0
	v_mul_f32_e64 v1, v32, v1
	v_mul_f32_e64 v2, v32, v2
	v_mul_f32_e64 v3, v32, v3
	s_waitcnt vmcnt(8)
	v_mov_b32_e32 v60, v215
	v_fma_f32 v52, v32, v12, v34
	v_fma_f32 v53, v32, v13, v35
	v_fma_f32 v54, v32, v14, v36
	v_fma_f32 v55, v32, v15, v37
	v_fma_f32 v56, v32, v8, v38
	v_fma_f32 v57, v32, v9, v39
	v_fma_f32 v58, v32, v10, v40
	v_fma_f32 v59, v32, v11, v41
	v_fma_f32 v4, v210, v12, -v4
	v_fma_f32 v5, v210, v13, -v5
	v_fma_f32 v6, v210, v14, -v6
	v_fma_f32 v7, v210, v15, -v7
	v_fma_f32 v0, v210, v8, -v0
	v_fma_f32 v1, v210, v9, -v1
	v_fma_f32 v2, v210, v10, -v2
	v_fma_f32 v3, v210, v11, -v3
	s_waitcnt vmcnt(4)
	v_mul_f32_e64 v8, v60, v28
	v_mul_f32_e64 v9, v60, v29
	v_mul_f32_e64 v10, v60, v30
	v_mul_f32_e64 v11, v60, v31
	v_mul_f32_e64 v12, v60, v24
	v_mul_f32_e64 v13, v60, v25
	v_mul_f32_e64 v14, v60, v26
	v_mul_f32_e64 v15, v60, v27
	v_mul_f32_e64 v62, v214, v28
	v_mul_f32_e64 v63, v214, v29
	v_mul_f32_e64 v70, v214, v30
	v_mul_f32_e64 v71, v214, v31
	v_cvt_pk_bf16_f32 v164, v4, v5
	v_cvt_pk_bf16_f32 v165, v6, v7
	v_cvt_pk_bf16_f32 v166, v0, v1
	v_cvt_pk_bf16_f32 v167, v2, v3
	v_fma_f32 v0, v214, v20, -v8
	v_fma_f32 v1, v214, v21, -v9
	v_fma_f32 v2, v214, v22, -v10
	v_fma_f32 v3, v214, v23, -v11
	v_fma_f32 v4, v214, v16, -v12
	v_fma_f32 v5, v214, v17, -v13
	v_fma_f32 v6, v214, v18, -v14
	v_fma_f32 v7, v214, v19, -v15
	v_mul_f32_e64 v24, v214, v24
	v_mul_f32_e64 v25, v214, v25
	v_mul_f32_e64 v26, v214, v26
	v_mul_f32_e64 v27, v214, v27
	v_cvt_pk_bf16_f32 v214, v52, v53
	v_cvt_pk_bf16_f32 v215, v54, v55
	v_cvt_pk_bf16_f32 v216, v56, v57
	v_cvt_pk_bf16_f32 v217, v58, v59
	v_cvt_pk_bf16_f32 v160, v0, v1
	v_cvt_pk_bf16_f32 v161, v2, v3
	v_cvt_pk_bf16_f32 v162, v4, v5
	v_cvt_pk_bf16_f32 v163, v6, v7
	s_waitcnt vmcnt(3)
	v_mfma_f32_32x32x16_bf16 v[0:15], v[48:51], v[214:217], 0
	v_fma_f32 v20, v60, v20, v62
	v_fma_f32 v21, v60, v21, v63
	v_fma_f32 v22, v60, v22, v70
	v_fma_f32 v23, v60, v23, v71
	v_fma_f32 v16, v60, v16, v24
	v_fma_f32 v17, v60, v17, v25
	v_fma_f32 v18, v60, v18, v26
	v_fma_f32 v19, v60, v19, v27
	v_pk_mul_f32 v[172:173], v[208:209], 0 op_sel_hi:[1,0]
	v_cvt_pk_bf16_f32 v218, v20, v21
	v_cvt_pk_bf16_f32 v219, v22, v23
	v_mfma_f32_32x32x16_bf16 v[80:95], v[48:51], v[164:167], 0
	v_cvt_pk_bf16_f32 v220, v16, v17
	v_cvt_pk_bf16_f32 v221, v18, v19
	v_add_f32_e32 v175, v173, v172
	v_sub_f32_e32 v174, v172, v173
	v_mul_f32_e64 v172, v212, 0
	v_mul_f32_e64 v173, v213, 0
	v_or_b32_e32 v210, s39, v229
	v_sub_f32_e32 v211, v172, v173
	s_waitcnt vmcnt(1)
	v_mfma_f32_32x32x16_bf16 v[128:143], v[168:171], v[164:167], 0
	s_nop 1
	v_add_f32_e32 v80, v174, v80
	v_add_f32_e32 v172, v173, v172
	v_mfma_f32_32x32x16_bf16 v[144:159], v[168:171], v[160:163], 0
	v_mfma_f32_32x32x16_bf16 v[176:191], v[168:171], v[214:217], 0
	v_mfma_f32_32x32x16_bf16 v[192:207], v[168:171], v[218:221], 0
	v_add_f32_e32 v168, v175, v0
	v_mul_f32_e64 v169, v208, v168
	v_mul_f32_e64 v168, v209, v168
	v_mov_b32_e32 v0, v81
	v_fma_f32 v170, v208, v80, -v168
	v_fma_f32 v171, v209, v81, -v169
	v_fma_f32 v81, v209, v80, v169
	v_fma_f32 v80, v208, v80, v168
	s_nop 0
	v_mov_b32_e32 v171, v81
	v_add_f32_e64 v0, v0, v170
	v_add_f32_e64 v1, v1, v171
	v_mfma_f32_32x32x16_bf16 v[16:31], v[48:51], v[218:221], 0
	v_mul_f32_e64 v80, v208, v0
	v_mul_f32_e64 v81, v209, v1
	v_mul_f32_e64 v0, v209, v0
	v_mul_f32_e64 v1, v208, v1
	v_sub_f32_e32 v80, v80, v81
	v_add_f32_e32 v1, v0, v1
	v_add_f32_e32 v0, v82, v80
	v_add_f32_e32 v80, v2, v1
	v_mul_f32_e64 v81, v208, v80
	v_mul_f32_e64 v80, v209, v80
	v_mov_b32_e32 v2, v83
	v_fma_f32 v82, v208, v0, -v80
	v_fma_f32 v83, v209, v1, -v81
	v_fma_f32 v1, v209, v0, v81
	v_fma_f32 v0, v208, v0, v80
	v_mfma_f32_32x32x16_bf16 v[32:47], v[48:51], v[160:163], 0
	v_mov_b32_e32 v83, v1
	v_add_f32_e64 v0, v2, v82
	v_add_f32_e64 v1, v3, v83
	v_mul_f32_e64 v2, v208, v0
	v_mul_f32_e64 v3, v209, v1
	v_mul_f32_e64 v0, v209, v0
	v_mul_f32_e64 v1, v208, v1
	v_sub_f32_e32 v2, v2, v3
	v_add_f32_e32 v1, v0, v1
	v_add_f32_e32 v0, v84, v2
	v_add_f32_e32 v2, v4, v1
	v_mul_f32_e64 v3, v208, v2
	v_mul_f32_e64 v2, v209, v2
	v_fma_f32 v80, v208, v0, -v2
	v_fma_f32 v81, v209, v1, -v3
	v_fma_f32 v1, v209, v0, v3
	v_fma_f32 v0, v208, v0, v2
	v_mov_b32_e32 v4, v85
	v_mov_b32_e32 v81, v1
	v_add_f32_e64 v0, v4, v80
	v_add_f32_e64 v1, v5, v81
	v_mfma_f32_32x32x16_bf16 v[96:111], v[64:67], v[164:167], 0
	v_mul_f32_e64 v2, v208, v0
	v_mul_f32_e64 v3, v209, v1
	v_mul_f32_e64 v0, v209, v0
	v_mul_f32_e64 v1, v208, v1
	v_sub_f32_e32 v2, v2, v3
	v_add_f32_e32 v1, v0, v1
	v_add_f32_e32 v0, v86, v2
	v_add_f32_e32 v2, v6, v1
	v_mul_f32_e64 v3, v208, v2
	v_mul_f32_e64 v2, v209, v2
	v_fma_f32 v4, v208, v0, -v2
	v_fma_f32 v5, v209, v1, -v3
	v_fma_f32 v1, v209, v0, v3
	v_fma_f32 v0, v208, v0, v2
	v_mov_b32_e32 v6, v87
	v_mov_b32_e32 v5, v1
	v_add_f32_e64 v0, v6, v4
	v_add_f32_e64 v1, v7, v5
	v_add_f32_e32 v6, v172, v16
	v_mul_f32_e64 v2, v208, v0
	v_mul_f32_e64 v3, v209, v1
	v_mul_f32_e64 v0, v209, v0
	v_mul_f32_e64 v1, v208, v1
	v_sub_f32_e32 v2, v2, v3
	v_add_f32_e32 v1, v0, v1
	v_add_f32_e32 v0, v88, v2
	v_add_f32_e32 v2, v8, v1
	v_mul_f32_e64 v3, v208, v2
	v_mul_f32_e64 v2, v209, v2
	v_fma_f32 v4, v208, v0, -v2
	v_fma_f32 v5, v209, v1, -v3
	v_fma_f32 v1, v209, v0, v3
	v_fma_f32 v0, v208, v0, v2
	v_mov_b32_e32 v8, v89
	v_mov_b32_e32 v5, v1
	v_add_f32_e64 v0, v8, v4
	v_add_f32_e64 v1, v9, v5
	v_mul_f32_e64 v7, v212, v6
	v_mul_f32_e64 v6, v213, v6
	v_mul_f32_e64 v2, v208, v0
	v_mul_f32_e64 v3, v209, v1
	v_mul_f32_e64 v0, v209, v0
	v_mul_f32_e64 v1, v208, v1
	v_sub_f32_e32 v2, v2, v3
	v_add_f32_e32 v1, v0, v1
	v_add_f32_e32 v0, v90, v2
	v_add_f32_e32 v2, v10, v1
	v_mul_f32_e64 v3, v208, v2
	v_mul_f32_e64 v2, v209, v2
	v_fma_f32 v4, v208, v0, -v2
	v_fma_f32 v5, v209, v1, -v3
	v_fma_f32 v1, v209, v0, v3
	v_fma_f32 v0, v208, v0, v2
	v_mov_b32_e32 v10, v91
	v_mov_b32_e32 v5, v1
	v_add_f32_e64 v0, v10, v4
	v_add_f32_e64 v1, v11, v5
	v_mov_b32_e32 v16, v33
	v_mul_f32_e64 v2, v208, v0
	v_mul_f32_e64 v3, v209, v1
	v_mul_f32_e64 v0, v209, v0
	v_mul_f32_e64 v1, v208, v1
	v_sub_f32_e32 v2, v2, v3
	v_add_f32_e32 v1, v0, v1
	v_add_f32_e32 v0, v92, v2
	v_add_f32_e32 v2, v12, v1
	v_mul_f32_e64 v3, v208, v2
	v_mul_f32_e64 v2, v209, v2
	v_fma_f32 v4, v208, v0, -v2
	v_fma_f32 v5, v209, v1, -v3
	v_fma_f32 v1, v209, v0, v3
	v_fma_f32 v0, v208, v0, v2
	v_mov_b32_e32 v12, v93
	v_mov_b32_e32 v5, v1
	v_add_f32_e64 v0, v12, v4
	v_add_f32_e64 v1, v13, v5
	v_add_f32_e32 v4, v211, v32
	v_fma_f32 v8, v212, v4, -v6
	v_fma_f32 v9, v213, v5, -v7
	v_fma_f32 v5, v213, v4, v7
	v_fma_f32 v4, v212, v4, v6
	v_mul_f32_e64 v2, v208, v0
	v_mul_f32_e64 v3, v209, v1
	v_mov_b32_e32 v9, v5
	v_add_f32_e64 v4, v16, v8
	v_add_f32_e64 v5, v17, v9
	v_mul_f32_e64 v0, v209, v0
	v_mul_f32_e64 v1, v208, v1
	v_mul_f32_e64 v6, v212, v4
	v_mul_f32_e64 v7, v213, v5
	v_mul_f32_e64 v4, v213, v4
	v_mul_f32_e64 v5, v212, v5
	v_sub_f32_e32 v2, v2, v3
	v_add_f32_e32 v1, v0, v1
	v_add_f32_e32 v3, v4, v5
	v_add_f32_e32 v0, v94, v2
	v_add_f32_e32 v2, v14, v1
	v_sub_f32_e32 v1, v6, v7
	v_add_f32_e32 v6, v18, v3
	v_add_f32_e32 v4, v34, v1
	v_mul_f32_e64 v7, v212, v6
	v_mul_f32_e64 v6, v213, v6
	v_fma_f32 v8, v212, v4, -v6
	v_fma_f32 v9, v213, v5, -v7
	v_fma_f32 v5, v213, v4, v7
	v_fma_f32 v4, v212, v4, v6
	v_mov_b32_e32 v18, v35
	v_mov_b32_e32 v9, v5
	v_add_f32_e64 v4, v18, v8
	v_add_f32_e64 v5, v19, v9
	v_mfma_f32_32x32x16_bf16 v[48:63], v[64:67], v[214:217], 0
	v_mul_f32_e64 v6, v212, v4
	v_mul_f32_e64 v7, v213, v5
	v_mul_f32_e64 v4, v213, v4
	v_mul_f32_e64 v5, v212, v5
	v_add_f32_e32 v3, v4, v5
	v_sub_f32_e32 v1, v6, v7
	v_add_f32_e32 v6, v20, v3
	v_add_f32_e32 v4, v36, v1
	v_mul_f32_e64 v7, v212, v6
	v_mul_f32_e64 v6, v213, v6
	v_fma_f32 v8, v212, v4, -v6
	v_fma_f32 v9, v213, v5, -v7
	v_fma_f32 v5, v213, v4, v7
	v_fma_f32 v4, v212, v4, v6
	v_mov_b32_e32 v20, v37
	v_mov_b32_e32 v9, v5
	v_add_f32_e64 v4, v20, v8
	v_add_f32_e64 v5, v21, v9
	v_mfma_f32_32x32x16_bf16 v[112:127], v[64:67], v[160:163], 0
	v_mul_f32_e64 v6, v212, v4
	v_mul_f32_e64 v7, v213, v5
	v_mul_f32_e64 v4, v213, v4
	v_mul_f32_e64 v5, v212, v5
	v_add_f32_e32 v3, v4, v5
	v_sub_f32_e32 v1, v6, v7
	v_add_f32_e32 v6, v22, v3
	v_add_f32_e32 v4, v38, v1
	v_mul_f32_e64 v7, v212, v6
	v_mul_f32_e64 v6, v213, v6
	v_fma_f32 v8, v212, v4, -v6
	v_fma_f32 v9, v213, v5, -v7
	v_fma_f32 v5, v213, v4, v7
	v_fma_f32 v4, v212, v4, v6
	v_mov_b32_e32 v22, v39
	v_mov_b32_e32 v9, v5
	v_add_f32_e64 v4, v22, v8
	v_add_f32_e64 v5, v23, v9
	v_mfma_f32_32x32x16_bf16 v[64:79], v[64:67], v[218:221], 0
	v_mul_f32_e64 v6, v212, v4
	v_mul_f32_e64 v7, v213, v5
	v_mul_f32_e64 v4, v213, v4
	v_mul_f32_e64 v5, v212, v5
	v_add_f32_e32 v3, v4, v5
	v_sub_f32_e32 v1, v6, v7
	v_add_f32_e32 v6, v24, v3
	v_add_f32_e32 v4, v40, v1
	v_mul_f32_e64 v7, v212, v6
	v_mul_f32_e64 v6, v213, v6
	v_fma_f32 v8, v212, v4, -v6
	v_fma_f32 v9, v213, v5, -v7
	v_fma_f32 v5, v213, v4, v7
	v_fma_f32 v4, v212, v4, v6
	v_mov_b32_e32 v24, v41
	v_mov_b32_e32 v9, v5
	v_add_f32_e64 v4, v24, v8
	v_add_f32_e64 v5, v25, v9
	v_mov_b32_e32 v14, v95
	v_mul_f32_e64 v6, v212, v4
	v_mul_f32_e64 v7, v213, v5
	v_mul_f32_e64 v4, v213, v4
	v_mul_f32_e64 v5, v212, v5
	v_add_f32_e32 v3, v4, v5
	v_sub_f32_e32 v1, v6, v7
	v_add_f32_e32 v6, v26, v3
	v_add_f32_e32 v4, v42, v1
	v_mul_f32_e64 v7, v212, v6
	v_mul_f32_e64 v6, v213, v6
	v_fma_f32 v8, v212, v4, -v6
	v_fma_f32 v9, v213, v5, -v7
	v_fma_f32 v5, v213, v4, v7
	v_fma_f32 v4, v212, v4, v6
	v_mov_b32_e32 v26, v43
	v_mov_b32_e32 v9, v5
	v_add_f32_e64 v4, v26, v8
	v_add_f32_e64 v5, v27, v9
	s_waitcnt vmcnt(0)
	v_mfma_f32_32x32x16_bf16 v[80:95], v[222:225], v[164:167], 0
	v_mul_f32_e64 v6, v212, v4
	v_mul_f32_e64 v7, v213, v5
	v_mul_f32_e64 v4, v213, v4
	v_mul_f32_e64 v5, v212, v5
	v_add_f32_e32 v3, v4, v5
	v_sub_f32_e32 v1, v6, v7
	v_add_f32_e32 v6, v28, v3
	v_add_f32_e32 v4, v44, v1
	v_mul_f32_e64 v7, v212, v6
	v_mul_f32_e64 v6, v213, v6
	v_fma_f32 v8, v212, v4, -v6
	v_fma_f32 v9, v213, v5, -v7
	v_fma_f32 v5, v213, v4, v7
	v_fma_f32 v4, v212, v4, v6
	v_mov_b32_e32 v28, v45
	v_mov_b32_e32 v9, v5
	v_add_f32_e64 v4, v28, v8
	v_add_f32_e64 v5, v29, v9
	v_mfma_f32_32x32x16_bf16 v[160:175], v[222:225], v[160:163], 0
	v_mul_f32_e64 v6, v212, v4
	v_mul_f32_e64 v7, v213, v5
	v_mul_f32_e64 v4, v213, v4
	v_mul_f32_e64 v5, v212, v5
	v_add_f32_e32 v3, v4, v5
	v_lshl_or_b32 v4, v210, 6, s38
	v_ashrrev_i32_e32 v5, 31, v4
	v_lshlrev_b64 v[4:5], 15, v[4:5]
	v_lshl_add_u64 v[4:5], s[4:5], 0, v[4:5]
	v_sub_f32_e32 v1, v6, v7
	v_add_f32_e32 v18, v30, v3
	v_lshl_add_u64 v[4:5], v[4:5], 0, s[20:21]
	v_mul_f32_e64 v3, v208, v2
	v_mul_f32_e64 v2, v209, v2
	v_add_f32_e32 v20, v46, v1
	v_lshl_add_u64 v[16:17], v[4:5], 0, v[230:231]
	v_fma_f32 v4, v208, v0, -v2
	v_fma_f32 v5, v209, v1, -v3
	v_fma_f32 v1, v209, v0, v3
	v_fma_f32 v0, v208, v0, v2
	v_mul_f32_e64 v19, v212, v18
	v_mul_f32_e64 v18, v213, v18
	v_mov_b32_e32 v5, v1
	v_fma_f32 v24, v212, v20, -v18
	v_fma_f32 v25, v213, v21, -v19
	v_fma_f32 v18, v212, v20, v18
	v_fma_f32 v19, v213, v20, v19
	v_mov_b32_e32 v30, v47
	v_add_f32_e64 v22, v14, v4
	v_add_f32_e64 v23, v15, v5
	v_mov_b32_e32 v25, v19
	v_add_f32_e64 v18, v30, v24
	v_add_f32_e64 v19, v31, v25
	v_mul_f32_e64 v20, v208, v22
	v_mul_f32_e64 v21, v209, v23
	v_mul_f32_e64 v22, v209, v22
	v_mul_f32_e64 v23, v208, v23
	v_mul_f32_e64 v24, v212, v18
	v_mul_f32_e64 v25, v213, v19
	v_mul_f32_e64 v18, v213, v18
	v_mul_f32_e64 v19, v212, v19
	v_sub_f32_e32 v20, v20, v21
	v_add_f32_e32 v21, v22, v23
	v_add_f32_e32 v19, v18, v19
	v_add_f32_e32 v18, v96, v20
	v_add_f32_e32 v20, v48, v21
	v_sub_f32_e32 v22, v24, v25
	v_add_f32_e32 v24, v64, v19
	v_mul_f32_e64 v21, v208, v20
	v_mul_f32_e64 v20, v209, v20
	v_add_f32_e32 v22, v112, v22
	v_mul_f32_e64 v25, v212, v24
	v_mul_f32_e64 v24, v213, v24
	v_fma_f32 v26, v208, v18, -v20
	v_fma_f32 v27, v209, v19, -v21
	v_fma_f32 v19, v209, v18, v21
	v_fma_f32 v18, v208, v18, v20
	v_mov_b32_e32 v48, v97
	v_fma_f32 v20, v212, v22, -v24
	v_fma_f32 v21, v213, v23, -v25
	v_fma_f32 v23, v213, v22, v25
	v_fma_f32 v22, v212, v22, v24
	v_mov_b32_e32 v27, v19
	v_mov_b32_e32 v64, v113
	v_mov_b32_e32 v21, v23
	v_add_f32_e64 v18, v48, v26
	v_add_f32_e64 v19, v49, v27
	v_add_f32_e64 v20, v64, v20
	v_add_f32_e64 v21, v65, v21
	v_mul_f32_e64 v22, v208, v18
	v_mul_f32_e64 v23, v209, v19
	v_mul_f32_e64 v18, v209, v18
	v_mul_f32_e64 v19, v208, v19
	v_mul_f32_e64 v24, v212, v20
	v_mul_f32_e64 v25, v213, v21
	v_mul_f32_e64 v20, v213, v20
	v_mul_f32_e64 v21, v212, v21
	v_add_f32_e32 v19, v18, v19
	v_sub_f32_e32 v22, v22, v23
	v_add_f32_e32 v21, v20, v21
	v_add_f32_e32 v20, v50, v19
	v_sub_f32_e32 v23, v24, v25
	v_add_f32_e32 v18, v98, v22
	v_add_f32_e32 v24, v66, v21
	v_mul_f32_e64 v21, v208, v20
	v_mul_f32_e64 v20, v209, v20
	v_add_f32_e32 v22, v114, v23
	v_mul_f32_e64 v25, v212, v24
	v_mul_f32_e64 v24, v213, v24
	v_fma_f32 v26, v208, v18, -v20
	v_fma_f32 v27, v209, v19, -v21
	v_fma_f32 v19, v209, v18, v21
	v_fma_f32 v18, v208, v18, v20
	v_mov_b32_e32 v50, v99
	v_fma_f32 v20, v212, v22, -v24
	v_fma_f32 v21, v213, v23, -v25
	v_fma_f32 v23, v213, v22, v25
	v_fma_f32 v22, v212, v22, v24
	v_mov_b32_e32 v27, v19
	v_mov_b32_e32 v66, v115
	v_mov_b32_e32 v21, v23
	v_add_f32_e64 v18, v50, v26
	v_add_f32_e64 v19, v51, v27
	v_add_f32_e64 v20, v66, v20
	v_add_f32_e64 v21, v67, v21
	v_mul_f32_e64 v22, v208, v18
	v_mul_f32_e64 v23, v209, v19
	v_mul_f32_e64 v18, v209, v18
	v_mul_f32_e64 v19, v208, v19
	v_mul_f32_e64 v24, v212, v20
	v_mul_f32_e64 v25, v213, v21
	v_mul_f32_e64 v20, v213, v20
	v_mul_f32_e64 v21, v212, v21
	v_add_f32_e32 v19, v18, v19
	v_sub_f32_e32 v22, v22, v23
	v_add_f32_e32 v21, v20, v21
	v_add_f32_e32 v20, v52, v19
	v_sub_f32_e32 v23, v24, v25
	v_add_f32_e32 v18, v100, v22
	v_add_f32_e32 v24, v68, v21
	v_mul_f32_e64 v21, v208, v20
	v_mul_f32_e64 v20, v209, v20
	v_add_f32_e32 v22, v116, v23
	v_mul_f32_e64 v25, v212, v24
	v_mul_f32_e64 v24, v213, v24
	v_fma_f32 v26, v208, v18, -v20
	v_fma_f32 v27, v209, v19, -v21
	v_fma_f32 v19, v209, v18, v21
	v_fma_f32 v18, v208, v18, v20
	v_mov_b32_e32 v52, v101
	v_fma_f32 v20, v212, v22, -v24
	v_fma_f32 v21, v213, v23, -v25
	v_fma_f32 v23, v213, v22, v25
	v_fma_f32 v22, v212, v22, v24
	v_mov_b32_e32 v27, v19
	v_mov_b32_e32 v68, v117
	v_mov_b32_e32 v21, v23
	v_add_f32_e64 v18, v52, v26
	v_add_f32_e64 v19, v53, v27
	v_add_f32_e64 v20, v68, v20
	v_add_f32_e64 v21, v69, v21
	v_mul_f32_e64 v22, v208, v18
	v_mul_f32_e64 v23, v209, v19
	v_mul_f32_e64 v18, v209, v18
	v_mul_f32_e64 v19, v208, v19
	v_mul_f32_e64 v24, v212, v20
	v_mul_f32_e64 v25, v213, v21
	v_mul_f32_e64 v20, v213, v20
	v_mul_f32_e64 v21, v212, v21
	v_add_f32_e32 v19, v18, v19
	v_sub_f32_e32 v22, v22, v23
	v_add_f32_e32 v21, v20, v21
	v_add_f32_e32 v20, v54, v19
	v_sub_f32_e32 v23, v24, v25
	v_add_f32_e32 v18, v102, v22
	v_add_f32_e32 v24, v70, v21
	v_mul_f32_e64 v21, v208, v20
	v_mul_f32_e64 v20, v209, v20
	v_add_f32_e32 v22, v118, v23
	v_mul_f32_e64 v25, v212, v24
	v_mul_f32_e64 v24, v213, v24
	v_fma_f32 v26, v208, v18, -v20
	v_fma_f32 v27, v209, v19, -v21
	v_fma_f32 v19, v209, v18, v21
	v_fma_f32 v18, v208, v18, v20
	v_mov_b32_e32 v54, v103
	v_fma_f32 v20, v212, v22, -v24
	v_fma_f32 v21, v213, v23, -v25
	v_fma_f32 v23, v213, v22, v25
	v_fma_f32 v22, v212, v22, v24
	v_mov_b32_e32 v27, v19
	v_mov_b32_e32 v70, v119
	v_mov_b32_e32 v21, v23
	v_add_f32_e64 v18, v54, v26
	v_add_f32_e64 v19, v55, v27
	v_add_f32_e64 v20, v70, v20
	v_add_f32_e64 v21, v71, v21
	v_mul_f32_e64 v22, v208, v18
	v_mul_f32_e64 v23, v209, v19
	v_mul_f32_e64 v18, v209, v18
	v_mul_f32_e64 v19, v208, v19
	v_mul_f32_e64 v24, v212, v20
	v_mul_f32_e64 v25, v213, v21
	v_mul_f32_e64 v20, v213, v20
	v_mul_f32_e64 v21, v212, v21
	v_add_f32_e32 v19, v18, v19
	v_sub_f32_e32 v22, v22, v23
	v_add_f32_e32 v21, v20, v21
	v_add_f32_e32 v20, v56, v19
	v_sub_f32_e32 v23, v24, v25
	v_add_f32_e32 v18, v104, v22
	v_add_f32_e32 v24, v72, v21
	v_mul_f32_e64 v21, v208, v20
	v_mul_f32_e64 v20, v209, v20
	v_add_f32_e32 v22, v120, v23
	v_mul_f32_e64 v25, v212, v24
	v_mul_f32_e64 v24, v213, v24
	v_fma_f32 v26, v208, v18, -v20
	v_fma_f32 v27, v209, v19, -v21
	v_fma_f32 v19, v209, v18, v21
	v_fma_f32 v18, v208, v18, v20
	v_mov_b32_e32 v56, v105
	v_fma_f32 v20, v212, v22, -v24
	v_fma_f32 v21, v213, v23, -v25
	v_fma_f32 v23, v213, v22, v25
	v_fma_f32 v22, v212, v22, v24
	v_mov_b32_e32 v27, v19
	v_mov_b32_e32 v72, v121
	v_mov_b32_e32 v21, v23
	v_add_f32_e64 v18, v56, v26
	v_add_f32_e64 v19, v57, v27
	v_add_f32_e64 v20, v72, v20
	v_add_f32_e64 v21, v73, v21
	v_mul_f32_e64 v22, v208, v18
	v_mul_f32_e64 v23, v209, v19
	v_mul_f32_e64 v18, v209, v18
	v_mul_f32_e64 v19, v208, v19
	v_mul_f32_e64 v24, v212, v20
	v_mul_f32_e64 v25, v213, v21
	v_mul_f32_e64 v20, v213, v20
	v_mul_f32_e64 v21, v212, v21
	v_add_f32_e32 v19, v18, v19
	v_sub_f32_e32 v22, v22, v23
	v_add_f32_e32 v21, v20, v21
	v_add_f32_e32 v20, v58, v19
	v_sub_f32_e32 v23, v24, v25
	v_add_f32_e32 v18, v106, v22
	v_add_f32_e32 v24, v74, v21
	v_mul_f32_e64 v21, v208, v20
	v_mul_f32_e64 v20, v209, v20
	v_add_f32_e32 v22, v122, v23
	v_mul_f32_e64 v25, v212, v24
	v_mul_f32_e64 v24, v213, v24
	v_fma_f32 v26, v208, v18, -v20
	v_fma_f32 v27, v209, v19, -v21
	v_fma_f32 v19, v209, v18, v21
	v_fma_f32 v18, v208, v18, v20
	v_mov_b32_e32 v58, v107
	v_fma_f32 v20, v212, v22, -v24
	v_fma_f32 v21, v213, v23, -v25
	v_fma_f32 v23, v213, v22, v25
	v_fma_f32 v22, v212, v22, v24
	v_mov_b32_e32 v27, v19
	v_mov_b32_e32 v74, v123
	v_mov_b32_e32 v21, v23
	v_add_f32_e64 v18, v58, v26
	v_add_f32_e64 v19, v59, v27
	v_add_f32_e64 v20, v74, v20
	v_add_f32_e64 v21, v75, v21
	v_mul_f32_e64 v22, v208, v18
	v_mul_f32_e64 v23, v209, v19
	v_mul_f32_e64 v18, v209, v18
	v_mul_f32_e64 v19, v208, v19
	v_mul_f32_e64 v24, v212, v20
	v_mul_f32_e64 v25, v213, v21
	v_mul_f32_e64 v20, v213, v20
	v_mul_f32_e64 v21, v212, v21
	v_add_f32_e32 v19, v18, v19
	v_sub_f32_e32 v22, v22, v23
	v_add_f32_e32 v21, v20, v21
	v_add_f32_e32 v20, v60, v19
	v_sub_f32_e32 v23, v24, v25
	v_add_f32_e32 v18, v108, v22
	v_add_f32_e32 v24, v76, v21
	v_mul_f32_e64 v21, v208, v20
	v_mul_f32_e64 v20, v209, v20
	v_add_f32_e32 v22, v124, v23
	v_mul_f32_e64 v25, v212, v24
	v_mul_f32_e64 v24, v213, v24
	v_fma_f32 v26, v208, v18, -v20
	v_fma_f32 v27, v209, v19, -v21
	v_fma_f32 v19, v209, v18, v21
	v_fma_f32 v18, v208, v18, v20
	v_mov_b32_e32 v60, v109
	v_fma_f32 v20, v212, v22, -v24
	v_fma_f32 v21, v213, v23, -v25
	v_fma_f32 v23, v213, v22, v25
	v_fma_f32 v22, v212, v22, v24
	v_mov_b32_e32 v27, v19
	v_mov_b32_e32 v76, v125
	v_mov_b32_e32 v21, v23
	v_add_f32_e64 v18, v60, v26
	v_add_f32_e64 v19, v61, v27
	v_add_f32_e64 v20, v76, v20
	v_add_f32_e64 v21, v77, v21
	v_mul_f32_e64 v22, v208, v18
	v_mul_f32_e64 v23, v209, v19
	v_mul_f32_e64 v18, v209, v18
	v_mul_f32_e64 v19, v208, v19
	v_mul_f32_e64 v24, v212, v20
	v_mul_f32_e64 v25, v213, v21
	v_mul_f32_e64 v20, v213, v20
	v_mul_f32_e64 v21, v212, v21
	v_add_f32_e32 v19, v18, v19
	v_sub_f32_e32 v22, v22, v23
	v_add_f32_e32 v21, v20, v21
	v_add_f32_e32 v20, v62, v19
	v_sub_f32_e32 v23, v24, v25
	v_add_f32_e32 v18, v110, v22
	v_add_f32_e32 v24, v78, v21
	v_mul_f32_e64 v21, v208, v20
	v_mul_f32_e64 v20, v209, v20
	v_add_f32_e32 v22, v126, v23
	v_mul_f32_e64 v25, v212, v24
	v_mul_f32_e64 v24, v213, v24
	v_fma_f32 v26, v208, v18, -v20
	v_fma_f32 v27, v209, v19, -v21
	v_fma_f32 v19, v209, v18, v21
	v_fma_f32 v18, v208, v18, v20
	v_mov_b32_e32 v62, v111
	v_fma_f32 v20, v212, v22, -v24
	v_fma_f32 v21, v213, v23, -v25
	v_fma_f32 v23, v213, v22, v25
	v_fma_f32 v22, v212, v22, v24
	v_mov_b32_e32 v27, v19
	v_mov_b32_e32 v78, v127
	v_mov_b32_e32 v21, v23
	v_add_f32_e64 v18, v62, v26
	v_add_f32_e64 v19, v63, v27
	v_add_f32_e64 v20, v78, v20
	v_add_f32_e64 v21, v79, v21
	v_mul_f32_e64 v22, v208, v18
	v_mul_f32_e64 v23, v209, v19
	v_mul_f32_e64 v18, v209, v18
	v_mul_f32_e64 v19, v208, v19
	v_mul_f32_e64 v24, v212, v20
	v_mul_f32_e64 v25, v213, v21
	v_mul_f32_e64 v20, v213, v20
	v_mul_f32_e64 v21, v212, v21
	v_add_f32_e32 v19, v18, v19
	v_sub_f32_e32 v22, v22, v23
	v_add_f32_e32 v21, v20, v21
	v_add_f32_e32 v20, v176, v19
	v_sub_f32_e32 v23, v24, v25
	v_add_f32_e32 v18, v128, v22
	v_add_f32_e32 v24, v192, v21
	v_mul_f32_e64 v21, v208, v20
	v_mul_f32_e64 v20, v209, v20
	v_add_f32_e32 v22, v144, v23
	v_mul_f32_e64 v25, v212, v24
	v_mul_f32_e64 v24, v213, v24
	v_fma_f32 v26, v208, v18, -v20
	v_fma_f32 v27, v209, v19, -v21
	v_fma_f32 v19, v209, v18, v21
	v_fma_f32 v18, v208, v18, v20
	v_mov_b32_e32 v176, v129
	v_fma_f32 v20, v212, v22, -v24
	v_fma_f32 v21, v213, v23, -v25
	v_fma_f32 v23, v213, v22, v25
	v_fma_f32 v22, v212, v22, v24
	v_mov_b32_e32 v27, v19
	v_mov_b32_e32 v192, v145
	v_mov_b32_e32 v21, v23
	v_add_f32_e64 v18, v176, v26
	v_add_f32_e64 v19, v177, v27
	v_add_f32_e64 v20, v192, v20
	v_add_f32_e64 v21, v193, v21
	v_mul_f32_e64 v22, v208, v18
	v_mul_f32_e64 v23, v209, v19
	v_mul_f32_e64 v18, v209, v18
	v_mul_f32_e64 v19, v208, v19
	v_mul_f32_e64 v24, v212, v20
	v_mul_f32_e64 v25, v213, v21
	v_mul_f32_e64 v20, v213, v20
	v_mul_f32_e64 v21, v212, v21
	v_add_f32_e32 v19, v18, v19
	v_sub_f32_e32 v22, v22, v23
	v_add_f32_e32 v21, v20, v21
	v_add_f32_e32 v20, v178, v19
	v_sub_f32_e32 v23, v24, v25
	v_add_f32_e32 v18, v130, v22
	v_add_f32_e32 v24, v194, v21
	v_mul_f32_e64 v21, v208, v20
	v_mul_f32_e64 v20, v209, v20
	v_add_f32_e32 v22, v146, v23
	v_mul_f32_e64 v25, v212, v24
	v_mul_f32_e64 v24, v213, v24
	v_fma_f32 v26, v208, v18, -v20
	v_fma_f32 v27, v209, v19, -v21
	v_fma_f32 v19, v209, v18, v21
	v_fma_f32 v18, v208, v18, v20
	v_mov_b32_e32 v178, v131
	v_fma_f32 v20, v212, v22, -v24
	v_fma_f32 v21, v213, v23, -v25
	v_fma_f32 v23, v213, v22, v25
	v_fma_f32 v22, v212, v22, v24
	v_mov_b32_e32 v27, v19
	v_mov_b32_e32 v194, v147
	v_mov_b32_e32 v21, v23
	v_add_f32_e64 v18, v178, v26
	v_add_f32_e64 v19, v179, v27
	v_add_f32_e64 v20, v194, v20
	v_add_f32_e64 v21, v195, v21
	v_mul_f32_e64 v22, v208, v18
	v_mul_f32_e64 v23, v209, v19
	v_mul_f32_e64 v18, v209, v18
	v_mul_f32_e64 v19, v208, v19
	v_mul_f32_e64 v24, v212, v20
	v_mul_f32_e64 v25, v213, v21
	v_mul_f32_e64 v20, v213, v20
	v_mul_f32_e64 v21, v212, v21
	v_add_f32_e32 v19, v18, v19
	v_sub_f32_e32 v22, v22, v23
	v_add_f32_e32 v21, v20, v21
	v_add_f32_e32 v20, v180, v19
	v_sub_f32_e32 v23, v24, v25
	v_add_f32_e32 v18, v132, v22
	v_add_f32_e32 v24, v196, v21
	v_mul_f32_e64 v21, v208, v20
	v_mul_f32_e64 v20, v209, v20
	v_add_f32_e32 v22, v148, v23
	v_mul_f32_e64 v25, v212, v24
	v_mul_f32_e64 v24, v213, v24
	v_fma_f32 v26, v208, v18, -v20
	v_fma_f32 v27, v209, v19, -v21
	v_fma_f32 v19, v209, v18, v21
	v_fma_f32 v18, v208, v18, v20
	v_mov_b32_e32 v180, v133
	v_fma_f32 v20, v212, v22, -v24
	v_fma_f32 v21, v213, v23, -v25
	v_fma_f32 v23, v213, v22, v25
	v_fma_f32 v22, v212, v22, v24
	v_mov_b32_e32 v27, v19
	v_mov_b32_e32 v196, v149
	v_mov_b32_e32 v21, v23
	v_add_f32_e64 v18, v180, v26
	v_add_f32_e64 v19, v181, v27
	v_add_f32_e64 v20, v196, v20
	v_add_f32_e64 v21, v197, v21
	v_mul_f32_e64 v22, v208, v18
	v_mul_f32_e64 v23, v209, v19
	v_mul_f32_e64 v18, v209, v18
	v_mul_f32_e64 v19, v208, v19
	v_mul_f32_e64 v24, v212, v20
	v_mul_f32_e64 v25, v213, v21
	v_mul_f32_e64 v20, v213, v20
	v_mul_f32_e64 v21, v212, v21
	v_add_f32_e32 v19, v18, v19
	v_sub_f32_e32 v22, v22, v23
	v_add_f32_e32 v21, v20, v21
	v_add_f32_e32 v20, v182, v19
	v_sub_f32_e32 v23, v24, v25
	v_add_f32_e32 v18, v134, v22
	v_add_f32_e32 v24, v198, v21
	v_mul_f32_e64 v21, v208, v20
	v_mul_f32_e64 v20, v209, v20
	v_add_f32_e32 v22, v150, v23
	v_mul_f32_e64 v25, v212, v24
	v_mul_f32_e64 v24, v213, v24
	v_fma_f32 v26, v208, v18, -v20
	v_fma_f32 v27, v209, v19, -v21
	v_fma_f32 v19, v209, v18, v21
	v_fma_f32 v18, v208, v18, v20
	v_mov_b32_e32 v182, v135
	v_fma_f32 v20, v212, v22, -v24
	v_fma_f32 v21, v213, v23, -v25
	v_fma_f32 v23, v213, v22, v25
	v_fma_f32 v22, v212, v22, v24
	v_mov_b32_e32 v27, v19
	v_mov_b32_e32 v198, v151
	v_mov_b32_e32 v21, v23
	v_add_f32_e64 v18, v182, v26
	v_add_f32_e64 v19, v183, v27
	v_add_f32_e64 v20, v198, v20
	v_add_f32_e64 v21, v199, v21
	v_mul_f32_e64 v22, v208, v18
	v_mul_f32_e64 v23, v209, v19
	v_mul_f32_e64 v18, v209, v18
	v_mul_f32_e64 v19, v208, v19
	v_mul_f32_e64 v24, v212, v20
	v_mul_f32_e64 v25, v213, v21
	v_mul_f32_e64 v20, v213, v20
	v_mul_f32_e64 v21, v212, v21
	v_add_f32_e32 v19, v18, v19
	v_sub_f32_e32 v22, v22, v23
	v_add_f32_e32 v21, v20, v21
	v_add_f32_e32 v20, v184, v19
	v_sub_f32_e32 v23, v24, v25
	v_add_f32_e32 v18, v136, v22
	v_add_f32_e32 v24, v200, v21
	v_mul_f32_e64 v21, v208, v20
	v_mul_f32_e64 v20, v209, v20
	v_add_f32_e32 v22, v152, v23
	v_mul_f32_e64 v25, v212, v24
	v_mul_f32_e64 v24, v213, v24
	v_fma_f32 v26, v208, v18, -v20
	v_fma_f32 v27, v209, v19, -v21
	v_fma_f32 v19, v209, v18, v21
	v_fma_f32 v18, v208, v18, v20
	v_mov_b32_e32 v184, v137
	v_fma_f32 v20, v212, v22, -v24
	v_fma_f32 v21, v213, v23, -v25
	v_fma_f32 v23, v213, v22, v25
	v_fma_f32 v22, v212, v22, v24
	v_mov_b32_e32 v27, v19
	v_mov_b32_e32 v200, v153
	v_mov_b32_e32 v21, v23
	v_add_f32_e64 v18, v184, v26
	v_add_f32_e64 v19, v185, v27
	v_add_f32_e64 v20, v200, v20
	v_add_f32_e64 v21, v201, v21
	v_mul_f32_e64 v22, v208, v18
	v_mul_f32_e64 v23, v209, v19
	v_mul_f32_e64 v18, v209, v18
	v_mul_f32_e64 v19, v208, v19
	v_mul_f32_e64 v24, v212, v20
	v_mul_f32_e64 v25, v213, v21
	v_mul_f32_e64 v20, v213, v20
	v_mul_f32_e64 v21, v212, v21
	v_add_f32_e32 v19, v18, v19
	v_sub_f32_e32 v22, v22, v23
	v_add_f32_e32 v21, v20, v21
	v_add_f32_e32 v20, v186, v19
	v_sub_f32_e32 v23, v24, v25
	v_add_f32_e32 v18, v138, v22
	v_add_f32_e32 v24, v202, v21
	v_mul_f32_e64 v21, v208, v20
	v_mul_f32_e64 v20, v209, v20
	v_add_f32_e32 v22, v154, v23
	v_mul_f32_e64 v25, v212, v24
	v_mul_f32_e64 v24, v213, v24
	v_fma_f32 v26, v208, v18, -v20
	v_fma_f32 v27, v209, v19, -v21
	v_fma_f32 v19, v209, v18, v21
	v_fma_f32 v18, v208, v18, v20
	v_mov_b32_e32 v186, v139
	v_fma_f32 v20, v212, v22, -v24
	v_fma_f32 v21, v213, v23, -v25
	v_fma_f32 v23, v213, v22, v25
	v_fma_f32 v22, v212, v22, v24
	v_mov_b32_e32 v27, v19
	v_mov_b32_e32 v202, v155
	v_mov_b32_e32 v21, v23
	v_add_f32_e64 v18, v186, v26
	v_add_f32_e64 v19, v187, v27
	v_add_f32_e64 v20, v202, v20
	v_add_f32_e64 v21, v203, v21
	v_mul_f32_e64 v22, v208, v18
	v_mul_f32_e64 v23, v209, v19
	v_mul_f32_e64 v18, v209, v18
	v_mul_f32_e64 v19, v208, v19
	v_mul_f32_e64 v24, v212, v20
	v_mul_f32_e64 v25, v213, v21
	v_mul_f32_e64 v20, v213, v20
	v_mul_f32_e64 v21, v212, v21
	v_add_f32_e32 v19, v18, v19
	v_sub_f32_e32 v22, v22, v23
	v_add_f32_e32 v21, v20, v21
	v_add_f32_e32 v20, v188, v19
	v_sub_f32_e32 v23, v24, v25
	v_add_f32_e32 v18, v140, v22
	v_add_f32_e32 v24, v204, v21
	v_mul_f32_e64 v21, v208, v20
	v_mul_f32_e64 v20, v209, v20
	v_add_f32_e32 v22, v156, v23
	v_mul_f32_e64 v25, v212, v24
	v_mul_f32_e64 v24, v213, v24
	v_fma_f32 v26, v208, v18, -v20
	v_fma_f32 v27, v209, v19, -v21
	v_fma_f32 v19, v209, v18, v21
	v_fma_f32 v18, v208, v18, v20
	v_mov_b32_e32 v188, v141
	v_fma_f32 v20, v212, v22, -v24
	v_fma_f32 v21, v213, v23, -v25
	v_fma_f32 v23, v213, v22, v25
	v_fma_f32 v22, v212, v22, v24
	v_mov_b32_e32 v27, v19
	v_mov_b32_e32 v204, v157
	v_mov_b32_e32 v21, v23
	v_add_f32_e64 v18, v188, v26
	v_add_f32_e64 v19, v189, v27
	v_add_f32_e64 v20, v204, v20
	v_add_f32_e64 v21, v205, v21
	v_mul_f32_e64 v22, v208, v18
	v_mul_f32_e64 v23, v209, v19
	v_mul_f32_e64 v18, v209, v18
	v_mul_f32_e64 v19, v208, v19
	v_mfma_f32_32x32x16_bf16 v[32:47], v[222:225], v[214:217], 0
	v_mul_f32_e64 v24, v212, v20
	v_mul_f32_e64 v25, v213, v21
	v_mul_f32_e64 v20, v213, v20
	v_mul_f32_e64 v21, v212, v21
	v_add_f32_e32 v19, v18, v19
	v_sub_f32_e32 v22, v22, v23
	v_add_f32_e32 v21, v20, v21
	v_add_f32_e32 v20, v190, v19
	v_sub_f32_e32 v23, v24, v25
	v_mfma_f32_32x32x16_bf16 v[0:15], v[222:225], v[218:221], 0
	v_add_f32_e32 v18, v142, v22
	v_add_f32_e32 v24, v206, v21
	v_mul_f32_e64 v21, v208, v20
	v_mul_f32_e64 v20, v209, v20
	v_add_f32_e32 v22, v158, v23
	v_mul_f32_e64 v25, v212, v24
	v_mul_f32_e64 v24, v213, v24
	v_fma_f32 v26, v208, v18, -v20
	v_fma_f32 v27, v209, v19, -v21
	v_fma_f32 v19, v209, v18, v21
	v_fma_f32 v18, v208, v18, v20
	v_mov_b32_e32 v190, v143
	v_fma_f32 v20, v212, v22, -v24
	v_fma_f32 v21, v213, v23, -v25
	v_fma_f32 v23, v213, v22, v25
	v_fma_f32 v22, v212, v22, v24
	v_mov_b32_e32 v27, v19
	v_mov_b32_e32 v206, v159
	v_mov_b32_e32 v21, v23
	v_add_f32_e64 v18, v190, v26
	v_add_f32_e64 v19, v191, v27
	v_add_f32_e64 v20, v206, v20
	v_add_f32_e64 v21, v207, v21
	v_mul_f32_e64 v22, v208, v18
	v_mul_f32_e64 v23, v209, v19
	v_mul_f32_e64 v18, v209, v18
	v_mul_f32_e64 v19, v208, v19
	v_mul_f32_e64 v24, v212, v20
	v_mul_f32_e64 v25, v213, v21
	v_mul_f32_e64 v20, v213, v20
	v_mul_f32_e64 v21, v212, v21
	v_add_f32_e32 v19, v18, v19
	v_sub_f32_e32 v22, v22, v23
	v_add_f32_e32 v21, v20, v21
	v_add_f32_e32 v20, v32, v19
	v_sub_f32_e32 v23, v24, v25
	v_add_f32_e32 v18, v80, v22
	v_add_f32_e32 v24, v0, v21
	v_mul_f32_e64 v21, v208, v20
	v_mul_f32_e64 v20, v209, v20
	v_add_f32_e32 v22, v160, v23
	v_mul_f32_e64 v25, v212, v24
	v_mul_f32_e64 v24, v213, v24
	v_fma_f32 v26, v208, v18, -v20
	v_fma_f32 v27, v209, v19, -v21
	v_fma_f32 v19, v209, v18, v21
	v_fma_f32 v18, v208, v18, v20
	v_mov_b32_e32 v32, v81
	v_fma_f32 v20, v212, v22, -v24
	v_fma_f32 v21, v213, v23, -v25
	v_fma_f32 v23, v213, v22, v25
	v_fma_f32 v22, v212, v22, v24
	v_mov_b32_e32 v27, v19
	v_mov_b32_e32 v0, v161
	v_mov_b32_e32 v21, v23
	v_add_f32_e64 v18, v32, v26
	v_add_f32_e64 v19, v33, v27
	v_add_f32_e64 v0, v0, v20
	v_add_f32_e64 v1, v1, v21
	v_mul_f32_e64 v20, v208, v18
	v_mul_f32_e64 v21, v209, v19
	v_mul_f32_e64 v18, v209, v18
	v_mul_f32_e64 v19, v208, v19
	v_mul_f32_e64 v22, v212, v0
	v_mul_f32_e64 v23, v213, v1
	v_mul_f32_e64 v0, v213, v0
	v_mul_f32_e64 v1, v212, v1
	v_add_f32_e32 v18, v18, v19
	v_sub_f32_e32 v20, v20, v21
	v_sub_f32_e32 v19, v22, v23
	v_add_f32_e32 v1, v0, v1
	v_add_f32_e32 v18, v34, v18
	v_add_f32_e32 v0, v82, v20
	v_add_f32_e32 v20, v162, v19
	v_add_f32_e32 v22, v2, v1
	v_mul_f32_e64 v19, v208, v18
	v_mul_f32_e64 v18, v209, v18
	v_mul_f32_e64 v23, v212, v22
	v_mul_f32_e64 v22, v213, v22
	v_fma_f32 v24, v208, v0, -v18
	v_fma_f32 v25, v209, v1, -v19
	v_fma_f32 v1, v209, v0, v19
	v_fma_f32 v0, v208, v0, v18
	v_mov_b32_e32 v34, v83
	v_fma_f32 v18, v212, v20, -v22
	v_fma_f32 v19, v213, v21, -v23
	v_fma_f32 v21, v213, v20, v23
	v_fma_f32 v20, v212, v20, v22
	v_mov_b32_e32 v25, v1
	v_mov_b32_e32 v2, v163
	v_mov_b32_e32 v19, v21
	v_add_f32_e64 v0, v34, v24
	v_add_f32_e64 v1, v35, v25
	v_add_f32_e64 v2, v2, v18
	v_add_f32_e64 v3, v3, v19
	v_mul_f32_e64 v18, v208, v0
	v_mul_f32_e64 v19, v209, v1
	v_mul_f32_e64 v0, v209, v0
	v_mul_f32_e64 v1, v208, v1
	v_mul_f32_e64 v20, v212, v2
	v_mul_f32_e64 v21, v213, v3
	v_mul_f32_e64 v2, v213, v2
	v_mul_f32_e64 v3, v212, v3
	v_add_f32_e32 v1, v0, v1
	v_sub_f32_e32 v18, v18, v19
	v_add_f32_e32 v3, v2, v3
	v_add_f32_e32 v2, v36, v1
	v_sub_f32_e32 v19, v20, v21
	v_add_f32_e32 v0, v84, v18
	v_add_f32_e32 v20, v4, v3
	v_mul_f32_e64 v3, v208, v2
	v_mul_f32_e64 v2, v209, v2
	v_add_f32_e32 v18, v164, v19
	v_mul_f32_e64 v21, v212, v20
	v_mul_f32_e64 v20, v213, v20
	v_fma_f32 v22, v208, v0, -v2
	v_fma_f32 v23, v209, v1, -v3
	v_fma_f32 v1, v209, v0, v3
	v_fma_f32 v0, v208, v0, v2
	v_mov_b32_e32 v36, v85
	v_fma_f32 v2, v212, v18, -v20
	v_fma_f32 v3, v213, v19, -v21
	v_fma_f32 v19, v213, v18, v21
	v_fma_f32 v18, v212, v18, v20
	v_mov_b32_e32 v23, v1
	v_mov_b32_e32 v4, v165
	v_mov_b32_e32 v3, v19
	v_add_f32_e64 v0, v36, v22
	v_add_f32_e64 v1, v37, v23
	v_add_f32_e64 v2, v4, v2
	v_add_f32_e64 v3, v5, v3
	v_mul_f32_e64 v4, v208, v0
	v_mul_f32_e64 v5, v209, v1
	v_mul_f32_e64 v0, v209, v0
	v_mul_f32_e64 v1, v208, v1
	v_mul_f32_e64 v18, v212, v2
	v_mul_f32_e64 v19, v213, v3
	v_mul_f32_e64 v2, v213, v2
	v_mul_f32_e64 v3, v212, v3
	v_add_f32_e32 v1, v0, v1
	v_sub_f32_e32 v4, v4, v5
	v_add_f32_e32 v3, v2, v3
	v_add_f32_e32 v2, v38, v1
	v_sub_f32_e32 v5, v18, v19
	v_add_f32_e32 v0, v86, v4
	v_add_f32_e32 v18, v6, v3
	v_mul_f32_e64 v3, v208, v2
	v_mul_f32_e64 v2, v209, v2
	v_add_f32_e32 v4, v166, v5
	v_mul_f32_e64 v19, v212, v18
	v_mul_f32_e64 v18, v213, v18
	v_fma_f32 v20, v208, v0, -v2
	v_fma_f32 v21, v209, v1, -v3
	v_fma_f32 v1, v209, v0, v3
	v_fma_f32 v0, v208, v0, v2
	v_mov_b32_e32 v38, v87
	v_fma_f32 v2, v212, v4, -v18
	v_fma_f32 v3, v213, v5, -v19
	v_fma_f32 v5, v213, v4, v19
	v_fma_f32 v4, v212, v4, v18
	v_mov_b32_e32 v21, v1
	v_mov_b32_e32 v6, v167
	v_mov_b32_e32 v3, v5
	v_add_f32_e64 v0, v38, v20
	v_add_f32_e64 v1, v39, v21
	v_add_f32_e64 v2, v6, v2
	v_add_f32_e64 v3, v7, v3
	v_mul_f32_e64 v4, v208, v0
	v_mul_f32_e64 v5, v209, v1
	v_mul_f32_e64 v0, v209, v0
	v_mul_f32_e64 v1, v208, v1
	v_mul_f32_e64 v6, v212, v2
	v_mul_f32_e64 v7, v213, v3
	v_mul_f32_e64 v2, v213, v2
	v_mul_f32_e64 v3, v212, v3
	v_add_f32_e32 v1, v0, v1
	v_sub_f32_e32 v4, v4, v5
	v_add_f32_e32 v3, v2, v3
	v_add_f32_e32 v2, v40, v1
	v_sub_f32_e32 v5, v6, v7
	v_add_f32_e32 v0, v88, v4
	v_add_f32_e32 v6, v8, v3
	v_mul_f32_e64 v3, v208, v2
	v_mul_f32_e64 v2, v209, v2
	v_add_f32_e32 v4, v168, v5
	v_mul_f32_e64 v7, v212, v6
	v_mul_f32_e64 v6, v213, v6
	v_fma_f32 v18, v208, v0, -v2
	v_fma_f32 v19, v209, v1, -v3
	v_fma_f32 v1, v209, v0, v3
	v_fma_f32 v0, v208, v0, v2
	v_mov_b32_e32 v40, v89
	v_fma_f32 v2, v212, v4, -v6
	v_fma_f32 v3, v213, v5, -v7
	v_fma_f32 v5, v213, v4, v7
	v_fma_f32 v4, v212, v4, v6
	v_mov_b32_e32 v19, v1
	v_mov_b32_e32 v8, v169
	v_mov_b32_e32 v3, v5
	v_add_f32_e64 v0, v40, v18
	v_add_f32_e64 v1, v41, v19
	v_add_f32_e64 v2, v8, v2
	v_add_f32_e64 v3, v9, v3
	v_mul_f32_e64 v4, v208, v0
	v_mul_f32_e64 v5, v209, v1
	v_mul_f32_e64 v0, v209, v0
	v_mul_f32_e64 v1, v208, v1
	v_mul_f32_e64 v6, v212, v2
	v_mul_f32_e64 v7, v213, v3
	v_mul_f32_e64 v2, v213, v2
	v_mul_f32_e64 v3, v212, v3
	v_add_f32_e32 v1, v0, v1
	v_sub_f32_e32 v4, v4, v5
	v_add_f32_e32 v3, v2, v3
	v_add_f32_e32 v2, v42, v1
	v_sub_f32_e32 v5, v6, v7
	v_add_f32_e32 v0, v90, v4
	v_add_f32_e32 v6, v10, v3
	v_mul_f32_e64 v3, v208, v2
	v_mul_f32_e64 v2, v209, v2
	v_add_f32_e32 v4, v170, v5
	v_mul_f32_e64 v7, v212, v6
	v_mul_f32_e64 v6, v213, v6
	v_fma_f32 v8, v208, v0, -v2
	v_fma_f32 v9, v209, v1, -v3
	v_fma_f32 v1, v209, v0, v3
	v_fma_f32 v0, v208, v0, v2
	v_mov_b32_e32 v42, v91
	v_fma_f32 v2, v212, v4, -v6
	v_fma_f32 v3, v213, v5, -v7
	v_fma_f32 v5, v213, v4, v7
	v_fma_f32 v4, v212, v4, v6
	v_mov_b32_e32 v9, v1
	v_mov_b32_e32 v10, v171
	v_mov_b32_e32 v3, v5
	v_add_f32_e64 v0, v42, v8
	v_add_f32_e64 v1, v43, v9
	v_add_f32_e64 v2, v10, v2
	v_add_f32_e64 v3, v11, v3
	v_mul_f32_e64 v4, v208, v0
	v_mul_f32_e64 v5, v209, v1
	v_mul_f32_e64 v0, v209, v0
	v_mul_f32_e64 v1, v208, v1
	v_mul_f32_e64 v6, v212, v2
	v_mul_f32_e64 v7, v213, v3
	v_mul_f32_e64 v2, v213, v2
	v_mul_f32_e64 v3, v212, v3
	v_add_f32_e32 v1, v0, v1
	v_sub_f32_e32 v4, v4, v5
	v_add_f32_e32 v3, v2, v3
	v_add_f32_e32 v2, v44, v1
	v_sub_f32_e32 v5, v6, v7
	v_add_f32_e32 v0, v92, v4
	v_add_f32_e32 v6, v12, v3
	v_mul_f32_e64 v3, v208, v2
	v_mul_f32_e64 v2, v209, v2
	v_add_f32_e32 v4, v172, v5
	v_mul_f32_e64 v7, v212, v6
	v_mul_f32_e64 v6, v213, v6
	v_fma_f32 v8, v208, v0, -v2
	v_fma_f32 v9, v209, v1, -v3
	v_fma_f32 v1, v209, v0, v3
	v_fma_f32 v0, v208, v0, v2
	v_mov_b32_e32 v44, v93
	v_fma_f32 v2, v212, v4, -v6
	v_fma_f32 v3, v213, v5, -v7
	v_fma_f32 v5, v213, v4, v7
	v_fma_f32 v4, v212, v4, v6
	v_mov_b32_e32 v9, v1
	v_mov_b32_e32 v12, v173
	v_mov_b32_e32 v3, v5
	v_add_f32_e64 v0, v44, v8
	v_add_f32_e64 v1, v45, v9
	v_add_f32_e64 v2, v12, v2
	v_add_f32_e64 v3, v13, v3
	v_mul_f32_e64 v4, v208, v0
	v_mul_f32_e64 v5, v209, v1
	v_mul_f32_e64 v0, v209, v0
	v_mul_f32_e64 v1, v208, v1
	v_mul_f32_e64 v6, v212, v2
	v_mul_f32_e64 v7, v213, v3
	v_mul_f32_e64 v2, v213, v2
	v_mul_f32_e64 v3, v212, v3
	v_add_f32_e32 v1, v0, v1
	v_sub_f32_e32 v4, v4, v5
	v_add_f32_e32 v3, v2, v3
	v_add_f32_e32 v2, v46, v1
	v_sub_f32_e32 v5, v6, v7
	v_add_f32_e32 v0, v94, v4
	v_add_f32_e32 v6, v14, v3
	v_mul_f32_e64 v3, v208, v2
	v_mul_f32_e64 v2, v209, v2
	v_add_f32_e32 v4, v174, v5
	v_mul_f32_e64 v7, v212, v6
	v_mul_f32_e64 v6, v213, v6
	v_fma_f32 v8, v208, v0, -v2
	v_fma_f32 v9, v209, v1, -v3
	v_fma_f32 v1, v209, v0, v3
	v_fma_f32 v0, v208, v0, v2
	v_mov_b32_e32 v46, v95
	v_fma_f32 v2, v212, v4, -v6
	v_fma_f32 v3, v213, v5, -v7
	v_fma_f32 v5, v213, v4, v7
	v_fma_f32 v4, v212, v4, v6
	v_mov_b32_e32 v9, v1
	v_mov_b32_e32 v14, v175
	v_mov_b32_e32 v3, v5
	v_add_f32_e64 v0, v46, v8
	v_add_f32_e64 v1, v47, v9
	v_add_f32_e64 v2, v14, v2
	v_add_f32_e64 v3, v15, v3
	global_store_dwordx2 v[16:17], v[0:1], off
	global_store_dwordx2 v[16:17], v[2:3], off offset:256
	s_cbranch_scc1 .LBB0_243

.LBB0_301:
	s_lshl_b32 s12, s25, 4
	v_or_b32_e32 v126, s12, v125
	v_lshlrev_b64 v[44:45], 8, v[126:127]
	v_lshl_or_b32 v44, v128, 2, v44
	v_lshl_add_u64 v[56:57], s[16:17], 0, v[44:45]
	global_load_dwordx4 v[32:35], v[56:57], off
	global_load_dwordx4 v[36:39], v[56:57], off offset:64
	global_load_dwordx4 v[40:43], v[56:57], off offset:128
	v_lshl_add_u64 v[58:59], s[14:15], 0, v[44:45]
	global_load_dwordx4 v[44:47], v[58:59], off
	global_load_dwordx4 v[48:51], v[58:59], off offset:64
	global_load_dwordx4 v[52:55], v[58:59], off offset:128
	s_waitcnt vmcnt(16)
	v_mov_b32_e32 v60, v67
	s_waitcnt vmcnt(13)
	v_mul_f32_e64 v74, v66, v16
	v_mul_f32_e64 v75, v66, v17
	v_mul_f32_e64 v16, v60, v16
	v_mul_f32_e64 v17, v60, v17
	s_waitcnt vmcnt(12)
	v_mul_f32_e64 v62, v66, v20
	v_mul_f32_e64 v63, v66, v21
	v_mul_f32_e64 v72, v66, v22
	v_mul_f32_e64 v73, v66, v23
	v_mul_f32_e64 v76, v66, v18
	v_mul_f32_e64 v77, v66, v19
	s_waitcnt vmcnt(10)
	v_mov_b32_e32 v78, v71
	s_waitcnt vmcnt(6)
	v_mul_f32_e64 v80, v70, v28
	v_mul_f32_e64 v81, v70, v29
	v_mul_f32_e64 v82, v70, v30
	v_mul_f32_e64 v83, v70, v31
	v_mul_f32_e64 v84, v70, v24
	v_mul_f32_e64 v85, v70, v25
	v_fma_f32 v74, v60, v0, v74
	v_fma_f32 v75, v60, v1, v75
	v_fma_f32 v0, v66, v0, -v16
	v_fma_f32 v1, v66, v1, -v17
	v_mul_f32_e64 v20, v60, v20
	v_mul_f32_e64 v21, v60, v21
	v_mul_f32_e64 v22, v60, v22
	v_mul_f32_e64 v23, v60, v23
	v_mul_f32_e64 v18, v60, v18
	v_mul_f32_e64 v19, v60, v19
	v_fma_f32 v62, v60, v4, v62
	v_fma_f32 v63, v60, v5, v63
	v_fma_f32 v72, v60, v6, v72
	v_fma_f32 v73, v60, v7, v73
	v_fma_f32 v61, v60, v3, v77
	v_fma_f32 v60, v60, v2, v76
	v_fma_f32 v76, v78, v12, v80
	v_fma_f32 v77, v78, v13, v81
	v_fma_f32 v80, v78, v14, v82
	v_fma_f32 v81, v78, v15, v83
	v_fma_f32 v82, v78, v8, v84
	v_fma_f32 v83, v78, v9, v85
	v_cvt_pk_bf16_f32 v100, v0, v1
	v_mul_f32_e64 v86, v70, v26
	v_mul_f32_e64 v87, v70, v27
	v_cvt_pk_bf16_f32 v88, v82, v83
	s_and_b32 s0, s24, -2
	v_mul_f32_e64 v28, v78, v28
	v_mul_f32_e64 v29, v78, v29
	v_mul_f32_e64 v30, v78, v30
	v_mul_f32_e64 v31, v78, v31
	v_mul_f32_e64 v24, v78, v24
	v_mul_f32_e64 v25, v78, v25
	v_mul_f32_e64 v26, v78, v26
	v_mul_f32_e64 v27, v78, v27
	v_fma_f32 v79, v78, v11, v87
	v_fma_f32 v78, v78, v10, v86
	v_cvt_pk_bf16_f32 v86, v76, v77
	v_cvt_pk_bf16_f32 v91, v72, v73
	v_fma_f32 v12, v70, v12, -v28
	v_fma_f32 v13, v70, v13, -v29
	v_fma_f32 v14, v70, v14, -v30
	v_fma_f32 v15, v70, v15, -v31
	v_fma_f32 v8, v70, v8, -v24
	v_fma_f32 v9, v70, v9, -v25
	v_fma_f32 v10, v70, v10, -v26
	v_fma_f32 v11, v70, v11, -v27
	global_load_dwordx4 v[106:109], v[58:59], off offset:192
	global_load_dwordx4 v[118:121], v[56:57], off offset:192
	v_fma_f32 v4, v66, v4, -v20
	v_fma_f32 v5, v66, v5, -v21
	v_fma_f32 v2, v66, v2, -v18
	v_fma_f32 v3, v66, v3, -v19
	s_lshl_b32 s1, s26, 6
	v_cvt_pk_bf16_f32 v98, v4, v5
	v_cvt_pk_bf16_f32 v101, v2, v3
	v_mov_b32_e32 v143, v127
	v_cvt_pk_bf16_f32 v89, v78, v79
	v_or_b32_e32 v168, s1, v125
	s_or_b32 s24, s24, 1
	v_lshlrev_b32_e32 v126, 1, v128
	v_or_b32_e32 v167, 16, v168
	v_fma_f32 v6, v66, v6, -v22
	v_fma_f32 v7, v66, v7, -v23
	v_cvt_pk_bf16_f32 v99, v6, v7
	v_cvt_pk_bf16_f32 v87, v80, v81
	v_or_b32_e32 v166, 32, v168
	v_cvt_pk_bf16_f32 v96, v8, v9
	v_cvt_pk_bf16_f32 v97, v10, v11
	v_cvt_pk_bf16_f32 v90, v62, v63
	v_cvt_pk_bf16_f32 v92, v74, v75
	v_cvt_pk_bf16_f32 v93, v60, v61
	v_cvt_pk_bf16_f32 v94, v12, v13
	v_cvt_pk_bf16_f32 v95, v14, v15
	v_mul_f32_e64 v170, v65, v156
	v_mul_f32_e64 v171, v64, v156
	v_fma_f32 v172, v64, v154, -v170
	v_fma_f32 v173, v65, v155, -v171
	v_fma_f32 v170, v64, v154, v170
	v_fma_f32 v171, v65, v154, v171
	v_add_u32_e32 v165, 0xe00, v129
	v_mov_b32_e32 v173, v171
	s_add_i32 s46, s46, s58
	s_add_i32 s37, s37, s38
	s_waitcnt vmcnt(7)
	v_xor_b32_e32 v0, 0x80000000, v32
	v_xor_b32_e32 v1, 0x80000000, v33
	s_waitcnt vmcnt(4)
	v_cvt_pk_bf16_f32 v82, v44, v0
	v_xor_b32_e32 v0, 0x80000000, v43
	v_cvt_pk_bf16_f32 v83, v45, v1
	s_waitcnt vmcnt(2)
	v_cvt_pk_bf16_f32 v77, v55, v0
	v_lshl_add_u64 v[0:1], s[12:13], 2, v[136:137]
	global_load_dwordx4 v[70:73], v[0:1], off
	v_or_b32_e32 v0, s0, v123
	v_ashrrev_i32_e32 v1, 31, v0
	v_lshlrev_b64 v[0:1], 12, v[0:1]
	v_xor_b32_e32 v2, 0x80000000, v34
	v_xor_b32_e32 v3, 0x80000000, v35
	v_xor_b32_e32 v4, 0x80000000, v36
	v_xor_b32_e32 v5, 0x80000000, v37
	v_or3_b32 v0, v0, v124, s1
	v_mov_b64_e32 v[36:37], s[6:7]
	v_cvt_pk_bf16_f32 v84, v46, v2
	v_cvt_pk_bf16_f32 v85, v47, v3
	v_mad_u64_u32 v[2:3], s[26:27], v0, s41, v[36:37]
	v_mad_i32_i24 v3, v1, s41, v3
	s_lshl_b32 s12, s25, 5
	v_lshl_add_u64 v[0:1], v[2:3], 0, s[12:13]
	v_lshl_add_u64 v[0:1], v[0:1], 0, v[142:143]
	v_add_co_u32_e32 v2, vcc, s42, v0
	v_cvt_pk_bf16_f32 v78, v48, v4
	s_nop 0
	v_addc_co_u32_e32 v3, vcc, 0, v1, vcc
	v_add_co_u32_e32 v4, vcc, s43, v0
	v_cvt_pk_bf16_f32 v79, v49, v5
	s_nop 0
	v_addc_co_u32_e32 v5, vcc, 0, v1, vcc
	global_load_dwordx4 v[32:35], v[2:3], off offset:2048
	global_load_dwordx4 v[114:117], v[4:5], off offset:2048
	v_add_co_u32_e32 v2, vcc, s44, v0
	s_ashr_i32 s1, s0, 31
	s_nop 0
	v_addc_co_u32_e32 v3, vcc, 0, v1, vcc
	v_add_co_u32_e32 v0, vcc, s45, v0
	s_lshl_b64 s[26:27], s[0:1], 12
	s_nop 0
	v_addc_co_u32_e32 v1, vcc, 0, v1, vcc
	global_load_dwordx4 v[110:113], v[2:3], off offset:2048
	global_load_dwordx4 v[102:105], v[0:1], off offset:2048
	v_or_b32_e32 v0, s26, v168
	v_mad_u64_u32 v[0:1], s[34:35], v0, s41, v[36:37]
	s_ashr_i32 s25, s24, 31
	s_lshl_b64 s[34:35], s[24:25], 12
	v_mad_i32_i24 v1, s27, v164, v1
	v_or_b32_e32 v2, s34, v168
	v_lshl_add_u64 v[0:1], v[0:1], 0, s[12:13]
	v_mad_u64_u32 v[2:3], s[48:49], v2, s41, v[36:37]
	v_lshl_add_u64 v[0:1], v[0:1], 0, v[126:127]
	v_mad_i32_i24 v3, s35, v164, v3
	v_or_b32_e32 v4, s26, v167
	v_xor_b32_e32 v6, 0x80000000, v38
	v_add_co_u32_e32 v0, vcc, s42, v0
	v_lshl_add_u64 v[2:3], v[2:3], 0, s[12:13]
	v_mad_u64_u32 v[4:5], s[48:49], v4, s41, v[36:37]
	v_xor_b32_e32 v7, 0x80000000, v39
	v_cvt_pk_bf16_f32 v80, v50, v6
	v_addc_co_u32_e32 v1, vcc, 0, v1, vcc
	v_lshl_add_u64 v[2:3], v[2:3], 0, v[126:127]
	v_mad_i32_i24 v5, s27, v164, v5
	v_or_b32_e32 v6, s34, v167
	v_cvt_pk_bf16_f32 v81, v51, v7
	v_add_co_u32_e32 v2, vcc, s42, v2
	v_lshl_add_u64 v[4:5], v[4:5], 0, s[12:13]
	v_mad_u64_u32 v[6:7], s[48:49], v6, s41, v[36:37]
	v_addc_co_u32_e32 v3, vcc, 0, v3, vcc
	v_lshl_add_u64 v[4:5], v[4:5], 0, v[126:127]
	v_mad_i32_i24 v7, s35, v164, v7
	v_add_co_u32_e32 v4, vcc, s42, v4
	v_lshl_add_u64 v[6:7], v[6:7], 0, s[12:13]
	s_nop 0
	v_addc_co_u32_e32 v5, vcc, 0, v5, vcc
	v_lshl_add_u64 v[6:7], v[6:7], 0, v[126:127]
	v_add_co_u32_e32 v6, vcc, s42, v6
	v_or_b32_e32 v143, 48, v168
	s_nop 0
	v_addc_co_u32_e32 v7, vcc, 0, v7, vcc
	global_load_dwordx2 v[160:161], v[0:1], off offset:2048
	global_load_dwordx2 v[158:159], v[2:3], off offset:2048
	global_load_dwordx2 v[152:153], v[4:5], off offset:2048
	global_load_dwordx2 v[150:151], v[6:7], off offset:2048
	v_or_b32_e32 v0, s26, v166
	v_mad_u64_u32 v[0:1], s[48:49], v0, s41, v[36:37]
	v_mad_i32_i24 v1, s27, v164, v1
	v_lshl_add_u64 v[0:1], v[0:1], 0, s[12:13]
	v_lshl_add_u64 v[0:1], v[0:1], 0, v[126:127]
	v_add_co_u32_e32 v38, vcc, s42, v0
	v_or_b32_e32 v0, s34, v166
	s_nop 0
	v_addc_co_u32_e32 v39, vcc, 0, v1, vcc
	v_mad_u64_u32 v[0:1], s[48:49], v0, s41, v[36:37]
	v_mad_i32_i24 v1, s35, v164, v1
	v_lshl_add_u64 v[0:1], v[0:1], 0, s[12:13]
	v_lshl_add_u64 v[0:1], v[0:1], 0, v[126:127]
	v_xor_b32_e32 v8, 0x80000000, v40
	v_add_co_u32_e32 v40, vcc, s42, v0
	v_or_b32_e32 v0, s26, v143
	v_xor_b32_e32 v9, 0x80000000, v41
	v_addc_co_u32_e32 v41, vcc, 0, v1, vcc
	v_mad_u64_u32 v[0:1], s[48:49], v0, s41, v[36:37]
	v_mad_i32_i24 v1, s27, v164, v1
	v_or_b32_e32 v44, s34, v143
	v_lshl_add_u64 v[0:1], v[0:1], 0, s[12:13]
	v_mad_u64_u32 v[36:37], s[26:27], v44, s41, v[36:37]
	v_xor_b32_e32 v10, 0x80000000, v42
	v_lshl_add_u64 v[42:43], v[0:1], 0, v[126:127]
	v_mad_i32_i24 v37, s35, v164, v37
	v_add_co_u32_e32 v42, vcc, s42, v42
	v_lshl_add_u64 v[36:37], v[36:37], 0, s[12:13]
	s_waitcnt vmcnt(7)
	v_mfma_f32_32x32x16_bf16 v[16:31], v[32:35], v[98:101], 0
	v_addc_co_u32_e32 v43, vcc, 0, v43, vcc
	v_lshl_add_u64 v[36:37], v[36:37], 0, v[126:127]
	v_cvt_pk_bf16_f32 v74, v52, v8
	v_cvt_pk_bf16_f32 v75, v53, v9
	v_cvt_pk_bf16_f32 v76, v54, v10
	v_add_co_u32_e32 v36, vcc, s42, v36
	v_mfma_f32_32x32x16_bf16 v[48:63], v[32:35], v[90:93], 0
	s_nop 0
	v_addc_co_u32_e32 v37, vcc, 0, v37, vcc
	global_load_dwordx2 v[148:149], v[38:39], off offset:2048
	global_load_dwordx2 v[146:147], v[40:41], off offset:2048
	global_load_dwordx2 v[144:145], v[42:43], off offset:2048
	global_load_dwordx2 v[66:67], v[36:37], off offset:2048
	v_mov_b32_e32 v170, v16
	v_mov_b32_e32 v16, v157
	v_mul_f32_e64 v156, v69, v16
	v_mul_f32_e64 v157, v68, v16
	s_lshl_b64 s[0:1], s[0:1], 23
	v_mfma_f32_32x32x16_bf16 v[0:15], v[32:35], v[94:97], 0
	s_nop 0
	v_mov_b32_e32 v171, v48
	v_add_f32_e64 v170, v172, v170
	v_add_f32_e64 v171, v173, v171
	v_fma_f32 v172, v68, v155, -v156
	v_fma_f32 v173, v69, v155, -v157
	v_fma_f32 v154, v68, v155, v156
	v_fma_f32 v155, v69, v155, v157
	v_mul_f32_e64 v156, v65, v171
	v_mul_f32_e64 v157, v64, v171
	v_mov_b32_e32 v173, v155
	v_cvt_pk_bf16_f32 v48, v170, v171
	v_mfma_f32_32x32x16_bf16 v[32:47], v[32:35], v[86:89], 0
	s_nop 0
	v_mov_b32_e32 v154, v0
	s_nop 9
	v_mov_b32_e32 v155, v32
	v_add_f32_e64 v154, v172, v154
	v_add_f32_e64 v155, v173, v155
	v_fma_f32 v172, v64, v170, -v156
	v_fma_f32 v173, v65, v171, -v157
	v_cvt_pk_bf16_f32 v0, v154, v155
	v_fma_f32 v156, v64, v170, v156
	v_fma_f32 v157, v65, v170, v157
	ds_write2_b32 v129, v48, v0 offset1:32
	v_mov_b32_e32 v173, v157
	v_mov_b32_e32 v48, v17
	v_add_f32_e64 v16, v48, v172
	v_add_f32_e64 v17, v49, v173
	v_mul_f32_e64 v48, v69, v155
	v_mul_f32_e64 v49, v68, v155
	v_fma_f32 v156, v68, v154, -v48
	v_fma_f32 v157, v69, v155, -v49
	v_fma_f32 v48, v68, v154, v48
	v_fma_f32 v49, v69, v154, v49
	v_mov_b32_e32 v32, v1
	v_mov_b32_e32 v157, v49
	v_add_f32_e64 v0, v32, v156
	v_add_f32_e64 v1, v33, v157
	v_cvt_pk_bf16_f32 v126, v16, v17
	v_cvt_pk_bf16_f32 v32, v0, v1
	ds_write2_b32 v129, v126, v32 offset0:68 offset1:100
	v_mul_f32_e64 v32, v65, v16
	v_mul_f32_e64 v33, v65, v17
	v_add_u32_e32 v154, 0x400, v129
	v_fma_f32 v48, v64, v16, -v33
	v_fma_f32 v49, v65, v17, -v32
	v_fma_f32 v16, v64, v16, v33
	v_fma_f32 v17, v64, v17, v32
	v_mov_b32_e32 v49, v17
	v_mov_b32_e32 v16, v18
	v_mov_b32_e32 v17, v50
	v_mul_f32_e64 v32, v69, v0
	v_mul_f32_e64 v33, v69, v1
	v_add_f32_e64 v16, v16, v48
	v_add_f32_e64 v17, v17, v49
	v_fma_f32 v48, v68, v0, -v33
	v_fma_f32 v49, v69, v1, -v32
	v_fma_f32 v0, v68, v0, v33
	v_fma_f32 v1, v68, v1, v32
	v_mov_b32_e32 v49, v1
	v_mov_b32_e32 v0, v2
	v_mov_b32_e32 v1, v34
	v_add_f32_e64 v0, v0, v48
	v_add_f32_e64 v1, v1, v49
	v_cvt_pk_bf16_f32 v18, v16, v17
	v_cvt_pk_bf16_f32 v2, v0, v1
	ds_write2_b32 v129, v18, v2 offset0:136 offset1:168
	v_mul_f32_e64 v32, v65, v16
	v_mul_f32_e64 v33, v65, v17
	v_mov_b32_e32 v50, v19
	v_mul_f32_e64 v18, v69, v0
	v_mul_f32_e64 v19, v69, v1
	v_fma_f32 v48, v64, v16, -v33
	v_fma_f32 v49, v65, v17, -v32
	v_fma_f32 v16, v64, v16, v33
	v_fma_f32 v17, v64, v17, v32
	v_fma_f32 v32, v68, v0, -v19
	v_fma_f32 v33, v69, v1, -v18
	v_fma_f32 v0, v68, v0, v19
	v_fma_f32 v1, v68, v1, v18
	v_mov_b32_e32 v49, v17
	v_mov_b32_e32 v33, v1
	v_mov_b32_e32 v34, v3
	v_add_f32_e64 v16, v50, v48
	v_add_f32_e64 v17, v51, v49
	v_add_f32_e64 v0, v34, v32
	v_add_f32_e64 v1, v35, v33
	v_cvt_pk_bf16_f32 v2, v16, v17
	v_cvt_pk_bf16_f32 v3, v0, v1
	ds_write2_b32 v129, v2, v3 offset0:204 offset1:236
	v_mul_f32_e64 v2, v65, v16
	v_mul_f32_e64 v3, v65, v17
	v_add_u32_e32 v155, 0x800, v129
	v_fma_f32 v18, v64, v16, -v3
	v_fma_f32 v19, v65, v17, -v2
	v_pk_fma_f32 v[2:3], v[64:65], v[16:17], v[2:3] op_sel:[0,0,1] op_sel_hi:[0,1,0]
	v_mov_b32_e32 v19, v3
	v_mov_b32_e32 v2, v20
	v_mov_b32_e32 v3, v52
	v_mul_f32_e64 v16, v69, v0
	v_mul_f32_e64 v17, v69, v1
	v_add_f32_e64 v2, v2, v18
	v_add_f32_e64 v3, v3, v19
	v_fma_f32 v18, v68, v0, -v17
	v_fma_f32 v19, v69, v1, -v16
	v_fma_f32 v0, v68, v0, v17
	v_fma_f32 v1, v68, v1, v16
	v_mov_b32_e32 v19, v1
	v_mov_b32_e32 v0, v4
	v_mov_b32_e32 v1, v36
	v_mul_f32_e64 v16, v65, v2
	v_mul_f32_e64 v17, v65, v3
	v_cvt_pk_bf16_f32 v20, v2, v3
	v_add_f32_e64 v0, v0, v18
	v_add_f32_e64 v1, v1, v19
	v_fma_f32 v18, v64, v2, -v17
	v_fma_f32 v19, v65, v3, -v16
	v_fma_f32 v2, v64, v2, v17
	v_fma_f32 v3, v64, v3, v16
	v_mov_b32_e32 v19, v3
	v_mov_b32_e32 v52, v21
	v_mul_f32_e64 v16, v69, v0
	v_mul_f32_e64 v17, v69, v1
	v_cvt_pk_bf16_f32 v4, v0, v1
	v_add_f32_e64 v2, v52, v18
	v_add_f32_e64 v3, v53, v19
	v_fma_f32 v18, v68, v0, -v17
	v_fma_f32 v19, v69, v1, -v16
	v_fma_f32 v0, v68, v0, v17
	v_fma_f32 v1, v68, v1, v16
	v_mov_b32_e32 v19, v1
	v_mov_b32_e32 v36, v5
	v_add_f32_e64 v0, v36, v18
	v_add_f32_e64 v1, v37, v19
	ds_write2_b32 v154, v20, v4 offset0:16 offset1:48
	v_cvt_pk_bf16_f32 v4, v2, v3
	v_cvt_pk_bf16_f32 v5, v0, v1
	ds_write2_b32 v154, v4, v5 offset0:84 offset1:116
	v_mul_f32_e64 v4, v65, v2
	v_mul_f32_e64 v5, v65, v3
	v_add_u32_e32 v157, 0xa00, v129
	v_fma_f32 v16, v64, v2, -v5
	v_fma_f32 v17, v65, v3, -v4
	v_fma_f32 v2, v64, v2, v5
	v_fma_f32 v3, v64, v3, v4
	v_mov_b32_e32 v17, v3
	v_mov_b32_e32 v2, v22
	v_mov_b32_e32 v3, v54
	v_mul_f32_e64 v4, v69, v0
	v_mul_f32_e64 v5, v69, v1
	v_add_f32_e64 v2, v2, v16
	v_add_f32_e64 v3, v3, v17
	v_fma_f32 v16, v68, v0, -v5
	v_fma_f32 v17, v69, v1, -v4
	v_fma_f32 v0, v68, v0, v5
	v_fma_f32 v1, v68, v1, v4
	v_mov_b32_e32 v17, v1
	v_mov_b32_e32 v0, v6
	v_mov_b32_e32 v1, v38
	v_add_f32_e64 v0, v0, v16
	v_add_f32_e64 v1, v1, v17
	v_cvt_pk_bf16_f32 v18, v2, v3
	v_cvt_pk_bf16_f32 v4, v0, v1
	ds_write2_b32 v154, v18, v4 offset0:152 offset1:184
	v_mul_f32_e64 v4, v65, v2
	v_mul_f32_e64 v5, v65, v3
	v_mov_b32_e32 v54, v23
	v_fma_f32 v16, v64, v2, -v5
	v_fma_f32 v17, v65, v3, -v4
	v_fma_f32 v2, v64, v2, v5
	v_fma_f32 v3, v64, v3, v4
	v_mov_b32_e32 v17, v3
	v_mul_f32_e64 v4, v69, v0
	v_mul_f32_e64 v5, v69, v1
	v_add_f32_e64 v2, v54, v16
	v_add_f32_e64 v3, v55, v17
	v_fma_f32 v16, v68, v0, -v5
	v_fma_f32 v17, v69, v1, -v4
	v_fma_f32 v0, v68, v0, v5
	v_fma_f32 v1, v68, v1, v4
	v_mov_b32_e32 v17, v1
	v_mov_b32_e32 v38, v7
	v_add_f32_e64 v0, v38, v16
	v_add_f32_e64 v1, v39, v17
	v_cvt_pk_bf16_f32 v6, v2, v3
	v_cvt_pk_bf16_f32 v4, v0, v1
	ds_write2_b32 v154, v6, v4 offset0:220 offset1:252
	v_mul_f32_e64 v4, v65, v2
	v_mul_f32_e64 v5, v65, v3
	v_add_u32_e32 v156, 0xc00, v129
	v_fma_f32 v6, v64, v2, -v5
	v_fma_f32 v7, v65, v3, -v4
	v_fma_f32 v2, v64, v2, v5
	v_fma_f32 v3, v64, v3, v4
	v_mov_b32_e32 v7, v3
	v_mov_b32_e32 v2, v24
	v_mov_b32_e32 v3, v56
	v_mul_f32_e64 v4, v69, v0
	v_mul_f32_e64 v5, v69, v1
	v_add_f32_e64 v2, v2, v6
	v_add_f32_e64 v3, v3, v7
	v_fma_f32 v6, v68, v0, -v5
	v_fma_f32 v7, v69, v1, -v4
	v_fma_f32 v0, v68, v0, v5
	v_fma_f32 v1, v68, v1, v4
	v_mov_b32_e32 v7, v1
	v_mov_b32_e32 v0, v8
	v_mov_b32_e32 v1, v40
	v_add_f32_e64 v0, v0, v6
	v_add_f32_e64 v1, v1, v7
	v_cvt_pk_bf16_f32 v16, v2, v3
	v_cvt_pk_bf16_f32 v4, v0, v1
	ds_write2_b32 v155, v16, v4 offset0:32 offset1:64
	v_mul_f32_e64 v4, v65, v2
	v_mul_f32_e64 v5, v65, v3
	v_mov_b32_e32 v56, v25
	v_fma_f32 v6, v64, v2, -v5
	v_fma_f32 v7, v65, v3, -v4
	v_fma_f32 v2, v64, v2, v5
	v_fma_f32 v3, v64, v3, v4
	v_mov_b32_e32 v7, v3
	v_mul_f32_e64 v4, v69, v0
	v_mul_f32_e64 v5, v69, v1
	v_add_f32_e64 v2, v56, v6
	v_add_f32_e64 v3, v57, v7
	v_fma_f32 v6, v68, v0, -v5
	v_fma_f32 v7, v69, v1, -v4
	v_fma_f32 v0, v68, v0, v5
	v_fma_f32 v1, v68, v1, v4
	v_mov_b32_e32 v7, v1
	v_mov_b32_e32 v40, v9
	v_add_f32_e64 v0, v40, v6
	v_add_f32_e64 v1, v41, v7
	v_cvt_pk_bf16_f32 v8, v2, v3
	v_cvt_pk_bf16_f32 v4, v0, v1
	ds_write2_b32 v155, v8, v4 offset0:100 offset1:132
	v_mul_f32_e64 v4, v65, v2
	v_mul_f32_e64 v5, v65, v3
	v_lshl_add_u64 v[32:33], v[130:131], 0, s[12:13]
	v_fma_f32 v6, v64, v2, -v5
	v_fma_f32 v7, v65, v3, -v4
	v_fma_f32 v2, v64, v2, v5
	v_fma_f32 v3, v64, v3, v4
	v_mov_b32_e32 v7, v3
	v_mov_b32_e32 v2, v26
	v_mov_b32_e32 v3, v58
	v_mul_f32_e64 v4, v69, v0
	v_mul_f32_e64 v5, v69, v1
	v_add_f32_e64 v2, v2, v6
	v_add_f32_e64 v3, v3, v7
	v_fma_f32 v6, v68, v0, -v5
	v_fma_f32 v7, v69, v1, -v4
	v_fma_f32 v0, v68, v0, v5
	v_fma_f32 v1, v68, v1, v4
	v_mov_b32_e32 v7, v1
	v_mov_b32_e32 v0, v10
	v_mov_b32_e32 v1, v42
	v_add_f32_e64 v0, v0, v6
	v_add_f32_e64 v1, v1, v7
	v_cvt_pk_bf16_f32 v8, v2, v3
	v_cvt_pk_bf16_f32 v4, v0, v1
	ds_write2_b32 v155, v8, v4 offset0:168 offset1:200
	v_mul_f32_e64 v4, v65, v2
	v_mul_f32_e64 v5, v65, v3
	v_mov_b32_e32 v58, v27
	v_fma_f32 v6, v64, v2, -v5
	v_fma_f32 v7, v65, v3, -v4
	v_fma_f32 v2, v64, v2, v5
	v_fma_f32 v3, v64, v3, v4
	v_mov_b32_e32 v7, v3
	v_mul_f32_e64 v4, v69, v0
	v_mul_f32_e64 v5, v69, v1
	v_add_f32_e64 v2, v58, v6
	v_add_f32_e64 v3, v59, v7
	v_fma_f32 v6, v68, v0, -v5
	v_fma_f32 v7, v69, v1, -v4
	v_fma_f32 v0, v68, v0, v5
	v_fma_f32 v1, v68, v1, v4
	v_mov_b32_e32 v7, v1
	v_mov_b32_e32 v42, v11
	v_add_f32_e64 v0, v42, v6
	v_add_f32_e64 v1, v43, v7
	v_cvt_pk_bf16_f32 v8, v2, v3
	v_cvt_pk_bf16_f32 v4, v0, v1
	ds_write2_b32 v157, v8, v4 offset0:108 offset1:140
	v_mul_f32_e64 v4, v65, v2
	v_mul_f32_e64 v5, v65, v3
	v_lshlrev_b32_e32 v126, 11, v168
	v_fma_f32 v6, v64, v2, -v5
	v_fma_f32 v7, v65, v3, -v4
	v_fma_f32 v2, v64, v2, v5
	v_fma_f32 v3, v64, v3, v4
	v_mov_b32_e32 v7, v3
	v_mov_b32_e32 v2, v28
	v_mov_b32_e32 v3, v60
	v_mul_f32_e64 v4, v69, v0
	v_mul_f32_e64 v5, v69, v1
	v_add_f32_e64 v2, v2, v6
	v_add_f32_e64 v3, v3, v7
	v_fma_f32 v6, v68, v0, -v5
	v_fma_f32 v7, v69, v1, -v4
	v_fma_f32 v0, v68, v0, v5
	v_fma_f32 v1, v68, v1, v4
	v_mov_b32_e32 v7, v1
	v_mov_b32_e32 v0, v12
	v_mov_b32_e32 v1, v44
	v_add_f32_e64 v0, v0, v6
	v_add_f32_e64 v1, v1, v7
	v_cvt_pk_bf16_f32 v8, v2, v3
	v_cvt_pk_bf16_f32 v4, v0, v1
	ds_write2_b32 v156, v8, v4 offset0:48 offset1:80
	v_mul_f32_e64 v4, v65, v2
	v_mul_f32_e64 v5, v65, v3
	v_mov_b32_e32 v60, v29
	v_fma_f32 v6, v64, v2, -v5
	v_fma_f32 v7, v65, v3, -v4
	v_fma_f32 v2, v64, v2, v5
	v_fma_f32 v3, v64, v3, v4
	v_mov_b32_e32 v7, v3
	v_mul_f32_e64 v4, v69, v0
	v_mul_f32_e64 v5, v69, v1
	v_add_f32_e64 v2, v60, v6
	v_add_f32_e64 v3, v61, v7
	v_fma_f32 v6, v68, v0, -v5
	v_fma_f32 v7, v69, v1, -v4
	v_fma_f32 v0, v68, v0, v5
	v_fma_f32 v1, v68, v1, v4
	v_mov_b32_e32 v7, v1
	v_mov_b32_e32 v44, v13
	v_add_f32_e64 v0, v44, v6
	v_add_f32_e64 v1, v45, v7
	v_cvt_pk_bf16_f32 v8, v2, v3
	v_cvt_pk_bf16_f32 v4, v0, v1
	ds_write2_b32 v156, v8, v4 offset0:116 offset1:148
	v_mul_f32_e64 v4, v65, v2
	v_mul_f32_e64 v5, v65, v3
	v_xor_b32_e32 v12, 0x80000000, v120
	v_fma_f32 v6, v64, v2, -v5
	v_fma_f32 v7, v65, v3, -v4
	v_fma_f32 v2, v64, v2, v5
	v_fma_f32 v3, v64, v3, v4
	v_mov_b32_e32 v7, v3
	v_mov_b32_e32 v2, v30
	v_mov_b32_e32 v3, v62
	v_mul_f32_e64 v4, v69, v0
	v_mul_f32_e64 v5, v69, v1
	v_add_f32_e64 v2, v2, v6
	v_add_f32_e64 v3, v3, v7
	v_fma_f32 v6, v68, v0, -v5
	v_fma_f32 v7, v69, v1, -v4
	v_fma_f32 v0, v68, v0, v5
	v_fma_f32 v1, v68, v1, v4
	v_mov_b32_e32 v7, v1
	v_mov_b32_e32 v0, v14
	v_mov_b32_e32 v1, v46
	v_add_f32_e64 v0, v0, v6
	v_add_f32_e64 v1, v1, v7
	v_cvt_pk_bf16_f32 v8, v2, v3
	v_cvt_pk_bf16_f32 v4, v0, v1
	ds_write2_b32 v156, v8, v4 offset0:184 offset1:216
	v_mul_f32_e64 v4, v65, v2
	v_mul_f32_e64 v5, v65, v3
	v_mov_b32_e32 v62, v31
	v_fma_f32 v6, v64, v2, -v5
	v_fma_f32 v7, v65, v3, -v4
	v_fma_f32 v2, v64, v2, v5
	v_fma_f32 v3, v64, v3, v4
	v_mov_b32_e32 v7, v3
	v_mul_f32_e64 v2, v69, v0
	v_mul_f32_e64 v3, v69, v1
	v_mov_b32_e32 v46, v15
	v_fma_f32 v4, v68, v0, -v3
	v_fma_f32 v5, v69, v1, -v2
	v_fma_f32 v0, v68, v0, v3
	v_fma_f32 v1, v68, v1, v2
	v_mov_b32_e32 v5, v1
	v_add_f32_e64 v170, v62, v6
	v_add_f32_e64 v171, v63, v7
	v_add_f32_e64 v172, v46, v4
	v_add_f32_e64 v173, v47, v5
	v_cvt_pk_bf16_f32 v6, v170, v171
	v_cvt_pk_bf16_f32 v0, v172, v173
	ds_write2_b32 v165, v6, v0 offset0:124 offset1:156
	s_waitcnt lgkmcnt(0)
	ds_read_b128 v[0:3], v163
	v_xor_b32_e32 v4, 0x80000000, v118
	v_cvt_pk_bf16_f32 v106, v106, v4
	ds_read_b128 v[4:7], v163 offset:64
	s_waitcnt lgkmcnt(1)
	v_mfma_f32_16x16x32_bf16 v[0:3], v[82:85], v[0:3], 0
	v_xor_b32_e32 v8, 0x80000000, v119
	v_cvt_pk_bf16_f32 v107, v107, v8
	ds_read_b128 v[8:11], v163 offset:128
	s_waitcnt lgkmcnt(1)
	v_mfma_f32_16x16x32_bf16 v[0:3], v[78:81], v[4:7], v[0:3]
	v_cvt_pk_bf16_f32 v108, v108, v12
	v_xor_b32_e32 v12, 0x80000000, v121
	ds_read_b128 v[4:7], v163 offset:192
	v_cvt_pk_bf16_f32 v109, v109, v12
	s_waitcnt lgkmcnt(1)
	v_mfma_f32_16x16x32_bf16 v[0:3], v[74:77], v[8:11], v[0:3]
	v_lshl_add_u64 v[118:119], v[32:33], 0, s[0:1]
	v_lshl_add_u64 v[44:45], v[118:119], 0, v[126:127]
	s_lshl_b64 s[0:1], s[24:25], 23
	s_waitcnt lgkmcnt(0)
	v_mfma_f32_16x16x32_bf16 v[0:3], v[106:109], v[4:7], v[0:3]
	s_waitcnt vmcnt(7)
	v_lshlrev_b32_e32 v4, 16, v160
	v_and_b32_e32 v5, 0xffff0000, v160
	v_lshl_add_u64 v[120:121], v[32:33], 0, s[0:1]
	v_mfma_f32_32x32x16_bf16 v[48:63], v[114:117], v[90:93], 0
	v_lshl_add_u64 v[32:33], v[120:121], 0, v[126:127]
	s_nop 1
	v_fma_f32 v8, v70, v4, v0
	v_fma_f32 v9, v71, v5, v1
	s_cmpk_gt_i32 s46, 0x3ff
	v_mul_f32_e32 v0, 0x3d372713, v8
	v_mul_f32_e32 v0, v8, v0
	v_mul_f32_e32 v1, 0x3d372713, v9
	v_fma_f32 v0, v8, v0, v8
	v_mul_f32_e32 v1, v9, v1
	v_mul_f32_e32 v0, 0x3fcc422a, v0
	v_fma_f32 v1, v9, v1, v9
	v_mul_f32_e32 v0, 0xbfb8aa3b, v0
	v_mul_f32_e32 v1, 0x3fcc422a, v1
	v_exp_f32_e32 v0, v0
	v_mul_f32_e32 v1, 0xbfb8aa3b, v1
	v_exp_f32_e32 v1, v1
	v_add_f32_e32 v0, 1.0, v0
	v_rcp_f32_e32 v10, v0
	v_add_f32_e32 v0, 1.0, v1
	v_rcp_f32_e32 v11, v0
	v_lshlrev_b32_e32 v0, 16, v161
	v_and_b32_e32 v1, 0xffff0000, v161
	v_fma_f32 v12, v72, v0, v2
	v_fma_f32 v13, v73, v1, v3
	v_mul_f32_e64 v16, v8, v10
	v_mul_f32_e64 v17, v9, v11
	v_mul_f32_e32 v0, 0x3d372713, v12
	v_mul_f32_e32 v0, v12, v0
	v_fma_f32 v0, v12, v0, v12
	v_mul_f32_e32 v0, 0x3fcc422a, v0
	v_mul_f32_e32 v0, 0xbfb8aa3b, v0
	v_exp_f32_e32 v4, v0
	v_mul_f32_e32 v0, 0x3d372713, v13
	v_mul_f32_e32 v0, v13, v0
	v_fma_f32 v0, v13, v0, v13
	v_mul_f32_e32 v0, 0x3fcc422a, v0
	v_mul_f32_e32 v0, 0xbfb8aa3b, v0
	v_exp_f32_e32 v5, v0
	ds_read_b128 v[0:3], v163 offset:4352
	v_add_f32_e32 v4, 1.0, v4
	v_rcp_f32_e32 v14, v4
	v_add_f32_e32 v15, 1.0, v5
	ds_read_b128 v[4:7], v163 offset:4416
	s_waitcnt lgkmcnt(1)
	v_mfma_f32_16x16x32_bf16 v[0:3], v[82:85], v[0:3], 0
	ds_read_b128 v[8:11], v163 offset:4480
	v_rcp_f32_e32 v15, v15
	v_cvt_pk_bf16_f32 v34, v16, v17
	s_waitcnt lgkmcnt(1)
	v_mfma_f32_16x16x32_bf16 v[0:3], v[78:81], v[4:7], v[0:3]
	ds_read_b128 v[4:7], v163 offset:4544
	v_mul_f32_e64 v12, v12, v14
	v_mul_f32_e64 v13, v13, v15
	s_waitcnt lgkmcnt(1)
	v_mfma_f32_16x16x32_bf16 v[0:3], v[74:77], v[8:11], v[0:3]
	v_cvt_pk_bf16_f32 v35, v12, v13
	global_store_dwordx2 v[44:45], v[34:35], off
	s_waitcnt lgkmcnt(0)
	v_mfma_f32_16x16x32_bf16 v[0:3], v[106:109], v[4:7], v[0:3]
	s_waitcnt vmcnt(7)
	v_lshlrev_b32_e32 v4, 16, v158
	v_and_b32_e32 v5, 0xffff0000, v158
	v_mfma_f32_32x32x16_bf16 v[16:31], v[114:117], v[98:101], 0
	s_nop 3
	v_fma_f32 v36, v70, v4, v0
	v_fma_f32 v37, v71, v5, v1
	v_mul_f32_e32 v0, 0x3d372713, v36
	v_mul_f32_e32 v0, v36, v0
	v_mul_f32_e32 v1, 0x3d372713, v37
	v_fma_f32 v0, v36, v0, v36
	v_mul_f32_e32 v1, v37, v1
	v_mul_f32_e32 v0, 0x3fcc422a, v0
	v_fma_f32 v1, v37, v1, v37
	v_mul_f32_e32 v0, 0xbfb8aa3b, v0
	v_mul_f32_e32 v1, 0x3fcc422a, v1
	v_exp_f32_e32 v0, v0
	v_mul_f32_e32 v1, 0xbfb8aa3b, v1
	v_exp_f32_e32 v1, v1
	v_add_f32_e32 v0, 1.0, v0
	v_rcp_f32_e32 v38, v0
	v_add_f32_e32 v0, 1.0, v1
	v_rcp_f32_e32 v39, v0
	v_lshlrev_b32_e32 v0, 16, v159
	v_and_b32_e32 v1, 0xffff0000, v159
	v_fma_f32 v40, v72, v0, v2
	v_fma_f32 v41, v73, v1, v3
	v_mul_f32_e64 v34, v36, v38
	v_mul_f32_e64 v35, v37, v39
	v_mul_f32_e32 v0, 0x3d372713, v40
	v_mul_f32_e32 v1, 0x3d372713, v41
	v_mul_f32_e32 v0, v40, v0
	v_mul_f32_e32 v1, v41, v1
	v_fma_f32 v0, v40, v0, v40
	v_fma_f32 v1, v41, v1, v41
	v_mul_f32_e32 v0, 0x3fcc422a, v0
	v_mul_f32_e32 v1, 0x3fcc422a, v1
	v_mul_f32_e32 v0, 0xbfb8aa3b, v0
	v_mul_f32_e32 v1, 0xbfb8aa3b, v1
	v_exp_f32_e32 v0, v0
	v_exp_f32_e32 v43, v1
	v_cvt_pk_bf16_f32 v34, v34, v35
	v_add_f32_e32 v42, 1.0, v0
	v_add_f32_e32 v43, 1.0, v43
	v_rcp_f32_e32 v42, v42
	v_rcp_f32_e32 v43, v43
	v_mfma_f32_32x32x16_bf16 v[0:15], v[114:117], v[94:97], 0
	v_mul_f32_e64 v36, v40, v42
	v_mul_f32_e64 v37, v41, v43
	v_cvt_pk_bf16_f32 v35, v36, v37
	global_store_dwordx2 v[32:33], v[34:35], off
	s_waitcnt lgkmcnt(0)
	v_mfma_f32_32x32x16_bf16 v[32:47], v[114:117], v[86:89], 0
	v_mul_f32_e64 v114, v65, v170
	v_mul_f32_e64 v115, v65, v171
	v_fma_f32 v116, v64, v170, -v115
	v_fma_f32 v117, v65, v171, -v114
	v_pk_fma_f32 v[114:115], v[64:65], v[170:171], v[114:115] op_sel:[0,0,1] op_sel_hi:[0,1,0]
	v_mov_b32_e32 v117, v115
	v_mov_b32_e32 v114, v16
	v_mov_b32_e32 v115, v48
	v_add_f32_e64 v114, v116, v114
	v_add_f32_e64 v115, v117, v115
	v_mul_f32_e64 v116, v69, v172
	v_mul_f32_e64 v117, v69, v173
	v_cvt_pk_bf16_f32 v16, v114, v115
	v_fma_f32 v158, v68, v172, -v117
	v_fma_f32 v159, v69, v173, -v116
	v_pk_fma_f32 v[116:117], v[68:69], v[172:173], v[116:117] op_sel:[0,0,1] op_sel_hi:[0,1,0]
	v_mov_b32_e32 v159, v117
	v_mov_b32_e32 v116, v0
	v_mov_b32_e32 v117, v32
	v_add_f32_e64 v116, v158, v116
	v_add_f32_e64 v117, v159, v117
	v_mul_f32_e64 v158, v65, v115
	v_mul_f32_e64 v159, v64, v115
	v_fma_f32 v160, v64, v114, -v158
	v_fma_f32 v161, v65, v115, -v159
	v_fma_f32 v115, v65, v114, v159
	v_fma_f32 v114, v64, v114, v158
	v_cvt_pk_bf16_f32 v0, v116, v117
	v_mov_b32_e32 v161, v115
	v_mov_b32_e32 v48, v17
	ds_write2_b32 v129, v16, v0 offset1:32
	v_add_f32_e64 v16, v48, v160
	v_add_f32_e64 v17, v49, v161
	v_mul_f32_e64 v48, v69, v117
	v_mul_f32_e64 v49, v68, v117
	v_fma_f32 v114, v68, v116, -v48
	v_fma_f32 v115, v69, v117, -v49
	v_fma_f32 v48, v68, v116, v48
	v_fma_f32 v49, v69, v116, v49
	v_mov_b32_e32 v32, v1
	v_mov_b32_e32 v115, v49
	v_add_f32_e64 v0, v32, v114
	v_add_f32_e64 v1, v33, v115
	v_cvt_pk_bf16_f32 v126, v16, v17
	v_cvt_pk_bf16_f32 v32, v0, v1
	ds_write2_b32 v129, v126, v32 offset0:68 offset1:100
	v_mul_f32_e64 v32, v65, v16
	v_mul_f32_e64 v33, v65, v17
	v_lshlrev_b32_e32 v126, 11, v167
	v_fma_f32 v48, v64, v16, -v33
	v_fma_f32 v49, v65, v17, -v32
	v_fma_f32 v16, v64, v16, v33
	v_fma_f32 v17, v64, v17, v32
	v_mov_b32_e32 v49, v17
	v_mov_b32_e32 v16, v18
	v_mov_b32_e32 v17, v50
	v_mul_f32_e64 v32, v69, v0
	v_mul_f32_e64 v33, v69, v1
	v_add_f32_e64 v16, v16, v48
	v_add_f32_e64 v17, v17, v49
	v_fma_f32 v48, v68, v0, -v33
	v_fma_f32 v49, v69, v1, -v32
	v_fma_f32 v0, v68, v0, v33
	v_fma_f32 v1, v68, v1, v32
	v_mov_b32_e32 v49, v1
	v_mov_b32_e32 v0, v2
	v_mov_b32_e32 v1, v34
	v_add_f32_e64 v0, v0, v48
	v_add_f32_e64 v1, v1, v49
	v_cvt_pk_bf16_f32 v18, v16, v17
	v_cvt_pk_bf16_f32 v2, v0, v1
	ds_write2_b32 v129, v18, v2 offset0:136 offset1:168
	v_mul_f32_e64 v32, v65, v16
	v_mul_f32_e64 v33, v65, v17
	v_mov_b32_e32 v50, v19
	v_mul_f32_e64 v18, v69, v0
	v_mul_f32_e64 v19, v69, v1
	v_fma_f32 v48, v64, v16, -v33
	v_fma_f32 v49, v65, v17, -v32
	v_fma_f32 v16, v64, v16, v33
	v_fma_f32 v17, v64, v17, v32
	v_fma_f32 v32, v68, v0, -v19
	v_fma_f32 v33, v69, v1, -v18
	v_fma_f32 v0, v68, v0, v19
	v_fma_f32 v1, v68, v1, v18
	v_mov_b32_e32 v49, v17
	v_mov_b32_e32 v33, v1
	v_mov_b32_e32 v34, v3
	v_add_f32_e64 v16, v50, v48
	v_add_f32_e64 v17, v51, v49
	v_add_f32_e64 v0, v34, v32
	v_add_f32_e64 v1, v35, v33
	v_cvt_pk_bf16_f32 v2, v16, v17
	v_cvt_pk_bf16_f32 v3, v0, v1
	ds_write2_b32 v129, v2, v3 offset0:204 offset1:236
	v_mul_f32_e64 v2, v65, v16
	v_mul_f32_e64 v3, v65, v17
	s_nop 0
	v_fma_f32 v18, v64, v16, -v3
	v_fma_f32 v19, v65, v17, -v2
	v_pk_fma_f32 v[2:3], v[64:65], v[16:17], v[2:3] op_sel:[0,0,1] op_sel_hi:[0,1,0]
	v_mov_b32_e32 v19, v3
	v_mov_b32_e32 v2, v20
	v_mov_b32_e32 v3, v52
	v_mul_f32_e64 v16, v69, v0
	v_mul_f32_e64 v17, v69, v1
	v_add_f32_e64 v2, v2, v18
	v_add_f32_e64 v3, v3, v19
	v_fma_f32 v18, v68, v0, -v17
	v_fma_f32 v19, v69, v1, -v16
	v_fma_f32 v0, v68, v0, v17
	v_fma_f32 v1, v68, v1, v16
	v_mov_b32_e32 v19, v1
	v_mov_b32_e32 v0, v4
	v_mov_b32_e32 v1, v36
	v_mul_f32_e64 v16, v65, v2
	v_mul_f32_e64 v17, v65, v3
	v_cvt_pk_bf16_f32 v20, v2, v3
	v_add_f32_e64 v0, v0, v18
	v_add_f32_e64 v1, v1, v19
	v_fma_f32 v18, v64, v2, -v17
	v_fma_f32 v19, v65, v3, -v16
	v_fma_f32 v2, v64, v2, v17
	v_fma_f32 v3, v64, v3, v16
	v_mov_b32_e32 v19, v3
	v_mov_b32_e32 v52, v21
	v_mul_f32_e64 v16, v69, v0
	v_mul_f32_e64 v17, v69, v1
	v_cvt_pk_bf16_f32 v4, v0, v1
	v_add_f32_e64 v2, v52, v18
	v_add_f32_e64 v3, v53, v19
	v_fma_f32 v18, v68, v0, -v17
	v_fma_f32 v19, v69, v1, -v16
	v_fma_f32 v0, v68, v0, v17
	v_fma_f32 v1, v68, v1, v16
	v_mov_b32_e32 v19, v1
	v_mov_b32_e32 v36, v5
	v_add_f32_e64 v0, v36, v18
	v_add_f32_e64 v1, v37, v19
	ds_write2_b32 v154, v20, v4 offset0:16 offset1:48
	v_cvt_pk_bf16_f32 v4, v2, v3
	v_cvt_pk_bf16_f32 v5, v0, v1
	ds_write2_b32 v154, v4, v5 offset0:84 offset1:116
	v_mul_f32_e64 v4, v65, v2
	v_mul_f32_e64 v5, v65, v3
	v_lshl_add_u64 v[36:37], v[118:119], 0, v[126:127]
	v_fma_f32 v16, v64, v2, -v5
	v_fma_f32 v17, v65, v3, -v4
	v_fma_f32 v2, v64, v2, v5
	v_fma_f32 v3, v64, v3, v4
	v_mov_b32_e32 v17, v3
	v_mov_b32_e32 v2, v22
	v_mov_b32_e32 v3, v54
	v_mul_f32_e64 v4, v69, v0
	v_mul_f32_e64 v5, v69, v1
	v_add_f32_e64 v2, v2, v16
	v_add_f32_e64 v3, v3, v17
	v_fma_f32 v16, v68, v0, -v5
	v_fma_f32 v17, v69, v1, -v4
	v_fma_f32 v0, v68, v0, v5
	v_fma_f32 v1, v68, v1, v4
	v_mov_b32_e32 v17, v1
	v_mov_b32_e32 v0, v6
	v_mov_b32_e32 v1, v38
	v_add_f32_e64 v0, v0, v16
	v_add_f32_e64 v1, v1, v17
	v_cvt_pk_bf16_f32 v18, v2, v3
	v_cvt_pk_bf16_f32 v4, v0, v1
	ds_write2_b32 v154, v18, v4 offset0:152 offset1:184
	v_mul_f32_e64 v4, v65, v2
	v_mul_f32_e64 v5, v65, v3
	v_mov_b32_e32 v54, v23
	v_fma_f32 v16, v64, v2, -v5
	v_fma_f32 v17, v65, v3, -v4
	v_fma_f32 v2, v64, v2, v5
	v_fma_f32 v3, v64, v3, v4
	v_mov_b32_e32 v17, v3
	v_mul_f32_e64 v4, v69, v0
	v_mul_f32_e64 v5, v69, v1
	v_add_f32_e64 v2, v54, v16
	v_add_f32_e64 v3, v55, v17
	v_fma_f32 v16, v68, v0, -v5
	v_fma_f32 v17, v69, v1, -v4
	v_fma_f32 v0, v68, v0, v5
	v_fma_f32 v1, v68, v1, v4
	v_mov_b32_e32 v17, v1
	v_mov_b32_e32 v38, v7
	v_add_f32_e64 v0, v38, v16
	v_add_f32_e64 v1, v39, v17
	v_cvt_pk_bf16_f32 v6, v2, v3
	v_cvt_pk_bf16_f32 v4, v0, v1
	ds_write2_b32 v154, v6, v4 offset0:220 offset1:252
	v_mul_f32_e64 v4, v65, v2
	v_mul_f32_e64 v5, v65, v3
	s_nop 0
	v_fma_f32 v6, v64, v2, -v5
	v_fma_f32 v7, v65, v3, -v4
	v_fma_f32 v2, v64, v2, v5
	v_fma_f32 v3, v64, v3, v4
	v_mov_b32_e32 v7, v3
	v_mov_b32_e32 v2, v24
	v_mov_b32_e32 v3, v56
	v_mul_f32_e64 v4, v69, v0
	v_mul_f32_e64 v5, v69, v1
	v_add_f32_e64 v2, v2, v6
	v_add_f32_e64 v3, v3, v7
	v_fma_f32 v6, v68, v0, -v5
	v_fma_f32 v7, v69, v1, -v4
	v_fma_f32 v0, v68, v0, v5
	v_fma_f32 v1, v68, v1, v4
	v_mov_b32_e32 v7, v1
	v_mov_b32_e32 v0, v8
	v_mov_b32_e32 v1, v40
	v_add_f32_e64 v0, v0, v6
	v_add_f32_e64 v1, v1, v7
	v_cvt_pk_bf16_f32 v16, v2, v3
	v_cvt_pk_bf16_f32 v4, v0, v1
	ds_write2_b32 v155, v16, v4 offset0:32 offset1:64
	v_mul_f32_e64 v4, v65, v2
	v_mul_f32_e64 v5, v65, v3
	v_mov_b32_e32 v56, v25
	v_fma_f32 v6, v64, v2, -v5
	v_fma_f32 v7, v65, v3, -v4
	v_fma_f32 v2, v64, v2, v5
	v_fma_f32 v3, v64, v3, v4
	v_mov_b32_e32 v7, v3
	v_mul_f32_e64 v4, v69, v0
	v_mul_f32_e64 v5, v69, v1
	v_add_f32_e64 v2, v56, v6
	v_add_f32_e64 v3, v57, v7
	v_fma_f32 v6, v68, v0, -v5
	v_fma_f32 v7, v69, v1, -v4
	v_fma_f32 v0, v68, v0, v5
	v_fma_f32 v1, v68, v1, v4
	v_mov_b32_e32 v7, v1
	v_mov_b32_e32 v40, v9
	v_add_f32_e64 v0, v40, v6
	v_add_f32_e64 v1, v41, v7
	v_cvt_pk_bf16_f32 v8, v2, v3
	v_cvt_pk_bf16_f32 v4, v0, v1
	ds_write2_b32 v155, v8, v4 offset0:100 offset1:132
	v_mul_f32_e64 v4, v65, v2
	v_mul_f32_e64 v5, v65, v3
	s_nop 0
	v_fma_f32 v6, v64, v2, -v5
	v_fma_f32 v7, v65, v3, -v4
	v_fma_f32 v2, v64, v2, v5
	v_fma_f32 v3, v64, v3, v4
	v_mov_b32_e32 v7, v3
	v_mov_b32_e32 v2, v26
	v_mov_b32_e32 v3, v58
	v_mul_f32_e64 v4, v69, v0
	v_mul_f32_e64 v5, v69, v1
	v_add_f32_e64 v2, v2, v6
	v_add_f32_e64 v3, v3, v7
	v_fma_f32 v6, v68, v0, -v5
	v_fma_f32 v7, v69, v1, -v4
	v_fma_f32 v0, v68, v0, v5
	v_fma_f32 v1, v68, v1, v4
	v_mov_b32_e32 v7, v1
	v_mov_b32_e32 v0, v10
	v_mov_b32_e32 v1, v42
	v_add_f32_e64 v0, v0, v6
	v_add_f32_e64 v1, v1, v7
	v_cvt_pk_bf16_f32 v8, v2, v3
	v_cvt_pk_bf16_f32 v4, v0, v1
	ds_write2_b32 v155, v8, v4 offset0:168 offset1:200
	v_mul_f32_e64 v4, v65, v2
	v_mul_f32_e64 v5, v65, v3
	v_mov_b32_e32 v58, v27
	v_fma_f32 v6, v64, v2, -v5
	v_fma_f32 v7, v65, v3, -v4
	v_fma_f32 v2, v64, v2, v5
	v_fma_f32 v3, v64, v3, v4
	v_mov_b32_e32 v7, v3
	v_mul_f32_e64 v4, v69, v0
	v_mul_f32_e64 v5, v69, v1
	v_add_f32_e64 v2, v58, v6
	v_add_f32_e64 v3, v59, v7
	v_fma_f32 v6, v68, v0, -v5
	v_fma_f32 v7, v69, v1, -v4
	v_fma_f32 v0, v68, v0, v5
	v_fma_f32 v1, v68, v1, v4
	v_mov_b32_e32 v7, v1
	v_mov_b32_e32 v42, v11
	v_add_f32_e64 v0, v42, v6
	v_add_f32_e64 v1, v43, v7
	v_cvt_pk_bf16_f32 v8, v2, v3
	v_cvt_pk_bf16_f32 v4, v0, v1
	ds_write2_b32 v157, v8, v4 offset0:108 offset1:140
	v_mul_f32_e64 v4, v65, v2
	v_mul_f32_e64 v5, v65, v3
	s_nop 0
	v_fma_f32 v6, v64, v2, -v5
	v_fma_f32 v7, v65, v3, -v4
	v_fma_f32 v2, v64, v2, v5
	v_fma_f32 v3, v64, v3, v4
	v_mov_b32_e32 v7, v3
	v_mov_b32_e32 v2, v28
	v_mov_b32_e32 v3, v60
	v_mul_f32_e64 v4, v69, v0
	v_mul_f32_e64 v5, v69, v1
	v_add_f32_e64 v2, v2, v6
	v_add_f32_e64 v3, v3, v7
	v_fma_f32 v6, v68, v0, -v5
	v_fma_f32 v7, v69, v1, -v4
	v_fma_f32 v0, v68, v0, v5
	v_fma_f32 v1, v68, v1, v4
	v_mov_b32_e32 v7, v1
	v_mov_b32_e32 v0, v12
	v_mov_b32_e32 v1, v44
	v_add_f32_e64 v0, v0, v6
	v_add_f32_e64 v1, v1, v7
	v_cvt_pk_bf16_f32 v8, v2, v3
	v_cvt_pk_bf16_f32 v4, v0, v1
	ds_write2_b32 v156, v8, v4 offset0:48 offset1:80
	v_mul_f32_e64 v4, v65, v2
	v_mul_f32_e64 v5, v65, v3
	v_mov_b32_e32 v60, v29
	v_fma_f32 v6, v64, v2, -v5
	v_fma_f32 v7, v65, v3, -v4
	v_fma_f32 v2, v64, v2, v5
	v_fma_f32 v3, v64, v3, v4
	v_mov_b32_e32 v7, v3
	v_mul_f32_e64 v4, v69, v0
	v_mul_f32_e64 v5, v69, v1
	v_add_f32_e64 v2, v60, v6
	v_add_f32_e64 v3, v61, v7
	v_fma_f32 v6, v68, v0, -v5
	v_fma_f32 v7, v69, v1, -v4
	v_fma_f32 v0, v68, v0, v5
	v_fma_f32 v1, v68, v1, v4
	v_mov_b32_e32 v7, v1
	v_mov_b32_e32 v44, v13
	v_add_f32_e64 v0, v44, v6
	v_add_f32_e64 v1, v45, v7
	v_cvt_pk_bf16_f32 v8, v2, v3
	v_cvt_pk_bf16_f32 v4, v0, v1
	ds_write2_b32 v156, v8, v4 offset0:116 offset1:148
	v_mul_f32_e64 v4, v65, v2
	v_mul_f32_e64 v5, v65, v3
	s_nop 0
	v_fma_f32 v6, v64, v2, -v5
	v_fma_f32 v7, v65, v3, -v4
	v_fma_f32 v2, v64, v2, v5
	v_fma_f32 v3, v64, v3, v4
	v_mov_b32_e32 v7, v3
	v_mov_b32_e32 v2, v30
	v_mov_b32_e32 v3, v62
	v_mul_f32_e64 v4, v69, v0
	v_mul_f32_e64 v5, v69, v1
	v_add_f32_e64 v2, v2, v6
	v_add_f32_e64 v3, v3, v7
	v_fma_f32 v6, v68, v0, -v5
	v_fma_f32 v7, v69, v1, -v4
	v_fma_f32 v0, v68, v0, v5
	v_fma_f32 v1, v68, v1, v4
	v_mov_b32_e32 v7, v1
	v_mov_b32_e32 v0, v14
	v_mov_b32_e32 v1, v46
	v_add_f32_e64 v0, v0, v6
	v_add_f32_e64 v1, v1, v7
	v_cvt_pk_bf16_f32 v8, v2, v3
	v_cvt_pk_bf16_f32 v4, v0, v1
	ds_write2_b32 v156, v8, v4 offset0:184 offset1:216
	v_mul_f32_e64 v4, v65, v2
	v_mul_f32_e64 v5, v65, v3
	v_mov_b32_e32 v62, v31
	v_fma_f32 v6, v64, v2, -v5
	v_fma_f32 v7, v65, v3, -v4
	v_fma_f32 v2, v64, v2, v5
	v_fma_f32 v3, v64, v3, v4
	v_mov_b32_e32 v7, v3
	v_mul_f32_e64 v2, v69, v0
	v_mul_f32_e64 v3, v69, v1
	v_mov_b32_e32 v46, v15
	v_fma_f32 v4, v68, v0, -v3
	v_fma_f32 v5, v69, v1, -v2
	v_fma_f32 v0, v68, v0, v3
	v_fma_f32 v1, v68, v1, v2
	v_mov_b32_e32 v5, v1
	v_add_f32_e64 v114, v62, v6
	v_add_f32_e64 v115, v63, v7
	v_add_f32_e64 v116, v46, v4
	v_add_f32_e64 v117, v47, v5
	v_cvt_pk_bf16_f32 v6, v114, v115
	v_cvt_pk_bf16_f32 v0, v116, v117
	ds_write2_b32 v165, v6, v0 offset0:124 offset1:156
	s_waitcnt lgkmcnt(0)
	ds_read_b128 v[0:3], v163
	ds_read_b128 v[4:7], v163 offset:64
	s_waitcnt lgkmcnt(1)
	v_mfma_f32_16x16x32_bf16 v[0:3], v[82:85], v[0:3], 0
	s_waitcnt lgkmcnt(0)
	v_mfma_f32_16x16x32_bf16 v[0:3], v[78:81], v[4:7], v[0:3]
	ds_read_b128 v[4:7], v163 offset:128
	ds_read_b128 v[8:11], v163 offset:192
	s_waitcnt lgkmcnt(1)
	v_mfma_f32_16x16x32_bf16 v[0:3], v[74:77], v[4:7], v[0:3]
	s_waitcnt vmcnt(7)
	v_lshlrev_b32_e32 v4, 16, v152
	v_and_b32_e32 v5, 0xffff0000, v152
	s_waitcnt lgkmcnt(0)
	v_mfma_f32_16x16x32_bf16 v[0:3], v[106:109], v[8:11], v[0:3]
	v_mfma_f32_32x32x16_bf16 v[48:63], v[110:113], v[90:93], 0
	s_nop 6
	v_fma_f32 v12, v70, v4, v0
	v_fma_f32 v13, v71, v5, v1
	v_and_b32_e32 v1, 0xffff0000, v153
	v_mul_f32_e32 v0, 0x3d372713, v12
	v_mul_f32_e32 v0, v12, v0
	v_fma_f32 v0, v12, v0, v12
	v_mul_f32_e32 v0, 0x3fcc422a, v0
	v_mul_f32_e32 v0, 0xbfb8aa3b, v0
	v_exp_f32_e32 v0, v0
	s_nop 0
	v_add_f32_e32 v4, 1.0, v0
	v_mul_f32_e32 v0, 0x3d372713, v13
	v_mul_f32_e32 v0, v13, v0
	v_fma_f32 v0, v13, v0, v13
	v_mul_f32_e32 v0, 0x3fcc422a, v0
	v_mul_f32_e32 v0, 0xbfb8aa3b, v0
	v_exp_f32_e32 v5, v0
	v_lshlrev_b32_e32 v0, 16, v153
	v_fma_f32 v14, v72, v0, v2
	v_fma_f32 v15, v73, v1, v3
	v_rcp_f32_e32 v16, v4
	v_mul_f32_e32 v0, 0x3d372713, v14
	v_mul_f32_e32 v0, v14, v0
	v_fma_f32 v0, v14, v0, v14
	v_mul_f32_e32 v0, 0x3fcc422a, v0
	v_mul_f32_e32 v0, 0xbfb8aa3b, v0
	v_exp_f32_e32 v0, v0
	v_add_f32_e32 v1, 1.0, v5
	v_rcp_f32_e32 v17, v1
	v_add_f32_e32 v4, 1.0, v0
	v_mul_f32_e32 v0, 0x3d372713, v15
	v_mul_f32_e32 v0, v15, v0
	v_fma_f32 v0, v15, v0, v15
	v_mul_f32_e32 v5, 0x3fcc422a, v0
	ds_read_b128 v[0:3], v163 offset:4352
	v_mul_f32_e32 v5, 0xbfb8aa3b, v5
	v_exp_f32_e32 v8, v5
	v_rcp_f32_e32 v18, v4
	ds_read_b128 v[4:7], v163 offset:4416
	s_waitcnt lgkmcnt(1)
	v_mfma_f32_16x16x32_bf16 v[0:3], v[82:85], v[0:3], 0
	v_add_f32_e32 v8, 1.0, v8
	v_rcp_f32_e32 v19, v8
	ds_read_b128 v[8:11], v163 offset:4480
	s_waitcnt lgkmcnt(1)
	v_mfma_f32_16x16x32_bf16 v[0:3], v[78:81], v[4:7], v[0:3]
	ds_read_b128 v[4:7], v163 offset:4544
	v_mul_f32_e64 v12, v12, v16
	v_mul_f32_e64 v13, v13, v17
	v_mul_f32_e64 v14, v14, v18
	v_mul_f32_e64 v15, v15, v19
	s_waitcnt lgkmcnt(1)
	v_mfma_f32_16x16x32_bf16 v[0:3], v[74:77], v[8:11], v[0:3]
	v_cvt_pk_bf16_f32 v32, v12, v13
	v_cvt_pk_bf16_f32 v33, v14, v15
	global_store_dwordx2 v[36:37], v[32:33], off
	s_waitcnt lgkmcnt(0)
	v_mfma_f32_16x16x32_bf16 v[0:3], v[106:109], v[4:7], v[0:3]
	s_waitcnt vmcnt(7)
	v_lshlrev_b32_e32 v4, 16, v150
	v_and_b32_e32 v5, 0xffff0000, v150
	v_mfma_f32_32x32x16_bf16 v[16:31], v[110:113], v[98:101], 0
	s_nop 3
	v_fma_f32 v34, v70, v4, v0
	v_fma_f32 v35, v71, v5, v1
	v_mul_f32_e32 v0, 0x3d372713, v34
	v_mul_f32_e32 v0, v34, v0
	v_mul_f32_e32 v1, 0x3d372713, v35
	v_fma_f32 v0, v34, v0, v34
	v_mul_f32_e32 v1, v35, v1
	v_mul_f32_e32 v0, 0x3fcc422a, v0
	v_fma_f32 v1, v35, v1, v35
	v_mul_f32_e32 v0, 0xbfb8aa3b, v0
	v_mul_f32_e32 v1, 0x3fcc422a, v1
	v_exp_f32_e32 v0, v0
	v_mul_f32_e32 v1, 0xbfb8aa3b, v1
	v_exp_f32_e32 v1, v1
	v_add_f32_e32 v0, 1.0, v0
	v_rcp_f32_e32 v38, v0
	v_add_f32_e32 v39, 1.0, v1
	v_lshlrev_b32_e32 v0, 16, v151
	v_and_b32_e32 v1, 0xffff0000, v151
	v_fma_f32 v40, v72, v0, v2
	v_fma_f32 v41, v73, v1, v3
	v_rcp_f32_e32 v39, v39
	v_mul_f32_e32 v0, 0x3d372713, v40
	v_mul_f32_e32 v0, v40, v0
	v_fma_f32 v0, v40, v0, v40
	v_mul_f32_e32 v0, 0x3fcc422a, v0
	v_mul_f32_e32 v0, 0xbfb8aa3b, v0
	v_exp_f32_e32 v42, v0
	v_mul_f32_e32 v0, 0x3d372713, v41
	v_mul_f32_e32 v0, v41, v0
	v_fma_f32 v0, v41, v0, v41
	v_mul_f32_e32 v0, 0x3fcc422a, v0
	v_mul_f32_e32 v43, 0xbfb8aa3b, v0
	v_exp_f32_e32 v43, v43
	v_add_f32_e32 v42, 1.0, v42
	v_rcp_f32_e32 v42, v42
	v_mul_f32_e64 v32, v34, v38
	v_mul_f32_e64 v33, v35, v39
	v_add_f32_e32 v43, 1.0, v43
	v_rcp_f32_e32 v43, v43
	v_cvt_pk_bf16_f32 v32, v32, v33
	v_mfma_f32_32x32x16_bf16 v[0:15], v[110:113], v[94:97], 0
	v_mul_f32_e64 v34, v40, v42
	v_mul_f32_e64 v35, v41, v43
	v_cvt_pk_bf16_f32 v33, v34, v35
	v_lshl_add_u64 v[34:35], v[120:121], 0, v[126:127]
	global_store_dwordx2 v[34:35], v[32:33], off
	s_waitcnt lgkmcnt(0)
	v_lshlrev_b32_e32 v126, 11, v166
	v_mfma_f32_32x32x16_bf16 v[32:47], v[110:113], v[86:89], 0
	v_mul_f32_e64 v110, v65, v114
	v_mul_f32_e64 v111, v65, v115
	v_fma_f32 v112, v64, v114, -v111
	v_fma_f32 v113, v65, v115, -v110
	v_pk_fma_f32 v[110:111], v[64:65], v[114:115], v[110:111] op_sel:[0,0,1] op_sel_hi:[0,1,0]
	v_mov_b32_e32 v113, v111
	v_mov_b32_e32 v110, v16
	v_mov_b32_e32 v111, v48
	v_add_f32_e64 v110, v112, v110
	v_add_f32_e64 v111, v113, v111
	v_mul_f32_e64 v112, v69, v116
	v_mul_f32_e64 v113, v69, v117
	v_cvt_pk_bf16_f32 v16, v110, v111
	v_fma_f32 v114, v68, v116, -v113
	v_fma_f32 v115, v69, v117, -v112
	v_pk_fma_f32 v[112:113], v[68:69], v[116:117], v[112:113] op_sel:[0,0,1] op_sel_hi:[0,1,0]
	v_mov_b32_e32 v115, v113
	v_mov_b32_e32 v112, v0
	v_mov_b32_e32 v113, v32
	v_add_f32_e64 v112, v114, v112
	v_add_f32_e64 v113, v115, v113
	v_mul_f32_e64 v114, v65, v111
	v_mul_f32_e64 v115, v64, v111
	v_fma_f32 v116, v64, v110, -v114
	v_fma_f32 v117, v65, v111, -v115
	v_fma_f32 v111, v65, v110, v115
	v_fma_f32 v110, v64, v110, v114
	v_cvt_pk_bf16_f32 v0, v112, v113
	v_mov_b32_e32 v117, v111
	v_mov_b32_e32 v48, v17
	ds_write2_b32 v129, v16, v0 offset1:32
	v_add_f32_e64 v16, v48, v116
	v_add_f32_e64 v17, v49, v117
	v_mul_f32_e64 v48, v69, v113
	v_mul_f32_e64 v49, v68, v113
	v_fma_f32 v110, v68, v112, -v48
	v_fma_f32 v111, v69, v113, -v49
	v_fma_f32 v48, v68, v112, v48
	v_fma_f32 v49, v69, v112, v49
	v_mov_b32_e32 v32, v1
	v_mov_b32_e32 v111, v49
	v_add_f32_e64 v0, v32, v110
	v_add_f32_e64 v1, v33, v111
	v_cvt_pk_bf16_f32 v114, v16, v17
	v_cvt_pk_bf16_f32 v32, v0, v1
	ds_write2_b32 v129, v114, v32 offset0:68 offset1:100
	v_mul_f32_e64 v32, v65, v16
	v_mul_f32_e64 v33, v65, v17
	s_nop 0
	v_fma_f32 v48, v64, v16, -v33
	v_fma_f32 v49, v65, v17, -v32
	v_fma_f32 v16, v64, v16, v33
	v_fma_f32 v17, v64, v17, v32
	v_mov_b32_e32 v49, v17
	v_mov_b32_e32 v16, v18
	v_mov_b32_e32 v17, v50
	v_mul_f32_e64 v32, v69, v0
	v_mul_f32_e64 v33, v69, v1
	v_add_f32_e64 v16, v16, v48
	v_add_f32_e64 v17, v17, v49
	v_fma_f32 v48, v68, v0, -v33
	v_fma_f32 v49, v69, v1, -v32
	v_fma_f32 v0, v68, v0, v33
	v_fma_f32 v1, v68, v1, v32
	v_mov_b32_e32 v49, v1
	v_mov_b32_e32 v0, v2
	v_mov_b32_e32 v1, v34
	v_add_f32_e64 v0, v0, v48
	v_add_f32_e64 v1, v1, v49
	v_cvt_pk_bf16_f32 v18, v16, v17
	v_cvt_pk_bf16_f32 v2, v0, v1
	ds_write2_b32 v129, v18, v2 offset0:136 offset1:168
	v_mul_f32_e64 v32, v65, v16
	v_mul_f32_e64 v33, v65, v17
	v_mov_b32_e32 v50, v19
	v_mul_f32_e64 v18, v69, v0
	v_mul_f32_e64 v19, v69, v1
	v_fma_f32 v48, v64, v16, -v33
	v_fma_f32 v49, v65, v17, -v32
	v_fma_f32 v16, v64, v16, v33
	v_fma_f32 v17, v64, v17, v32
	v_fma_f32 v32, v68, v0, -v19
	v_fma_f32 v33, v69, v1, -v18
	v_fma_f32 v0, v68, v0, v19
	v_fma_f32 v1, v68, v1, v18
	v_mov_b32_e32 v49, v17
	v_mov_b32_e32 v33, v1
	v_mov_b32_e32 v34, v3
	v_add_f32_e64 v16, v50, v48
	v_add_f32_e64 v17, v51, v49
	v_add_f32_e64 v0, v34, v32
	v_add_f32_e64 v1, v35, v33
	v_cvt_pk_bf16_f32 v2, v16, v17
	v_cvt_pk_bf16_f32 v3, v0, v1
	ds_write2_b32 v129, v2, v3 offset0:204 offset1:236
	v_mul_f32_e64 v2, v65, v16
	v_mul_f32_e64 v3, v65, v17
	s_nop 0
	v_fma_f32 v18, v64, v16, -v3
	v_fma_f32 v19, v65, v17, -v2
	v_pk_fma_f32 v[2:3], v[64:65], v[16:17], v[2:3] op_sel:[0,0,1] op_sel_hi:[0,1,0]
	v_mov_b32_e32 v19, v3
	v_mov_b32_e32 v2, v20
	v_mov_b32_e32 v3, v52
	v_mul_f32_e64 v16, v69, v0
	v_mul_f32_e64 v17, v69, v1
	v_add_f32_e64 v2, v2, v18
	v_add_f32_e64 v3, v3, v19
	v_fma_f32 v18, v68, v0, -v17
	v_fma_f32 v19, v69, v1, -v16
	v_fma_f32 v0, v68, v0, v17
	v_fma_f32 v1, v68, v1, v16
	v_mov_b32_e32 v19, v1
	v_mov_b32_e32 v0, v4
	v_mov_b32_e32 v1, v36
	v_mul_f32_e64 v16, v65, v2
	v_mul_f32_e64 v17, v65, v3
	v_cvt_pk_bf16_f32 v20, v2, v3
	v_add_f32_e64 v0, v0, v18
	v_add_f32_e64 v1, v1, v19
	v_fma_f32 v18, v64, v2, -v17
	v_fma_f32 v19, v65, v3, -v16
	v_fma_f32 v2, v64, v2, v17
	v_fma_f32 v3, v64, v3, v16
	v_mov_b32_e32 v19, v3
	v_mov_b32_e32 v52, v21
	v_mul_f32_e64 v16, v69, v0
	v_mul_f32_e64 v17, v69, v1
	v_cvt_pk_bf16_f32 v4, v0, v1
	v_add_f32_e64 v2, v52, v18
	v_add_f32_e64 v3, v53, v19
	v_fma_f32 v18, v68, v0, -v17
	v_fma_f32 v19, v69, v1, -v16
	v_fma_f32 v0, v68, v0, v17
	v_fma_f32 v1, v68, v1, v16
	v_mov_b32_e32 v19, v1
	v_mov_b32_e32 v36, v5
	v_add_f32_e64 v0, v36, v18
	v_add_f32_e64 v1, v37, v19
	ds_write2_b32 v154, v20, v4 offset0:16 offset1:48
	v_cvt_pk_bf16_f32 v4, v2, v3
	v_cvt_pk_bf16_f32 v5, v0, v1
	ds_write2_b32 v154, v4, v5 offset0:84 offset1:116
	v_mul_f32_e64 v4, v65, v2
	v_mul_f32_e64 v5, v65, v3
	v_lshl_add_u64 v[36:37], v[118:119], 0, v[126:127]
	v_fma_f32 v16, v64, v2, -v5
	v_fma_f32 v17, v65, v3, -v4
	v_fma_f32 v2, v64, v2, v5
	v_fma_f32 v3, v64, v3, v4
	v_mov_b32_e32 v17, v3
	v_mov_b32_e32 v2, v22
	v_mov_b32_e32 v3, v54
	v_mul_f32_e64 v4, v69, v0
	v_mul_f32_e64 v5, v69, v1
	v_add_f32_e64 v2, v2, v16
	v_add_f32_e64 v3, v3, v17
	v_fma_f32 v16, v68, v0, -v5
	v_fma_f32 v17, v69, v1, -v4
	v_fma_f32 v0, v68, v0, v5
	v_fma_f32 v1, v68, v1, v4
	v_mov_b32_e32 v17, v1
	v_mov_b32_e32 v0, v6
	v_mov_b32_e32 v1, v38
	v_add_f32_e64 v0, v0, v16
	v_add_f32_e64 v1, v1, v17
	v_cvt_pk_bf16_f32 v18, v2, v3
	v_cvt_pk_bf16_f32 v4, v0, v1
	ds_write2_b32 v154, v18, v4 offset0:152 offset1:184
	v_mul_f32_e64 v4, v65, v2
	v_mul_f32_e64 v5, v65, v3
	v_mov_b32_e32 v54, v23
	v_fma_f32 v16, v64, v2, -v5
	v_fma_f32 v17, v65, v3, -v4
	v_fma_f32 v2, v64, v2, v5
	v_fma_f32 v3, v64, v3, v4
	v_mov_b32_e32 v17, v3
	v_mul_f32_e64 v4, v69, v0
	v_mul_f32_e64 v5, v69, v1
	v_add_f32_e64 v2, v54, v16
	v_add_f32_e64 v3, v55, v17
	v_fma_f32 v16, v68, v0, -v5
	v_fma_f32 v17, v69, v1, -v4
	v_fma_f32 v0, v68, v0, v5
	v_fma_f32 v1, v68, v1, v4
	v_mov_b32_e32 v17, v1
	v_mov_b32_e32 v38, v7
	v_add_f32_e64 v0, v38, v16
	v_add_f32_e64 v1, v39, v17
	v_cvt_pk_bf16_f32 v6, v2, v3
	v_cvt_pk_bf16_f32 v4, v0, v1
	ds_write2_b32 v154, v6, v4 offset0:220 offset1:252
	v_mul_f32_e64 v4, v65, v2
	v_mul_f32_e64 v5, v65, v3
	s_nop 0
	v_fma_f32 v6, v64, v2, -v5
	v_fma_f32 v7, v65, v3, -v4
	v_fma_f32 v2, v64, v2, v5
	v_fma_f32 v3, v64, v3, v4
	v_mov_b32_e32 v7, v3
	v_mov_b32_e32 v2, v24
	v_mov_b32_e32 v3, v56
	v_mul_f32_e64 v4, v69, v0
	v_mul_f32_e64 v5, v69, v1
	v_add_f32_e64 v2, v2, v6
	v_add_f32_e64 v3, v3, v7
	v_fma_f32 v6, v68, v0, -v5
	v_fma_f32 v7, v69, v1, -v4
	v_fma_f32 v0, v68, v0, v5
	v_fma_f32 v1, v68, v1, v4
	v_mov_b32_e32 v7, v1
	v_mov_b32_e32 v0, v8
	v_mov_b32_e32 v1, v40
	v_add_f32_e64 v0, v0, v6
	v_add_f32_e64 v1, v1, v7
	v_cvt_pk_bf16_f32 v16, v2, v3
	v_cvt_pk_bf16_f32 v4, v0, v1
	ds_write2_b32 v155, v16, v4 offset0:32 offset1:64
	v_mul_f32_e64 v4, v65, v2
	v_mul_f32_e64 v5, v65, v3
	v_mov_b32_e32 v56, v25
	v_fma_f32 v6, v64, v2, -v5
	v_fma_f32 v7, v65, v3, -v4
	v_fma_f32 v2, v64, v2, v5
	v_fma_f32 v3, v64, v3, v4
	v_mov_b32_e32 v7, v3
	v_mul_f32_e64 v4, v69, v0
	v_mul_f32_e64 v5, v69, v1
	v_add_f32_e64 v2, v56, v6
	v_add_f32_e64 v3, v57, v7
	v_fma_f32 v6, v68, v0, -v5
	v_fma_f32 v7, v69, v1, -v4
	v_fma_f32 v0, v68, v0, v5
	v_fma_f32 v1, v68, v1, v4
	v_mov_b32_e32 v7, v1
	v_mov_b32_e32 v40, v9
	v_add_f32_e64 v0, v40, v6
	v_add_f32_e64 v1, v41, v7
	v_cvt_pk_bf16_f32 v8, v2, v3
	v_cvt_pk_bf16_f32 v4, v0, v1
	ds_write2_b32 v155, v8, v4 offset0:100 offset1:132
	v_mul_f32_e64 v4, v65, v2
	v_mul_f32_e64 v5, v65, v3
	s_nop 0
	v_fma_f32 v6, v64, v2, -v5
	v_fma_f32 v7, v65, v3, -v4
	v_fma_f32 v2, v64, v2, v5
	v_fma_f32 v3, v64, v3, v4
	v_mov_b32_e32 v7, v3
	v_mov_b32_e32 v2, v26
	v_mov_b32_e32 v3, v58
	v_mul_f32_e64 v4, v69, v0
	v_mul_f32_e64 v5, v69, v1
	v_add_f32_e64 v2, v2, v6
	v_add_f32_e64 v3, v3, v7
	v_fma_f32 v6, v68, v0, -v5
	v_fma_f32 v7, v69, v1, -v4
	v_fma_f32 v0, v68, v0, v5
	v_fma_f32 v1, v68, v1, v4
	v_mov_b32_e32 v7, v1
	v_mov_b32_e32 v0, v10
	v_mov_b32_e32 v1, v42
	v_add_f32_e64 v0, v0, v6
	v_add_f32_e64 v1, v1, v7
	v_cvt_pk_bf16_f32 v8, v2, v3
	v_cvt_pk_bf16_f32 v4, v0, v1
	ds_write2_b32 v155, v8, v4 offset0:168 offset1:200
	v_mul_f32_e64 v4, v65, v2
	v_mul_f32_e64 v5, v65, v3
	v_mov_b32_e32 v58, v27
	v_fma_f32 v6, v64, v2, -v5
	v_fma_f32 v7, v65, v3, -v4
	v_fma_f32 v2, v64, v2, v5
	v_fma_f32 v3, v64, v3, v4
	v_mov_b32_e32 v7, v3
	v_mul_f32_e64 v4, v69, v0
	v_mul_f32_e64 v5, v69, v1
	v_add_f32_e64 v2, v58, v6
	v_add_f32_e64 v3, v59, v7
	v_fma_f32 v6, v68, v0, -v5
	v_fma_f32 v7, v69, v1, -v4
	v_fma_f32 v0, v68, v0, v5
	v_fma_f32 v1, v68, v1, v4
	v_mov_b32_e32 v7, v1
	v_mov_b32_e32 v42, v11
	v_add_f32_e64 v0, v42, v6
	v_add_f32_e64 v1, v43, v7
	v_cvt_pk_bf16_f32 v8, v2, v3
	v_cvt_pk_bf16_f32 v4, v0, v1
	ds_write2_b32 v157, v8, v4 offset0:108 offset1:140
	v_mul_f32_e64 v4, v65, v2
	v_mul_f32_e64 v5, v65, v3
	s_nop 0
	v_fma_f32 v6, v64, v2, -v5
	v_fma_f32 v7, v65, v3, -v4
	v_fma_f32 v2, v64, v2, v5
	v_fma_f32 v3, v64, v3, v4
	v_mov_b32_e32 v7, v3
	v_mov_b32_e32 v2, v28
	v_mov_b32_e32 v3, v60
	v_mul_f32_e64 v4, v69, v0
	v_mul_f32_e64 v5, v69, v1
	v_add_f32_e64 v2, v2, v6
	v_add_f32_e64 v3, v3, v7
	v_fma_f32 v6, v68, v0, -v5
	v_fma_f32 v7, v69, v1, -v4
	v_fma_f32 v0, v68, v0, v5
	v_fma_f32 v1, v68, v1, v4
	v_mov_b32_e32 v7, v1
	v_mov_b32_e32 v0, v12
	v_mov_b32_e32 v1, v44
	v_add_f32_e64 v0, v0, v6
	v_add_f32_e64 v1, v1, v7
	v_cvt_pk_bf16_f32 v8, v2, v3
	v_cvt_pk_bf16_f32 v4, v0, v1
	ds_write2_b32 v156, v8, v4 offset0:48 offset1:80
	v_mul_f32_e64 v4, v65, v2
	v_mul_f32_e64 v5, v65, v3
	v_mov_b32_e32 v60, v29
	v_fma_f32 v6, v64, v2, -v5
	v_fma_f32 v7, v65, v3, -v4
	v_fma_f32 v2, v64, v2, v5
	v_fma_f32 v3, v64, v3, v4
	v_mov_b32_e32 v7, v3
	v_mul_f32_e64 v4, v69, v0
	v_mul_f32_e64 v5, v69, v1
	v_add_f32_e64 v2, v60, v6
	v_add_f32_e64 v3, v61, v7
	v_fma_f32 v6, v68, v0, -v5
	v_fma_f32 v7, v69, v1, -v4
	v_fma_f32 v0, v68, v0, v5
	v_fma_f32 v1, v68, v1, v4
	v_mov_b32_e32 v7, v1
	v_mov_b32_e32 v44, v13
	v_add_f32_e64 v0, v44, v6
	v_add_f32_e64 v1, v45, v7
	v_cvt_pk_bf16_f32 v8, v2, v3
	v_cvt_pk_bf16_f32 v4, v0, v1
	ds_write2_b32 v156, v8, v4 offset0:116 offset1:148
	v_mul_f32_e64 v4, v65, v2
	v_mul_f32_e64 v5, v65, v3
	s_nop 0
	v_fma_f32 v6, v64, v2, -v5
	v_fma_f32 v7, v65, v3, -v4
	v_fma_f32 v2, v64, v2, v5
	v_fma_f32 v3, v64, v3, v4
	v_mov_b32_e32 v7, v3
	v_mov_b32_e32 v2, v30
	v_mov_b32_e32 v3, v62
	v_mul_f32_e64 v4, v69, v0
	v_mul_f32_e64 v5, v69, v1
	v_add_f32_e64 v2, v2, v6
	v_add_f32_e64 v3, v3, v7
	v_fma_f32 v6, v68, v0, -v5
	v_fma_f32 v7, v69, v1, -v4
	v_fma_f32 v0, v68, v0, v5
	v_fma_f32 v1, v68, v1, v4
	v_mov_b32_e32 v7, v1
	v_mov_b32_e32 v0, v14
	v_mov_b32_e32 v1, v46
	v_add_f32_e64 v0, v0, v6
	v_add_f32_e64 v1, v1, v7
	v_cvt_pk_bf16_f32 v8, v2, v3
	v_cvt_pk_bf16_f32 v4, v0, v1
	ds_write2_b32 v156, v8, v4 offset0:184 offset1:216
	v_mul_f32_e64 v4, v65, v2
	v_mul_f32_e64 v5, v65, v3
	v_mov_b32_e32 v62, v31
	v_fma_f32 v6, v64, v2, -v5
	v_fma_f32 v7, v65, v3, -v4
	v_fma_f32 v2, v64, v2, v5
	v_fma_f32 v3, v64, v3, v4
	v_mov_b32_e32 v7, v3
	v_mul_f32_e64 v2, v69, v0
	v_mul_f32_e64 v3, v69, v1
	v_mov_b32_e32 v46, v15
	v_fma_f32 v4, v68, v0, -v3
	v_fma_f32 v5, v69, v1, -v2
	v_fma_f32 v0, v68, v0, v3
	v_fma_f32 v1, v68, v1, v2
	v_mov_b32_e32 v5, v1
	v_add_f32_e64 v110, v62, v6
	v_add_f32_e64 v111, v63, v7
	v_add_f32_e64 v112, v46, v4
	v_add_f32_e64 v113, v47, v5
	v_cvt_pk_bf16_f32 v6, v110, v111
	v_cvt_pk_bf16_f32 v0, v112, v113
	ds_write2_b32 v165, v6, v0 offset0:124 offset1:156
	s_waitcnt lgkmcnt(0)
	ds_read_b128 v[0:3], v163
	ds_read_b128 v[4:7], v163 offset:64
	s_waitcnt lgkmcnt(1)
	v_mfma_f32_16x16x32_bf16 v[0:3], v[82:85], v[0:3], 0
	s_waitcnt lgkmcnt(0)
	v_mfma_f32_16x16x32_bf16 v[0:3], v[78:81], v[4:7], v[0:3]
	ds_read_b128 v[4:7], v163 offset:128
	ds_read_b128 v[8:11], v163 offset:192
	s_waitcnt lgkmcnt(1)
	v_mfma_f32_16x16x32_bf16 v[0:3], v[74:77], v[4:7], v[0:3]
	s_waitcnt vmcnt(7)
	v_lshlrev_b32_e32 v4, 16, v148
	v_and_b32_e32 v5, 0xffff0000, v148
	s_waitcnt lgkmcnt(0)
	v_mfma_f32_16x16x32_bf16 v[0:3], v[106:109], v[8:11], v[0:3]
	v_mfma_f32_32x32x16_bf16 v[48:63], v[102:105], v[90:93], 0
	s_nop 6
	v_fma_f32 v12, v70, v4, v0
	v_fma_f32 v13, v71, v5, v1
	v_and_b32_e32 v1, 0xffff0000, v149
	v_mul_f32_e32 v0, 0x3d372713, v12
	v_mul_f32_e32 v0, v12, v0
	v_fma_f32 v0, v12, v0, v12
	v_mul_f32_e32 v0, 0x3fcc422a, v0
	v_mul_f32_e32 v0, 0xbfb8aa3b, v0
	v_exp_f32_e32 v0, v0
	s_nop 0
	v_add_f32_e32 v4, 1.0, v0
	v_mul_f32_e32 v0, 0x3d372713, v13
	v_mul_f32_e32 v0, v13, v0
	v_fma_f32 v0, v13, v0, v13
	v_mul_f32_e32 v0, 0x3fcc422a, v0
	v_mul_f32_e32 v0, 0xbfb8aa3b, v0
	v_exp_f32_e32 v5, v0
	v_lshlrev_b32_e32 v0, 16, v149
	v_fma_f32 v14, v72, v0, v2
	v_fma_f32 v15, v73, v1, v3
	v_rcp_f32_e32 v16, v4
	v_mul_f32_e32 v0, 0x3d372713, v14
	v_mul_f32_e32 v0, v14, v0
	v_fma_f32 v0, v14, v0, v14
	v_mul_f32_e32 v0, 0x3fcc422a, v0
	v_mul_f32_e32 v0, 0xbfb8aa3b, v0
	v_exp_f32_e32 v0, v0
	v_add_f32_e32 v1, 1.0, v5
	v_rcp_f32_e32 v17, v1
	v_add_f32_e32 v4, 1.0, v0
	v_mul_f32_e32 v0, 0x3d372713, v15
	v_mul_f32_e32 v0, v15, v0
	v_fma_f32 v0, v15, v0, v15
	v_mul_f32_e32 v5, 0x3fcc422a, v0
	ds_read_b128 v[0:3], v163 offset:4352
	v_mul_f32_e32 v5, 0xbfb8aa3b, v5
	v_exp_f32_e32 v8, v5
	v_rcp_f32_e32 v18, v4
	ds_read_b128 v[4:7], v163 offset:4416
	s_waitcnt lgkmcnt(1)
	v_mfma_f32_16x16x32_bf16 v[0:3], v[82:85], v[0:3], 0
	v_add_f32_e32 v8, 1.0, v8
	v_rcp_f32_e32 v19, v8
	ds_read_b128 v[8:11], v163 offset:4480
	s_waitcnt lgkmcnt(1)
	v_mfma_f32_16x16x32_bf16 v[0:3], v[78:81], v[4:7], v[0:3]
	ds_read_b128 v[4:7], v163 offset:4544
	v_mul_f32_e64 v12, v12, v16
	v_mul_f32_e64 v13, v13, v17
	v_mul_f32_e64 v14, v14, v18
	v_mul_f32_e64 v15, v15, v19
	s_waitcnt lgkmcnt(1)
	v_mfma_f32_16x16x32_bf16 v[0:3], v[74:77], v[8:11], v[0:3]
	v_cvt_pk_bf16_f32 v32, v12, v13
	v_cvt_pk_bf16_f32 v33, v14, v15
	global_store_dwordx2 v[36:37], v[32:33], off
	s_waitcnt lgkmcnt(0)
	v_mfma_f32_16x16x32_bf16 v[0:3], v[106:109], v[4:7], v[0:3]
	s_waitcnt vmcnt(7)
	v_lshlrev_b32_e32 v4, 16, v146
	v_and_b32_e32 v5, 0xffff0000, v146
	v_mfma_f32_32x32x16_bf16 v[16:31], v[102:105], v[98:101], 0
	s_nop 3
	v_fma_f32 v34, v70, v4, v0
	v_fma_f32 v35, v71, v5, v1
	v_mul_f32_e32 v0, 0x3d372713, v34
	v_mul_f32_e32 v0, v34, v0
	v_mul_f32_e32 v1, 0x3d372713, v35
	v_fma_f32 v0, v34, v0, v34
	v_mul_f32_e32 v1, v35, v1
	v_mul_f32_e32 v0, 0x3fcc422a, v0
	v_fma_f32 v1, v35, v1, v35
	v_mul_f32_e32 v0, 0xbfb8aa3b, v0
	v_mul_f32_e32 v1, 0x3fcc422a, v1
	v_exp_f32_e32 v0, v0
	v_mul_f32_e32 v1, 0xbfb8aa3b, v1
	v_exp_f32_e32 v1, v1
	v_add_f32_e32 v0, 1.0, v0
	v_rcp_f32_e32 v38, v0
	v_add_f32_e32 v39, 1.0, v1
	v_lshlrev_b32_e32 v0, 16, v147
	v_and_b32_e32 v1, 0xffff0000, v147
	v_fma_f32 v40, v72, v0, v2
	v_fma_f32 v41, v73, v1, v3
	v_rcp_f32_e32 v39, v39
	v_mul_f32_e32 v0, 0x3d372713, v40
	v_mul_f32_e32 v0, v40, v0
	v_fma_f32 v0, v40, v0, v40
	v_mul_f32_e32 v0, 0x3fcc422a, v0
	v_mul_f32_e32 v0, 0xbfb8aa3b, v0
	v_exp_f32_e32 v42, v0
	v_mul_f32_e32 v0, 0x3d372713, v41
	v_mul_f32_e32 v0, v41, v0
	v_fma_f32 v0, v41, v0, v41
	v_mul_f32_e32 v0, 0x3fcc422a, v0
	v_mul_f32_e32 v43, 0xbfb8aa3b, v0
	v_exp_f32_e32 v43, v43
	v_add_f32_e32 v42, 1.0, v42
	v_rcp_f32_e32 v42, v42
	v_mul_f32_e64 v32, v34, v38
	v_mul_f32_e64 v33, v35, v39
	v_add_f32_e32 v43, 1.0, v43
	v_rcp_f32_e32 v43, v43
	v_cvt_pk_bf16_f32 v32, v32, v33
	v_mfma_f32_32x32x16_bf16 v[0:15], v[102:105], v[94:97], 0
	v_mul_f32_e64 v34, v40, v42
	v_mul_f32_e64 v35, v41, v43
	v_cvt_pk_bf16_f32 v33, v34, v35
	v_lshl_add_u64 v[34:35], v[120:121], 0, v[126:127]
	global_store_dwordx2 v[34:35], v[32:33], off
	s_waitcnt lgkmcnt(0)
	v_lshlrev_b32_e32 v126, 11, v143
	v_mfma_f32_32x32x16_bf16 v[32:47], v[102:105], v[86:89], 0
	v_mul_f32_e64 v86, v65, v110
	v_mul_f32_e64 v87, v65, v111
	v_fma_f32 v88, v64, v110, -v87
	v_fma_f32 v89, v65, v111, -v86
	v_pk_fma_f32 v[86:87], v[64:65], v[110:111], v[86:87] op_sel:[0,0,1] op_sel_hi:[0,1,0]
	v_mov_b32_e32 v89, v87
	v_mov_b32_e32 v86, v16
	v_mov_b32_e32 v87, v48
	v_add_f32_e64 v86, v88, v86
	v_add_f32_e64 v87, v89, v87
	v_mul_f32_e64 v88, v69, v112
	v_mul_f32_e64 v89, v69, v113
	v_cvt_pk_bf16_f32 v16, v86, v87
	v_fma_f32 v90, v68, v112, -v89
	v_fma_f32 v91, v69, v113, -v88
	v_pk_fma_f32 v[88:89], v[68:69], v[112:113], v[88:89] op_sel:[0,0,1] op_sel_hi:[0,1,0]
	v_mov_b32_e32 v91, v89
	v_mov_b32_e32 v88, v0
	v_mov_b32_e32 v89, v32
	v_add_f32_e64 v88, v90, v88
	v_add_f32_e64 v89, v91, v89
	v_mul_f32_e64 v90, v65, v87
	v_mul_f32_e64 v91, v64, v87
	v_fma_f32 v92, v64, v86, -v90
	v_fma_f32 v93, v65, v87, -v91
	v_fma_f32 v87, v65, v86, v91
	v_fma_f32 v86, v64, v86, v90
	v_cvt_pk_bf16_f32 v0, v88, v89
	v_mov_b32_e32 v93, v87
	v_mov_b32_e32 v48, v17
	ds_write2_b32 v129, v16, v0 offset1:32
	v_add_f32_e64 v16, v48, v92
	v_add_f32_e64 v17, v49, v93
	v_mul_f32_e64 v48, v69, v89
	v_mul_f32_e64 v49, v68, v89
	v_fma_f32 v86, v68, v88, -v48
	v_fma_f32 v87, v69, v89, -v49
	v_fma_f32 v48, v68, v88, v48
	v_fma_f32 v49, v69, v88, v49
	v_mov_b32_e32 v32, v1
	v_mov_b32_e32 v87, v49
	v_add_f32_e64 v0, v32, v86
	v_add_f32_e64 v1, v33, v87
	v_cvt_pk_bf16_f32 v90, v16, v17
	v_cvt_pk_bf16_f32 v32, v0, v1
	ds_write2_b32 v129, v90, v32 offset0:68 offset1:100
	v_mul_f32_e64 v32, v65, v16
	v_mul_f32_e64 v33, v65, v17
	s_nop 0
	v_fma_f32 v48, v64, v16, -v33
	v_fma_f32 v49, v65, v17, -v32
	v_fma_f32 v16, v64, v16, v33
	v_fma_f32 v17, v64, v17, v32
	v_mov_b32_e32 v49, v17
	v_mov_b32_e32 v16, v18
	v_mov_b32_e32 v17, v50
	v_mul_f32_e64 v32, v69, v0
	v_mul_f32_e64 v33, v69, v1
	v_add_f32_e64 v16, v16, v48
	v_add_f32_e64 v17, v17, v49
	v_fma_f32 v48, v68, v0, -v33
	v_fma_f32 v49, v69, v1, -v32
	v_fma_f32 v0, v68, v0, v33
	v_fma_f32 v1, v68, v1, v32
	v_mov_b32_e32 v49, v1
	v_mov_b32_e32 v0, v2
	v_mov_b32_e32 v1, v34
	v_add_f32_e64 v0, v0, v48
	v_add_f32_e64 v1, v1, v49
	v_cvt_pk_bf16_f32 v18, v16, v17
	v_cvt_pk_bf16_f32 v2, v0, v1
	ds_write2_b32 v129, v18, v2 offset0:136 offset1:168
	v_mul_f32_e64 v32, v65, v16
	v_mul_f32_e64 v33, v65, v17
	v_mov_b32_e32 v50, v19
	v_mul_f32_e64 v18, v69, v0
	v_mul_f32_e64 v19, v69, v1
	v_fma_f32 v48, v64, v16, -v33
	v_fma_f32 v49, v65, v17, -v32
	v_fma_f32 v16, v64, v16, v33
	v_fma_f32 v17, v64, v17, v32
	v_fma_f32 v32, v68, v0, -v19
	v_fma_f32 v33, v69, v1, -v18
	v_fma_f32 v0, v68, v0, v19
	v_fma_f32 v1, v68, v1, v18
	v_mov_b32_e32 v49, v17
	v_mov_b32_e32 v33, v1
	v_mov_b32_e32 v34, v3
	v_add_f32_e64 v16, v50, v48
	v_add_f32_e64 v17, v51, v49
	v_add_f32_e64 v0, v34, v32
	v_add_f32_e64 v1, v35, v33
	v_cvt_pk_bf16_f32 v2, v16, v17
	v_cvt_pk_bf16_f32 v3, v0, v1
	ds_write2_b32 v129, v2, v3 offset0:204 offset1:236
	v_mul_f32_e64 v2, v65, v16
	v_mul_f32_e64 v3, v65, v17
	s_nop 0
	v_fma_f32 v18, v64, v16, -v3
	v_fma_f32 v19, v65, v17, -v2
	v_pk_fma_f32 v[2:3], v[64:65], v[16:17], v[2:3] op_sel:[0,0,1] op_sel_hi:[0,1,0]
	v_mov_b32_e32 v19, v3
	v_mov_b32_e32 v2, v20
	v_mov_b32_e32 v3, v52
	v_mul_f32_e64 v16, v69, v0
	v_mul_f32_e64 v17, v69, v1
	v_add_f32_e64 v2, v2, v18
	v_add_f32_e64 v3, v3, v19
	v_fma_f32 v18, v68, v0, -v17
	v_fma_f32 v19, v69, v1, -v16
	v_fma_f32 v0, v68, v0, v17
	v_fma_f32 v1, v68, v1, v16
	v_mov_b32_e32 v19, v1
	v_mov_b32_e32 v0, v4
	v_mov_b32_e32 v1, v36
	v_mul_f32_e64 v16, v65, v2
	v_mul_f32_e64 v17, v65, v3
	v_cvt_pk_bf16_f32 v20, v2, v3
	v_add_f32_e64 v0, v0, v18
	v_add_f32_e64 v1, v1, v19
	v_fma_f32 v18, v64, v2, -v17
	v_fma_f32 v19, v65, v3, -v16
	v_fma_f32 v2, v64, v2, v17
	v_fma_f32 v3, v64, v3, v16
	v_mov_b32_e32 v19, v3
	v_mov_b32_e32 v52, v21
	v_mul_f32_e64 v16, v69, v0
	v_mul_f32_e64 v17, v69, v1
	v_cvt_pk_bf16_f32 v4, v0, v1
	v_add_f32_e64 v2, v52, v18
	v_add_f32_e64 v3, v53, v19
	v_fma_f32 v18, v68, v0, -v17
	v_fma_f32 v19, v69, v1, -v16
	v_fma_f32 v0, v68, v0, v17
	v_fma_f32 v1, v68, v1, v16
	v_mov_b32_e32 v19, v1
	v_mov_b32_e32 v36, v5
	v_add_f32_e64 v0, v36, v18
	v_add_f32_e64 v1, v37, v19
	ds_write2_b32 v154, v20, v4 offset0:16 offset1:48
	v_cvt_pk_bf16_f32 v4, v2, v3
	v_cvt_pk_bf16_f32 v5, v0, v1
	ds_write2_b32 v154, v4, v5 offset0:84 offset1:116
	v_mul_f32_e64 v4, v65, v2
	v_mul_f32_e64 v5, v65, v3
	s_nop 0
	v_fma_f32 v16, v64, v2, -v5
	v_fma_f32 v17, v65, v3, -v4
	v_fma_f32 v2, v64, v2, v5
	v_fma_f32 v3, v64, v3, v4
	v_mov_b32_e32 v17, v3
	v_mov_b32_e32 v2, v22
	v_mov_b32_e32 v3, v54
	v_mul_f32_e64 v4, v69, v0
	v_mul_f32_e64 v5, v69, v1
	v_add_f32_e64 v2, v2, v16
	v_add_f32_e64 v3, v3, v17
	v_fma_f32 v16, v68, v0, -v5
	v_fma_f32 v17, v69, v1, -v4
	v_fma_f32 v0, v68, v0, v5
	v_fma_f32 v1, v68, v1, v4
	v_mov_b32_e32 v17, v1
	v_mov_b32_e32 v0, v6
	v_mov_b32_e32 v1, v38
	v_add_f32_e64 v0, v0, v16
	v_add_f32_e64 v1, v1, v17
	v_cvt_pk_bf16_f32 v18, v2, v3
	v_cvt_pk_bf16_f32 v4, v0, v1
	ds_write2_b32 v154, v18, v4 offset0:152 offset1:184
	v_mul_f32_e64 v4, v65, v2
	v_mul_f32_e64 v5, v65, v3
	v_mov_b32_e32 v54, v23
	v_fma_f32 v16, v64, v2, -v5
	v_fma_f32 v17, v65, v3, -v4
	v_fma_f32 v2, v64, v2, v5
	v_fma_f32 v3, v64, v3, v4
	v_mov_b32_e32 v17, v3
	v_mul_f32_e64 v4, v69, v0
	v_mul_f32_e64 v5, v69, v1
	v_add_f32_e64 v2, v54, v16
	v_add_f32_e64 v3, v55, v17
	v_fma_f32 v16, v68, v0, -v5
	v_fma_f32 v17, v69, v1, -v4
	v_fma_f32 v0, v68, v0, v5
	v_fma_f32 v1, v68, v1, v4
	v_mov_b32_e32 v17, v1
	v_mov_b32_e32 v38, v7
	v_add_f32_e64 v0, v38, v16
	v_add_f32_e64 v1, v39, v17
	v_cvt_pk_bf16_f32 v6, v2, v3
	v_cvt_pk_bf16_f32 v4, v0, v1
	ds_write2_b32 v154, v6, v4 offset0:220 offset1:252
	v_mul_f32_e64 v4, v65, v2
	v_mul_f32_e64 v5, v65, v3
	s_nop 0
	v_fma_f32 v6, v64, v2, -v5
	v_fma_f32 v7, v65, v3, -v4
	v_fma_f32 v2, v64, v2, v5
	v_fma_f32 v3, v64, v3, v4
	v_mov_b32_e32 v7, v3
	v_mov_b32_e32 v2, v24
	v_mov_b32_e32 v3, v56
	v_mul_f32_e64 v4, v69, v0
	v_mul_f32_e64 v5, v69, v1
	v_add_f32_e64 v2, v2, v6
	v_add_f32_e64 v3, v3, v7
	v_fma_f32 v6, v68, v0, -v5
	v_fma_f32 v7, v69, v1, -v4
	v_fma_f32 v0, v68, v0, v5
	v_fma_f32 v1, v68, v1, v4
	v_mov_b32_e32 v7, v1
	v_mov_b32_e32 v0, v8
	v_mov_b32_e32 v1, v40
	v_add_f32_e64 v0, v0, v6
	v_add_f32_e64 v1, v1, v7
	v_cvt_pk_bf16_f32 v16, v2, v3
	v_cvt_pk_bf16_f32 v4, v0, v1
	ds_write2_b32 v155, v16, v4 offset0:32 offset1:64
	v_mul_f32_e64 v4, v65, v2
	v_mul_f32_e64 v5, v65, v3
	v_mov_b32_e32 v56, v25
	v_fma_f32 v6, v64, v2, -v5
	v_fma_f32 v7, v65, v3, -v4
	v_fma_f32 v2, v64, v2, v5
	v_fma_f32 v3, v64, v3, v4
	v_mov_b32_e32 v7, v3
	v_mul_f32_e64 v4, v69, v0
	v_mul_f32_e64 v5, v69, v1
	v_add_f32_e64 v2, v56, v6
	v_add_f32_e64 v3, v57, v7
	v_fma_f32 v6, v68, v0, -v5
	v_fma_f32 v7, v69, v1, -v4
	v_fma_f32 v0, v68, v0, v5
	v_fma_f32 v1, v68, v1, v4
	v_mov_b32_e32 v7, v1
	v_mov_b32_e32 v40, v9
	v_add_f32_e64 v0, v40, v6
	v_add_f32_e64 v1, v41, v7
	v_cvt_pk_bf16_f32 v8, v2, v3
	v_cvt_pk_bf16_f32 v4, v0, v1
	ds_write2_b32 v155, v8, v4 offset0:100 offset1:132
	v_mul_f32_e64 v4, v65, v2
	v_mul_f32_e64 v5, v65, v3
	s_nop 0
	v_fma_f32 v6, v64, v2, -v5
	v_fma_f32 v7, v65, v3, -v4
	v_fma_f32 v2, v64, v2, v5
	v_fma_f32 v3, v64, v3, v4
	v_mov_b32_e32 v7, v3
	v_mov_b32_e32 v2, v26
	v_mov_b32_e32 v3, v58
	v_mul_f32_e64 v4, v69, v0
	v_mul_f32_e64 v5, v69, v1
	v_add_f32_e64 v2, v2, v6
	v_add_f32_e64 v3, v3, v7
	v_fma_f32 v6, v68, v0, -v5
	v_fma_f32 v7, v69, v1, -v4
	v_fma_f32 v0, v68, v0, v5
	v_fma_f32 v1, v68, v1, v4
	v_mov_b32_e32 v7, v1
	v_mov_b32_e32 v0, v10
	v_mov_b32_e32 v1, v42
	v_add_f32_e64 v0, v0, v6
	v_add_f32_e64 v1, v1, v7
	v_cvt_pk_bf16_f32 v8, v2, v3
	v_cvt_pk_bf16_f32 v4, v0, v1
	ds_write2_b32 v155, v8, v4 offset0:168 offset1:200
	v_mul_f32_e64 v4, v65, v2
	v_mul_f32_e64 v5, v65, v3
	v_mov_b32_e32 v58, v27
	v_fma_f32 v6, v64, v2, -v5
	v_fma_f32 v7, v65, v3, -v4
	v_fma_f32 v2, v64, v2, v5
	v_fma_f32 v3, v64, v3, v4
	v_mov_b32_e32 v7, v3
	v_mul_f32_e64 v4, v69, v0
	v_mul_f32_e64 v5, v69, v1
	v_add_f32_e64 v2, v58, v6
	v_add_f32_e64 v3, v59, v7
	v_fma_f32 v6, v68, v0, -v5
	v_fma_f32 v7, v69, v1, -v4
	v_fma_f32 v0, v68, v0, v5
	v_fma_f32 v1, v68, v1, v4
	v_mov_b32_e32 v7, v1
	v_mov_b32_e32 v42, v11
	v_add_f32_e64 v0, v42, v6
	v_add_f32_e64 v1, v43, v7
	v_cvt_pk_bf16_f32 v8, v2, v3
	v_cvt_pk_bf16_f32 v4, v0, v1
	ds_write2_b32 v157, v8, v4 offset0:108 offset1:140
	v_mul_f32_e64 v4, v65, v2
	v_mul_f32_e64 v5, v65, v3
	s_nop 0
	v_fma_f32 v6, v64, v2, -v5
	v_fma_f32 v7, v65, v3, -v4
	v_fma_f32 v2, v64, v2, v5
	v_fma_f32 v3, v64, v3, v4
	v_mov_b32_e32 v7, v3
	v_mov_b32_e32 v2, v28
	v_mov_b32_e32 v3, v60
	v_mul_f32_e64 v4, v69, v0
	v_mul_f32_e64 v5, v69, v1
	v_add_f32_e64 v2, v2, v6
	v_add_f32_e64 v3, v3, v7
	v_fma_f32 v6, v68, v0, -v5
	v_fma_f32 v7, v69, v1, -v4
	v_fma_f32 v0, v68, v0, v5
	v_fma_f32 v1, v68, v1, v4
	v_mov_b32_e32 v7, v1
	v_mov_b32_e32 v0, v12
	v_mov_b32_e32 v1, v44
	v_add_f32_e64 v0, v0, v6
	v_add_f32_e64 v1, v1, v7
	v_cvt_pk_bf16_f32 v8, v2, v3
	v_cvt_pk_bf16_f32 v4, v0, v1
	ds_write2_b32 v156, v8, v4 offset0:48 offset1:80
	v_mul_f32_e64 v4, v65, v2
	v_mul_f32_e64 v5, v65, v3
	v_mov_b32_e32 v60, v29
	v_fma_f32 v6, v64, v2, -v5
	v_fma_f32 v7, v65, v3, -v4
	v_fma_f32 v2, v64, v2, v5
	v_fma_f32 v3, v64, v3, v4
	v_mov_b32_e32 v7, v3
	v_mul_f32_e64 v4, v69, v0
	v_mul_f32_e64 v5, v69, v1
	v_add_f32_e64 v2, v60, v6
	v_add_f32_e64 v3, v61, v7
	v_fma_f32 v6, v68, v0, -v5
	v_fma_f32 v7, v69, v1, -v4
	v_fma_f32 v0, v68, v0, v5
	v_fma_f32 v1, v68, v1, v4
	v_mov_b32_e32 v7, v1
	v_mov_b32_e32 v44, v13
	v_add_f32_e64 v0, v44, v6
	v_add_f32_e64 v1, v45, v7
	v_cvt_pk_bf16_f32 v8, v2, v3
	v_cvt_pk_bf16_f32 v4, v0, v1
	ds_write2_b32 v156, v8, v4 offset0:116 offset1:148
	v_mul_f32_e64 v4, v65, v2
	v_mul_f32_e64 v5, v65, v3
	s_nop 0
	v_fma_f32 v6, v64, v2, -v5
	v_fma_f32 v7, v65, v3, -v4
	v_fma_f32 v2, v64, v2, v5
	v_fma_f32 v3, v64, v3, v4
	v_mov_b32_e32 v7, v3
	v_mov_b32_e32 v2, v30
	v_mov_b32_e32 v3, v62
	v_mul_f32_e64 v4, v69, v0
	v_mul_f32_e64 v5, v69, v1
	v_add_f32_e64 v2, v2, v6
	v_add_f32_e64 v3, v3, v7
	v_fma_f32 v6, v68, v0, -v5
	v_fma_f32 v7, v69, v1, -v4
	v_fma_f32 v0, v68, v0, v5
	v_fma_f32 v1, v68, v1, v4
	v_mov_b32_e32 v7, v1
	v_mov_b32_e32 v0, v14
	v_mov_b32_e32 v1, v46
	v_add_f32_e64 v0, v0, v6
	v_add_f32_e64 v1, v1, v7
	v_cvt_pk_bf16_f32 v8, v2, v3
	v_cvt_pk_bf16_f32 v4, v0, v1
	ds_write2_b32 v156, v8, v4 offset0:184 offset1:216
	v_mul_f32_e64 v4, v65, v2
	v_mul_f32_e64 v5, v65, v3
	v_mov_b32_e32 v62, v31
	v_fma_f32 v6, v64, v2, -v5
	v_fma_f32 v7, v65, v3, -v4
	v_fma_f32 v2, v64, v2, v5
	v_fma_f32 v3, v64, v3, v4
	v_mov_b32_e32 v7, v3
	v_add_f32_e64 v2, v62, v6
	v_add_f32_e64 v3, v63, v7
	v_mov_b32_e32 v46, v15
	v_cvt_pk_bf16_f32 v6, v2, v3
	v_mul_f32_e64 v2, v69, v0
	v_mul_f32_e64 v3, v69, v1
	s_nop 0
	v_fma_f32 v4, v68, v0, -v3
	v_fma_f32 v5, v69, v1, -v2
	v_fma_f32 v0, v68, v0, v3
	v_fma_f32 v1, v68, v1, v2
	v_mov_b32_e32 v5, v1
	v_add_f32_e64 v0, v46, v4
	v_add_f32_e64 v1, v47, v5
	s_nop 0
	v_cvt_pk_bf16_f32 v0, v0, v1
	ds_write2_b32 v165, v6, v0 offset0:124 offset1:156
	s_waitcnt lgkmcnt(0)
	ds_read_b128 v[0:3], v163
	ds_read_b128 v[4:7], v163 offset:64
	s_waitcnt lgkmcnt(1)
	v_mfma_f32_16x16x32_bf16 v[0:3], v[82:85], v[0:3], 0
	s_waitcnt lgkmcnt(0)
	v_mfma_f32_16x16x32_bf16 v[0:3], v[78:81], v[4:7], v[0:3]
	ds_read_b128 v[4:7], v163 offset:128
	ds_read_b128 v[8:11], v163 offset:192
	s_waitcnt lgkmcnt(1)
	v_mfma_f32_16x16x32_bf16 v[0:3], v[74:77], v[4:7], v[0:3]
	s_waitcnt vmcnt(7)
	v_lshlrev_b32_e32 v4, 16, v144
	v_and_b32_e32 v5, 0xffff0000, v144
	s_waitcnt lgkmcnt(0)
	v_mfma_f32_16x16x32_bf16 v[0:3], v[106:109], v[8:11], v[0:3]
	s_nop 7
	v_fma_f32 v12, v70, v4, v0
	v_fma_f32 v13, v71, v5, v1
	v_and_b32_e32 v1, 0xffff0000, v145
	v_mul_f32_e32 v0, 0x3d372713, v12
	v_mul_f32_e32 v0, v12, v0
	v_fma_f32 v0, v12, v0, v12
	v_mul_f32_e32 v0, 0x3fcc422a, v0
	v_mul_f32_e32 v0, 0xbfb8aa3b, v0
	v_exp_f32_e32 v0, v0
	s_nop 0
	v_add_f32_e32 v4, 1.0, v0
	v_mul_f32_e32 v0, 0x3d372713, v13
	v_mul_f32_e32 v0, v13, v0
	v_fma_f32 v0, v13, v0, v13
	v_mul_f32_e32 v0, 0x3fcc422a, v0
	v_mul_f32_e32 v0, 0xbfb8aa3b, v0
	v_exp_f32_e32 v5, v0
	v_lshlrev_b32_e32 v0, 16, v145
	v_fma_f32 v14, v72, v0, v2
	v_fma_f32 v15, v73, v1, v3
	v_rcp_f32_e32 v16, v4
	v_mul_f32_e32 v0, 0x3d372713, v14
	v_mul_f32_e32 v0, v14, v0
	v_fma_f32 v0, v14, v0, v14
	v_mul_f32_e32 v0, 0x3fcc422a, v0
	v_mul_f32_e32 v0, 0xbfb8aa3b, v0
	v_exp_f32_e32 v0, v0
	v_add_f32_e32 v1, 1.0, v5
	v_rcp_f32_e32 v17, v1
	v_add_f32_e32 v8, 1.0, v0
	v_mul_f32_e32 v0, 0x3d372713, v15
	v_mul_f32_e32 v0, v15, v0
	v_fma_f32 v4, v15, v0, v15
	ds_read_b128 v[0:3], v163 offset:4352
	v_mul_f32_e32 v4, 0x3fcc422a, v4
	v_mul_f32_e32 v4, 0xbfb8aa3b, v4
	v_exp_f32_e32 v9, v4
	ds_read_b128 v[4:7], v163 offset:4416
	s_waitcnt lgkmcnt(1)
	v_mfma_f32_16x16x32_bf16 v[0:3], v[82:85], v[0:3], 0
	v_rcp_f32_e32 v18, v8
	v_add_f32_e32 v19, 1.0, v9
	ds_read_b128 v[8:11], v163 offset:4480
	s_waitcnt lgkmcnt(1)
	v_mfma_f32_16x16x32_bf16 v[0:3], v[78:81], v[4:7], v[0:3]
	ds_read_b128 v[4:7], v163 offset:4544
	v_rcp_f32_e32 v19, v19
	v_mul_f32_e64 v12, v12, v16
	v_mul_f32_e64 v13, v13, v17
	s_waitcnt lgkmcnt(1)
	v_mfma_f32_16x16x32_bf16 v[0:3], v[74:77], v[8:11], v[0:3]
	v_cvt_pk_bf16_f32 v10, v12, v13
	v_mul_f32_e64 v8, v14, v18
	v_mul_f32_e64 v9, v15, v19
	s_waitcnt lgkmcnt(0)
	v_mfma_f32_16x16x32_bf16 v[0:3], v[106:109], v[4:7], v[0:3]
	s_waitcnt vmcnt(6)
	v_lshlrev_b32_e32 v4, 16, v66
	v_and_b32_e32 v5, 0xffff0000, v66
	v_lshlrev_b32_e32 v6, 16, v67
	v_and_b32_e32 v7, 0xffff0000, v67
	v_cvt_pk_bf16_f32 v11, v8, v9
	s_nop 1
	v_fma_f32 v0, v70, v4, v0
	v_fma_f32 v1, v71, v5, v1
	v_fma_f32 v2, v72, v6, v2
	v_fma_f32 v3, v73, v7, v3
	v_mul_f32_e32 v4, 0x3d372713, v0
	v_mul_f32_e32 v5, 0x3d372713, v1
	v_mul_f32_e32 v6, 0x3d372713, v2
	v_mul_f32_e32 v7, 0x3d372713, v3
	v_mul_f32_e32 v4, v0, v4
	v_mul_f32_e32 v5, v1, v5
	v_mul_f32_e32 v6, v2, v6
	v_mul_f32_e32 v7, v3, v7
	v_fma_f32 v4, v0, v4, v0
	v_fma_f32 v5, v1, v5, v1
	v_fma_f32 v6, v2, v6, v2
	v_fma_f32 v7, v3, v7, v3
	v_mul_f32_e32 v4, 0x3fcc422a, v4
	v_mul_f32_e32 v5, 0x3fcc422a, v5
	v_mul_f32_e32 v6, 0x3fcc422a, v6
	v_mul_f32_e32 v7, 0x3fcc422a, v7
	v_mul_f32_e32 v4, 0xbfb8aa3b, v4
	v_mul_f32_e32 v5, 0xbfb8aa3b, v5
	v_mul_f32_e32 v6, 0xbfb8aa3b, v6
	v_mul_f32_e32 v7, 0xbfb8aa3b, v7
	v_exp_f32_e32 v4, v4
	v_exp_f32_e32 v5, v5
	v_exp_f32_e32 v6, v6
	v_exp_f32_e32 v7, v7
	v_add_f32_e32 v4, 1.0, v4
	v_add_f32_e32 v5, 1.0, v5
	v_add_f32_e32 v6, 1.0, v6
	v_add_f32_e32 v7, 1.0, v7
	v_rcp_f32_e32 v4, v4
	v_rcp_f32_e32 v5, v5
	v_rcp_f32_e32 v6, v6
	v_rcp_f32_e32 v7, v7
	v_lshl_add_u64 v[8:9], v[118:119], 0, v[126:127]
	v_mul_f32_e64 v0, v0, v4
	v_mul_f32_e64 v1, v1, v5
	global_store_dwordx2 v[8:9], v[10:11], off
	v_mul_f32_e64 v2, v2, v6
	v_mul_f32_e64 v3, v3, v7
	v_cvt_pk_bf16_f32 v0, v0, v1
	v_cvt_pk_bf16_f32 v1, v2, v3
	v_lshl_add_u64 v[2:3], v[120:121], 0, v[126:127]
	global_store_dwordx2 v[2:3], v[0:1], off
	s_waitcnt lgkmcnt(0)
	s_cbranch_scc1 .LBB0_310

.LBB0_305:
	v_add_co_u32_e64 v40, s[0:1], s39, v36
	v_add_co_u32_e32 v38, vcc, 0xfffe8000, v36
	s_nop 0
	v_addc_co_u32_e64 v41, s[0:1], -1, v37, s[0:1]
	v_add_co_u32_e64 v42, s[0:1], s40, v36
	v_addc_co_u32_e32 v39, vcc, -1, v37, vcc
	s_nop 0
	v_addc_co_u32_e64 v43, s[0:1], -1, v37, s[0:1]
	global_load_dwordx2 v[44:45], v[42:43], off offset:-256
	s_nop 0
	global_load_dwordx2 v[42:43], v[42:43], off
	s_nop 0
	global_load_dwordx2 v[46:47], v[36:37], off offset:-256
	global_load_dwordx2 v[48:49], v[38:39], off offset:-256
	s_nop 0
	global_load_dwordx2 v[38:39], v[38:39], off
	s_nop 0
	global_load_dwordx2 v[50:51], v[40:41], off offset:-256
	s_nop 0
	global_load_dwordx2 v[40:41], v[40:41], off
	s_nop 0
	global_load_dwordx2 v[52:53], v[36:37], off
	v_mov_b32_e32 v54, v155
	v_mov_b32_e32 v55, v157
	s_waitcnt vmcnt(19)
	v_mul_f32_e32 v56, v32, v154
	v_mul_f32_e32 v62, v33, v154
	v_mov_b32_e32 v154, v157
	s_waitcnt vmcnt(13)
	v_mul_f32_e64 v54, v34, v54
	v_mul_f32_e64 v55, v35, v55
	v_mul_f32_e64 v72, v34, v154
	v_mul_f32_e64 v73, v35, v155
	v_mul_f32_e32 v58, v33, v156
	v_mul_f32_e32 v60, v32, v156
	v_mov_b32_e32 v57, v54
	v_mov_b32_e32 v59, v55
	v_mov_b32_e32 v63, v73
	v_mov_b32_e32 v61, v72
	v_add_f32_e64 v54, v56, -v58
	v_add_f32_e64 v55, v57, -v59
	v_add_f32_e64 v56, v62, v60
	v_add_f32_e64 v57, v63, v61
	s_add_i32 s34, s34, 4
	v_lshl_add_u64 v[36:37], v[36:37], 0, s[18:19]
	s_cmp_eq_u32 s33, s34
	s_waitcnt vmcnt(7)
	v_mov_b32_e32 v58, v44
	s_waitcnt vmcnt(6)
	v_mov_b32_e32 v59, v42
	v_mov_b32_e32 v42, v45
	s_waitcnt vmcnt(5)
	v_mov_b32_e32 v44, v46
	s_waitcnt vmcnt(4)
	v_mov_b32_e32 v46, v48
	s_waitcnt vmcnt(2)
	v_mov_b32_e32 v48, v50
	s_waitcnt vmcnt(0)
	v_mov_b32_e32 v45, v52
	v_mov_b32_e32 v52, v47
	v_mov_b32_e32 v47, v38
	v_mov_b32_e32 v38, v49
	v_add_f32_e64 v46, v46, v54
	v_add_f32_e64 v47, v47, v55
	v_add_f32_e64 v38, v38, v56
	v_add_f32_e64 v39, v39, v57
	v_mul_f32_e32 v50, v32, v46
	v_mul_f32_e32 v54, v33, v38
	v_mul_f32_e32 v56, v32, v38
	v_mul_f32_e32 v60, v33, v46
	v_mov_b32_e32 v38, v47
	v_mov_b32_e32 v46, v39
	v_mul_f32_e64 v38, v34, v38
	v_mul_f32_e64 v39, v35, v39
	v_mul_f32_e64 v46, v34, v46
	v_mul_f32_e64 v47, v35, v47
	v_mov_b32_e32 v49, v40
	v_mov_b32_e32 v40, v51
	v_mov_b32_e32 v51, v38
	v_mov_b32_e32 v55, v39
	v_mov_b32_e32 v61, v47
	v_mov_b32_e32 v57, v46
	v_add_f32_e64 v38, v50, -v54
	v_add_f32_e64 v39, v51, -v55
	v_add_f32_e64 v46, v60, v56
	v_add_f32_e64 v47, v61, v57
	v_add_f32_e64 v38, v48, v38
	v_add_f32_e64 v39, v49, v39
	v_add_f32_e64 v40, v40, v46
	v_add_f32_e64 v41, v41, v47
	v_mul_f32_e32 v46, v32, v38
	v_mul_f32_e32 v48, v33, v40
	v_mul_f32_e32 v50, v32, v40
	v_mul_f32_e32 v54, v33, v38
	v_mov_b32_e32 v40, v39
	v_mov_b32_e32 v38, v41
	v_mul_f32_e64 v40, v34, v40
	v_mul_f32_e64 v41, v35, v41
	v_mul_f32_e64 v38, v34, v38
	v_mul_f32_e64 v39, v35, v39
	v_mov_b32_e32 v47, v40
	v_mov_b32_e32 v49, v41
	v_mov_b32_e32 v55, v39
	v_mov_b32_e32 v51, v38
	v_add_f32_e64 v38, v46, -v48
	v_add_f32_e64 v39, v47, -v49
	v_add_f32_e64 v40, v54, v50
	v_add_f32_e64 v41, v55, v51
	v_add_f32_e64 v38, v58, v38
	v_add_f32_e64 v39, v59, v39
	v_add_f32_e64 v40, v42, v40
	v_add_f32_e64 v41, v43, v41
	v_mul_f32_e32 v42, v32, v38
	v_mul_f32_e32 v46, v33, v40
	v_mul_f32_e32 v48, v32, v40
	v_mul_f32_e32 v50, v33, v38
	v_mov_b32_e32 v40, v39
	v_mov_b32_e32 v38, v41
	v_mul_f32_e64 v40, v34, v40
	v_mul_f32_e64 v41, v35, v41
	v_mul_f32_e64 v38, v34, v38
	v_mul_f32_e64 v39, v35, v39
	v_mov_b32_e32 v43, v40
	v_mov_b32_e32 v47, v41
	v_mov_b32_e32 v51, v39
	v_mov_b32_e32 v49, v38
	v_add_f32_e64 v38, v42, -v46
	v_add_f32_e64 v39, v43, -v47
	v_add_f32_e64 v40, v50, v48
	v_add_f32_e64 v41, v51, v49
	v_add_f32_e64 v154, v44, v38
	v_add_f32_e64 v155, v45, v39
	v_add_f32_e64 v156, v52, v40
	v_add_f32_e64 v157, v53, v41
	s_cbranch_scc0 .LBB0_305
	s_bfe_u32 s0, s46, 0x20003
	s_cmp_eq_u32 s0, 0
	s_cbranch_scc0 .LBB0_308
	s_branch .LBB0_301

.LBB0_309:
	global_load_dwordx2 v[38:39], v[36:37], off offset:-256
	global_load_dwordx2 v[40:41], v[36:37], off
	s_waitcnt vmcnt(13)
	v_mul_f32_e32 v42, v33, v156
	v_mul_f32_e32 v44, v32, v156
	v_mul_f32_e32 v46, v32, v154
	v_mul_f32_e32 v48, v33, v154
	v_mov_b32_e32 v156, v155
	v_mov_b32_e32 v154, v157
	s_waitcnt vmcnt(7)
	v_mul_f32_e64 v50, v34, v156
	v_mul_f32_e64 v51, v35, v157
	v_mul_f32_e64 v52, v34, v154
	v_mul_f32_e64 v53, v35, v155
	v_mov_b32_e32 v47, v50
	v_mov_b32_e32 v43, v51
	v_mov_b32_e32 v49, v53
	v_mov_b32_e32 v45, v52
	s_add_i32 s0, s0, -1
	v_add_f32_e64 v42, v46, -v42
	v_add_f32_e64 v43, v47, -v43
	v_add_f32_e64 v44, v48, v44
	v_add_f32_e64 v45, v49, v45
	v_lshl_add_u64 v[36:37], v[36:37], 0, s[20:21]
	s_cmp_lg_u32 s0, 0
	s_waitcnt vmcnt(1)
	v_mov_b32_e32 v46, v38
	s_waitcnt vmcnt(0)
	v_mov_b32_e32 v47, v40
	v_mov_b32_e32 v40, v39
	v_add_f32_e64 v154, v46, v42
	v_add_f32_e64 v155, v47, v43
	v_add_f32_e64 v156, v40, v44
	v_add_f32_e64 v157, v41, v45
	s_cbranch_scc1 .LBB0_309
	s_branch .LBB0_301

.LBB0_381:
	v_lshl_or_b32 v128, s33, 8, v162
	v_ashrrev_i32_e32 v129, 31, v128
	v_lshl_add_u64 v[152:153], v[128:129], 2, s[22:23]
	v_lshl_add_u32 v156, s36, 8, v160
	v_mov_b64_e32 v[158:159], s[12:13]
	global_load_dwordx4 v[166:169], v[152:153], off
	global_load_dwordx4 v[170:173], v[152:153], off offset:16
	v_mad_i64_i32 v[130:131], s[38:39], v156, s70, v[158:159]
	v_lshlrev_b64 v[154:155], 1, v[128:129]
	v_lshl_add_u64 v[128:129], v[130:131], 0, v[154:155]
	global_load_dwordx4 v[174:177], v[128:129], off
	v_ashrrev_i32_e32 v157, 31, v156
	v_lshlrev_b64 v[130:131], 11, v[156:157]
	v_lshl_add_u64 v[130:131], s[6:7], 0, v[130:131]
	v_lshl_add_u64 v[130:131], v[130:131], 0, v[154:155]
	global_load_dwordx4 v[178:181], v[130:131], off
	global_load_dwordx4 v[132:135], v[128:129], off offset:256
	s_nop 0
	global_load_dwordx4 v[128:131], v[130:131], off offset:256
	s_andn2_b64 vcc, exec, s[0:1]
	s_mov_b64 s[0:1], -1
	s_waitcnt vmcnt(0)
	v_add_f32_e32 v126, v126, v168
	v_add_f32_e32 v127, v127, v169
	v_add_f32_e32 v124, v124, v166
	v_add_f32_e32 v125, v125, v167
	v_add_f32_e32 v166, v120, v170
	v_add_f32_e32 v167, v121, v171
	v_add_f32_e32 v168, v122, v172
	v_mul_f32_e32 v171, 0xbfb8aa3b, v126
	v_mul_f32_e32 v172, 0xbfb8aa3b, v127
	v_add_f32_e32 v186, v123, v173
	v_mul_f32_e32 v169, 0xbfb8aa3b, v124
	v_mul_f32_e32 v170, 0xbfb8aa3b, v125
	v_mul_f32_e32 v173, 0xbfb8aa3b, v166
	v_exp_f32_e32 v171, v171
	v_exp_f32_e32 v172, v172
	v_lshlrev_b32_e32 v120, 16, v174
	v_and_b32_e32 v121, 0xffff0000, v174
	v_mul_f32_e32 v174, 0xbfb8aa3b, v167
	v_lshlrev_b32_e32 v124, 16, v176
	v_and_b32_e32 v125, 0xffff0000, v176
	v_exp_f32_e32 v176, v169
	v_exp_f32_e32 v170, v170
	v_exp_f32_e32 v173, v173
	v_lshlrev_b32_e32 v122, 16, v175
	v_and_b32_e32 v123, 0xffff0000, v175
	v_mul_f32_e32 v175, 0xbfb8aa3b, v168
	v_mul_f32_e32 v182, 0xbfb8aa3b, v120
	v_exp_f32_e32 v174, v174
	v_exp_f32_e32 v187, v175
	v_exp_f32_e32 v175, v182
	v_mul_f32_e32 v183, 0xbfb8aa3b, v122
	v_mul_f32_e32 v184, 0xbfb8aa3b, v124
	v_add_f32_e32 v185, 1.0, v171
	v_add_f32_e32 v188, 1.0, v172
	v_exp_f32_e32 v182, v183
	v_exp_f32_e32 v183, v184
	v_add_f32_e32 v176, 1.0, v176
	v_add_f32_e32 v184, 1.0, v170
	v_add_f32_e32 v189, 1.0, v173
	v_rcp_f32_e32 v172, v185
	v_rcp_f32_e32 v173, v188
	v_add_f32_e32 v190, 1.0, v174
	v_rcp_f32_e32 v170, v176
	v_rcp_f32_e32 v171, v184
	v_add_f32_e32 v176, 1.0, v175
	v_rcp_f32_e32 v174, v189
	v_rcp_f32_e32 v175, v190
	v_lshlrev_b32_e32 v166, 16, v179
	v_and_b32_e32 v167, 0xffff0000, v179
	v_lshlrev_b32_e32 v126, 16, v178
	v_and_b32_e32 v127, 0xffff0000, v178
	v_mul_f32_e64 v166, v172, v166
	v_mul_f32_e64 v167, v173, v167
	v_mul_f32_e32 v179, 0xbfb8aa3b, v123
	v_lshlrev_b32_e32 v168, 16, v180
	v_and_b32_e32 v169, 0xffff0000, v180
	v_mul_f32_e64 v126, v170, v126
	v_mul_f32_e64 v127, v171, v127
	v_mul_f32_e64 v122, v166, v122
	v_mul_f32_e64 v123, v167, v123
	v_lshlrev_b32_e32 v166, 16, v177
	v_mul_f32_e32 v178, 0xbfb8aa3b, v121
	v_mul_f32_e32 v180, 0xbfb8aa3b, v125
	v_mul_f32_e64 v168, v174, v168
	v_mul_f32_e64 v169, v175, v169
	v_mul_f32_e64 v120, v126, v120
	v_mul_f32_e64 v121, v127, v121
	v_mul_f32_e32 v126, 0xbfb8aa3b, v186
	v_mul_f32_e32 v167, 0xbfb8aa3b, v166
	v_exp_f32_e32 v178, v178
	v_exp_f32_e32 v179, v179
	v_exp_f32_e32 v180, v180
	v_mul_f32_e64 v124, v168, v124
	v_mul_f32_e64 v125, v169, v125
	v_exp_f32_e32 v127, v126
	v_exp_f32_e32 v168, v167
	v_and_b32_e32 v167, 0xffff0000, v177
	v_mul_f32_e32 v169, 0xbfb8aa3b, v167
	v_exp_f32_e32 v169, v169
	v_add_f32_e32 v184, 1.0, v178
	v_add_f32_e32 v182, 1.0, v182
	v_add_f32_e32 v185, 1.0, v179
	v_add_f32_e32 v188, 1.0, v183
	v_add_f32_e32 v180, 1.0, v180
	v_add_f32_e32 v126, 1.0, v187
	v_add_f32_e32 v127, 1.0, v127
	v_rcp_f32_e32 v178, v176
	v_rcp_f32_e32 v179, v184
	v_rcp_f32_e32 v182, v182
	v_rcp_f32_e32 v183, v185
	v_rcp_f32_e32 v184, v188
	v_rcp_f32_e32 v185, v180
	v_rcp_f32_e32 v126, v126
	v_rcp_f32_e32 v127, v127
	v_add_f32_e32 v168, 1.0, v168
	v_add_f32_e32 v169, 1.0, v169
	v_rcp_f32_e32 v168, v168
	v_rcp_f32_e32 v169, v169
	v_lshlrev_b32_e32 v170, 16, v181
	v_and_b32_e32 v171, 0xffff0000, v181
	v_mul_f32_e64 v120, v178, v120
	v_mul_f32_e64 v121, v179, v121
	v_mul_f32_e64 v122, v182, v122
	v_mul_f32_e64 v123, v183, v123
	v_mul_f32_e64 v124, v184, v124
	v_mul_f32_e64 v125, v185, v125
	v_mul_f32_e64 v126, v126, v170
	v_mul_f32_e64 v127, v127, v171
	v_cvt_pk_bf16_f32 v120, v120, v121
	v_mul_f32_e64 v126, v126, v166
	v_mul_f32_e64 v127, v127, v167
	v_cvt_pk_bf16_f32 v121, v122, v123
	v_cvt_pk_bf16_f32 v122, v124, v125
	v_lshlrev_b64 v[124:125], 12, v[156:157]
	v_mul_f32_e64 v126, v168, v126
	v_mul_f32_e64 v127, v169, v127
	v_lshl_add_u64 v[124:125], s[14:15], 0, v[124:125]
	v_cvt_pk_bf16_f32 v123, v126, v127
	v_lshl_add_u64 v[166:167], v[124:125], 0, v[154:155]
	global_store_dwordx4 v[166:167], v[120:123], off
	global_load_dwordx4 v[120:123], v[152:153], off offset:512
	s_nop 0
	global_load_dwordx4 v[124:127], v[152:153], off offset:528
	v_lshlrev_b32_e32 v170, 16, v134
	v_and_b32_e32 v171, 0xffff0000, v134
	v_mul_f32_e32 v176, 0xbfb8aa3b, v170
	v_exp_f32_e32 v178, v176
	v_and_b32_e32 v169, 0xffff0000, v132
	v_lshlrev_b32_e32 v168, 16, v132
	v_lshlrev_b32_e32 v132, 16, v133
	v_and_b32_e32 v133, 0xffff0000, v133
	v_mul_f32_e32 v157, 0xbfb8aa3b, v169
	v_mul_f32_e32 v175, 0xbfb8aa3b, v133
	v_exp_f32_e32 v157, v157
	v_exp_f32_e32 v175, v175
	v_lshlrev_b32_e32 v172, 16, v128
	v_and_b32_e32 v173, 0xffff0000, v128
	v_lshlrev_b32_e32 v128, 16, v129
	v_and_b32_e32 v129, 0xffff0000, v129
	v_mul_f32_e32 v174, 0xbfb8aa3b, v132
	v_add_f32_e32 v157, 1.0, v157
	v_mul_f32_e32 v134, 0xbfb8aa3b, v168
	v_add_f32_e32 v177, 1.0, v175
	v_rcp_f32_e32 v175, v157
	v_exp_f32_e32 v134, v134
	v_exp_f32_e32 v174, v174
	v_rcp_f32_e32 v177, v177
	v_add_f32_e32 v134, 1.0, v134
	v_add_f32_e32 v176, 1.0, v174
	v_rcp_f32_e32 v174, v134
	v_rcp_f32_e32 v176, v176
	s_waitcnt vmcnt(1)
	v_add_f32_e32 v117, v117, v121
	v_add_f32_e32 v119, v119, v123
	s_waitcnt vmcnt(0)
	v_add_f32_e32 v113, v113, v125
	v_mul_f32_e32 v117, 0xbfb8aa3b, v117
	v_mul_f32_e32 v119, 0xbfb8aa3b, v119
	v_mul_f32_e32 v113, 0xbfb8aa3b, v113
	v_exp_f32_e32 v117, v117
	v_exp_f32_e32 v119, v119
	v_exp_f32_e32 v113, v113
	v_add_f32_e32 v116, v116, v120
	v_add_f32_e32 v118, v118, v122
	v_add_f32_e32 v112, v112, v124
	v_mul_f32_e32 v116, 0xbfb8aa3b, v116
	v_mul_f32_e32 v118, 0xbfb8aa3b, v118
	v_mul_f32_e32 v112, 0xbfb8aa3b, v112
	v_exp_f32_e32 v116, v116
	v_exp_f32_e32 v118, v118
	v_exp_f32_e32 v112, v112
	v_add_f32_e32 v117, 1.0, v117
	v_add_f32_e32 v119, 1.0, v119
	v_add_f32_e32 v121, 1.0, v113
	v_rcp_f32_e32 v113, v117
	v_rcp_f32_e32 v117, v119
	v_rcp_f32_e32 v119, v121
	v_mul_f32_e32 v121, 0xbfb8aa3b, v171
	v_exp_f32_e32 v121, v121
	v_add_f32_e32 v116, 1.0, v116
	v_add_f32_e32 v118, 1.0, v118
	v_add_f32_e32 v120, 1.0, v112
	v_rcp_f32_e32 v112, v116
	v_rcp_f32_e32 v116, v118
	v_rcp_f32_e32 v118, v120
	v_add_f32_e32 v120, 1.0, v178
	v_add_f32_e32 v121, 1.0, v121
	v_add_f32_e32 v114, v114, v126
	v_rcp_f32_e32 v120, v120
	v_lshlrev_b32_e32 v122, 16, v130
	v_and_b32_e32 v123, 0xffff0000, v130
	v_rcp_f32_e32 v121, v121
	v_mul_f32_e32 v114, 0xbfb8aa3b, v114
	v_mul_f32_e64 v118, v118, v122
	v_mul_f32_e64 v119, v119, v123
	v_exp_f32_e32 v122, v114
	v_add_f32_e32 v114, v115, v127
	v_mul_f32_e64 v116, v116, v128
	v_mul_f32_e64 v117, v117, v129
	v_mul_f32_e32 v114, 0xbfb8aa3b, v114
	v_mul_f32_e64 v116, v116, v132
	v_mul_f32_e64 v117, v117, v133
	v_mul_f32_e64 v118, v118, v170
	v_mul_f32_e64 v119, v119, v171
	v_exp_f32_e32 v123, v114
	v_lshlrev_b32_e32 v132, 16, v135
	v_and_b32_e32 v133, 0xffff0000, v135
	v_mul_f32_e64 v114, v120, v118
	v_mul_f32_e64 v115, v121, v119
	v_mul_f32_e32 v120, 0xbfb8aa3b, v132
	v_mul_f32_e32 v157, 0xbfb8aa3b, v133
	v_exp_f32_e32 v130, v120
	v_exp_f32_e32 v157, v157
	v_add_f32_e32 v118, 1.0, v122
	v_add_f32_e32 v119, 1.0, v123
	v_rcp_f32_e32 v118, v118
	v_rcp_f32_e32 v119, v119
	v_mul_f32_e64 v112, v112, v172
	v_mul_f32_e64 v113, v113, v173
	v_add_f32_e32 v130, 1.0, v130
	v_add_f32_e32 v157, 1.0, v157
	v_mul_f32_e64 v112, v112, v168
	v_mul_f32_e64 v113, v113, v169
	v_rcp_f32_e32 v168, v130
	v_rcp_f32_e32 v169, v157
	v_lshlrev_b32_e32 v130, 16, v131
	v_and_b32_e32 v131, 0xffff0000, v131
	v_or_b32_e32 v128, 16, v156
	v_mul_f32_e64 v118, v118, v130
	v_mul_f32_e64 v119, v119, v131
	v_ashrrev_i32_e32 v129, 31, v128
	v_mul_f32_e64 v118, v118, v132
	v_mul_f32_e64 v119, v119, v133
	v_mul_f32_e64 v112, v174, v112
	v_mul_f32_e64 v113, v175, v113
	v_mul_f32_e64 v116, v176, v116
	v_mul_f32_e64 v117, v177, v117
	v_lshlrev_b64 v[120:121], 11, v[128:129]
	v_mul_f32_e64 v118, v168, v118
	v_mul_f32_e64 v119, v169, v119
	v_mad_i64_i32 v[122:123], s[38:39], v128, s70, v[158:159]
	v_lshl_add_u64 v[120:121], s[6:7], 0, v[120:121]
	v_cvt_pk_bf16_f32 v112, v112, v113
	v_cvt_pk_bf16_f32 v113, v116, v117
	v_cvt_pk_bf16_f32 v114, v114, v115
	v_cvt_pk_bf16_f32 v115, v118, v119
	v_lshl_add_u64 v[134:135], v[122:123], 0, v[154:155]
	v_lshl_add_u64 v[170:171], v[120:121], 0, v[154:155]
	global_store_dwordx4 v[166:167], v[112:115], off offset:256
	global_load_dwordx4 v[124:127], v[134:135], off
	global_load_dwordx4 v[120:123], v[170:171], off
	global_load_dwordx4 v[130:133], v[152:153], off
	s_nop 0
	global_load_dwordx4 v[166:169], v[152:153], off offset:16
	global_load_dwordx4 v[116:119], v[134:135], off offset:256
	global_load_dwordx4 v[112:115], v[170:171], off offset:256
	s_waitcnt vmcnt(3)
	v_add_f32_e32 v110, v110, v132
	v_add_f32_e32 v111, v111, v133
	v_mul_f32_e32 v110, 0xbfb8aa3b, v110
	v_mul_f32_e32 v111, 0xbfb8aa3b, v111
	v_lshlrev_b32_e32 v134, 16, v124
	v_and_b32_e32 v135, 0xffff0000, v124
	v_lshlrev_b32_e32 v124, 16, v125
	v_and_b32_e32 v125, 0xffff0000, v125
	v_exp_f32_e32 v110, v110
	v_exp_f32_e32 v111, v111
	v_lshlrev_b32_e32 v170, 16, v120
	v_and_b32_e32 v171, 0xffff0000, v120
	v_mul_f32_e32 v120, 0xbfb8aa3b, v134
	v_mul_f32_e32 v172, 0xbfb8aa3b, v124
	v_mul_f32_e32 v174, 0xbfb8aa3b, v125
	v_exp_f32_e32 v120, v120
	v_exp_f32_e32 v172, v172
	v_exp_f32_e32 v132, v174
	v_add_f32_e32 v110, 1.0, v110
	v_add_f32_e32 v111, 1.0, v111
	v_rcp_f32_e32 v110, v110
	v_rcp_f32_e32 v111, v111
	v_add_f32_e32 v120, 1.0, v120
	v_add_f32_e32 v175, 1.0, v172
	v_add_f32_e32 v108, v108, v130
	v_add_f32_e32 v109, v109, v131
	v_lshlrev_b32_e32 v130, 16, v121
	v_and_b32_e32 v131, 0xffff0000, v121
	v_add_f32_e32 v121, 1.0, v132
	v_rcp_f32_e32 v172, v120
	v_rcp_f32_e32 v120, v175
	v_rcp_f32_e32 v121, v121
	s_waitcnt vmcnt(2)
	v_add_f32_e32 v104, v104, v166
	v_add_f32_e32 v105, v105, v167
	v_mul_f32_e32 v104, 0xbfb8aa3b, v104
	v_mul_f32_e32 v105, 0xbfb8aa3b, v105
	v_exp_f32_e32 v104, v104
	v_mul_f32_e64 v110, v110, v130
	v_mul_f32_e64 v111, v111, v131
	v_exp_f32_e32 v105, v105
	v_mul_f32_e64 v110, v110, v124
	v_mul_f32_e64 v111, v111, v125
	v_add_f32_e32 v104, 1.0, v104
	v_mul_f32_e64 v110, v120, v110
	v_mul_f32_e64 v111, v121, v111
	v_lshlrev_b32_e32 v120, 16, v126
	v_mul_f32_e32 v121, 0xbfb8aa3b, v120
	v_exp_f32_e32 v124, v121
	v_add_f32_e32 v105, 1.0, v105
	v_and_b32_e32 v121, 0xffff0000, v126
	v_rcp_f32_e32 v104, v104
	v_rcp_f32_e32 v105, v105
	v_mul_f32_e32 v125, 0xbfb8aa3b, v121
	v_exp_f32_e32 v125, v125
	v_lshlrev_b32_e32 v130, 16, v122
	v_and_b32_e32 v131, 0xffff0000, v122
	v_mul_f32_e64 v104, v104, v130
	v_mul_f32_e64 v105, v105, v131
	v_add_f32_e32 v106, v106, v168
	v_mul_f32_e64 v104, v104, v120
	v_mul_f32_e64 v105, v105, v121
	v_add_f32_e32 v120, 1.0, v125
	v_mul_f32_e32 v106, 0xbfb8aa3b, v106
	v_add_f32_e32 v124, 1.0, v124
	v_rcp_f32_e32 v125, v120
	v_exp_f32_e32 v120, v106
	v_add_f32_e32 v106, v107, v169
	v_rcp_f32_e32 v124, v124
	v_mul_f32_e32 v106, 0xbfb8aa3b, v106
	v_exp_f32_e32 v121, v106
	v_mul_f32_e32 v108, 0xbfb8aa3b, v108
	v_mul_f32_e32 v109, 0xbfb8aa3b, v109
	v_mul_f32_e64 v106, v124, v104
	v_mul_f32_e64 v107, v125, v105
	v_add_f32_e32 v104, 1.0, v120
	v_lshlrev_b32_e32 v120, 16, v127
	v_exp_f32_e32 v108, v108
	v_exp_f32_e32 v109, v109
	v_add_f32_e32 v105, 1.0, v121
	v_mul_f32_e32 v121, 0xbfb8aa3b, v120
	v_mul_f32_e32 v157, 0xbfb8aa3b, v135
	v_exp_f32_e32 v122, v121
	v_and_b32_e32 v121, 0xffff0000, v127
	v_exp_f32_e32 v157, v157
	v_mul_f32_e32 v124, 0xbfb8aa3b, v121
	v_exp_f32_e32 v125, v124
	v_add_f32_e32 v108, 1.0, v108
	v_add_f32_e32 v109, 1.0, v109
	v_rcp_f32_e32 v108, v108
	v_rcp_f32_e32 v109, v109
	v_add_f32_e32 v157, 1.0, v157
	v_rcp_f32_e32 v104, v104
	v_rcp_f32_e32 v105, v105
	v_rcp_f32_e32 v173, v157
	v_add_f32_e32 v122, 1.0, v122
	v_add_f32_e32 v125, 1.0, v125
	v_rcp_f32_e32 v124, v122
	v_rcp_f32_e32 v125, v125
	v_mul_f32_e64 v108, v108, v170
	v_mul_f32_e64 v109, v109, v171
	v_lshlrev_b32_e32 v122, 16, v123
	v_and_b32_e32 v123, 0xffff0000, v123
	v_mul_f32_e64 v108, v108, v134
	v_mul_f32_e64 v109, v109, v135
	v_mul_f32_e64 v104, v104, v122
	v_mul_f32_e64 v105, v105, v123
	v_mul_f32_e64 v108, v172, v108
	v_mul_f32_e64 v109, v173, v109
	v_mul_f32_e64 v104, v104, v120
	v_mul_f32_e64 v105, v105, v121
	v_cvt_pk_bf16_f32 v106, v106, v107
	v_mul_f32_e64 v120, v124, v104
	v_mul_f32_e64 v121, v125, v105
	v_cvt_pk_bf16_f32 v104, v108, v109
	v_lshlrev_b64 v[108:109], 12, v[128:129]
	v_lshl_add_u64 v[108:109], s[14:15], 0, v[108:109]
	v_cvt_pk_bf16_f32 v105, v110, v111
	v_cvt_pk_bf16_f32 v107, v120, v121
	v_lshl_add_u64 v[120:121], v[108:109], 0, v[154:155]
	global_store_dwordx4 v[120:121], v[104:107], off
	global_load_dwordx4 v[104:107], v[152:153], off offset:512
	s_nop 0
	global_load_dwordx4 v[108:111], v[152:153], off offset:528
	s_waitcnt vmcnt(4)
	v_lshlrev_b32_e32 v122, 16, v116
	v_and_b32_e32 v123, 0xffff0000, v116
	s_waitcnt vmcnt(3)
	v_lshlrev_b32_e32 v124, 16, v112
	v_mul_f32_e32 v116, 0xbfb8aa3b, v122
	v_and_b32_e32 v125, 0xffff0000, v112
	v_mul_f32_e32 v112, 0xbfb8aa3b, v123
	v_exp_f32_e32 v116, v116
	v_exp_f32_e32 v112, v112
	v_add_f32_e32 v116, 1.0, v116
	v_add_f32_e32 v112, 1.0, v112
	s_waitcnt vmcnt(1)
	v_add_f32_e32 v100, v100, v104
	v_add_f32_e32 v101, v101, v105
	v_mul_f32_e32 v100, 0xbfb8aa3b, v100
	v_mul_f32_e32 v101, 0xbfb8aa3b, v101
	v_exp_f32_e32 v104, v100
	v_exp_f32_e32 v101, v101
	v_rcp_f32_e32 v100, v116
	v_add_f32_e32 v102, v102, v106
	v_add_f32_e32 v104, 1.0, v104
	v_add_f32_e32 v101, 1.0, v101
	v_rcp_f32_e32 v104, v104
	v_rcp_f32_e32 v105, v101
	v_rcp_f32_e32 v101, v112
	v_add_f32_e32 v103, v103, v107
	v_mul_f32_e32 v102, 0xbfb8aa3b, v102
	v_mul_f32_e64 v104, v104, v124
	v_mul_f32_e64 v105, v105, v125
	v_mul_f32_e32 v103, 0xbfb8aa3b, v103
	v_mul_f32_e64 v104, v104, v122
	v_mul_f32_e64 v105, v105, v123
	v_exp_f32_e32 v102, v102
	v_mul_f32_e64 v100, v100, v104
	v_mul_f32_e64 v101, v101, v105
	v_lshlrev_b32_e32 v104, 16, v117
	v_exp_f32_e32 v103, v103
	v_mul_f32_e32 v105, 0xbfb8aa3b, v104
	v_exp_f32_e32 v106, v105
	v_and_b32_e32 v105, 0xffff0000, v117
	v_mul_f32_e32 v107, 0xbfb8aa3b, v105
	v_exp_f32_e32 v107, v107
	v_add_f32_e32 v102, 1.0, v102
	v_add_f32_e32 v103, 1.0, v103
	v_rcp_f32_e32 v102, v102
	v_rcp_f32_e32 v103, v103
	s_waitcnt vmcnt(0)
	v_add_f32_e32 v96, v96, v108
	v_add_f32_e32 v97, v97, v109
	v_add_f32_e32 v106, 1.0, v106
	v_add_f32_e32 v107, 1.0, v107
	v_mul_f32_e32 v96, 0xbfb8aa3b, v96
	v_mul_f32_e32 v97, 0xbfb8aa3b, v97
	v_rcp_f32_e32 v106, v106
	v_lshlrev_b32_e32 v112, 16, v113
	v_and_b32_e32 v113, 0xffff0000, v113
	v_rcp_f32_e32 v107, v107
	v_exp_f32_e32 v96, v96
	v_exp_f32_e32 v97, v97
	v_mul_f32_e64 v102, v102, v112
	v_mul_f32_e64 v103, v103, v113
	v_lshlrev_b32_e32 v108, 16, v114
	v_mul_f32_e64 v102, v102, v104
	v_mul_f32_e64 v103, v103, v105
	v_lshlrev_b32_e32 v104, 16, v118
	v_mul_f32_e32 v105, 0xbfb8aa3b, v104
	v_mul_f32_e64 v102, v106, v102
	v_mul_f32_e64 v103, v107, v103
	v_add_f32_e32 v96, 1.0, v96
	v_exp_f32_e32 v106, v105
	v_add_f32_e32 v97, 1.0, v97
	v_and_b32_e32 v105, 0xffff0000, v118
	v_rcp_f32_e32 v96, v96
	v_rcp_f32_e32 v97, v97
	v_mul_f32_e32 v107, 0xbfb8aa3b, v105
	v_exp_f32_e32 v107, v107
	v_and_b32_e32 v109, 0xffff0000, v114
	v_mul_f32_e64 v96, v96, v108
	v_mul_f32_e64 v97, v97, v109
	v_add_f32_e32 v98, v98, v110
	v_mul_f32_e64 v96, v96, v104
	v_mul_f32_e64 v97, v97, v105
	v_add_f32_e32 v104, 1.0, v107
	v_mul_f32_e32 v98, 0xbfb8aa3b, v98
	v_add_f32_e32 v106, 1.0, v106
	v_rcp_f32_e32 v107, v104
	v_exp_f32_e32 v104, v98
	v_add_f32_e32 v98, v99, v111
	v_rcp_f32_e32 v106, v106
	v_mul_f32_e32 v98, 0xbfb8aa3b, v98
	v_exp_f32_e32 v105, v98
	v_lshlrev_b32_e32 v108, 16, v115
	v_mul_f32_e64 v98, v106, v96
	v_mul_f32_e64 v99, v107, v97
	v_add_f32_e32 v96, 1.0, v104
	v_lshlrev_b32_e32 v104, 16, v119
	v_add_f32_e32 v97, 1.0, v105
	v_mul_f32_e32 v105, 0xbfb8aa3b, v104
	v_exp_f32_e32 v106, v105
	v_and_b32_e32 v105, 0xffff0000, v119
	v_mul_f32_e32 v107, 0xbfb8aa3b, v105
	v_exp_f32_e32 v107, v107
	v_rcp_f32_e32 v96, v96
	v_rcp_f32_e32 v97, v97
	v_add_f32_e32 v106, 1.0, v106
	v_add_f32_e32 v107, 1.0, v107
	v_rcp_f32_e32 v106, v106
	v_rcp_f32_e32 v107, v107
	v_and_b32_e32 v109, 0xffff0000, v115
	v_mul_f32_e64 v96, v96, v108
	v_mul_f32_e64 v97, v97, v109
	v_cvt_pk_bf16_f32 v98, v98, v99
	v_mul_f32_e64 v96, v96, v104
	v_mul_f32_e64 v97, v97, v105
	v_or_b32_e32 v118, 32, v156
	v_mul_f32_e64 v104, v106, v96
	v_mul_f32_e64 v105, v107, v97
	v_cvt_pk_bf16_f32 v96, v100, v101
	v_cvt_pk_bf16_f32 v97, v102, v103
	v_cvt_pk_bf16_f32 v99, v104, v105
	global_store_dwordx4 v[120:121], v[96:99], off offset:256
	global_load_dwordx4 v[98:101], v[152:153], off
	v_ashrrev_i32_e32 v119, 31, v118
	v_mad_i64_i32 v[96:97], s[38:39], v118, s70, v[158:159]
	v_lshl_add_u64 v[96:97], v[96:97], 0, v[154:155]
	global_load_dwordx4 v[102:105], v[96:97], off
	v_lshlrev_b64 v[106:107], 11, v[118:119]
	v_lshl_add_u64 v[106:107], s[6:7], 0, v[106:107]
	v_lshl_add_u64 v[120:121], v[106:107], 0, v[154:155]
	global_load_dwordx4 v[106:109], v[120:121], off
	global_load_dwordx4 v[110:113], v[152:153], off offset:16
	global_load_dwordx4 v[114:117], v[96:97], off offset:256
	s_waitcnt vmcnt(4)
	v_add_f32_e32 v94, v94, v100
	v_add_f32_e32 v95, v95, v101
	v_mul_f32_e32 v94, 0xbfb8aa3b, v94
	v_mul_f32_e32 v95, 0xbfb8aa3b, v95
	v_exp_f32_e32 v94, v94
	s_waitcnt vmcnt(3)
	v_lshlrev_b32_e32 v122, 16, v102
	v_mul_f32_e32 v96, 0xbfb8aa3b, v122
	v_exp_f32_e32 v96, v96
	v_and_b32_e32 v123, 0xffff0000, v102
	v_lshlrev_b32_e32 v100, 16, v103
	v_exp_f32_e32 v95, v95
	v_add_f32_e32 v96, 1.0, v96
	v_rcp_f32_e32 v124, v96
	v_mul_f32_e32 v96, 0xbfb8aa3b, v123
	v_exp_f32_e32 v102, v96
	v_mul_f32_e32 v101, 0xbfb8aa3b, v100
	v_add_f32_e32 v94, 1.0, v94
	v_add_f32_e32 v95, 1.0, v95
	v_add_f32_e32 v102, 1.0, v102
	v_rcp_f32_e32 v125, v102
	v_exp_f32_e32 v102, v101
	v_and_b32_e32 v101, 0xffff0000, v103
	v_mul_f32_e32 v103, 0xbfb8aa3b, v101
	v_exp_f32_e32 v103, v103
	v_rcp_f32_e32 v94, v94
	v_rcp_f32_e32 v95, v95
	s_waitcnt vmcnt(1)
	v_add_f32_e32 v88, v88, v110
	v_add_f32_e32 v89, v89, v111
	v_add_f32_e32 v102, 1.0, v102
	v_add_f32_e32 v103, 1.0, v103
	v_mul_f32_e32 v88, 0xbfb8aa3b, v88
	v_mul_f32_e32 v89, 0xbfb8aa3b, v89
	v_add_f32_e32 v92, v92, v98
	v_add_f32_e32 v93, v93, v99
	global_load_dwordx4 v[96:99], v[120:121], off offset:256
	v_lshlrev_b32_e32 v120, 16, v106
	v_and_b32_e32 v121, 0xffff0000, v106
	v_rcp_f32_e32 v102, v102
	v_lshlrev_b32_e32 v106, 16, v107
	v_and_b32_e32 v107, 0xffff0000, v107
	v_rcp_f32_e32 v103, v103
	v_exp_f32_e32 v88, v88
	v_exp_f32_e32 v89, v89
	v_mul_f32_e64 v94, v94, v106
	v_mul_f32_e64 v95, v95, v107
	v_lshlrev_b32_e32 v106, 16, v108
	v_mul_f32_e64 v94, v94, v100
	v_mul_f32_e64 v95, v95, v101
	v_lshlrev_b32_e32 v100, 16, v104
	v_mul_f32_e32 v101, 0xbfb8aa3b, v100
	v_mul_f32_e64 v94, v102, v94
	v_mul_f32_e64 v95, v103, v95
	v_add_f32_e32 v88, 1.0, v88
	v_exp_f32_e32 v102, v101
	v_add_f32_e32 v89, 1.0, v89
	v_and_b32_e32 v101, 0xffff0000, v104
	v_rcp_f32_e32 v88, v88
	v_rcp_f32_e32 v89, v89
	v_mul_f32_e32 v103, 0xbfb8aa3b, v101
	v_exp_f32_e32 v103, v103
	v_and_b32_e32 v107, 0xffff0000, v108
	v_mul_f32_e64 v88, v88, v106
	v_mul_f32_e64 v89, v89, v107
	v_add_f32_e32 v90, v90, v112
	v_mul_f32_e64 v88, v88, v100
	v_mul_f32_e64 v89, v89, v101
	v_add_f32_e32 v100, 1.0, v103
	v_mul_f32_e32 v90, 0xbfb8aa3b, v90
	v_add_f32_e32 v102, 1.0, v102
	v_rcp_f32_e32 v103, v100
	v_exp_f32_e32 v100, v90
	v_add_f32_e32 v90, v91, v113
	v_rcp_f32_e32 v102, v102
	v_mul_f32_e32 v90, 0xbfb8aa3b, v90
	v_exp_f32_e32 v101, v90
	v_mul_f32_e32 v92, 0xbfb8aa3b, v92
	v_mul_f32_e32 v93, 0xbfb8aa3b, v93
	v_mul_f32_e64 v90, v102, v88
	v_mul_f32_e64 v91, v103, v89
	v_add_f32_e32 v88, 1.0, v100
	v_lshlrev_b32_e32 v100, 16, v105
	v_exp_f32_e32 v92, v92
	v_exp_f32_e32 v93, v93
	v_add_f32_e32 v89, 1.0, v101
	v_mul_f32_e32 v101, 0xbfb8aa3b, v100
	v_exp_f32_e32 v102, v101
	v_and_b32_e32 v101, 0xffff0000, v105
	v_mul_f32_e32 v103, 0xbfb8aa3b, v101
	v_exp_f32_e32 v103, v103
	v_add_f32_e32 v92, 1.0, v92
	v_add_f32_e32 v93, 1.0, v93
	v_rcp_f32_e32 v92, v92
	v_rcp_f32_e32 v93, v93
	v_rcp_f32_e32 v88, v88
	v_rcp_f32_e32 v89, v89
	v_add_f32_e32 v102, 1.0, v102
	v_add_f32_e32 v103, 1.0, v103
	v_rcp_f32_e32 v102, v102
	v_rcp_f32_e32 v103, v103
	v_mul_f32_e64 v92, v92, v120
	v_mul_f32_e64 v93, v93, v121
	v_lshlrev_b32_e32 v104, 16, v109
	v_and_b32_e32 v105, 0xffff0000, v109
	v_mul_f32_e64 v92, v92, v122
	v_mul_f32_e64 v93, v93, v123
	v_mul_f32_e64 v88, v88, v104
	v_mul_f32_e64 v89, v89, v105
	v_mul_f32_e64 v92, v124, v92
	v_mul_f32_e64 v93, v125, v93
	v_mul_f32_e64 v88, v88, v100
	v_mul_f32_e64 v89, v89, v101
	v_cvt_pk_bf16_f32 v90, v90, v91
	v_mul_f32_e64 v100, v102, v88
	v_mul_f32_e64 v101, v103, v89
	v_cvt_pk_bf16_f32 v88, v92, v93
	v_lshlrev_b64 v[92:93], 12, v[118:119]
	v_lshl_add_u64 v[92:93], s[14:15], 0, v[92:93]
	v_cvt_pk_bf16_f32 v89, v94, v95
	v_cvt_pk_bf16_f32 v91, v100, v101
	v_lshl_add_u64 v[100:101], v[92:93], 0, v[154:155]
	global_store_dwordx4 v[100:101], v[88:91], off
	global_load_dwordx4 v[88:91], v[152:153], off offset:512
	s_nop 0
	global_load_dwordx4 v[92:95], v[152:153], off offset:528
	s_waitcnt vmcnt(3)
	v_lshlrev_b32_e32 v104, 16, v96
	v_and_b32_e32 v105, 0xffff0000, v96
	s_waitcnt vmcnt(1)
	v_add_f32_e32 v84, v84, v88
	v_add_f32_e32 v85, v85, v89
	v_mul_f32_e32 v84, 0xbfb8aa3b, v84
	v_mul_f32_e32 v85, 0xbfb8aa3b, v85
	v_exp_f32_e32 v84, v84
	v_exp_f32_e32 v85, v85
	v_lshlrev_b32_e32 v88, 16, v114
	v_mul_f32_e32 v89, 0xbfb8aa3b, v88
	v_add_f32_e32 v84, 1.0, v84
	v_add_f32_e32 v85, 1.0, v85
	v_rcp_f32_e32 v84, v84
	v_rcp_f32_e32 v85, v85
	v_exp_f32_e32 v102, v89
	v_and_b32_e32 v89, 0xffff0000, v114
	v_add_f32_e32 v86, v86, v90
	v_mul_f32_e64 v84, v84, v104
	v_mul_f32_e64 v85, v85, v105
	v_add_f32_e32 v87, v87, v91
	v_mul_f32_e32 v86, 0xbfb8aa3b, v86
	v_mul_f32_e64 v84, v84, v88
	v_mul_f32_e64 v85, v85, v89
	v_mul_f32_e32 v87, 0xbfb8aa3b, v87
	v_lshlrev_b32_e32 v88, 16, v115
	v_mul_f32_e32 v103, 0xbfb8aa3b, v89
	v_exp_f32_e32 v86, v86
	v_exp_f32_e32 v87, v87
	v_mul_f32_e32 v89, 0xbfb8aa3b, v88
	v_exp_f32_e32 v90, v89
	v_and_b32_e32 v89, 0xffff0000, v115
	v_mul_f32_e32 v91, 0xbfb8aa3b, v89
	v_exp_f32_e32 v103, v103
	v_exp_f32_e32 v91, v91
	v_add_f32_e32 v86, 1.0, v86
	v_add_f32_e32 v87, 1.0, v87
	v_rcp_f32_e32 v86, v86
	v_rcp_f32_e32 v87, v87
	s_waitcnt vmcnt(0)
	v_add_f32_e32 v80, v80, v92
	v_add_f32_e32 v81, v81, v93
	v_add_f32_e32 v96, 1.0, v103
	v_add_f32_e32 v90, 1.0, v90
	v_add_f32_e32 v91, 1.0, v91
	v_mul_f32_e32 v80, 0xbfb8aa3b, v80
	v_mul_f32_e32 v81, 0xbfb8aa3b, v81
	v_rcp_f32_e32 v103, v96
	v_rcp_f32_e32 v90, v90
	v_lshlrev_b32_e32 v96, 16, v97
	v_and_b32_e32 v97, 0xffff0000, v97
	v_rcp_f32_e32 v91, v91
	v_exp_f32_e32 v80, v80
	v_exp_f32_e32 v81, v81
	v_mul_f32_e64 v86, v86, v96
	v_mul_f32_e64 v87, v87, v97
	v_lshlrev_b32_e32 v92, 16, v98
	v_mul_f32_e64 v86, v86, v88
	v_mul_f32_e64 v87, v87, v89
	v_lshlrev_b32_e32 v88, 16, v116
	v_mul_f32_e32 v89, 0xbfb8aa3b, v88
	v_mul_f32_e64 v86, v90, v86
	v_mul_f32_e64 v87, v91, v87
	v_add_f32_e32 v80, 1.0, v80
	v_exp_f32_e32 v90, v89
	v_add_f32_e32 v81, 1.0, v81
	v_and_b32_e32 v89, 0xffff0000, v116
	v_rcp_f32_e32 v80, v80
	v_rcp_f32_e32 v81, v81
	v_mul_f32_e32 v91, 0xbfb8aa3b, v89
	v_exp_f32_e32 v91, v91
	v_and_b32_e32 v93, 0xffff0000, v98
	v_mul_f32_e64 v80, v80, v92
	v_mul_f32_e64 v81, v81, v93
	v_add_f32_e32 v82, v82, v94
	v_mul_f32_e64 v80, v80, v88
	v_mul_f32_e64 v81, v81, v89
	v_add_f32_e32 v88, 1.0, v91
	v_mul_f32_e32 v82, 0xbfb8aa3b, v82
	v_add_f32_e32 v90, 1.0, v90
	v_rcp_f32_e32 v91, v88
	v_exp_f32_e32 v88, v82
	v_add_f32_e32 v82, v83, v95
	v_rcp_f32_e32 v90, v90
	v_mul_f32_e32 v82, 0xbfb8aa3b, v82
	v_exp_f32_e32 v89, v82
	v_add_f32_e32 v102, 1.0, v102
	v_mul_f32_e64 v82, v90, v80
	v_mul_f32_e64 v83, v91, v81
	v_add_f32_e32 v80, 1.0, v88
	v_lshlrev_b32_e32 v88, 16, v117
	v_add_f32_e32 v81, 1.0, v89
	v_mul_f32_e32 v89, 0xbfb8aa3b, v88
	v_exp_f32_e32 v90, v89
	v_and_b32_e32 v89, 0xffff0000, v117
	v_mul_f32_e32 v91, 0xbfb8aa3b, v89
	v_exp_f32_e32 v91, v91
	v_rcp_f32_e32 v80, v80
	v_rcp_f32_e32 v81, v81
	v_add_f32_e32 v90, 1.0, v90
	v_add_f32_e32 v91, 1.0, v91
	v_rcp_f32_e32 v102, v102
	v_rcp_f32_e32 v90, v90
	v_rcp_f32_e32 v91, v91
	v_lshlrev_b32_e32 v92, 16, v99
	v_and_b32_e32 v93, 0xffff0000, v99
	v_mul_f32_e64 v80, v80, v92
	v_mul_f32_e64 v81, v81, v93
	v_mul_f32_e64 v84, v102, v84
	v_mul_f32_e64 v85, v103, v85
	v_mul_f32_e64 v80, v80, v88
	v_mul_f32_e64 v81, v81, v89
	v_cvt_pk_bf16_f32 v82, v82, v83
	v_mul_f32_e64 v88, v90, v80
	v_mul_f32_e64 v89, v91, v81
	v_cvt_pk_bf16_f32 v80, v84, v85
	v_cvt_pk_bf16_f32 v81, v86, v87
	v_cvt_pk_bf16_f32 v83, v88, v89
	v_or_b32_e32 v102, 48, v156
	global_store_dwordx4 v[100:101], v[80:83], off offset:256
	global_load_dwordx4 v[82:85], v[152:153], off
	v_ashrrev_i32_e32 v103, 31, v102
	v_mad_i64_i32 v[80:81], s[38:39], v102, s70, v[158:159]
	v_lshl_add_u64 v[80:81], v[80:81], 0, v[154:155]
	global_load_dwordx4 v[86:89], v[80:81], off
	v_lshlrev_b64 v[90:91], 11, v[102:103]
	v_lshl_add_u64 v[90:91], s[6:7], 0, v[90:91]
	v_lshl_add_u64 v[104:105], v[90:91], 0, v[154:155]
	global_load_dwordx4 v[90:93], v[104:105], off
	global_load_dwordx4 v[94:97], v[152:153], off offset:16
	global_load_dwordx4 v[98:101], v[80:81], off offset:256
	s_waitcnt vmcnt(4)
	v_add_f32_e32 v78, v78, v84
	v_add_f32_e32 v79, v79, v85
	v_mul_f32_e32 v78, 0xbfb8aa3b, v78
	v_mul_f32_e32 v79, 0xbfb8aa3b, v79
	v_exp_f32_e32 v78, v78
	s_waitcnt vmcnt(3)
	v_lshlrev_b32_e32 v106, 16, v86
	v_mul_f32_e32 v80, 0xbfb8aa3b, v106
	v_exp_f32_e32 v80, v80
	v_and_b32_e32 v107, 0xffff0000, v86
	v_lshlrev_b32_e32 v84, 16, v87
	v_exp_f32_e32 v79, v79
	v_add_f32_e32 v80, 1.0, v80
	v_rcp_f32_e32 v108, v80
	v_mul_f32_e32 v80, 0xbfb8aa3b, v107
	v_exp_f32_e32 v86, v80
	v_mul_f32_e32 v85, 0xbfb8aa3b, v84
	v_add_f32_e32 v78, 1.0, v78
	v_add_f32_e32 v79, 1.0, v79
	v_add_f32_e32 v86, 1.0, v86
	v_rcp_f32_e32 v109, v86
	v_exp_f32_e32 v86, v85
	v_and_b32_e32 v85, 0xffff0000, v87
	v_mul_f32_e32 v87, 0xbfb8aa3b, v85
	v_exp_f32_e32 v87, v87
	v_rcp_f32_e32 v78, v78
	v_rcp_f32_e32 v79, v79
	s_waitcnt vmcnt(1)
	v_add_f32_e32 v72, v72, v94
	v_add_f32_e32 v73, v73, v95
	v_add_f32_e32 v86, 1.0, v86
	v_add_f32_e32 v87, 1.0, v87
	v_mul_f32_e32 v72, 0xbfb8aa3b, v72
	v_mul_f32_e32 v73, 0xbfb8aa3b, v73
	v_add_f32_e32 v76, v76, v82
	v_add_f32_e32 v77, v77, v83
	global_load_dwordx4 v[80:83], v[104:105], off offset:256
	v_lshlrev_b32_e32 v104, 16, v90
	v_and_b32_e32 v105, 0xffff0000, v90
	v_rcp_f32_e32 v86, v86
	v_lshlrev_b32_e32 v90, 16, v91
	v_and_b32_e32 v91, 0xffff0000, v91
	v_rcp_f32_e32 v87, v87
	v_exp_f32_e32 v72, v72
	v_exp_f32_e32 v73, v73
	v_mul_f32_e64 v78, v78, v90
	v_mul_f32_e64 v79, v79, v91
	v_lshlrev_b32_e32 v90, 16, v92
	v_mul_f32_e64 v78, v78, v84
	v_mul_f32_e64 v79, v79, v85
	v_lshlrev_b32_e32 v84, 16, v88
	v_mul_f32_e32 v85, 0xbfb8aa3b, v84
	v_mul_f32_e64 v78, v86, v78
	v_mul_f32_e64 v79, v87, v79
	v_add_f32_e32 v72, 1.0, v72
	v_exp_f32_e32 v86, v85
	v_add_f32_e32 v73, 1.0, v73
	v_and_b32_e32 v85, 0xffff0000, v88
	v_rcp_f32_e32 v72, v72
	v_rcp_f32_e32 v73, v73
	v_mul_f32_e32 v87, 0xbfb8aa3b, v85
	v_exp_f32_e32 v87, v87
	v_and_b32_e32 v91, 0xffff0000, v92
	v_mul_f32_e64 v72, v72, v90
	v_mul_f32_e64 v73, v73, v91
	v_add_f32_e32 v74, v74, v96
	v_mul_f32_e64 v72, v72, v84
	v_mul_f32_e64 v73, v73, v85
	v_add_f32_e32 v84, 1.0, v87
	v_mul_f32_e32 v74, 0xbfb8aa3b, v74
	v_add_f32_e32 v86, 1.0, v86
	v_rcp_f32_e32 v87, v84
	v_exp_f32_e32 v84, v74
	v_add_f32_e32 v74, v75, v97
	v_rcp_f32_e32 v86, v86
	v_mul_f32_e32 v74, 0xbfb8aa3b, v74
	v_exp_f32_e32 v85, v74
	v_mul_f32_e32 v76, 0xbfb8aa3b, v76
	v_mul_f32_e32 v77, 0xbfb8aa3b, v77
	v_mul_f32_e64 v74, v86, v72
	v_mul_f32_e64 v75, v87, v73
	v_add_f32_e32 v72, 1.0, v84
	v_lshlrev_b32_e32 v84, 16, v89
	v_exp_f32_e32 v76, v76
	v_exp_f32_e32 v77, v77
	v_add_f32_e32 v73, 1.0, v85
	v_mul_f32_e32 v85, 0xbfb8aa3b, v84
	v_exp_f32_e32 v86, v85
	v_and_b32_e32 v85, 0xffff0000, v89
	v_mul_f32_e32 v87, 0xbfb8aa3b, v85
	v_exp_f32_e32 v87, v87
	v_add_f32_e32 v76, 1.0, v76
	v_add_f32_e32 v77, 1.0, v77
	v_rcp_f32_e32 v76, v76
	v_rcp_f32_e32 v77, v77
	v_rcp_f32_e32 v72, v72
	v_rcp_f32_e32 v73, v73
	v_add_f32_e32 v86, 1.0, v86
	v_add_f32_e32 v87, 1.0, v87
	v_rcp_f32_e32 v86, v86
	v_rcp_f32_e32 v87, v87
	v_mul_f32_e64 v76, v76, v104
	v_mul_f32_e64 v77, v77, v105
	v_lshlrev_b32_e32 v88, 16, v93
	v_and_b32_e32 v89, 0xffff0000, v93
	v_mul_f32_e64 v76, v76, v106
	v_mul_f32_e64 v77, v77, v107
	v_mul_f32_e64 v72, v72, v88
	v_mul_f32_e64 v73, v73, v89
	v_mul_f32_e64 v76, v108, v76
	v_mul_f32_e64 v77, v109, v77
	v_mul_f32_e64 v72, v72, v84
	v_mul_f32_e64 v73, v73, v85
	v_cvt_pk_bf16_f32 v74, v74, v75
	v_mul_f32_e64 v84, v86, v72
	v_mul_f32_e64 v85, v87, v73
	v_cvt_pk_bf16_f32 v72, v76, v77
	v_lshlrev_b64 v[76:77], 12, v[102:103]
	v_lshl_add_u64 v[76:77], s[14:15], 0, v[76:77]
	v_cvt_pk_bf16_f32 v73, v78, v79
	v_cvt_pk_bf16_f32 v75, v84, v85
	v_lshl_add_u64 v[84:85], v[76:77], 0, v[154:155]
	global_store_dwordx4 v[84:85], v[72:75], off
	global_load_dwordx4 v[72:75], v[152:153], off offset:512
	s_nop 0
	global_load_dwordx4 v[76:79], v[152:153], off offset:528
	s_waitcnt vmcnt(3)
	v_lshlrev_b32_e32 v88, 16, v80
	v_and_b32_e32 v89, 0xffff0000, v80
	s_waitcnt vmcnt(1)
	v_add_f32_e32 v68, v68, v72
	v_add_f32_e32 v69, v69, v73
	v_mul_f32_e32 v68, 0xbfb8aa3b, v68
	v_mul_f32_e32 v69, 0xbfb8aa3b, v69
	v_exp_f32_e32 v68, v68
	v_exp_f32_e32 v69, v69
	v_lshlrev_b32_e32 v72, 16, v98
	v_mul_f32_e32 v73, 0xbfb8aa3b, v72
	v_add_f32_e32 v68, 1.0, v68
	v_add_f32_e32 v69, 1.0, v69
	v_rcp_f32_e32 v68, v68
	v_rcp_f32_e32 v69, v69
	v_exp_f32_e32 v86, v73
	v_and_b32_e32 v73, 0xffff0000, v98
	v_add_f32_e32 v70, v70, v74
	v_mul_f32_e64 v68, v68, v88
	v_mul_f32_e64 v69, v69, v89
	v_add_f32_e32 v71, v71, v75
	v_mul_f32_e32 v70, 0xbfb8aa3b, v70
	v_mul_f32_e64 v68, v68, v72
	v_mul_f32_e64 v69, v69, v73
	v_mul_f32_e32 v71, 0xbfb8aa3b, v71
	v_lshlrev_b32_e32 v72, 16, v99
	v_mul_f32_e32 v87, 0xbfb8aa3b, v73
	v_exp_f32_e32 v70, v70
	v_exp_f32_e32 v71, v71
	v_mul_f32_e32 v73, 0xbfb8aa3b, v72
	v_exp_f32_e32 v74, v73
	v_and_b32_e32 v73, 0xffff0000, v99
	v_mul_f32_e32 v75, 0xbfb8aa3b, v73
	v_exp_f32_e32 v87, v87
	v_exp_f32_e32 v75, v75
	v_add_f32_e32 v70, 1.0, v70
	v_add_f32_e32 v71, 1.0, v71
	v_rcp_f32_e32 v70, v70
	v_rcp_f32_e32 v71, v71
	s_waitcnt vmcnt(0)
	v_add_f32_e32 v64, v64, v76
	v_add_f32_e32 v65, v65, v77
	v_add_f32_e32 v80, 1.0, v87
	v_add_f32_e32 v74, 1.0, v74
	v_add_f32_e32 v75, 1.0, v75
	v_mul_f32_e32 v64, 0xbfb8aa3b, v64
	v_mul_f32_e32 v65, 0xbfb8aa3b, v65
	v_rcp_f32_e32 v87, v80
	v_rcp_f32_e32 v74, v74
	v_lshlrev_b32_e32 v80, 16, v81
	v_and_b32_e32 v81, 0xffff0000, v81
	v_rcp_f32_e32 v75, v75
	v_exp_f32_e32 v64, v64
	v_exp_f32_e32 v65, v65
	v_mul_f32_e64 v70, v70, v80
	v_mul_f32_e64 v71, v71, v81
	v_lshlrev_b32_e32 v76, 16, v82
	v_mul_f32_e64 v70, v70, v72
	v_mul_f32_e64 v71, v71, v73
	v_lshlrev_b32_e32 v72, 16, v100
	v_mul_f32_e32 v73, 0xbfb8aa3b, v72
	v_mul_f32_e64 v70, v74, v70
	v_mul_f32_e64 v71, v75, v71
	v_add_f32_e32 v64, 1.0, v64
	v_exp_f32_e32 v74, v73
	v_add_f32_e32 v65, 1.0, v65
	v_and_b32_e32 v73, 0xffff0000, v100
	v_rcp_f32_e32 v64, v64
	v_rcp_f32_e32 v65, v65
	v_mul_f32_e32 v75, 0xbfb8aa3b, v73
	v_exp_f32_e32 v75, v75
	v_and_b32_e32 v77, 0xffff0000, v82
	v_mul_f32_e64 v64, v64, v76
	v_mul_f32_e64 v65, v65, v77
	v_add_f32_e32 v66, v66, v78
	v_mul_f32_e64 v64, v64, v72
	v_mul_f32_e64 v65, v65, v73
	v_add_f32_e32 v72, 1.0, v75
	v_mul_f32_e32 v66, 0xbfb8aa3b, v66
	v_add_f32_e32 v74, 1.0, v74
	v_rcp_f32_e32 v75, v72
	v_exp_f32_e32 v72, v66
	v_add_f32_e32 v66, v67, v79
	v_rcp_f32_e32 v74, v74
	v_mul_f32_e32 v66, 0xbfb8aa3b, v66
	v_exp_f32_e32 v73, v66
	v_add_f32_e32 v86, 1.0, v86
	v_mul_f32_e64 v66, v74, v64
	v_mul_f32_e64 v67, v75, v65
	v_add_f32_e32 v64, 1.0, v72
	v_lshlrev_b32_e32 v72, 16, v101
	v_add_f32_e32 v65, 1.0, v73
	v_mul_f32_e32 v73, 0xbfb8aa3b, v72
	v_exp_f32_e32 v74, v73
	v_and_b32_e32 v73, 0xffff0000, v101
	v_mul_f32_e32 v75, 0xbfb8aa3b, v73
	v_exp_f32_e32 v75, v75
	v_rcp_f32_e32 v64, v64
	v_rcp_f32_e32 v65, v65
	v_add_f32_e32 v74, 1.0, v74
	v_add_f32_e32 v75, 1.0, v75
	v_rcp_f32_e32 v86, v86
	v_rcp_f32_e32 v74, v74
	v_rcp_f32_e32 v75, v75
	v_lshlrev_b32_e32 v76, 16, v83
	v_and_b32_e32 v77, 0xffff0000, v83
	v_mul_f32_e64 v64, v64, v76
	v_mul_f32_e64 v65, v65, v77
	v_mul_f32_e64 v68, v86, v68
	v_mul_f32_e64 v69, v87, v69
	v_mul_f32_e64 v64, v64, v72
	v_mul_f32_e64 v65, v65, v73
	v_cvt_pk_bf16_f32 v66, v66, v67
	v_mul_f32_e64 v72, v74, v64
	v_mul_f32_e64 v73, v75, v65
	v_cvt_pk_bf16_f32 v64, v68, v69
	v_cvt_pk_bf16_f32 v65, v70, v71
	v_cvt_pk_bf16_f32 v67, v72, v73
	v_add_u32_e32 v86, 0x80, v156
	global_store_dwordx4 v[84:85], v[64:67], off offset:256
	global_load_dwordx4 v[66:69], v[152:153], off
	v_ashrrev_i32_e32 v87, 31, v86
	v_mad_i64_i32 v[64:65], s[38:39], v86, s70, v[158:159]
	v_lshl_add_u64 v[64:65], v[64:65], 0, v[154:155]
	global_load_dwordx4 v[70:73], v[64:65], off
	v_lshlrev_b64 v[74:75], 11, v[86:87]
	v_lshl_add_u64 v[74:75], s[6:7], 0, v[74:75]
	v_lshl_add_u64 v[88:89], v[74:75], 0, v[154:155]
	global_load_dwordx4 v[74:77], v[88:89], off
	global_load_dwordx4 v[78:81], v[152:153], off offset:16
	global_load_dwordx4 v[82:85], v[64:65], off offset:256
	s_waitcnt vmcnt(4)
	v_add_f32_e32 v62, v62, v68
	v_add_f32_e32 v63, v63, v69
	v_mul_f32_e32 v62, 0xbfb8aa3b, v62
	v_mul_f32_e32 v63, 0xbfb8aa3b, v63
	v_exp_f32_e32 v62, v62
	s_waitcnt vmcnt(3)
	v_lshlrev_b32_e32 v90, 16, v70
	v_mul_f32_e32 v64, 0xbfb8aa3b, v90
	v_exp_f32_e32 v64, v64
	v_and_b32_e32 v91, 0xffff0000, v70
	v_lshlrev_b32_e32 v68, 16, v71
	v_exp_f32_e32 v63, v63
	v_add_f32_e32 v64, 1.0, v64
	v_rcp_f32_e32 v92, v64
	v_mul_f32_e32 v64, 0xbfb8aa3b, v91
	v_exp_f32_e32 v70, v64
	v_mul_f32_e32 v69, 0xbfb8aa3b, v68
	v_add_f32_e32 v62, 1.0, v62
	v_add_f32_e32 v63, 1.0, v63
	v_add_f32_e32 v70, 1.0, v70
	v_rcp_f32_e32 v93, v70
	v_exp_f32_e32 v70, v69
	v_and_b32_e32 v69, 0xffff0000, v71
	v_mul_f32_e32 v71, 0xbfb8aa3b, v69
	v_exp_f32_e32 v71, v71
	v_rcp_f32_e32 v62, v62
	v_rcp_f32_e32 v63, v63
	s_waitcnt vmcnt(1)
	v_add_f32_e32 v56, v56, v78
	v_add_f32_e32 v57, v57, v79
	v_add_f32_e32 v70, 1.0, v70
	v_add_f32_e32 v71, 1.0, v71
	v_mul_f32_e32 v56, 0xbfb8aa3b, v56
	v_mul_f32_e32 v57, 0xbfb8aa3b, v57
	v_add_f32_e32 v60, v60, v66
	v_add_f32_e32 v61, v61, v67
	global_load_dwordx4 v[64:67], v[88:89], off offset:256
	v_lshlrev_b32_e32 v88, 16, v74
	v_and_b32_e32 v89, 0xffff0000, v74
	v_rcp_f32_e32 v70, v70
	v_lshlrev_b32_e32 v74, 16, v75
	v_and_b32_e32 v75, 0xffff0000, v75
	v_rcp_f32_e32 v71, v71
	v_exp_f32_e32 v56, v56
	v_exp_f32_e32 v57, v57
	v_mul_f32_e64 v62, v62, v74
	v_mul_f32_e64 v63, v63, v75
	v_lshlrev_b32_e32 v74, 16, v76
	v_mul_f32_e64 v62, v62, v68
	v_mul_f32_e64 v63, v63, v69
	v_lshlrev_b32_e32 v68, 16, v72
	v_mul_f32_e32 v69, 0xbfb8aa3b, v68
	v_mul_f32_e64 v62, v70, v62
	v_mul_f32_e64 v63, v71, v63
	v_add_f32_e32 v56, 1.0, v56
	v_exp_f32_e32 v70, v69
	v_add_f32_e32 v57, 1.0, v57
	v_and_b32_e32 v69, 0xffff0000, v72
	v_rcp_f32_e32 v56, v56
	v_rcp_f32_e32 v57, v57
	v_mul_f32_e32 v71, 0xbfb8aa3b, v69
	v_exp_f32_e32 v71, v71
	v_and_b32_e32 v75, 0xffff0000, v76
	v_mul_f32_e64 v56, v56, v74
	v_mul_f32_e64 v57, v57, v75
	v_add_f32_e32 v58, v58, v80
	v_mul_f32_e64 v56, v56, v68
	v_mul_f32_e64 v57, v57, v69
	v_add_f32_e32 v68, 1.0, v71
	v_mul_f32_e32 v58, 0xbfb8aa3b, v58
	v_add_f32_e32 v70, 1.0, v70
	v_rcp_f32_e32 v71, v68
	v_exp_f32_e32 v68, v58
	v_add_f32_e32 v58, v59, v81
	v_rcp_f32_e32 v70, v70
	v_mul_f32_e32 v58, 0xbfb8aa3b, v58
	v_exp_f32_e32 v69, v58
	v_mul_f32_e32 v60, 0xbfb8aa3b, v60
	v_mul_f32_e32 v61, 0xbfb8aa3b, v61
	v_mul_f32_e64 v58, v70, v56
	v_mul_f32_e64 v59, v71, v57
	v_add_f32_e32 v56, 1.0, v68
	v_lshlrev_b32_e32 v68, 16, v73
	v_exp_f32_e32 v60, v60
	v_exp_f32_e32 v61, v61
	v_add_f32_e32 v57, 1.0, v69
	v_mul_f32_e32 v69, 0xbfb8aa3b, v68
	v_exp_f32_e32 v70, v69
	v_and_b32_e32 v69, 0xffff0000, v73
	v_mul_f32_e32 v71, 0xbfb8aa3b, v69
	v_exp_f32_e32 v71, v71
	v_add_f32_e32 v60, 1.0, v60
	v_add_f32_e32 v61, 1.0, v61
	v_rcp_f32_e32 v60, v60
	v_rcp_f32_e32 v61, v61
	v_rcp_f32_e32 v56, v56
	v_rcp_f32_e32 v57, v57
	v_add_f32_e32 v70, 1.0, v70
	v_add_f32_e32 v71, 1.0, v71
	v_rcp_f32_e32 v70, v70
	v_rcp_f32_e32 v71, v71
	v_mul_f32_e64 v60, v60, v88
	v_mul_f32_e64 v61, v61, v89
	v_lshlrev_b32_e32 v72, 16, v77
	v_and_b32_e32 v73, 0xffff0000, v77
	v_mul_f32_e64 v60, v60, v90
	v_mul_f32_e64 v61, v61, v91
	v_mul_f32_e64 v56, v56, v72
	v_mul_f32_e64 v57, v57, v73
	v_mul_f32_e64 v60, v92, v60
	v_mul_f32_e64 v61, v93, v61
	v_mul_f32_e64 v56, v56, v68
	v_mul_f32_e64 v57, v57, v69
	v_cvt_pk_bf16_f32 v58, v58, v59
	v_mul_f32_e64 v68, v70, v56
	v_mul_f32_e64 v69, v71, v57
	v_cvt_pk_bf16_f32 v56, v60, v61
	v_lshlrev_b64 v[60:61], 12, v[86:87]
	v_lshl_add_u64 v[60:61], s[14:15], 0, v[60:61]
	v_cvt_pk_bf16_f32 v57, v62, v63
	v_cvt_pk_bf16_f32 v59, v68, v69
	v_lshl_add_u64 v[68:69], v[60:61], 0, v[154:155]
	global_store_dwordx4 v[68:69], v[56:59], off
	global_load_dwordx4 v[56:59], v[152:153], off offset:512
	s_nop 0
	global_load_dwordx4 v[60:63], v[152:153], off offset:528
	s_waitcnt vmcnt(3)
	v_lshlrev_b32_e32 v72, 16, v64
	v_and_b32_e32 v73, 0xffff0000, v64
	s_waitcnt vmcnt(1)
	v_add_f32_e32 v52, v52, v56
	v_add_f32_e32 v53, v53, v57
	v_mul_f32_e32 v52, 0xbfb8aa3b, v52
	v_mul_f32_e32 v53, 0xbfb8aa3b, v53
	v_exp_f32_e32 v52, v52
	v_exp_f32_e32 v53, v53
	v_lshlrev_b32_e32 v56, 16, v82
	v_mul_f32_e32 v57, 0xbfb8aa3b, v56
	v_add_f32_e32 v52, 1.0, v52
	v_add_f32_e32 v53, 1.0, v53
	v_rcp_f32_e32 v52, v52
	v_rcp_f32_e32 v53, v53
	v_exp_f32_e32 v70, v57
	v_and_b32_e32 v57, 0xffff0000, v82
	v_add_f32_e32 v54, v54, v58
	v_mul_f32_e64 v52, v52, v72
	v_mul_f32_e64 v53, v53, v73
	v_add_f32_e32 v55, v55, v59
	v_mul_f32_e32 v54, 0xbfb8aa3b, v54
	v_mul_f32_e64 v52, v52, v56
	v_mul_f32_e64 v53, v53, v57
	v_mul_f32_e32 v55, 0xbfb8aa3b, v55
	v_lshlrev_b32_e32 v56, 16, v83
	v_mul_f32_e32 v71, 0xbfb8aa3b, v57
	v_exp_f32_e32 v54, v54
	v_exp_f32_e32 v55, v55
	v_mul_f32_e32 v57, 0xbfb8aa3b, v56
	v_exp_f32_e32 v58, v57
	v_and_b32_e32 v57, 0xffff0000, v83
	v_mul_f32_e32 v59, 0xbfb8aa3b, v57
	v_exp_f32_e32 v71, v71
	v_exp_f32_e32 v59, v59
	v_add_f32_e32 v54, 1.0, v54
	v_add_f32_e32 v55, 1.0, v55
	v_rcp_f32_e32 v54, v54
	v_rcp_f32_e32 v55, v55
	s_waitcnt vmcnt(0)
	v_add_f32_e32 v48, v48, v60
	v_add_f32_e32 v49, v49, v61
	v_add_f32_e32 v64, 1.0, v71
	v_add_f32_e32 v58, 1.0, v58
	v_add_f32_e32 v59, 1.0, v59
	v_mul_f32_e32 v48, 0xbfb8aa3b, v48
	v_mul_f32_e32 v49, 0xbfb8aa3b, v49
	v_rcp_f32_e32 v71, v64
	v_rcp_f32_e32 v58, v58
	v_lshlrev_b32_e32 v64, 16, v65
	v_and_b32_e32 v65, 0xffff0000, v65
	v_rcp_f32_e32 v59, v59
	v_exp_f32_e32 v48, v48
	v_exp_f32_e32 v49, v49
	v_mul_f32_e64 v54, v54, v64
	v_mul_f32_e64 v55, v55, v65
	v_lshlrev_b32_e32 v60, 16, v66
	v_mul_f32_e64 v54, v54, v56
	v_mul_f32_e64 v55, v55, v57
	v_lshlrev_b32_e32 v56, 16, v84
	v_mul_f32_e32 v57, 0xbfb8aa3b, v56
	v_mul_f32_e64 v54, v58, v54
	v_mul_f32_e64 v55, v59, v55
	v_add_f32_e32 v48, 1.0, v48
	v_exp_f32_e32 v58, v57
	v_add_f32_e32 v49, 1.0, v49
	v_and_b32_e32 v57, 0xffff0000, v84
	v_rcp_f32_e32 v48, v48
	v_rcp_f32_e32 v49, v49
	v_mul_f32_e32 v59, 0xbfb8aa3b, v57
	v_exp_f32_e32 v59, v59
	v_and_b32_e32 v61, 0xffff0000, v66
	v_mul_f32_e64 v48, v48, v60
	v_mul_f32_e64 v49, v49, v61
	v_add_f32_e32 v50, v50, v62
	v_mul_f32_e64 v48, v48, v56
	v_mul_f32_e64 v49, v49, v57
	v_add_f32_e32 v56, 1.0, v59
	v_mul_f32_e32 v50, 0xbfb8aa3b, v50
	v_add_f32_e32 v58, 1.0, v58
	v_rcp_f32_e32 v59, v56
	v_exp_f32_e32 v56, v50
	v_add_f32_e32 v50, v51, v63
	v_rcp_f32_e32 v58, v58
	v_mul_f32_e32 v50, 0xbfb8aa3b, v50
	v_exp_f32_e32 v57, v50
	v_add_f32_e32 v70, 1.0, v70
	v_mul_f32_e64 v50, v58, v48
	v_mul_f32_e64 v51, v59, v49
	v_add_f32_e32 v48, 1.0, v56
	v_lshlrev_b32_e32 v56, 16, v85
	v_add_f32_e32 v49, 1.0, v57
	v_mul_f32_e32 v57, 0xbfb8aa3b, v56
	v_exp_f32_e32 v58, v57
	v_and_b32_e32 v57, 0xffff0000, v85
	v_mul_f32_e32 v59, 0xbfb8aa3b, v57
	v_exp_f32_e32 v59, v59
	v_rcp_f32_e32 v48, v48
	v_rcp_f32_e32 v49, v49
	v_add_f32_e32 v58, 1.0, v58
	v_add_f32_e32 v59, 1.0, v59
	v_rcp_f32_e32 v70, v70
	v_rcp_f32_e32 v58, v58
	v_rcp_f32_e32 v59, v59
	v_lshlrev_b32_e32 v60, 16, v67
	v_and_b32_e32 v61, 0xffff0000, v67
	v_mul_f32_e64 v48, v48, v60
	v_mul_f32_e64 v49, v49, v61
	v_mul_f32_e64 v52, v70, v52
	v_mul_f32_e64 v53, v71, v53
	v_mul_f32_e64 v48, v48, v56
	v_mul_f32_e64 v49, v49, v57
	v_cvt_pk_bf16_f32 v50, v50, v51
	v_mul_f32_e64 v56, v58, v48
	v_mul_f32_e64 v57, v59, v49
	v_cvt_pk_bf16_f32 v48, v52, v53
	v_cvt_pk_bf16_f32 v49, v54, v55
	v_cvt_pk_bf16_f32 v51, v56, v57
	v_add_u32_e32 v70, 0x90, v156
	global_store_dwordx4 v[68:69], v[48:51], off offset:256
	global_load_dwordx4 v[50:53], v[152:153], off
	v_ashrrev_i32_e32 v71, 31, v70
	v_mad_i64_i32 v[48:49], s[38:39], v70, s70, v[158:159]
	v_lshl_add_u64 v[48:49], v[48:49], 0, v[154:155]
	global_load_dwordx4 v[54:57], v[48:49], off
	v_lshlrev_b64 v[58:59], 11, v[70:71]
	v_lshl_add_u64 v[58:59], s[6:7], 0, v[58:59]
	v_lshl_add_u64 v[72:73], v[58:59], 0, v[154:155]
	global_load_dwordx4 v[58:61], v[72:73], off
	global_load_dwordx4 v[62:65], v[152:153], off offset:16
	global_load_dwordx4 v[66:69], v[48:49], off offset:256
	s_waitcnt vmcnt(4)
	v_add_f32_e32 v46, v46, v52
	v_add_f32_e32 v47, v47, v53
	v_mul_f32_e32 v46, 0xbfb8aa3b, v46
	v_mul_f32_e32 v47, 0xbfb8aa3b, v47
	v_exp_f32_e32 v46, v46
	s_waitcnt vmcnt(3)
	v_lshlrev_b32_e32 v74, 16, v54
	v_mul_f32_e32 v48, 0xbfb8aa3b, v74
	v_exp_f32_e32 v48, v48
	v_and_b32_e32 v75, 0xffff0000, v54
	v_lshlrev_b32_e32 v52, 16, v55
	v_exp_f32_e32 v47, v47
	v_add_f32_e32 v48, 1.0, v48
	v_rcp_f32_e32 v76, v48
	v_mul_f32_e32 v48, 0xbfb8aa3b, v75
	v_exp_f32_e32 v54, v48
	v_mul_f32_e32 v53, 0xbfb8aa3b, v52
	v_add_f32_e32 v46, 1.0, v46
	v_add_f32_e32 v47, 1.0, v47
	v_add_f32_e32 v54, 1.0, v54
	v_rcp_f32_e32 v77, v54
	v_exp_f32_e32 v54, v53
	v_and_b32_e32 v53, 0xffff0000, v55
	v_mul_f32_e32 v55, 0xbfb8aa3b, v53
	v_exp_f32_e32 v55, v55
	v_rcp_f32_e32 v46, v46
	v_rcp_f32_e32 v47, v47
	s_waitcnt vmcnt(1)
	v_add_f32_e32 v40, v40, v62
	v_add_f32_e32 v41, v41, v63
	v_add_f32_e32 v54, 1.0, v54
	v_add_f32_e32 v55, 1.0, v55
	v_mul_f32_e32 v40, 0xbfb8aa3b, v40
	v_mul_f32_e32 v41, 0xbfb8aa3b, v41
	v_add_f32_e32 v44, v44, v50
	v_add_f32_e32 v45, v45, v51
	global_load_dwordx4 v[48:51], v[72:73], off offset:256
	v_lshlrev_b32_e32 v72, 16, v58
	v_and_b32_e32 v73, 0xffff0000, v58
	v_rcp_f32_e32 v54, v54
	v_lshlrev_b32_e32 v58, 16, v59
	v_and_b32_e32 v59, 0xffff0000, v59
	v_rcp_f32_e32 v55, v55
	v_exp_f32_e32 v40, v40
	v_exp_f32_e32 v41, v41
	v_mul_f32_e64 v46, v46, v58
	v_mul_f32_e64 v47, v47, v59
	v_lshlrev_b32_e32 v58, 16, v60
	v_mul_f32_e64 v46, v46, v52
	v_mul_f32_e64 v47, v47, v53
	v_lshlrev_b32_e32 v52, 16, v56
	v_mul_f32_e32 v53, 0xbfb8aa3b, v52
	v_mul_f32_e64 v46, v54, v46
	v_mul_f32_e64 v47, v55, v47
	v_add_f32_e32 v40, 1.0, v40
	v_exp_f32_e32 v54, v53
	v_add_f32_e32 v41, 1.0, v41
	v_and_b32_e32 v53, 0xffff0000, v56
	v_rcp_f32_e32 v40, v40
	v_rcp_f32_e32 v41, v41
	v_mul_f32_e32 v55, 0xbfb8aa3b, v53
	v_exp_f32_e32 v55, v55
	v_and_b32_e32 v59, 0xffff0000, v60
	v_mul_f32_e64 v40, v40, v58
	v_mul_f32_e64 v41, v41, v59
	v_add_f32_e32 v42, v42, v64
	v_mul_f32_e64 v40, v40, v52
	v_mul_f32_e64 v41, v41, v53
	v_add_f32_e32 v52, 1.0, v55
	v_mul_f32_e32 v42, 0xbfb8aa3b, v42
	v_add_f32_e32 v54, 1.0, v54
	v_rcp_f32_e32 v55, v52
	v_exp_f32_e32 v52, v42
	v_add_f32_e32 v42, v43, v65
	v_rcp_f32_e32 v54, v54
	v_mul_f32_e32 v42, 0xbfb8aa3b, v42
	v_exp_f32_e32 v53, v42
	v_mul_f32_e32 v44, 0xbfb8aa3b, v44
	v_mul_f32_e32 v45, 0xbfb8aa3b, v45
	v_mul_f32_e64 v42, v54, v40
	v_mul_f32_e64 v43, v55, v41
	v_add_f32_e32 v40, 1.0, v52
	v_lshlrev_b32_e32 v52, 16, v57
	v_exp_f32_e32 v44, v44
	v_exp_f32_e32 v45, v45
	v_add_f32_e32 v41, 1.0, v53
	v_mul_f32_e32 v53, 0xbfb8aa3b, v52
	v_exp_f32_e32 v54, v53
	v_and_b32_e32 v53, 0xffff0000, v57
	v_mul_f32_e32 v55, 0xbfb8aa3b, v53
	v_exp_f32_e32 v55, v55
	v_add_f32_e32 v44, 1.0, v44
	v_add_f32_e32 v45, 1.0, v45
	v_rcp_f32_e32 v44, v44
	v_rcp_f32_e32 v45, v45
	v_rcp_f32_e32 v40, v40
	v_rcp_f32_e32 v41, v41
	v_add_f32_e32 v54, 1.0, v54
	v_add_f32_e32 v55, 1.0, v55
	v_rcp_f32_e32 v54, v54
	v_rcp_f32_e32 v55, v55
	v_mul_f32_e64 v44, v44, v72
	v_mul_f32_e64 v45, v45, v73
	v_lshlrev_b32_e32 v56, 16, v61
	v_and_b32_e32 v57, 0xffff0000, v61
	v_mul_f32_e64 v44, v44, v74
	v_mul_f32_e64 v45, v45, v75
	v_mul_f32_e64 v40, v40, v56
	v_mul_f32_e64 v41, v41, v57
	v_mul_f32_e64 v44, v76, v44
	v_mul_f32_e64 v45, v77, v45
	v_mul_f32_e64 v40, v40, v52
	v_mul_f32_e64 v41, v41, v53
	v_cvt_pk_bf16_f32 v42, v42, v43
	v_mul_f32_e64 v52, v54, v40
	v_mul_f32_e64 v53, v55, v41
	v_cvt_pk_bf16_f32 v40, v44, v45
	v_lshlrev_b64 v[44:45], 12, v[70:71]
	v_lshl_add_u64 v[44:45], s[14:15], 0, v[44:45]
	v_cvt_pk_bf16_f32 v41, v46, v47
	v_cvt_pk_bf16_f32 v43, v52, v53
	v_lshl_add_u64 v[52:53], v[44:45], 0, v[154:155]
	global_store_dwordx4 v[52:53], v[40:43], off
	global_load_dwordx4 v[40:43], v[152:153], off offset:512
	s_nop 0
	global_load_dwordx4 v[44:47], v[152:153], off offset:528
	s_waitcnt vmcnt(3)
	v_lshlrev_b32_e32 v56, 16, v48
	v_and_b32_e32 v57, 0xffff0000, v48
	s_waitcnt vmcnt(1)
	v_add_f32_e32 v36, v36, v40
	v_add_f32_e32 v37, v37, v41
	v_mul_f32_e32 v36, 0xbfb8aa3b, v36
	v_mul_f32_e32 v37, 0xbfb8aa3b, v37
	v_exp_f32_e32 v36, v36
	v_exp_f32_e32 v37, v37
	v_lshlrev_b32_e32 v40, 16, v66
	v_mul_f32_e32 v41, 0xbfb8aa3b, v40
	v_add_f32_e32 v36, 1.0, v36
	v_add_f32_e32 v37, 1.0, v37
	v_rcp_f32_e32 v36, v36
	v_rcp_f32_e32 v37, v37
	v_exp_f32_e32 v54, v41
	v_and_b32_e32 v41, 0xffff0000, v66
	v_add_f32_e32 v38, v38, v42
	v_mul_f32_e64 v36, v36, v56
	v_mul_f32_e64 v37, v37, v57
	v_add_f32_e32 v39, v39, v43
	v_mul_f32_e32 v38, 0xbfb8aa3b, v38
	v_mul_f32_e64 v36, v36, v40
	v_mul_f32_e64 v37, v37, v41
	v_mul_f32_e32 v39, 0xbfb8aa3b, v39
	v_lshlrev_b32_e32 v40, 16, v67
	v_mul_f32_e32 v55, 0xbfb8aa3b, v41
	v_exp_f32_e32 v38, v38
	v_exp_f32_e32 v39, v39
	v_mul_f32_e32 v41, 0xbfb8aa3b, v40
	v_exp_f32_e32 v42, v41
	v_and_b32_e32 v41, 0xffff0000, v67
	v_mul_f32_e32 v43, 0xbfb8aa3b, v41
	v_exp_f32_e32 v55, v55
	v_exp_f32_e32 v43, v43
	v_add_f32_e32 v38, 1.0, v38
	v_add_f32_e32 v39, 1.0, v39
	v_rcp_f32_e32 v38, v38
	v_rcp_f32_e32 v39, v39
	s_waitcnt vmcnt(0)
	v_add_f32_e32 v32, v32, v44
	v_add_f32_e32 v33, v33, v45
	v_add_f32_e32 v48, 1.0, v55
	v_add_f32_e32 v42, 1.0, v42
	v_add_f32_e32 v43, 1.0, v43
	v_mul_f32_e32 v32, 0xbfb8aa3b, v32
	v_mul_f32_e32 v33, 0xbfb8aa3b, v33
	v_rcp_f32_e32 v55, v48
	v_rcp_f32_e32 v42, v42
	v_lshlrev_b32_e32 v48, 16, v49
	v_and_b32_e32 v49, 0xffff0000, v49
	v_rcp_f32_e32 v43, v43
	v_exp_f32_e32 v32, v32
	v_exp_f32_e32 v33, v33
	v_mul_f32_e64 v38, v38, v48
	v_mul_f32_e64 v39, v39, v49
	v_lshlrev_b32_e32 v44, 16, v50
	v_mul_f32_e64 v38, v38, v40
	v_mul_f32_e64 v39, v39, v41
	v_lshlrev_b32_e32 v40, 16, v68
	v_mul_f32_e32 v41, 0xbfb8aa3b, v40
	v_mul_f32_e64 v38, v42, v38
	v_mul_f32_e64 v39, v43, v39
	v_add_f32_e32 v32, 1.0, v32
	v_exp_f32_e32 v42, v41
	v_add_f32_e32 v33, 1.0, v33
	v_and_b32_e32 v41, 0xffff0000, v68
	v_rcp_f32_e32 v32, v32
	v_rcp_f32_e32 v33, v33
	v_mul_f32_e32 v43, 0xbfb8aa3b, v41
	v_exp_f32_e32 v43, v43
	v_and_b32_e32 v45, 0xffff0000, v50
	v_mul_f32_e64 v32, v32, v44
	v_mul_f32_e64 v33, v33, v45
	v_add_f32_e32 v34, v34, v46
	v_mul_f32_e64 v32, v32, v40
	v_mul_f32_e64 v33, v33, v41
	v_add_f32_e32 v40, 1.0, v43
	v_mul_f32_e32 v34, 0xbfb8aa3b, v34
	v_add_f32_e32 v42, 1.0, v42
	v_rcp_f32_e32 v43, v40
	v_exp_f32_e32 v40, v34
	v_add_f32_e32 v34, v35, v47
	v_rcp_f32_e32 v42, v42
	v_mul_f32_e32 v34, 0xbfb8aa3b, v34
	v_exp_f32_e32 v41, v34
	v_add_f32_e32 v54, 1.0, v54
	v_mul_f32_e64 v34, v42, v32
	v_mul_f32_e64 v35, v43, v33
	v_add_f32_e32 v32, 1.0, v40
	v_lshlrev_b32_e32 v40, 16, v69
	v_add_f32_e32 v33, 1.0, v41
	v_mul_f32_e32 v41, 0xbfb8aa3b, v40
	v_exp_f32_e32 v42, v41
	v_and_b32_e32 v41, 0xffff0000, v69
	v_mul_f32_e32 v43, 0xbfb8aa3b, v41
	v_exp_f32_e32 v43, v43
	v_rcp_f32_e32 v32, v32
	v_rcp_f32_e32 v33, v33
	v_add_f32_e32 v42, 1.0, v42
	v_add_f32_e32 v43, 1.0, v43
	v_rcp_f32_e32 v54, v54
	v_rcp_f32_e32 v42, v42
	v_rcp_f32_e32 v43, v43
	v_lshlrev_b32_e32 v44, 16, v51
	v_and_b32_e32 v45, 0xffff0000, v51
	v_mul_f32_e64 v32, v32, v44
	v_mul_f32_e64 v33, v33, v45
	v_mul_f32_e64 v36, v54, v36
	v_mul_f32_e64 v37, v55, v37
	v_mul_f32_e64 v32, v32, v40
	v_mul_f32_e64 v33, v33, v41
	v_cvt_pk_bf16_f32 v34, v34, v35
	v_mul_f32_e64 v40, v42, v32
	v_mul_f32_e64 v41, v43, v33
	v_cvt_pk_bf16_f32 v32, v36, v37
	v_cvt_pk_bf16_f32 v33, v38, v39
	v_cvt_pk_bf16_f32 v35, v40, v41
	v_add_u32_e32 v54, 0xa0, v156
	global_store_dwordx4 v[52:53], v[32:35], off offset:256
	global_load_dwordx4 v[34:37], v[152:153], off
	v_ashrrev_i32_e32 v55, 31, v54
	v_mad_i64_i32 v[32:33], s[38:39], v54, s70, v[158:159]
	v_lshl_add_u64 v[32:33], v[32:33], 0, v[154:155]
	global_load_dwordx4 v[38:41], v[32:33], off
	v_lshlrev_b64 v[42:43], 11, v[54:55]
	v_lshl_add_u64 v[42:43], s[6:7], 0, v[42:43]
	v_lshl_add_u64 v[56:57], v[42:43], 0, v[154:155]
	global_load_dwordx4 v[42:45], v[56:57], off
	global_load_dwordx4 v[46:49], v[152:153], off offset:16
	global_load_dwordx4 v[50:53], v[32:33], off offset:256
	s_waitcnt vmcnt(4)
	v_add_f32_e32 v30, v30, v36
	v_add_f32_e32 v31, v31, v37
	v_mul_f32_e32 v30, 0xbfb8aa3b, v30
	v_mul_f32_e32 v31, 0xbfb8aa3b, v31
	v_exp_f32_e32 v30, v30
	s_waitcnt vmcnt(3)
	v_lshlrev_b32_e32 v58, 16, v38
	v_mul_f32_e32 v32, 0xbfb8aa3b, v58
	v_exp_f32_e32 v32, v32
	v_and_b32_e32 v59, 0xffff0000, v38
	v_lshlrev_b32_e32 v36, 16, v39
	v_exp_f32_e32 v31, v31
	v_add_f32_e32 v32, 1.0, v32
	v_rcp_f32_e32 v60, v32
	v_mul_f32_e32 v32, 0xbfb8aa3b, v59
	v_exp_f32_e32 v38, v32
	v_mul_f32_e32 v37, 0xbfb8aa3b, v36
	v_add_f32_e32 v30, 1.0, v30
	v_add_f32_e32 v31, 1.0, v31
	v_add_f32_e32 v38, 1.0, v38
	v_rcp_f32_e32 v61, v38
	v_exp_f32_e32 v38, v37
	v_and_b32_e32 v37, 0xffff0000, v39
	v_mul_f32_e32 v39, 0xbfb8aa3b, v37
	v_exp_f32_e32 v39, v39
	v_rcp_f32_e32 v30, v30
	v_rcp_f32_e32 v31, v31
	s_waitcnt vmcnt(1)
	v_add_f32_e32 v24, v24, v46
	v_add_f32_e32 v25, v25, v47
	v_add_f32_e32 v38, 1.0, v38
	v_add_f32_e32 v39, 1.0, v39
	v_mul_f32_e32 v24, 0xbfb8aa3b, v24
	v_mul_f32_e32 v25, 0xbfb8aa3b, v25
	v_add_f32_e32 v28, v28, v34
	v_add_f32_e32 v29, v29, v35
	global_load_dwordx4 v[32:35], v[56:57], off offset:256
	v_lshlrev_b32_e32 v56, 16, v42
	v_and_b32_e32 v57, 0xffff0000, v42
	v_rcp_f32_e32 v38, v38
	v_lshlrev_b32_e32 v42, 16, v43
	v_and_b32_e32 v43, 0xffff0000, v43
	v_rcp_f32_e32 v39, v39
	v_exp_f32_e32 v24, v24
	v_exp_f32_e32 v25, v25
	v_mul_f32_e64 v30, v30, v42
	v_mul_f32_e64 v31, v31, v43
	v_lshlrev_b32_e32 v42, 16, v44
	v_mul_f32_e64 v30, v30, v36
	v_mul_f32_e64 v31, v31, v37
	v_lshlrev_b32_e32 v36, 16, v40
	v_mul_f32_e32 v37, 0xbfb8aa3b, v36
	v_mul_f32_e64 v30, v38, v30
	v_mul_f32_e64 v31, v39, v31
	v_add_f32_e32 v24, 1.0, v24
	v_exp_f32_e32 v38, v37
	v_add_f32_e32 v25, 1.0, v25
	v_and_b32_e32 v37, 0xffff0000, v40
	v_rcp_f32_e32 v24, v24
	v_rcp_f32_e32 v25, v25
	v_mul_f32_e32 v39, 0xbfb8aa3b, v37
	v_exp_f32_e32 v39, v39
	v_and_b32_e32 v43, 0xffff0000, v44
	v_mul_f32_e64 v24, v24, v42
	v_mul_f32_e64 v25, v25, v43
	v_add_f32_e32 v26, v26, v48
	v_mul_f32_e64 v24, v24, v36
	v_mul_f32_e64 v25, v25, v37
	v_add_f32_e32 v36, 1.0, v39
	v_mul_f32_e32 v26, 0xbfb8aa3b, v26
	v_add_f32_e32 v38, 1.0, v38
	v_rcp_f32_e32 v39, v36
	v_exp_f32_e32 v36, v26
	v_add_f32_e32 v26, v27, v49
	v_rcp_f32_e32 v38, v38
	v_mul_f32_e32 v26, 0xbfb8aa3b, v26
	v_exp_f32_e32 v37, v26
	v_mul_f32_e32 v28, 0xbfb8aa3b, v28
	v_mul_f32_e32 v29, 0xbfb8aa3b, v29
	v_mul_f32_e64 v26, v38, v24
	v_mul_f32_e64 v27, v39, v25
	v_add_f32_e32 v24, 1.0, v36
	v_lshlrev_b32_e32 v36, 16, v41
	v_exp_f32_e32 v28, v28
	v_exp_f32_e32 v29, v29
	v_add_f32_e32 v25, 1.0, v37
	v_mul_f32_e32 v37, 0xbfb8aa3b, v36
	v_exp_f32_e32 v38, v37
	v_and_b32_e32 v37, 0xffff0000, v41
	v_mul_f32_e32 v39, 0xbfb8aa3b, v37
	v_exp_f32_e32 v39, v39
	v_add_f32_e32 v28, 1.0, v28
	v_add_f32_e32 v29, 1.0, v29
	v_rcp_f32_e32 v28, v28
	v_rcp_f32_e32 v29, v29
	v_rcp_f32_e32 v24, v24
	v_rcp_f32_e32 v25, v25
	v_add_f32_e32 v38, 1.0, v38
	v_add_f32_e32 v39, 1.0, v39
	v_rcp_f32_e32 v38, v38
	v_rcp_f32_e32 v39, v39
	v_mul_f32_e64 v28, v28, v56
	v_mul_f32_e64 v29, v29, v57
	v_lshlrev_b32_e32 v40, 16, v45
	v_and_b32_e32 v41, 0xffff0000, v45
	v_mul_f32_e64 v28, v28, v58
	v_mul_f32_e64 v29, v29, v59
	v_mul_f32_e64 v24, v24, v40
	v_mul_f32_e64 v25, v25, v41
	v_mul_f32_e64 v28, v60, v28
	v_mul_f32_e64 v29, v61, v29
	v_mul_f32_e64 v24, v24, v36
	v_mul_f32_e64 v25, v25, v37
	v_cvt_pk_bf16_f32 v26, v26, v27
	v_mul_f32_e64 v36, v38, v24
	v_mul_f32_e64 v37, v39, v25
	v_cvt_pk_bf16_f32 v24, v28, v29
	v_lshlrev_b64 v[28:29], 12, v[54:55]
	v_lshl_add_u64 v[28:29], s[14:15], 0, v[28:29]
	v_cvt_pk_bf16_f32 v25, v30, v31
	v_cvt_pk_bf16_f32 v27, v36, v37
	v_lshl_add_u64 v[36:37], v[28:29], 0, v[154:155]
	global_store_dwordx4 v[36:37], v[24:27], off
	global_load_dwordx4 v[24:27], v[152:153], off offset:512
	s_nop 0
	global_load_dwordx4 v[28:31], v[152:153], off offset:528
	s_waitcnt vmcnt(3)
	v_lshlrev_b32_e32 v40, 16, v32
	v_and_b32_e32 v41, 0xffff0000, v32
	s_waitcnt vmcnt(1)
	v_add_f32_e32 v20, v20, v24
	v_add_f32_e32 v21, v21, v25
	v_mul_f32_e32 v20, 0xbfb8aa3b, v20
	v_mul_f32_e32 v21, 0xbfb8aa3b, v21
	v_exp_f32_e32 v20, v20
	v_exp_f32_e32 v21, v21
	v_lshlrev_b32_e32 v24, 16, v50
	v_mul_f32_e32 v25, 0xbfb8aa3b, v24
	v_add_f32_e32 v20, 1.0, v20
	v_add_f32_e32 v21, 1.0, v21
	v_rcp_f32_e32 v20, v20
	v_rcp_f32_e32 v21, v21
	v_exp_f32_e32 v38, v25
	v_and_b32_e32 v25, 0xffff0000, v50
	v_add_f32_e32 v22, v22, v26
	v_mul_f32_e64 v20, v20, v40
	v_mul_f32_e64 v21, v21, v41
	v_add_f32_e32 v23, v23, v27
	v_mul_f32_e32 v22, 0xbfb8aa3b, v22
	v_mul_f32_e64 v20, v20, v24
	v_mul_f32_e64 v21, v21, v25
	v_mul_f32_e32 v23, 0xbfb8aa3b, v23
	v_lshlrev_b32_e32 v24, 16, v51
	v_mul_f32_e32 v39, 0xbfb8aa3b, v25
	v_exp_f32_e32 v22, v22
	v_exp_f32_e32 v23, v23
	v_mul_f32_e32 v25, 0xbfb8aa3b, v24
	v_exp_f32_e32 v26, v25
	v_and_b32_e32 v25, 0xffff0000, v51
	v_mul_f32_e32 v27, 0xbfb8aa3b, v25
	v_exp_f32_e32 v39, v39
	v_exp_f32_e32 v27, v27
	v_add_f32_e32 v22, 1.0, v22
	v_add_f32_e32 v23, 1.0, v23
	v_rcp_f32_e32 v22, v22
	v_rcp_f32_e32 v23, v23
	s_waitcnt vmcnt(0)
	v_add_f32_e32 v16, v16, v28
	v_add_f32_e32 v17, v17, v29
	v_add_f32_e32 v32, 1.0, v39
	v_add_f32_e32 v26, 1.0, v26
	v_add_f32_e32 v27, 1.0, v27
	v_mul_f32_e32 v16, 0xbfb8aa3b, v16
	v_mul_f32_e32 v17, 0xbfb8aa3b, v17
	v_rcp_f32_e32 v39, v32
	v_rcp_f32_e32 v26, v26
	v_lshlrev_b32_e32 v32, 16, v33
	v_and_b32_e32 v33, 0xffff0000, v33
	v_rcp_f32_e32 v27, v27
	v_exp_f32_e32 v16, v16
	v_exp_f32_e32 v17, v17
	v_mul_f32_e64 v22, v22, v32
	v_mul_f32_e64 v23, v23, v33
	v_lshlrev_b32_e32 v28, 16, v34
	v_mul_f32_e64 v22, v22, v24
	v_mul_f32_e64 v23, v23, v25
	v_lshlrev_b32_e32 v24, 16, v52
	v_mul_f32_e32 v25, 0xbfb8aa3b, v24
	v_mul_f32_e64 v22, v26, v22
	v_mul_f32_e64 v23, v27, v23
	v_add_f32_e32 v16, 1.0, v16
	v_exp_f32_e32 v26, v25
	v_add_f32_e32 v17, 1.0, v17
	v_and_b32_e32 v25, 0xffff0000, v52
	v_rcp_f32_e32 v16, v16
	v_rcp_f32_e32 v17, v17
	v_mul_f32_e32 v27, 0xbfb8aa3b, v25
	v_exp_f32_e32 v27, v27
	v_and_b32_e32 v29, 0xffff0000, v34
	v_mul_f32_e64 v16, v16, v28
	v_mul_f32_e64 v17, v17, v29
	v_add_f32_e32 v18, v18, v30
	v_mul_f32_e64 v16, v16, v24
	v_mul_f32_e64 v17, v17, v25
	v_add_f32_e32 v24, 1.0, v27
	v_mul_f32_e32 v18, 0xbfb8aa3b, v18
	v_add_f32_e32 v26, 1.0, v26
	v_rcp_f32_e32 v27, v24
	v_exp_f32_e32 v24, v18
	v_add_f32_e32 v18, v19, v31
	v_rcp_f32_e32 v26, v26
	v_mul_f32_e32 v18, 0xbfb8aa3b, v18
	v_exp_f32_e32 v25, v18
	v_add_f32_e32 v38, 1.0, v38
	v_mul_f32_e64 v18, v26, v16
	v_mul_f32_e64 v19, v27, v17
	v_add_f32_e32 v16, 1.0, v24
	v_lshlrev_b32_e32 v24, 16, v53
	v_add_f32_e32 v17, 1.0, v25
	v_mul_f32_e32 v25, 0xbfb8aa3b, v24
	v_exp_f32_e32 v26, v25
	v_and_b32_e32 v25, 0xffff0000, v53
	v_mul_f32_e32 v27, 0xbfb8aa3b, v25
	v_exp_f32_e32 v27, v27
	v_rcp_f32_e32 v16, v16
	v_rcp_f32_e32 v17, v17
	v_add_f32_e32 v26, 1.0, v26
	v_add_f32_e32 v27, 1.0, v27
	v_rcp_f32_e32 v38, v38
	v_rcp_f32_e32 v26, v26
	v_rcp_f32_e32 v27, v27
	v_lshlrev_b32_e32 v28, 16, v35
	v_and_b32_e32 v29, 0xffff0000, v35
	v_mul_f32_e64 v16, v16, v28
	v_mul_f32_e64 v17, v17, v29
	v_mul_f32_e64 v20, v38, v20
	v_mul_f32_e64 v21, v39, v21
	v_mul_f32_e64 v16, v16, v24
	v_mul_f32_e64 v17, v17, v25
	v_cvt_pk_bf16_f32 v18, v18, v19
	v_mul_f32_e64 v24, v26, v16
	v_mul_f32_e64 v25, v27, v17
	v_cvt_pk_bf16_f32 v16, v20, v21
	v_cvt_pk_bf16_f32 v17, v22, v23
	v_cvt_pk_bf16_f32 v19, v24, v25
	global_store_dwordx4 v[36:37], v[16:19], off offset:256
	global_load_dwordx4 v[16:19], v[152:153], off
	v_add_u32_e32 v40, 0xb0, v156
	v_mad_i64_i32 v[20:21], s[38:39], v40, s70, v[158:159]
	v_lshl_add_u64 v[32:33], v[20:21], 0, v[154:155]
	global_load_dwordx4 v[20:23], v[32:33], off
	v_ashrrev_i32_e32 v41, 31, v40
	v_lshlrev_b64 v[24:25], 11, v[40:41]
	v_lshl_add_u64 v[24:25], s[6:7], 0, v[24:25]
	v_lshl_add_u64 v[36:37], v[24:25], 0, v[154:155]
	global_load_dwordx4 v[24:27], v[36:37], off
	global_load_dwordx4 v[28:31], v[152:153], off offset:16
	s_waitcnt vmcnt(3)
	v_add_f32_e32 v12, v12, v16
	v_add_f32_e32 v13, v13, v17
	v_mul_f32_e32 v12, 0xbfb8aa3b, v12
	v_mul_f32_e32 v13, 0xbfb8aa3b, v13
	v_exp_f32_e32 v12, v12
	v_exp_f32_e32 v13, v13
	s_waitcnt vmcnt(2)
	v_lshlrev_b32_e32 v16, 16, v20
	v_mul_f32_e32 v17, 0xbfb8aa3b, v16
	v_add_f32_e32 v12, 1.0, v12
	v_add_f32_e32 v13, 1.0, v13
	v_rcp_f32_e32 v12, v12
	v_rcp_f32_e32 v13, v13
	v_exp_f32_e32 v38, v17
	s_waitcnt vmcnt(1)
	v_lshlrev_b32_e32 v44, 16, v24
	v_and_b32_e32 v45, 0xffff0000, v24
	v_and_b32_e32 v17, 0xffff0000, v20
	v_add_f32_e32 v14, v14, v18
	v_mul_f32_e64 v12, v12, v44
	v_mul_f32_e64 v13, v13, v45
	v_add_f32_e32 v15, v15, v19
	v_add_f32_e32 v20, 1.0, v38
	v_mul_f32_e32 v14, 0xbfb8aa3b, v14
	v_mul_f32_e64 v12, v12, v16
	v_mul_f32_e64 v13, v13, v17
	v_mul_f32_e32 v15, 0xbfb8aa3b, v15
	v_lshlrev_b32_e32 v16, 16, v21
	v_rcp_f32_e32 v42, v20
	v_mul_f32_e32 v20, 0xbfb8aa3b, v17
	v_exp_f32_e32 v14, v14
	v_exp_f32_e32 v15, v15
	v_mul_f32_e32 v17, 0xbfb8aa3b, v16
	v_exp_f32_e32 v18, v17
	v_and_b32_e32 v17, 0xffff0000, v21
	v_mul_f32_e32 v19, 0xbfb8aa3b, v17
	v_exp_f32_e32 v20, v20
	v_exp_f32_e32 v19, v19
	v_add_f32_e32 v14, 1.0, v14
	v_add_f32_e32 v15, 1.0, v15
	v_rcp_f32_e32 v14, v14
	v_rcp_f32_e32 v15, v15
	s_waitcnt vmcnt(0)
	v_add_f32_e32 v8, v8, v28
	v_add_f32_e32 v9, v9, v29
	v_add_f32_e32 v20, 1.0, v20
	v_add_f32_e32 v18, 1.0, v18
	v_add_f32_e32 v19, 1.0, v19
	v_mul_f32_e32 v8, 0xbfb8aa3b, v8
	v_mul_f32_e32 v9, 0xbfb8aa3b, v9
	v_rcp_f32_e32 v43, v20
	v_rcp_f32_e32 v18, v18
	v_lshlrev_b32_e32 v20, 16, v25
	v_and_b32_e32 v21, 0xffff0000, v25
	v_rcp_f32_e32 v19, v19
	v_exp_f32_e32 v8, v8
	v_exp_f32_e32 v9, v9
	v_mul_f32_e64 v14, v14, v20
	v_mul_f32_e64 v15, v15, v21
	v_lshlrev_b32_e32 v20, 16, v26
	v_mul_f32_e64 v14, v14, v16
	v_mul_f32_e64 v15, v15, v17
	v_lshlrev_b32_e32 v16, 16, v22
	v_mul_f32_e32 v17, 0xbfb8aa3b, v16
	v_mul_f32_e64 v14, v18, v14
	v_mul_f32_e64 v15, v19, v15
	v_add_f32_e32 v8, 1.0, v8
	v_exp_f32_e32 v18, v17
	v_add_f32_e32 v9, 1.0, v9
	v_and_b32_e32 v17, 0xffff0000, v22
	v_rcp_f32_e32 v8, v8
	v_rcp_f32_e32 v9, v9
	v_mul_f32_e32 v19, 0xbfb8aa3b, v17
	v_exp_f32_e32 v19, v19
	v_and_b32_e32 v21, 0xffff0000, v26
	v_mul_f32_e64 v8, v8, v20
	v_mul_f32_e64 v9, v9, v21
	v_add_f32_e32 v10, v10, v30
	v_mul_f32_e64 v8, v8, v16
	v_mul_f32_e64 v9, v9, v17
	v_add_f32_e32 v16, 1.0, v19
	v_mul_f32_e32 v10, 0xbfb8aa3b, v10
	v_add_f32_e32 v18, 1.0, v18
	v_rcp_f32_e32 v19, v16
	v_exp_f32_e32 v16, v10
	v_add_f32_e32 v10, v11, v31
	v_rcp_f32_e32 v18, v18
	v_mul_f32_e32 v10, 0xbfb8aa3b, v10
	v_exp_f32_e32 v17, v10
	v_lshlrev_b32_e32 v20, 16, v27
	v_mul_f32_e64 v10, v18, v8
	v_mul_f32_e64 v11, v19, v9
	v_add_f32_e32 v8, 1.0, v16
	v_lshlrev_b32_e32 v16, 16, v23
	v_add_f32_e32 v9, 1.0, v17
	v_mul_f32_e32 v17, 0xbfb8aa3b, v16
	v_exp_f32_e32 v18, v17
	v_and_b32_e32 v17, 0xffff0000, v23
	v_mul_f32_e32 v19, 0xbfb8aa3b, v17
	v_exp_f32_e32 v19, v19
	v_rcp_f32_e32 v8, v8
	v_rcp_f32_e32 v9, v9
	v_add_f32_e32 v18, 1.0, v18
	v_add_f32_e32 v19, 1.0, v19
	v_rcp_f32_e32 v18, v18
	v_rcp_f32_e32 v19, v19
	v_and_b32_e32 v21, 0xffff0000, v27
	v_mul_f32_e64 v8, v8, v20
	v_mul_f32_e64 v9, v9, v21
	v_mul_f32_e64 v12, v42, v12
	v_mul_f32_e64 v13, v43, v13
	v_mul_f32_e64 v8, v8, v16
	v_mul_f32_e64 v9, v9, v17
	v_cvt_pk_bf16_f32 v10, v10, v11
	v_mul_f32_e64 v16, v18, v8
	v_mul_f32_e64 v17, v19, v9
	v_cvt_pk_bf16_f32 v8, v12, v13
	v_lshlrev_b64 v[12:13], 12, v[40:41]
	v_lshl_add_u64 v[12:13], s[14:15], 0, v[12:13]
	v_cvt_pk_bf16_f32 v9, v14, v15
	v_cvt_pk_bf16_f32 v11, v16, v17
	v_lshl_add_u64 v[16:17], v[12:13], 0, v[154:155]
	global_store_dwordx4 v[16:17], v[8:11], off
	global_load_dwordx4 v[32:35], v[32:33], off offset:256
	s_nop 0
	global_load_dwordx4 v[36:39], v[36:37], off offset:256
	s_nop 0
	global_load_dwordx4 v[8:11], v[152:153], off offset:512
	global_load_dwordx4 v[12:15], v[152:153], off offset:528
	s_waitcnt vmcnt(1)
	v_add_f32_e32 v4, v4, v8
	v_add_f32_e32 v5, v5, v9
	v_mul_f32_e32 v4, 0xbfb8aa3b, v4
	v_mul_f32_e32 v5, 0xbfb8aa3b, v5
	v_exp_f32_e32 v4, v4
	v_exp_f32_e32 v5, v5
	v_lshlrev_b32_e32 v8, 16, v32
	s_waitcnt vmcnt(0)
	v_add_f32_e32 v3, v3, v15
	v_add_f32_e32 v4, 1.0, v4
	v_add_f32_e32 v5, 1.0, v5
	v_rcp_f32_e32 v4, v4
	v_rcp_f32_e32 v5, v5
	v_and_b32_e32 v9, 0xffff0000, v32
	v_mul_f32_e32 v15, 0xbfb8aa3b, v8
	v_exp_f32_e32 v15, v15
	v_mul_f32_e32 v18, 0xbfb8aa3b, v9
	v_lshlrev_b32_e32 v20, 16, v36
	v_and_b32_e32 v21, 0xffff0000, v36
	v_add_f32_e32 v6, v6, v10
	v_add_f32_e32 v7, v7, v11
	v_exp_f32_e32 v19, v18
	v_mul_f32_e64 v4, v4, v20
	v_mul_f32_e64 v5, v5, v21
	v_mul_f32_e32 v6, 0xbfb8aa3b, v6
	v_mul_f32_e32 v7, 0xbfb8aa3b, v7
	v_mul_f32_e64 v4, v4, v8
	v_mul_f32_e64 v5, v5, v9
	v_exp_f32_e32 v6, v6
	v_exp_f32_e32 v7, v7
	v_lshlrev_b32_e32 v8, 16, v33
	v_and_b32_e32 v9, 0xffff0000, v33
	v_mul_f32_e32 v10, 0xbfb8aa3b, v8
	v_mul_f32_e32 v11, 0xbfb8aa3b, v9
	v_add_f32_e32 v15, 1.0, v15
	v_exp_f32_e32 v10, v10
	v_exp_f32_e32 v11, v11
	v_rcp_f32_e32 v18, v15
	v_add_f32_e32 v15, 1.0, v19
	v_rcp_f32_e32 v19, v15
	v_add_f32_e32 v6, 1.0, v6
	v_add_f32_e32 v7, 1.0, v7
	v_rcp_f32_e32 v6, v6
	v_rcp_f32_e32 v7, v7
	v_add_f32_e32 v0, v0, v12
	v_add_f32_e32 v1, v1, v13
	v_add_f32_e32 v10, 1.0, v10
	v_add_f32_e32 v11, 1.0, v11
	v_mul_f32_e32 v0, 0xbfb8aa3b, v0
	v_mul_f32_e32 v1, 0xbfb8aa3b, v1
	v_rcp_f32_e32 v10, v10
	v_rcp_f32_e32 v11, v11
	v_exp_f32_e32 v0, v0
	v_exp_f32_e32 v1, v1
	v_mul_f32_e64 v4, v18, v4
	v_mul_f32_e64 v5, v19, v5
	v_lshlrev_b32_e32 v18, 16, v37
	v_and_b32_e32 v19, 0xffff0000, v37
	v_mul_f32_e64 v6, v6, v18
	v_mul_f32_e64 v7, v7, v19
	v_add_f32_e32 v0, 1.0, v0
	v_mul_f32_e64 v6, v6, v8
	v_mul_f32_e64 v7, v7, v9
	v_lshlrev_b32_e32 v8, 16, v34
	v_and_b32_e32 v9, 0xffff0000, v34
	v_mul_f32_e64 v6, v10, v6
	v_mul_f32_e64 v7, v11, v7
	v_add_f32_e32 v1, 1.0, v1
	v_mul_f32_e32 v10, 0xbfb8aa3b, v8
	v_mul_f32_e32 v11, 0xbfb8aa3b, v9
	v_rcp_f32_e32 v0, v0
	v_exp_f32_e32 v10, v10
	v_exp_f32_e32 v11, v11
	v_rcp_f32_e32 v1, v1
	v_lshlrev_b32_e32 v12, 16, v38
	v_and_b32_e32 v13, 0xffff0000, v38
	v_add_f32_e32 v2, v2, v14
	v_add_f32_e32 v10, 1.0, v10
	v_add_f32_e32 v11, 1.0, v11
	v_mul_f32_e64 v0, v0, v12
	v_mul_f32_e64 v1, v1, v13
	v_mul_f32_e32 v2, 0xbfb8aa3b, v2
	v_rcp_f32_e32 v10, v10
	v_rcp_f32_e32 v11, v11
	v_mul_f32_e64 v0, v0, v8
	v_mul_f32_e64 v1, v1, v9
	v_exp_f32_e32 v8, v2
	v_mul_f32_e32 v2, 0xbfb8aa3b, v3
	v_exp_f32_e32 v9, v2
	v_mul_f32_e64 v2, v10, v0
	v_mul_f32_e64 v3, v11, v1
	v_add_f32_e32 v0, 1.0, v8
	v_lshlrev_b32_e32 v8, 16, v35
	v_add_f32_e32 v1, 1.0, v9
	v_mul_f32_e32 v9, 0xbfb8aa3b, v8
	v_exp_f32_e32 v10, v9
	v_and_b32_e32 v9, 0xffff0000, v35
	v_mul_f32_e32 v11, 0xbfb8aa3b, v9
	v_exp_f32_e32 v11, v11
	v_rcp_f32_e32 v0, v0
	v_rcp_f32_e32 v1, v1
	v_add_f32_e32 v10, 1.0, v10
	v_add_f32_e32 v11, 1.0, v11
	v_rcp_f32_e32 v10, v10
	v_rcp_f32_e32 v11, v11
	v_lshlrev_b32_e32 v12, 16, v39
	v_and_b32_e32 v13, 0xffff0000, v39
	v_mul_f32_e64 v0, v0, v12
	v_mul_f32_e64 v1, v1, v13
	v_cvt_pk_bf16_f32 v2, v2, v3
	v_mul_f32_e64 v0, v0, v8
	v_mul_f32_e64 v1, v1, v9
	s_nop 0
	v_mul_f32_e64 v8, v10, v0
	v_mul_f32_e64 v9, v11, v1
	v_cvt_pk_bf16_f32 v0, v4, v5
	v_cvt_pk_bf16_f32 v1, v6, v7
	v_cvt_pk_bf16_f32 v3, v8, v9
	global_store_dwordx4 v[16:17], v[0:3], off offset:256
	s_cbranch_vccnz .LBB0_370
	s_andn2_b64 vcc, exec, s[10:11]
	s_cbranch_vccnz .LBB0_369
	s_barrier
	s_branch .LBB0_369

.LBB0_462:
	v_lshl_add_u32 v170, s34, 8, v184
	v_lshl_or_b32 v168, s36, 8, v186
	v_ashrrev_i32_e32 v171, 31, v170
	v_ashrrev_i32_e32 v169, 31, v168
	v_lshlrev_b64 v[128:129], 11, v[170:171]
	v_or_b32_e32 v180, 16, v170
	v_lshl_add_u64 v[128:129], v[128:129], 0, v[168:169]
	v_ashrrev_i32_e32 v181, 31, v180
	v_lshl_add_u64 v[202:203], v[128:129], 1, s[12:13]
	v_lshlrev_b64 v[128:129], 11, v[180:181]
	v_or_b32_e32 v176, 32, v170
	v_lshl_add_u64 v[128:129], v[128:129], 0, v[168:169]
	v_ashrrev_i32_e32 v177, 31, v176
	v_lshl_add_u64 v[182:183], v[128:129], 1, s[12:13]
	v_lshlrev_b64 v[128:129], 11, v[176:177]
	v_or_b32_e32 v172, 48, v170
	v_lshl_add_u64 v[128:129], v[128:129], 0, v[168:169]
	v_ashrrev_i32_e32 v173, 31, v172
	v_lshl_add_u64 v[178:179], v[128:129], 1, s[12:13]
	v_lshlrev_b64 v[128:129], 11, v[172:173]
	v_lshl_add_u64 v[128:129], v[128:129], 0, v[168:169]
	v_lshl_add_u64 v[174:175], v[128:129], 1, s[12:13]
	global_load_dwordx4 v[194:197], v[202:203], off
	global_load_dwordx4 v[198:201], v[202:203], off offset:256
	global_load_dwordx4 v[148:151], v[182:183], off
	global_load_dwordx4 v[144:147], v[182:183], off offset:256
	global_load_dwordx4 v[140:143], v[178:179], off
	global_load_dwordx4 v[136:139], v[178:179], off offset:256
	global_load_dwordx4 v[132:135], v[174:175], off
	global_load_dwordx4 v[128:131], v[174:175], off offset:256
	v_and_b32_e32 v192, 64, v190
	v_xor_b32_e32 v191, 16, v190
	v_add_u32_e32 v192, 64, v192
	v_xor_b32_e32 v193, 32, v190
	v_cmp_lt_i32_e32 vcc, v191, v192
	s_waitcnt vmcnt(0)
	v_lshlrev_b32_e32 v204, 16, v194
	v_cndmask_b32_e32 v191, v190, v191, vcc
	v_cmp_lt_i32_e32 vcc, v193, v192
	v_lshlrev_b32_e32 v192, 2, v191
	v_and_b32_e32 v205, 0xffff0000, v194
	v_cndmask_b32_e32 v193, v190, v193, vcc
	v_lshlrev_b32_e32 v191, 2, v193
	v_lshlrev_b32_e32 v194, 16, v195
	v_and_b32_e32 v195, 0xffff0000, v195
	v_lshlrev_b32_e32 v206, 16, v196
	v_and_b32_e32 v207, 0xffff0000, v196
	v_lshlrev_b32_e32 v196, 16, v197
	v_and_b32_e32 v197, 0xffff0000, v197
	v_lshlrev_b32_e32 v208, 16, v198
	v_and_b32_e32 v209, 0xffff0000, v198
	v_lshlrev_b32_e32 v198, 16, v199
	v_and_b32_e32 v199, 0xffff0000, v199
	v_lshlrev_b32_e32 v210, 16, v200
	v_and_b32_e32 v211, 0xffff0000, v200
	v_lshlrev_b32_e32 v200, 16, v201
	v_and_b32_e32 v201, 0xffff0000, v201
	v_add_f32_e64 v124, v124, v204
	v_add_f32_e64 v125, v125, v205
	v_add_f32_e64 v126, v126, v194
	v_add_f32_e64 v127, v127, v195
	v_add_f32_e64 v194, v122, v196
	v_add_f32_e64 v195, v123, v197
	v_add_f32_e64 v122, v120, v206
	v_add_f32_e64 v123, v121, v207
	v_cvt_pk_bf16_f32 v120, v124, v125
	v_mul_f32_e32 v125, v125, v125
	v_fmac_f32_e32 v125, v124, v124
	v_mul_f32_e32 v124, v127, v127
	v_fmac_f32_e32 v124, v126, v126
	v_add_f32_e32 v124, v125, v124
	v_mul_f32_e32 v125, v123, v123
	v_add_f32_e64 v118, v118, v198
	v_add_f32_e64 v119, v119, v199
	v_add_f32_e64 v116, v116, v208
	v_add_f32_e64 v117, v117, v209
	v_cvt_pk_bf16_f32 v121, v126, v127
	v_fmac_f32_e32 v125, v122, v122
	v_add_f32_e64 v126, v112, v210
	v_add_f32_e64 v127, v113, v211
	v_mul_f32_e32 v112, v117, v117
	v_mul_f32_e32 v113, v119, v119
	v_add_f32_e32 v124, v125, v124
	v_mul_f32_e32 v125, v195, v195
	v_fmac_f32_e32 v112, v116, v116
	v_fmac_f32_e32 v113, v118, v118
	v_fmac_f32_e32 v125, v194, v194
	v_add_f32_e32 v112, v112, v113
	v_mul_f32_e32 v113, v127, v127
	v_add_f32_e32 v193, v125, v124
	v_add_f32_e64 v124, v114, v200
	v_add_f32_e64 v125, v115, v201
	v_fmac_f32_e32 v113, v126, v126
	v_add_f32_e32 v112, v113, v112
	v_mul_f32_e32 v113, v125, v125
	v_fmac_f32_e32 v113, v124, v124
	v_add_f32_e32 v112, v113, v112
	v_add_f32_e32 v112, v193, v112
	ds_bpermute_b32 v113, v192, v112
	v_cvt_pk_bf16_f32 v122, v122, v123
	v_cvt_pk_bf16_f32 v123, v194, v195
	v_cvt_pk_bf16_f32 v114, v116, v117
	v_cvt_pk_bf16_f32 v115, v118, v119
	s_waitcnt lgkmcnt(0)
	v_add_f32_e32 v112, v112, v113
	ds_bpermute_b32 v113, v191, v112
	v_cvt_pk_bf16_f32 v116, v126, v127
	v_cvt_pk_bf16_f32 v117, v124, v125
	global_store_dwordx4 v[202:203], v[120:123], off
	global_store_dwordx4 v[202:203], v[114:117], off offset:256
	s_and_saveexec_b64 s[34:35], s[0:1]
	s_cbranch_execz .LBB0_464
	v_lshl_add_u64 v[114:115], v[170:171], 2, s[14:15]
	s_waitcnt lgkmcnt(0)
	v_add_f32_e32 v112, v112, v113
	global_atomic_add_f32 v[114:115], v112, off
.LBB0_464:
	s_or_b64 exec, exec, s[34:35]
	v_lshlrev_b32_e32 v112, 16, v148
	s_waitcnt lgkmcnt(0)
	v_and_b32_e32 v113, 0xffff0000, v148
	v_lshlrev_b32_e32 v114, 16, v149
	v_and_b32_e32 v115, 0xffff0000, v149
	v_lshlrev_b32_e32 v116, 16, v150
	v_and_b32_e32 v117, 0xffff0000, v150
	v_lshlrev_b32_e32 v118, 16, v151
	v_and_b32_e32 v119, 0xffff0000, v151
	v_add_f32_e64 v108, v108, v112
	v_add_f32_e64 v109, v109, v113
	v_add_f32_e64 v110, v110, v114
	v_add_f32_e64 v111, v111, v115
	v_add_f32_e64 v112, v106, v118
	v_add_f32_e64 v113, v107, v119
	v_add_f32_e64 v106, v104, v116
	v_add_f32_e64 v107, v105, v117
	v_cvt_pk_bf16_f32 v104, v108, v109
	v_mul_f32_e32 v109, v109, v109
	v_fmac_f32_e32 v109, v108, v108
	v_mul_f32_e32 v108, v111, v111
	v_lshlrev_b32_e32 v120, 16, v144
	v_and_b32_e32 v121, 0xffff0000, v144
	v_lshlrev_b32_e32 v122, 16, v145
	v_and_b32_e32 v123, 0xffff0000, v145
	v_fmac_f32_e32 v108, v110, v110
	v_lshlrev_b32_e32 v124, 16, v146
	v_and_b32_e32 v125, 0xffff0000, v146
	v_add_f32_e32 v108, v109, v108
	v_mul_f32_e32 v109, v107, v107
	v_add_f32_e64 v102, v102, v122
	v_add_f32_e64 v103, v103, v123
	v_add_f32_e64 v100, v100, v120
	v_add_f32_e64 v101, v101, v121
	v_cvt_pk_bf16_f32 v105, v110, v111
	v_fmac_f32_e32 v109, v106, v106
	v_add_f32_e64 v110, v96, v124
	v_add_f32_e64 v111, v97, v125
	v_mul_f32_e32 v96, v101, v101
	v_mul_f32_e32 v97, v103, v103
	v_add_f32_e32 v108, v109, v108
	v_mul_f32_e32 v109, v113, v113
	v_fmac_f32_e32 v96, v100, v100
	v_fmac_f32_e32 v97, v102, v102
	v_lshlrev_b32_e32 v126, 16, v147
	v_and_b32_e32 v127, 0xffff0000, v147
	v_fmac_f32_e32 v109, v112, v112
	v_add_f32_e32 v96, v96, v97
	v_mul_f32_e32 v97, v111, v111
	v_add_f32_e32 v114, v109, v108
	v_add_f32_e64 v108, v98, v126
	v_add_f32_e64 v109, v99, v127
	v_fmac_f32_e32 v97, v110, v110
	v_add_f32_e32 v96, v97, v96
	v_mul_f32_e32 v97, v109, v109
	v_fmac_f32_e32 v97, v108, v108
	v_add_f32_e32 v96, v97, v96
	v_add_f32_e32 v96, v114, v96
	ds_bpermute_b32 v97, v192, v96
	v_cvt_pk_bf16_f32 v106, v106, v107
	v_cvt_pk_bf16_f32 v107, v112, v113
	v_cvt_pk_bf16_f32 v98, v100, v101
	v_cvt_pk_bf16_f32 v99, v102, v103
	s_waitcnt lgkmcnt(0)
	v_add_f32_e32 v96, v96, v97
	ds_bpermute_b32 v97, v191, v96
	v_cvt_pk_bf16_f32 v100, v110, v111
	v_cvt_pk_bf16_f32 v101, v108, v109
	global_store_dwordx4 v[182:183], v[104:107], off
	global_store_dwordx4 v[182:183], v[98:101], off offset:256
	s_and_saveexec_b64 s[34:35], s[0:1]
	s_cbranch_execz .LBB0_466
	v_lshl_add_u64 v[98:99], v[180:181], 2, s[14:15]
	s_waitcnt lgkmcnt(0)
	v_add_f32_e32 v96, v96, v97
	global_atomic_add_f32 v[98:99], v96, off
.LBB0_466:
	s_or_b64 exec, exec, s[34:35]
	v_lshlrev_b32_e32 v96, 16, v140
	s_waitcnt lgkmcnt(0)
	v_and_b32_e32 v97, 0xffff0000, v140
	v_lshlrev_b32_e32 v98, 16, v141
	v_and_b32_e32 v99, 0xffff0000, v141
	v_lshlrev_b32_e32 v100, 16, v142
	v_and_b32_e32 v101, 0xffff0000, v142
	v_lshlrev_b32_e32 v102, 16, v143
	v_and_b32_e32 v103, 0xffff0000, v143
	v_add_f32_e64 v92, v92, v96
	v_add_f32_e64 v93, v93, v97
	v_add_f32_e64 v94, v94, v98
	v_add_f32_e64 v95, v95, v99
	v_add_f32_e64 v96, v90, v102
	v_add_f32_e64 v97, v91, v103
	v_add_f32_e64 v90, v88, v100
	v_add_f32_e64 v91, v89, v101
	v_cvt_pk_bf16_f32 v88, v92, v93
	v_mul_f32_e32 v93, v93, v93
	v_fmac_f32_e32 v93, v92, v92
	v_mul_f32_e32 v92, v95, v95
	v_lshlrev_b32_e32 v104, 16, v136
	v_and_b32_e32 v105, 0xffff0000, v136
	v_lshlrev_b32_e32 v106, 16, v137
	v_and_b32_e32 v107, 0xffff0000, v137
	v_fmac_f32_e32 v92, v94, v94
	v_lshlrev_b32_e32 v108, 16, v138
	v_and_b32_e32 v109, 0xffff0000, v138
	v_add_f32_e32 v92, v93, v92
	v_mul_f32_e32 v93, v91, v91
	v_add_f32_e64 v86, v86, v106
	v_add_f32_e64 v87, v87, v107
	v_add_f32_e64 v84, v84, v104
	v_add_f32_e64 v85, v85, v105
	v_cvt_pk_bf16_f32 v89, v94, v95
	v_fmac_f32_e32 v93, v90, v90
	v_add_f32_e64 v94, v80, v108
	v_add_f32_e64 v95, v81, v109
	v_mul_f32_e32 v80, v85, v85
	v_mul_f32_e32 v81, v87, v87
	v_add_f32_e32 v92, v93, v92
	v_mul_f32_e32 v93, v97, v97
	v_fmac_f32_e32 v80, v84, v84
	v_fmac_f32_e32 v81, v86, v86
	v_lshlrev_b32_e32 v110, 16, v139
	v_and_b32_e32 v111, 0xffff0000, v139
	v_fmac_f32_e32 v93, v96, v96
	v_add_f32_e32 v80, v80, v81
	v_mul_f32_e32 v81, v95, v95
	v_add_f32_e32 v98, v93, v92
	v_add_f32_e64 v92, v82, v110
	v_add_f32_e64 v93, v83, v111
	v_fmac_f32_e32 v81, v94, v94
	v_add_f32_e32 v80, v81, v80
	v_mul_f32_e32 v81, v93, v93
	v_fmac_f32_e32 v81, v92, v92
	v_add_f32_e32 v80, v81, v80
	v_add_f32_e32 v80, v98, v80
	ds_bpermute_b32 v81, v192, v80
	v_cvt_pk_bf16_f32 v90, v90, v91
	v_cvt_pk_bf16_f32 v91, v96, v97
	v_cvt_pk_bf16_f32 v82, v84, v85
	v_cvt_pk_bf16_f32 v83, v86, v87
	s_waitcnt lgkmcnt(0)
	v_add_f32_e32 v80, v80, v81
	ds_bpermute_b32 v81, v191, v80
	v_cvt_pk_bf16_f32 v84, v94, v95
	v_cvt_pk_bf16_f32 v85, v92, v93
	global_store_dwordx4 v[178:179], v[88:91], off
	global_store_dwordx4 v[178:179], v[82:85], off offset:256
	s_and_saveexec_b64 s[34:35], s[0:1]
	s_cbranch_execz .LBB0_468
	v_lshl_add_u64 v[82:83], v[176:177], 2, s[14:15]
	s_waitcnt lgkmcnt(0)
	v_add_f32_e32 v80, v80, v81
	global_atomic_add_f32 v[82:83], v80, off
.LBB0_468:
	s_or_b64 exec, exec, s[34:35]
	v_lshlrev_b32_e32 v80, 16, v132
	s_waitcnt lgkmcnt(0)
	v_and_b32_e32 v81, 0xffff0000, v132
	v_lshlrev_b32_e32 v82, 16, v133
	v_and_b32_e32 v83, 0xffff0000, v133
	v_lshlrev_b32_e32 v84, 16, v134
	v_and_b32_e32 v85, 0xffff0000, v134
	v_lshlrev_b32_e32 v86, 16, v135
	v_and_b32_e32 v87, 0xffff0000, v135
	v_add_f32_e64 v76, v76, v80
	v_add_f32_e64 v77, v77, v81
	v_add_f32_e64 v78, v78, v82
	v_add_f32_e64 v79, v79, v83
	v_add_f32_e64 v80, v74, v86
	v_add_f32_e64 v81, v75, v87
	v_add_f32_e64 v74, v72, v84
	v_add_f32_e64 v75, v73, v85
	v_cvt_pk_bf16_f32 v72, v76, v77
	v_mul_f32_e32 v77, v77, v77
	v_fmac_f32_e32 v77, v76, v76
	v_mul_f32_e32 v76, v79, v79
	v_lshlrev_b32_e32 v88, 16, v128
	v_and_b32_e32 v89, 0xffff0000, v128
	v_lshlrev_b32_e32 v90, 16, v129
	v_and_b32_e32 v91, 0xffff0000, v129
	v_fmac_f32_e32 v76, v78, v78
	v_lshlrev_b32_e32 v92, 16, v130
	v_and_b32_e32 v93, 0xffff0000, v130
	v_add_f32_e32 v76, v77, v76
	v_mul_f32_e32 v77, v75, v75
	v_add_f32_e64 v70, v70, v90
	v_add_f32_e64 v71, v71, v91
	v_add_f32_e64 v68, v68, v88
	v_add_f32_e64 v69, v69, v89
	v_cvt_pk_bf16_f32 v73, v78, v79
	v_fmac_f32_e32 v77, v74, v74
	v_add_f32_e64 v78, v64, v92
	v_add_f32_e64 v79, v65, v93
	v_mul_f32_e32 v64, v69, v69
	v_mul_f32_e32 v65, v71, v71
	v_add_f32_e32 v76, v77, v76
	v_mul_f32_e32 v77, v81, v81
	v_fmac_f32_e32 v64, v68, v68
	v_fmac_f32_e32 v65, v70, v70
	v_lshlrev_b32_e32 v94, 16, v131
	v_and_b32_e32 v95, 0xffff0000, v131
	v_fmac_f32_e32 v77, v80, v80
	v_add_f32_e32 v64, v64, v65
	v_mul_f32_e32 v65, v79, v79
	v_add_f32_e32 v82, v77, v76
	v_add_f32_e64 v76, v66, v94
	v_add_f32_e64 v77, v67, v95
	v_fmac_f32_e32 v65, v78, v78
	v_add_f32_e32 v64, v65, v64
	v_mul_f32_e32 v65, v77, v77
	v_fmac_f32_e32 v65, v76, v76
	v_add_f32_e32 v64, v65, v64
	v_add_f32_e32 v64, v82, v64
	ds_bpermute_b32 v65, v192, v64
	v_cvt_pk_bf16_f32 v74, v74, v75
	v_cvt_pk_bf16_f32 v75, v80, v81
	v_cvt_pk_bf16_f32 v66, v68, v69
	v_cvt_pk_bf16_f32 v67, v70, v71
	s_waitcnt lgkmcnt(0)
	v_add_f32_e32 v64, v64, v65
	ds_bpermute_b32 v65, v191, v64
	v_cvt_pk_bf16_f32 v68, v78, v79
	v_cvt_pk_bf16_f32 v69, v76, v77
	global_store_dwordx4 v[174:175], v[72:75], off
	global_store_dwordx4 v[174:175], v[66:69], off offset:256
	s_and_saveexec_b64 s[34:35], s[0:1]
	s_cbranch_execz .LBB0_470
	v_lshl_add_u64 v[66:67], v[172:173], 2, s[14:15]
	s_waitcnt lgkmcnt(0)
	v_add_f32_e32 v64, v64, v65
	global_atomic_add_f32 v[66:67], v64, off
.LBB0_470:
	s_or_b64 exec, exec, s[34:35]
	v_add_u32_e32 v100, 0x80, v170
	v_ashrrev_i32_e32 v101, 31, v100
	s_waitcnt lgkmcnt(0)
	v_lshlrev_b64 v[64:65], 11, v[100:101]
	v_add_u32_e32 v96, 0x90, v170
	v_lshl_add_u64 v[64:65], v[64:65], 0, v[168:169]
	v_ashrrev_i32_e32 v97, 31, v96
	v_lshl_add_u64 v[110:111], v[64:65], 1, s[12:13]
	v_lshlrev_b64 v[64:65], 11, v[96:97]
	v_add_u32_e32 v92, 0xa0, v170
	v_lshl_add_u64 v[64:65], v[64:65], 0, v[168:169]
	v_ashrrev_i32_e32 v93, 31, v92
	v_lshl_add_u64 v[98:99], v[64:65], 1, s[12:13]
	v_lshlrev_b64 v[64:65], 11, v[92:93]
	v_add_u32_e32 v88, 0xb0, v170
	v_lshl_add_u64 v[64:65], v[64:65], 0, v[168:169]
	v_ashrrev_i32_e32 v89, 31, v88
	v_lshl_add_u64 v[94:95], v[64:65], 1, s[12:13]
	v_lshlrev_b64 v[64:65], 11, v[88:89]
	v_lshl_add_u64 v[64:65], v[64:65], 0, v[168:169]
	v_lshl_add_u64 v[90:91], v[64:65], 1, s[12:13]
	global_load_dwordx4 v[102:105], v[110:111], off
	global_load_dwordx4 v[106:109], v[110:111], off offset:256
	global_load_dwordx4 v[84:87], v[98:99], off
	global_load_dwordx4 v[80:83], v[98:99], off offset:256
	global_load_dwordx4 v[76:79], v[94:95], off
	global_load_dwordx4 v[72:75], v[94:95], off offset:256
	global_load_dwordx4 v[68:71], v[90:91], off
	global_load_dwordx4 v[64:67], v[90:91], off offset:256
	s_waitcnt vmcnt(7)
	v_lshlrev_b32_e32 v112, 16, v102
	v_and_b32_e32 v113, 0xffff0000, v102
	v_lshlrev_b32_e32 v102, 16, v103
	v_and_b32_e32 v103, 0xffff0000, v103
	v_lshlrev_b32_e32 v114, 16, v104
	v_and_b32_e32 v115, 0xffff0000, v104
	v_lshlrev_b32_e32 v104, 16, v105
	v_and_b32_e32 v105, 0xffff0000, v105
	s_waitcnt vmcnt(6)
	v_lshlrev_b32_e32 v116, 16, v106
	v_and_b32_e32 v117, 0xffff0000, v106
	v_lshlrev_b32_e32 v106, 16, v107
	v_and_b32_e32 v107, 0xffff0000, v107
	v_lshlrev_b32_e32 v118, 16, v108
	v_and_b32_e32 v119, 0xffff0000, v108
	v_lshlrev_b32_e32 v108, 16, v109
	v_and_b32_e32 v109, 0xffff0000, v109
	v_add_f32_e64 v60, v60, v112
	v_add_f32_e64 v61, v61, v113
	v_add_f32_e64 v62, v62, v102
	v_add_f32_e64 v63, v63, v103
	v_add_f32_e64 v102, v58, v104
	v_add_f32_e64 v103, v59, v105
	v_add_f32_e64 v58, v56, v114
	v_add_f32_e64 v59, v57, v115
	v_cvt_pk_bf16_f32 v56, v60, v61
	v_mul_f32_e32 v61, v61, v61
	v_fmac_f32_e32 v61, v60, v60
	v_mul_f32_e32 v60, v63, v63
	v_fmac_f32_e32 v60, v62, v62
	v_add_f32_e32 v60, v61, v60
	v_mul_f32_e32 v61, v59, v59
	v_add_f32_e64 v54, v54, v106
	v_add_f32_e64 v55, v55, v107
	v_add_f32_e64 v52, v52, v116
	v_add_f32_e64 v53, v53, v117
	v_cvt_pk_bf16_f32 v57, v62, v63
	v_fmac_f32_e32 v61, v58, v58
	v_add_f32_e64 v62, v48, v118
	v_add_f32_e64 v63, v49, v119
	v_mul_f32_e32 v48, v53, v53
	v_mul_f32_e32 v49, v55, v55
	v_add_f32_e32 v60, v61, v60
	v_mul_f32_e32 v61, v103, v103
	v_fmac_f32_e32 v48, v52, v52
	v_fmac_f32_e32 v49, v54, v54
	v_fmac_f32_e32 v61, v102, v102
	v_add_f32_e32 v48, v48, v49
	v_mul_f32_e32 v49, v63, v63
	v_add_f32_e32 v104, v61, v60
	v_add_f32_e64 v60, v50, v108
	v_add_f32_e64 v61, v51, v109
	v_fmac_f32_e32 v49, v62, v62
	v_add_f32_e32 v48, v49, v48
	v_mul_f32_e32 v49, v61, v61
	v_fmac_f32_e32 v49, v60, v60
	v_add_f32_e32 v48, v49, v48
	v_add_f32_e32 v48, v104, v48
	ds_bpermute_b32 v49, v192, v48
	v_cvt_pk_bf16_f32 v58, v58, v59
	v_cvt_pk_bf16_f32 v59, v102, v103
	v_cvt_pk_bf16_f32 v50, v52, v53
	v_cvt_pk_bf16_f32 v51, v54, v55
	s_waitcnt lgkmcnt(0)
	v_add_f32_e32 v48, v48, v49
	ds_bpermute_b32 v49, v191, v48
	v_cvt_pk_bf16_f32 v52, v62, v63
	v_cvt_pk_bf16_f32 v53, v60, v61
	global_store_dwordx4 v[110:111], v[56:59], off
	global_store_dwordx4 v[110:111], v[50:53], off offset:256
	s_and_saveexec_b64 s[34:35], s[0:1]
	s_cbranch_execz .LBB0_472
	v_lshl_add_u64 v[50:51], v[100:101], 2, s[14:15]
	s_waitcnt lgkmcnt(0)
	v_add_f32_e32 v48, v48, v49
	global_atomic_add_f32 v[50:51], v48, off
.LBB0_472:
	s_or_b64 exec, exec, s[34:35]
	s_waitcnt vmcnt(7)
	v_lshlrev_b32_e32 v48, 16, v84
	s_waitcnt lgkmcnt(0)
	v_and_b32_e32 v49, 0xffff0000, v84
	v_lshlrev_b32_e32 v50, 16, v85
	v_and_b32_e32 v51, 0xffff0000, v85
	v_lshlrev_b32_e32 v52, 16, v86
	v_and_b32_e32 v53, 0xffff0000, v86
	v_lshlrev_b32_e32 v54, 16, v87
	v_and_b32_e32 v55, 0xffff0000, v87
	v_add_f32_e64 v44, v44, v48
	v_add_f32_e64 v45, v45, v49
	v_add_f32_e64 v46, v46, v50
	v_add_f32_e64 v47, v47, v51
	v_add_f32_e64 v48, v42, v54
	v_add_f32_e64 v49, v43, v55
	v_add_f32_e64 v42, v40, v52
	v_add_f32_e64 v43, v41, v53
	v_cvt_pk_bf16_f32 v40, v44, v45
	v_mul_f32_e32 v45, v45, v45
	v_fmac_f32_e32 v45, v44, v44
	v_mul_f32_e32 v44, v47, v47
	s_waitcnt vmcnt(6)
	v_lshlrev_b32_e32 v56, 16, v80
	v_and_b32_e32 v57, 0xffff0000, v80
	v_lshlrev_b32_e32 v58, 16, v81
	v_and_b32_e32 v59, 0xffff0000, v81
	v_fmac_f32_e32 v44, v46, v46
	v_lshlrev_b32_e32 v60, 16, v82
	v_and_b32_e32 v61, 0xffff0000, v82
	v_add_f32_e32 v44, v45, v44
	v_mul_f32_e32 v45, v43, v43
	v_add_f32_e64 v38, v38, v58
	v_add_f32_e64 v39, v39, v59
	v_add_f32_e64 v36, v36, v56
	v_add_f32_e64 v37, v37, v57
	v_cvt_pk_bf16_f32 v41, v46, v47
	v_fmac_f32_e32 v45, v42, v42
	v_add_f32_e64 v46, v32, v60
	v_add_f32_e64 v47, v33, v61
	v_mul_f32_e32 v32, v37, v37
	v_mul_f32_e32 v33, v39, v39
	v_add_f32_e32 v44, v45, v44
	v_mul_f32_e32 v45, v49, v49
	v_fmac_f32_e32 v32, v36, v36
	v_fmac_f32_e32 v33, v38, v38
	v_lshlrev_b32_e32 v62, 16, v83
	v_and_b32_e32 v63, 0xffff0000, v83
	v_fmac_f32_e32 v45, v48, v48
	v_add_f32_e32 v32, v32, v33
	v_mul_f32_e32 v33, v47, v47
	v_add_f32_e32 v50, v45, v44
	v_add_f32_e64 v44, v34, v62
	v_add_f32_e64 v45, v35, v63
	v_fmac_f32_e32 v33, v46, v46
	v_add_f32_e32 v32, v33, v32
	v_mul_f32_e32 v33, v45, v45
	v_fmac_f32_e32 v33, v44, v44
	v_add_f32_e32 v32, v33, v32
	v_add_f32_e32 v32, v50, v32
	ds_bpermute_b32 v33, v192, v32
	v_cvt_pk_bf16_f32 v42, v42, v43
	v_cvt_pk_bf16_f32 v43, v48, v49
	v_cvt_pk_bf16_f32 v34, v36, v37
	v_cvt_pk_bf16_f32 v35, v38, v39
	s_waitcnt lgkmcnt(0)
	v_add_f32_e32 v32, v32, v33
	ds_bpermute_b32 v33, v191, v32
	v_cvt_pk_bf16_f32 v36, v46, v47
	v_cvt_pk_bf16_f32 v37, v44, v45
	global_store_dwordx4 v[98:99], v[40:43], off
	global_store_dwordx4 v[98:99], v[34:37], off offset:256
	s_and_saveexec_b64 s[34:35], s[0:1]
	s_cbranch_execz .LBB0_474
	v_lshl_add_u64 v[34:35], v[96:97], 2, s[14:15]
	s_waitcnt lgkmcnt(0)
	v_add_f32_e32 v32, v32, v33
	global_atomic_add_f32 v[34:35], v32, off
.LBB0_474:
	s_or_b64 exec, exec, s[34:35]
	s_waitcnt vmcnt(7)
	v_lshlrev_b32_e32 v32, 16, v76
	s_waitcnt lgkmcnt(0)
	v_and_b32_e32 v33, 0xffff0000, v76
	v_lshlrev_b32_e32 v34, 16, v77
	v_and_b32_e32 v35, 0xffff0000, v77
	v_lshlrev_b32_e32 v36, 16, v78
	v_and_b32_e32 v37, 0xffff0000, v78
	v_lshlrev_b32_e32 v38, 16, v79
	v_and_b32_e32 v39, 0xffff0000, v79
	v_add_f32_e64 v28, v28, v32
	v_add_f32_e64 v29, v29, v33
	v_add_f32_e64 v30, v30, v34
	v_add_f32_e64 v31, v31, v35
	v_add_f32_e64 v32, v26, v38
	v_add_f32_e64 v33, v27, v39
	v_add_f32_e64 v26, v24, v36
	v_add_f32_e64 v27, v25, v37
	v_cvt_pk_bf16_f32 v24, v28, v29
	v_mul_f32_e32 v29, v29, v29
	v_fmac_f32_e32 v29, v28, v28
	v_mul_f32_e32 v28, v31, v31
	s_waitcnt vmcnt(6)
	v_lshlrev_b32_e32 v40, 16, v72
	v_and_b32_e32 v41, 0xffff0000, v72
	v_lshlrev_b32_e32 v42, 16, v73
	v_and_b32_e32 v43, 0xffff0000, v73
	v_fmac_f32_e32 v28, v30, v30
	v_lshlrev_b32_e32 v44, 16, v74
	v_and_b32_e32 v45, 0xffff0000, v74
	v_add_f32_e32 v28, v29, v28
	v_mul_f32_e32 v29, v27, v27
	v_add_f32_e64 v22, v22, v42
	v_add_f32_e64 v23, v23, v43
	v_add_f32_e64 v20, v20, v40
	v_add_f32_e64 v21, v21, v41
	v_cvt_pk_bf16_f32 v25, v30, v31
	v_fmac_f32_e32 v29, v26, v26
	v_add_f32_e64 v30, v16, v44
	v_add_f32_e64 v31, v17, v45
	v_mul_f32_e32 v16, v21, v21
	v_mul_f32_e32 v17, v23, v23
	v_add_f32_e32 v28, v29, v28
	v_mul_f32_e32 v29, v33, v33
	v_fmac_f32_e32 v16, v20, v20
	v_fmac_f32_e32 v17, v22, v22
	v_lshlrev_b32_e32 v46, 16, v75
	v_and_b32_e32 v47, 0xffff0000, v75
	v_fmac_f32_e32 v29, v32, v32
	v_add_f32_e32 v16, v16, v17
	v_mul_f32_e32 v17, v31, v31
	v_add_f32_e32 v34, v29, v28
	v_add_f32_e64 v28, v18, v46
	v_add_f32_e64 v29, v19, v47
	v_fmac_f32_e32 v17, v30, v30
	v_add_f32_e32 v16, v17, v16
	v_mul_f32_e32 v17, v29, v29
	v_fmac_f32_e32 v17, v28, v28
	v_add_f32_e32 v16, v17, v16
	v_add_f32_e32 v16, v34, v16
	ds_bpermute_b32 v17, v192, v16
	v_cvt_pk_bf16_f32 v26, v26, v27
	v_cvt_pk_bf16_f32 v27, v32, v33
	v_cvt_pk_bf16_f32 v18, v20, v21
	v_cvt_pk_bf16_f32 v19, v22, v23
	s_waitcnt lgkmcnt(0)
	v_add_f32_e32 v16, v16, v17
	ds_bpermute_b32 v17, v191, v16
	v_cvt_pk_bf16_f32 v20, v30, v31
	v_cvt_pk_bf16_f32 v21, v28, v29
	global_store_dwordx4 v[94:95], v[24:27], off
	global_store_dwordx4 v[94:95], v[18:21], off offset:256
	s_and_saveexec_b64 s[34:35], s[0:1]
	s_cbranch_execz .LBB0_476
	v_lshl_add_u64 v[18:19], v[92:93], 2, s[14:15]
	s_waitcnt lgkmcnt(0)
	v_add_f32_e32 v16, v16, v17
	global_atomic_add_f32 v[18:19], v16, off
.LBB0_476:
	s_or_b64 exec, exec, s[34:35]
	s_waitcnt vmcnt(7)
	v_lshlrev_b32_e32 v16, 16, v68
	s_waitcnt lgkmcnt(0)
	v_and_b32_e32 v17, 0xffff0000, v68
	v_lshlrev_b32_e32 v18, 16, v69
	v_and_b32_e32 v19, 0xffff0000, v69
	v_lshlrev_b32_e32 v20, 16, v70
	v_and_b32_e32 v21, 0xffff0000, v70
	v_lshlrev_b32_e32 v22, 16, v71
	v_and_b32_e32 v23, 0xffff0000, v71
	v_add_f32_e64 v12, v12, v16
	v_add_f32_e64 v13, v13, v17
	v_add_f32_e64 v14, v14, v18
	v_add_f32_e64 v15, v15, v19
	v_add_f32_e64 v16, v10, v22
	v_add_f32_e64 v17, v11, v23
	v_add_f32_e64 v10, v8, v20
	v_add_f32_e64 v11, v9, v21
	v_cvt_pk_bf16_f32 v8, v12, v13
	v_mul_f32_e32 v13, v13, v13
	v_fmac_f32_e32 v13, v12, v12
	v_mul_f32_e32 v12, v15, v15
	s_waitcnt vmcnt(6)
	v_lshlrev_b32_e32 v24, 16, v64
	v_and_b32_e32 v25, 0xffff0000, v64
	v_lshlrev_b32_e32 v26, 16, v65
	v_and_b32_e32 v27, 0xffff0000, v65
	v_fmac_f32_e32 v12, v14, v14
	v_lshlrev_b32_e32 v28, 16, v66
	v_and_b32_e32 v29, 0xffff0000, v66
	v_add_f32_e32 v12, v13, v12
	v_mul_f32_e32 v13, v11, v11
	v_add_f32_e64 v6, v6, v26
	v_add_f32_e64 v7, v7, v27
	v_add_f32_e64 v4, v4, v24
	v_add_f32_e64 v5, v5, v25
	v_cvt_pk_bf16_f32 v9, v14, v15
	v_fmac_f32_e32 v13, v10, v10
	v_add_f32_e64 v14, v0, v28
	v_add_f32_e64 v15, v1, v29
	v_mul_f32_e32 v0, v5, v5
	v_mul_f32_e32 v1, v7, v7
	v_add_f32_e32 v12, v13, v12
	v_mul_f32_e32 v13, v17, v17
	v_fmac_f32_e32 v0, v4, v4
	v_fmac_f32_e32 v1, v6, v6
	v_lshlrev_b32_e32 v30, 16, v67
	v_and_b32_e32 v31, 0xffff0000, v67
	v_fmac_f32_e32 v13, v16, v16
	v_add_f32_e32 v0, v0, v1
	v_mul_f32_e32 v1, v15, v15
	v_add_f32_e32 v18, v13, v12
	v_add_f32_e64 v12, v2, v30
	v_add_f32_e64 v13, v3, v31
	v_fmac_f32_e32 v1, v14, v14
	v_add_f32_e32 v0, v1, v0
	v_mul_f32_e32 v1, v13, v13
	v_fmac_f32_e32 v1, v12, v12
	v_add_f32_e32 v0, v1, v0
	v_add_f32_e32 v0, v18, v0
	ds_bpermute_b32 v1, v192, v0
	v_cvt_pk_bf16_f32 v10, v10, v11
	v_cvt_pk_bf16_f32 v11, v16, v17
	v_cvt_pk_bf16_f32 v2, v4, v5
	v_cvt_pk_bf16_f32 v3, v6, v7
	s_waitcnt lgkmcnt(0)
	v_add_f32_e32 v0, v0, v1
	ds_bpermute_b32 v1, v191, v0
	v_cvt_pk_bf16_f32 v4, v14, v15
	v_cvt_pk_bf16_f32 v5, v12, v13
	global_store_dwordx4 v[90:91], v[8:11], off
	global_store_dwordx4 v[90:91], v[2:5], off offset:256
	s_and_saveexec_b64 s[34:35], s[0:1]
	s_cbranch_execz .LBB0_478
	v_lshl_add_u64 v[2:3], v[88:89], 2, s[14:15]
	s_waitcnt lgkmcnt(0)
	v_add_f32_e32 v0, v0, v1
	global_atomic_add_f32 v[2:3], v0, off

.LBB0_564:
	v_lshl_add_u32 v150, s4, 8, v152
	v_ashrrev_i32_e32 v151, 31, v150
	v_lshl_add_u64 v[144:145], v[150:151], 2, s[16:17]
	s_nop 0
	v_lshl_or_b32 v146, s5, 8, v154
	s_cmp_lt_i32 s5, 8
	v_ashrrev_i32_e32 v147, 31, v146
	s_cselect_b64 vcc, -1, 0
	v_lshlrev_b64 v[148:149], 1, v[146:147]
	v_cndmask_b32_e32 v161, 1.0, v160, vcc
	v_lshlrev_b64 v[164:165], 14, v[150:151]
	v_or_b32_e32 v162, 16, v150
	s_nop 0
	v_fmamk_f32 v146, v242, 0x3a000000, v158
	v_rsq_f32_e32 v252, v146
	s_nop 0
	v_mul_f32_e32 v252, v252, v161
	v_ashrrev_i32_e32 v163, 31, v162
	v_lshl_add_u64 v[146:147], s[10:11], 0, v[164:165]
	v_lshl_add_u64 v[146:147], v[146:147], 0, v[148:149]
	v_lshl_add_u64 v[164:165], v[162:163], 2, s[16:17]
	v_mul_f32_e64 v126, v126, v252
	v_mul_f32_e64 v127, v127, v252
	v_mul_f32_e64 v124, v124, v252
	v_mul_f32_e64 v125, v125, v252
	v_mul_f32_e64 v122, v122, v252
	v_mul_f32_e64 v123, v123, v252
	v_mul_f32_e64 v120, v120, v252
	v_mul_f32_e64 v121, v121, v252
	v_mul_f32_e64 v118, v118, v252
	v_mul_f32_e64 v119, v119, v252
	v_mul_f32_e64 v116, v116, v252
	v_mul_f32_e64 v117, v117, v252
	v_mul_f32_e64 v168, v114, v252
	v_mul_f32_e64 v169, v115, v252
	v_mul_f32_e64 v166, v112, v252
	v_mul_f32_e64 v167, v113, v252
	v_cvt_pk_bf16_f32 v112, v124, v125
	v_cvt_pk_bf16_f32 v113, v126, v127
	v_cvt_pk_bf16_f32 v114, v120, v121
	v_cvt_pk_bf16_f32 v115, v122, v123
	v_cvt_pk_bf16_f32 v116, v116, v117
	v_cvt_pk_bf16_f32 v117, v118, v119
	v_cvt_pk_bf16_f32 v118, v166, v167
	v_cvt_pk_bf16_f32 v119, v168, v169
	global_store_dwordx4 v[146:147], v[112:115], off
	global_store_dwordx4 v[146:147], v[116:119], off offset:256
	s_nop 0
	v_or_b32_e32 v112, 32, v150
	v_ashrrev_i32_e32 v113, 31, v112
	v_lshl_add_u64 v[116:117], v[112:113], 2, s[16:17]
	s_nop 0
	v_fmamk_f32 v114, v243, 0x3a000000, v158
	v_rsq_f32_e32 v252, v114
	s_nop 0
	v_mul_f32_e32 v252, v252, v161
	v_lshlrev_b64 v[114:115], 14, v[162:163]
	v_lshl_add_u64 v[114:115], s[10:11], 0, v[114:115]
	v_lshl_add_u64 v[114:115], v[114:115], 0, v[148:149]
	v_mul_f32_e64 v110, v110, v252
	v_mul_f32_e64 v111, v111, v252
	v_mul_f32_e64 v108, v108, v252
	v_mul_f32_e64 v109, v109, v252
	v_mul_f32_e64 v106, v106, v252
	v_mul_f32_e64 v107, v107, v252
	v_mul_f32_e64 v104, v104, v252
	v_mul_f32_e64 v105, v105, v252
	v_mul_f32_e64 v102, v102, v252
	v_mul_f32_e64 v103, v103, v252
	v_mul_f32_e64 v100, v100, v252
	v_mul_f32_e64 v101, v101, v252
	v_mul_f32_e64 v120, v98, v252
	v_mul_f32_e64 v121, v99, v252
	v_mul_f32_e64 v118, v96, v252
	v_mul_f32_e64 v119, v97, v252
	v_cvt_pk_bf16_f32 v96, v108, v109
	v_cvt_pk_bf16_f32 v97, v110, v111
	v_cvt_pk_bf16_f32 v98, v104, v105
	v_cvt_pk_bf16_f32 v99, v106, v107
	v_cvt_pk_bf16_f32 v100, v100, v101
	v_cvt_pk_bf16_f32 v101, v102, v103
	v_cvt_pk_bf16_f32 v102, v118, v119
	v_cvt_pk_bf16_f32 v103, v120, v121
	global_store_dwordx4 v[114:115], v[96:99], off
	global_store_dwordx4 v[114:115], v[100:103], off offset:256
	s_nop 0
	v_or_b32_e32 v96, 48, v150
	v_ashrrev_i32_e32 v97, 31, v96
	v_lshl_add_u64 v[100:101], v[96:97], 2, s[16:17]
	s_nop 0
	v_fmamk_f32 v98, v244, 0x3a000000, v158
	v_rsq_f32_e32 v252, v98
	s_nop 0
	v_mul_f32_e32 v252, v252, v161
	v_lshlrev_b64 v[98:99], 14, v[112:113]
	v_lshl_add_u64 v[98:99], s[10:11], 0, v[98:99]
	v_lshl_add_u64 v[98:99], v[98:99], 0, v[148:149]
	v_mul_f32_e64 v94, v94, v252
	v_mul_f32_e64 v95, v95, v252
	v_mul_f32_e64 v92, v92, v252
	v_mul_f32_e64 v93, v93, v252
	v_mul_f32_e64 v90, v90, v252
	v_mul_f32_e64 v91, v91, v252
	v_mul_f32_e64 v88, v88, v252
	v_mul_f32_e64 v89, v89, v252
	v_mul_f32_e64 v86, v86, v252
	v_mul_f32_e64 v87, v87, v252
	v_mul_f32_e64 v84, v84, v252
	v_mul_f32_e64 v85, v85, v252
	v_mul_f32_e64 v104, v82, v252
	v_mul_f32_e64 v105, v83, v252
	v_mul_f32_e64 v102, v80, v252
	v_mul_f32_e64 v103, v81, v252
	v_cvt_pk_bf16_f32 v80, v92, v93
	v_cvt_pk_bf16_f32 v81, v94, v95
	v_cvt_pk_bf16_f32 v82, v88, v89
	v_cvt_pk_bf16_f32 v83, v90, v91
	v_cvt_pk_bf16_f32 v84, v84, v85
	v_cvt_pk_bf16_f32 v85, v86, v87
	v_cvt_pk_bf16_f32 v86, v102, v103
	v_cvt_pk_bf16_f32 v87, v104, v105
	global_store_dwordx4 v[98:99], v[80:83], off
	global_store_dwordx4 v[98:99], v[84:87], off offset:256
	s_nop 0
	s_nop 0
	v_fmamk_f32 v80, v245, 0x3a000000, v158
	v_rsq_f32_e32 v252, v80
	s_nop 0
	v_mul_f32_e32 v252, v252, v161
	v_lshlrev_b64 v[80:81], 14, v[96:97]
	v_lshl_add_u64 v[80:81], s[10:11], 0, v[80:81]
	v_lshl_add_u64 v[80:81], v[80:81], 0, v[148:149]
	v_mul_f32_e64 v78, v78, v252
	v_mul_f32_e64 v79, v79, v252
	v_mul_f32_e64 v76, v76, v252
	v_mul_f32_e64 v77, v77, v252
	v_mul_f32_e64 v74, v74, v252
	v_mul_f32_e64 v75, v75, v252
	v_mul_f32_e64 v72, v72, v252
	v_mul_f32_e64 v73, v73, v252
	v_mul_f32_e64 v70, v70, v252
	v_mul_f32_e64 v71, v71, v252
	v_mul_f32_e64 v68, v68, v252
	v_mul_f32_e64 v69, v69, v252
	v_mul_f32_e64 v84, v66, v252
	v_mul_f32_e64 v85, v67, v252
	v_mul_f32_e64 v82, v64, v252
	v_mul_f32_e64 v83, v65, v252
	v_cvt_pk_bf16_f32 v64, v76, v77
	v_cvt_pk_bf16_f32 v65, v78, v79
	v_cvt_pk_bf16_f32 v66, v72, v73
	v_cvt_pk_bf16_f32 v67, v74, v75
	v_cvt_pk_bf16_f32 v68, v68, v69
	v_cvt_pk_bf16_f32 v69, v70, v71
	v_cvt_pk_bf16_f32 v70, v82, v83
	v_cvt_pk_bf16_f32 v71, v84, v85
	global_store_dwordx4 v[80:81], v[64:67], off
	global_store_dwordx4 v[80:81], v[68:71], off offset:256
	s_nop 0
	s_nop 0
	v_fmamk_f32 v64, v246, 0x3a000000, v158
	v_rsq_f32_e32 v252, v64
	s_nop 0
	v_mul_f32_e32 v252, v252, v161
	v_lshl_add_u64 v[64:65], v[146:147], 0, s[20:21]
	v_add_co_u32_e32 v66, vcc, s75, v146
	v_addc_co_u32_e32 v67, vcc, 0, v147, vcc
	v_mul_f32_e64 v62, v62, v252
	v_mul_f32_e64 v63, v63, v252
	v_mul_f32_e64 v60, v60, v252
	v_mul_f32_e64 v61, v61, v252
	v_mul_f32_e64 v58, v58, v252
	v_mul_f32_e64 v59, v59, v252
	v_mul_f32_e64 v56, v56, v252
	v_mul_f32_e64 v57, v57, v252
	v_mul_f32_e64 v54, v54, v252
	v_mul_f32_e64 v55, v55, v252
	v_mul_f32_e64 v52, v52, v252
	v_mul_f32_e64 v53, v53, v252
	v_mul_f32_e64 v70, v50, v252
	v_mul_f32_e64 v71, v51, v252
	v_mul_f32_e64 v68, v48, v252
	v_mul_f32_e64 v69, v49, v252
	v_cvt_pk_bf16_f32 v48, v60, v61
	v_cvt_pk_bf16_f32 v49, v62, v63
	v_cvt_pk_bf16_f32 v50, v56, v57
	v_cvt_pk_bf16_f32 v51, v58, v59
	v_cvt_pk_bf16_f32 v52, v52, v53
	v_cvt_pk_bf16_f32 v53, v54, v55
	v_cvt_pk_bf16_f32 v54, v68, v69
	v_cvt_pk_bf16_f32 v55, v70, v71
	global_store_dwordx4 v[66:67], v[48:51], off
	global_store_dwordx4 v[64:65], v[52:55], off offset:256
	s_nop 0
	s_nop 0
	v_fmamk_f32 v48, v247, 0x3a000000, v158
	v_rsq_f32_e32 v252, v48
	s_nop 0
	v_mul_f32_e32 v252, v252, v161
	v_lshl_add_u64 v[48:49], v[146:147], 0, s[22:23]
	v_add_co_u32_e32 v50, vcc, s76, v146
	v_addc_co_u32_e32 v51, vcc, 0, v147, vcc
	v_mul_f32_e64 v46, v46, v252
	v_mul_f32_e64 v47, v47, v252
	v_mul_f32_e64 v44, v44, v252
	v_mul_f32_e64 v45, v45, v252
	v_mul_f32_e64 v42, v42, v252
	v_mul_f32_e64 v43, v43, v252
	v_mul_f32_e64 v40, v40, v252
	v_mul_f32_e64 v41, v41, v252
	v_mul_f32_e64 v38, v38, v252
	v_mul_f32_e64 v39, v39, v252
	v_mul_f32_e64 v36, v36, v252
	v_mul_f32_e64 v37, v37, v252
	v_mul_f32_e64 v54, v34, v252
	v_mul_f32_e64 v55, v35, v252
	v_mul_f32_e64 v52, v32, v252
	v_mul_f32_e64 v53, v33, v252
	v_cvt_pk_bf16_f32 v32, v44, v45
	v_cvt_pk_bf16_f32 v33, v46, v47
	v_cvt_pk_bf16_f32 v34, v40, v41
	v_cvt_pk_bf16_f32 v35, v42, v43
	v_cvt_pk_bf16_f32 v36, v36, v37
	v_cvt_pk_bf16_f32 v37, v38, v39
	v_cvt_pk_bf16_f32 v38, v52, v53
	v_cvt_pk_bf16_f32 v39, v54, v55
	global_store_dwordx4 v[50:51], v[32:35], off
	global_store_dwordx4 v[48:49], v[36:39], off offset:256
	s_nop 0
	s_nop 0
	v_fmamk_f32 v32, v248, 0x3a000000, v158
	v_rsq_f32_e32 v252, v32
	s_nop 0
	v_mul_f32_e32 v252, v252, v161
	v_lshl_add_u64 v[32:33], v[146:147], 0, s[24:25]
	v_add_co_u32_e32 v34, vcc, s77, v146
	v_addc_co_u32_e32 v35, vcc, 0, v147, vcc
	v_mul_f32_e64 v30, v30, v252
	v_mul_f32_e64 v31, v31, v252
	v_mul_f32_e64 v28, v28, v252
	v_mul_f32_e64 v29, v29, v252
	v_mul_f32_e64 v26, v26, v252
	v_mul_f32_e64 v27, v27, v252
	v_mul_f32_e64 v24, v24, v252
	v_mul_f32_e64 v25, v25, v252
	v_mul_f32_e64 v22, v22, v252
	v_mul_f32_e64 v23, v23, v252
	v_mul_f32_e64 v20, v20, v252
	v_mul_f32_e64 v21, v21, v252
	v_mul_f32_e64 v38, v18, v252
	v_mul_f32_e64 v39, v19, v252
	v_mul_f32_e64 v36, v16, v252
	v_mul_f32_e64 v37, v17, v252
	v_cvt_pk_bf16_f32 v16, v28, v29
	v_cvt_pk_bf16_f32 v17, v30, v31
	v_cvt_pk_bf16_f32 v18, v24, v25
	v_cvt_pk_bf16_f32 v19, v26, v27
	v_cvt_pk_bf16_f32 v20, v20, v21
	v_cvt_pk_bf16_f32 v21, v22, v23
	v_cvt_pk_bf16_f32 v22, v36, v37
	v_cvt_pk_bf16_f32 v23, v38, v39
	global_store_dwordx4 v[34:35], v[16:19], off
	global_store_dwordx4 v[32:33], v[20:23], off offset:256
	s_nop 0
	s_nop 0
	v_fmamk_f32 v16, v249, 0x3a000000, v158
	v_rsq_f32_e32 v252, v16
	s_nop 0
	v_mul_f32_e32 v252, v252, v161
	v_lshl_add_u64 v[16:17], v[146:147], 0, s[26:27]
	v_add_co_u32_e32 v18, vcc, s78, v146
	v_addc_co_u32_e32 v19, vcc, 0, v147, vcc
	v_mul_f32_e64 v14, v14, v252
	v_mul_f32_e64 v15, v15, v252
	v_mul_f32_e64 v12, v12, v252
	v_mul_f32_e64 v13, v13, v252
	v_mul_f32_e64 v10, v10, v252
	v_mul_f32_e64 v11, v11, v252
	v_mul_f32_e64 v8, v8, v252
	v_mul_f32_e64 v9, v9, v252
	s_andn2_b64 vcc, exec, s[0:1]
	v_mul_f32_e64 v6, v6, v252
	v_mul_f32_e64 v7, v7, v252
	v_mul_f32_e64 v4, v4, v252
	v_mul_f32_e64 v5, v5, v252
	v_mul_f32_e64 v22, v2, v252
	v_mul_f32_e64 v23, v3, v252
	v_mul_f32_e64 v20, v0, v252
	v_mul_f32_e64 v21, v1, v252
	v_cvt_pk_bf16_f32 v0, v12, v13
	v_cvt_pk_bf16_f32 v1, v14, v15
	v_cvt_pk_bf16_f32 v2, v8, v9
	v_cvt_pk_bf16_f32 v3, v10, v11
	s_mov_b64 s[0:1], -1
	v_cvt_pk_bf16_f32 v4, v4, v5
	v_cvt_pk_bf16_f32 v5, v6, v7
	v_cvt_pk_bf16_f32 v6, v20, v21
	v_cvt_pk_bf16_f32 v7, v22, v23
	global_store_dwordx4 v[18:19], v[0:3], off
	global_store_dwordx4 v[16:17], v[4:7], off offset:256
	s_cbranch_vccnz .LBB0_553
	s_andn2_b64 vcc, exec, s[6:7]
	s_cbranch_vccnz .LBB0_552
	s_barrier
	s_branch .LBB0_552

.LBB0_625:
	s_setprio 0
	v_mov_b32_e32 v0, v196
	v_nop
	v_nop
	v_permlane32_swap_b32 v196, v0
	s_mulk_i32 s22, 0x110
	v_add_f32_e32 v146, v196, v0
	v_ashrrev_i32_e32 v0, 31, v147
	v_lshrrev_b32_e32 v0, 28, v0
	v_add_u32_e32 v0, v147, v0
	s_waitcnt vmcnt(0)
	v_ashrrev_i32_e32 v144, 4, v0
	v_and_b32_e32 v0, -16, v0
	v_sub_u32_e32 v148, v147, v0
	v_lshlrev_b32_e32 v68, 3, v148
	v_ashrrev_i32_e32 v69, 31, v68
	v_add_u32_e32 v0, 64, v147
	v_lshlrev_b64 v[140:141], 1, v[68:69]
	v_ashrrev_i32_e32 v68, 31, v0
	v_lshrrev_b32_e32 v68, 28, v68
	v_ashrrev_i32_e32 v145, 31, v144
	v_add_u32_e32 v68, v0, v68
	v_lshl_add_u64 v[138:139], s[4:5], 0, v[144:145]
	v_ashrrev_i32_e32 v142, 4, v68
	v_lshlrev_b64 v[66:67], 14, v[138:139]
	v_and_b32_e32 v68, -16, v68
	v_ashrrev_i32_e32 v143, 31, v142
	v_lshl_add_u64 v[66:67], s[12:13], 0, v[66:67]
	v_sub_u32_e32 v145, v0, v68
	v_lshl_add_u64 v[132:133], s[4:5], 0, v[142:143]
	v_lshl_add_u64 v[66:67], v[66:67], 0, s[16:17]
	v_lshlrev_b64 v[68:69], 14, v[132:133]
	v_lshlrev_b32_e32 v70, 3, v145
	v_lshl_add_u64 v[66:67], v[66:67], 0, v[140:141]
	v_lshl_add_u64 v[68:69], s[12:13], 0, v[68:69]
	v_ashrrev_i32_e32 v71, 31, v70
	v_add_co_u32_e32 v66, vcc, s48, v66
	v_lshl_add_u64 v[68:69], v[68:69], 0, s[16:17]
	v_lshlrev_b64 v[134:135], 1, v[70:71]
	v_addc_co_u32_e32 v67, vcc, 0, v67, vcc
	v_lshl_add_u64 v[68:69], v[68:69], 0, v[134:135]
	v_add_co_u32_e32 v68, vcc, s48, v68
	v_add_u32_e32 v0, 0x80, v147
	s_nop 0
	v_addc_co_u32_e32 v69, vcc, 0, v69, vcc
	global_load_dwordx4 v[94:97], v[66:67], off
	global_load_dwordx4 v[90:93], v[68:69], off
	v_ashrrev_i32_e32 v66, 31, v0
	v_lshrrev_b32_e32 v66, 28, v66
	v_add_u32_e32 v66, v0, v66
	v_ashrrev_i32_e32 v136, 4, v66
	v_and_b32_e32 v66, -16, v66
	v_sub_u32_e32 v143, v0, v66
	v_lshlrev_b32_e32 v68, 3, v143
	v_ashrrev_i32_e32 v69, 31, v68
	v_add_u32_e32 v0, 0xc0, v147
	v_lshlrev_b64 v[128:129], 1, v[68:69]
	v_ashrrev_i32_e32 v68, 31, v0
	v_lshrrev_b32_e32 v68, 28, v68
	v_ashrrev_i32_e32 v137, 31, v136
	v_add_u32_e32 v68, v0, v68
	v_lshl_add_u64 v[126:127], s[4:5], 0, v[136:137]
	v_ashrrev_i32_e32 v130, 4, v68
	v_lshlrev_b64 v[66:67], 14, v[126:127]
	v_and_b32_e32 v68, -16, v68
	v_ashrrev_i32_e32 v131, 31, v130
	v_lshl_add_u64 v[66:67], s[12:13], 0, v[66:67]
	v_sub_u32_e32 v137, v0, v68
	v_lshl_add_u64 v[120:121], s[4:5], 0, v[130:131]
	v_lshl_add_u64 v[66:67], v[66:67], 0, s[16:17]
	v_lshlrev_b64 v[68:69], 14, v[120:121]
	v_lshlrev_b32_e32 v70, 3, v137
	v_lshl_add_u64 v[66:67], v[66:67], 0, v[128:129]
	v_lshl_add_u64 v[68:69], s[12:13], 0, v[68:69]
	v_ashrrev_i32_e32 v71, 31, v70
	v_add_co_u32_e32 v66, vcc, s48, v66
	v_lshl_add_u64 v[68:69], v[68:69], 0, s[16:17]
	v_lshlrev_b64 v[122:123], 1, v[70:71]
	v_addc_co_u32_e32 v67, vcc, 0, v67, vcc
	v_lshl_add_u64 v[68:69], v[68:69], 0, v[122:123]
	v_add_co_u32_e32 v68, vcc, s48, v68
	v_add_u32_e32 v0, 0x100, v147
	s_nop 0
	v_addc_co_u32_e32 v69, vcc, 0, v69, vcc
	global_load_dwordx4 v[86:89], v[66:67], off
	global_load_dwordx4 v[82:85], v[68:69], off
	v_ashrrev_i32_e32 v66, 31, v0
	v_lshrrev_b32_e32 v66, 28, v66
	v_add_u32_e32 v66, v0, v66
	v_ashrrev_i32_e32 v124, 4, v66
	v_and_b32_e32 v66, -16, v66
	v_sub_u32_e32 v131, v0, v66
	v_lshlrev_b32_e32 v68, 3, v131
	v_ashrrev_i32_e32 v69, 31, v68
	v_add_u32_e32 v0, 0x140, v147
	v_lshlrev_b64 v[116:117], 1, v[68:69]
	v_ashrrev_i32_e32 v68, 31, v0
	v_lshrrev_b32_e32 v68, 28, v68
	v_ashrrev_i32_e32 v125, 31, v124
	v_add_u32_e32 v68, v0, v68
	v_lshl_add_u64 v[114:115], s[4:5], 0, v[124:125]
	v_ashrrev_i32_e32 v118, 4, v68
	v_lshlrev_b64 v[66:67], 14, v[114:115]
	v_and_b32_e32 v68, -16, v68
	v_ashrrev_i32_e32 v119, 31, v118
	v_lshl_add_u64 v[66:67], s[12:13], 0, v[66:67]
	v_sub_u32_e32 v125, v0, v68
	v_lshl_add_u64 v[108:109], s[4:5], 0, v[118:119]
	v_lshl_add_u64 v[66:67], v[66:67], 0, s[16:17]
	v_lshlrev_b64 v[68:69], 14, v[108:109]
	v_lshlrev_b32_e32 v70, 3, v125
	v_lshl_add_u64 v[66:67], v[66:67], 0, v[116:117]
	v_lshl_add_u64 v[68:69], s[12:13], 0, v[68:69]
	v_ashrrev_i32_e32 v71, 31, v70
	v_add_co_u32_e32 v66, vcc, s48, v66
	v_lshl_add_u64 v[68:69], v[68:69], 0, s[16:17]
	v_lshlrev_b64 v[110:111], 1, v[70:71]
	v_addc_co_u32_e32 v67, vcc, 0, v67, vcc
	v_lshl_add_u64 v[68:69], v[68:69], 0, v[110:111]
	v_add_co_u32_e32 v68, vcc, s48, v68
	v_add_u32_e32 v0, 0x180, v147
	s_nop 0
	v_addc_co_u32_e32 v69, vcc, 0, v69, vcc
	global_load_dwordx4 v[78:81], v[66:67], off
	global_load_dwordx4 v[74:77], v[68:69], off
	v_ashrrev_i32_e32 v66, 31, v0
	v_lshrrev_b32_e32 v66, 28, v66
	v_add_u32_e32 v66, v0, v66
	v_ashrrev_i32_e32 v112, 4, v66
	v_and_b32_e32 v66, -16, v66
	v_sub_u32_e32 v119, v0, v66
	v_lshlrev_b32_e32 v68, 3, v119
	v_ashrrev_i32_e32 v69, 31, v68
	v_add_u32_e32 v0, 0x1c0, v147
	v_lshlrev_b64 v[104:105], 1, v[68:69]
	v_ashrrev_i32_e32 v68, 31, v0
	v_lshrrev_b32_e32 v68, 28, v68
	v_ashrrev_i32_e32 v113, 31, v112
	v_add_u32_e32 v68, v0, v68
	v_lshl_add_u64 v[102:103], s[4:5], 0, v[112:113]
	v_ashrrev_i32_e32 v106, 4, v68
	v_lshlrev_b64 v[66:67], 14, v[102:103]
	v_and_b32_e32 v68, -16, v68
	v_ashrrev_i32_e32 v107, 31, v106
	v_lshl_add_u64 v[66:67], s[12:13], 0, v[66:67]
	v_sub_u32_e32 v0, v0, v68
	v_lshl_add_u64 v[98:99], s[4:5], 0, v[106:107]
	v_lshl_add_u64 v[66:67], v[66:67], 0, s[16:17]
	v_lshlrev_b64 v[68:69], 14, v[98:99]
	v_lshlrev_b32_e32 v70, 3, v0
	v_div_scale_f32 v107, s[4:5], v146, v146, 1.0
	v_lshl_add_u64 v[66:67], v[66:67], 0, v[104:105]
	v_lshl_add_u64 v[68:69], s[12:13], 0, v[68:69]
	v_ashrrev_i32_e32 v71, 31, v70
	v_rcp_f32_e32 v113, v107
	v_add_co_u32_e32 v66, vcc, s48, v66
	v_lshl_add_u64 v[68:69], v[68:69], 0, s[16:17]
	v_lshlrev_b64 v[100:101], 1, v[70:71]
	v_addc_co_u32_e32 v67, vcc, 0, v67, vcc
	v_lshl_add_u64 v[68:69], v[68:69], 0, v[100:101]
	v_add_co_u32_e32 v68, vcc, s48, v68
	v_fma_f32 v149, -v107, v113, 1.0
	s_nop 0
	v_addc_co_u32_e32 v69, vcc, 0, v69, vcc
	v_fmac_f32_e32 v113, v149, v113
	v_div_scale_f32 v149, vcc, 1.0, v146, 1.0
	v_mul_f32_e32 v150, v149, v113
	v_fma_f32 v151, -v107, v150, v149
	v_fmac_f32_e32 v150, v151, v113
	v_fma_f32 v107, -v107, v150, v149
	v_div_fmas_f32 v107, v107, v113, v150
	v_div_fixup_f32 v146, v107, v146, 1.0
	v_mul_f32_e64 v50, v50, v146
	v_mul_f32_e64 v51, v51, v146
	v_mul_f32_e64 v52, v52, v146
	v_mul_f32_e64 v53, v53, v146
	v_and_b32_e32 v107, 31, v147
	v_cvt_pk_bf16_f32 v50, v50, v51
	v_cvt_pk_bf16_f32 v51, v52, v53
	v_ashrrev_i32_e32 v52, 2, v147
	v_mul_f32_e64 v2, v2, v146
	v_mul_f32_e64 v3, v3, v146
	v_mul_f32_e64 v4, v4, v146
	v_mul_f32_e64 v5, v5, v146
	s_add_i32 s4, s22, 0
	v_mul_u32_u24_e32 v107, 0x110, v107
	v_and_b32_e32 v52, -8, v52
	v_cvt_pk_bf16_f32 v2, v2, v3
	v_cvt_pk_bf16_f32 v3, v4, v5
	v_mul_f32_e64 v4, v6, v146
	v_mul_f32_e64 v5, v7, v146
	v_mul_f32_e64 v6, v8, v146
	v_mul_f32_e64 v7, v9, v146
	v_add3_u32 v107, s4, v107, v52
	v_cvt_pk_bf16_f32 v4, v4, v5
	v_cvt_pk_bf16_f32 v5, v6, v7
	global_load_dwordx4 v[70:73], v[66:67], off
	s_nop 0
	global_load_dwordx4 v[66:69], v[68:69], off
	v_mul_f32_e64 v34, v34, v146
	v_mul_f32_e64 v35, v35, v146
	v_mul_f32_e64 v36, v36, v146
	v_mul_f32_e64 v37, v37, v146
	v_mul_f32_e64 v18, v18, v146
	v_mul_f32_e64 v19, v19, v146
	v_mul_f32_e64 v20, v20, v146
	v_mul_f32_e64 v21, v21, v146
	ds_write2_b64 v107, v[2:3], v[4:5] offset0:24 offset1:26
	v_mul_f32_e64 v2, v10, v146
	v_mul_f32_e64 v3, v11, v146
	v_mul_f32_e64 v4, v12, v146
	v_mul_f32_e64 v5, v13, v146
	v_mul_f32_e64 v52, v54, v146
	v_mul_f32_e64 v53, v55, v146
	v_mul_f32_e64 v54, v56, v146
	v_mul_f32_e64 v55, v57, v146
	v_cvt_pk_bf16_f32 v34, v34, v35
	v_cvt_pk_bf16_f32 v35, v36, v37
	v_mul_f32_e64 v36, v38, v146
	v_mul_f32_e64 v37, v39, v146
	v_mul_f32_e64 v38, v40, v146
	v_mul_f32_e64 v39, v41, v146
	v_cvt_pk_bf16_f32 v18, v18, v19
	v_cvt_pk_bf16_f32 v19, v20, v21
	v_mul_f32_e64 v20, v22, v146
	v_mul_f32_e64 v21, v23, v146
	v_mul_f32_e64 v22, v24, v146
	v_mul_f32_e64 v23, v25, v146
	v_cvt_pk_bf16_f32 v2, v2, v3
	v_cvt_pk_bf16_f32 v3, v4, v5
	v_mul_f32_e64 v4, v14, v146
	v_mul_f32_e64 v5, v15, v146
	v_mul_f32_e64 v6, v16, v146
	v_mul_f32_e64 v7, v17, v146
	v_cvt_pk_bf16_f32 v52, v52, v53
	v_cvt_pk_bf16_f32 v53, v54, v55
	v_cvt_pk_bf16_f32 v36, v36, v37
	v_cvt_pk_bf16_f32 v37, v38, v39
	v_cvt_pk_bf16_f32 v20, v20, v21
	v_cvt_pk_bf16_f32 v21, v22, v23
	v_cvt_pk_bf16_f32 v4, v4, v5
	v_cvt_pk_bf16_f32 v5, v6, v7
	ds_write2_b64 v107, v[50:51], v[52:53] offset1:2
	v_mul_f32_e64 v50, v58, v146
	v_mul_f32_e64 v51, v59, v146
	v_mul_f32_e64 v52, v60, v146
	v_mul_f32_e64 v53, v61, v146
	ds_write2_b64 v107, v[34:35], v[36:37] offset0:8 offset1:10
	v_mul_f32_e64 v34, v42, v146
	v_mul_f32_e64 v35, v43, v146
	v_mul_f32_e64 v36, v44, v146
	v_mul_f32_e64 v37, v45, v146
	ds_write2_b64 v107, v[18:19], v[20:21] offset0:16 offset1:18
	v_mul_f32_e64 v18, v26, v146
	v_mul_f32_e64 v19, v27, v146
	v_mul_f32_e64 v20, v28, v146
	v_mul_f32_e64 v21, v29, v146
	ds_write2_b64 v107, v[2:3], v[4:5] offset0:28 offset1:30
	v_mul_lo_u32 v2, v144, s45
	v_lshlrev_b32_e32 v3, 4, v148
	s_waitcnt vmcnt(7)
	v_lshlrev_b32_e32 v10, 16, v94
	v_cvt_pk_bf16_f32 v50, v50, v51
	v_cvt_pk_bf16_f32 v51, v52, v53
	v_mul_f32_e64 v52, v62, v146
	v_mul_f32_e64 v53, v63, v146
	v_mul_f32_e64 v54, v64, v146
	v_mul_f32_e64 v55, v65, v146
	v_cvt_pk_bf16_f32 v34, v34, v35
	v_cvt_pk_bf16_f32 v35, v36, v37
	v_mul_f32_e64 v36, v46, v146
	v_mul_f32_e64 v37, v47, v146
	v_mul_f32_e64 v38, v48, v146
	v_mul_f32_e64 v39, v49, v146
	v_cvt_pk_bf16_f32 v18, v18, v19
	v_cvt_pk_bf16_f32 v19, v20, v21
	v_mul_f32_e64 v20, v30, v146
	v_mul_f32_e64 v21, v31, v146
	v_mul_f32_e64 v22, v32, v146
	v_mul_f32_e64 v23, v33, v146
	v_add3_u32 v2, s4, v2, v3
	v_and_b32_e32 v13, 0xffff0000, v94
	v_mul_f32_e32 v3, 0xbfb8aa3b, v10
	v_cvt_pk_bf16_f32 v52, v52, v53
	v_cvt_pk_bf16_f32 v53, v54, v55
	v_cvt_pk_bf16_f32 v36, v36, v37
	v_cvt_pk_bf16_f32 v37, v38, v39
	v_cvt_pk_bf16_f32 v20, v20, v21
	v_cvt_pk_bf16_f32 v21, v22, v23
	v_exp_f32_e32 v6, v3
	v_mul_f32_e32 v3, 0xbfb8aa3b, v13
	ds_write2_b64 v107, v[50:51], v[52:53] offset0:4 offset1:6
	ds_write2_b64 v107, v[34:35], v[36:37] offset0:12 offset1:14
	ds_write2_b64 v107, v[18:19], v[20:21] offset0:20 offset1:22
	v_exp_f32_e32 v7, v3
	s_waitcnt lgkmcnt(0)
	ds_read_b128 v[2:5], v2
	v_add_f32_e32 v6, 1.0, v6
	v_rcp_f32_e32 v14, v6
	v_add_f32_e32 v6, 1.0, v7
	v_rcp_f32_e32 v15, v6
	v_mul_lo_u32 v6, v142, s45
	v_lshlrev_b32_e32 v7, 4, v145
	v_add3_u32 v6, s4, v6, v7
	ds_read_b128 v[6:9], v6
	s_waitcnt lgkmcnt(1)
	v_and_b32_e32 v11, 0xffff0000, v2
	v_lshlrev_b32_e32 v12, 16, v2
	v_mul_f32_e64 v10, v12, v10
	v_mul_f32_e64 v11, v13, v11
	v_lshlrev_b32_e32 v12, 16, v95
	v_mul_f32_e64 v10, v14, v10
	v_mul_f32_e64 v11, v15, v11
	v_and_b32_e32 v15, 0xffff0000, v95
	v_mul_f32_e32 v2, 0xbfb8aa3b, v12
	v_exp_f32_e32 v13, v2
	v_mul_f32_e32 v2, 0xbfb8aa3b, v15
	v_exp_f32_e32 v14, v2
	v_cvt_pk_bf16_f32 v2, v10, v11
	v_add_f32_e32 v10, 1.0, v13
	v_rcp_f32_e32 v10, v10
	v_add_f32_e32 v11, 1.0, v14
	v_rcp_f32_e32 v11, v11
	v_and_b32_e32 v13, 0xffff0000, v3
	v_lshlrev_b32_e32 v14, 16, v3
	v_mul_f32_e64 v12, v14, v12
	v_mul_f32_e64 v13, v15, v13
	v_and_b32_e32 v15, 0xffff0000, v96
	v_mul_f32_e64 v10, v10, v12
	v_mul_f32_e64 v11, v11, v13
	v_lshlrev_b32_e32 v12, 16, v96
	v_mul_f32_e32 v3, 0xbfb8aa3b, v12
	v_exp_f32_e32 v13, v3
	v_mul_f32_e32 v3, 0xbfb8aa3b, v15
	v_exp_f32_e32 v14, v3
	v_cvt_pk_bf16_f32 v3, v10, v11
	v_add_f32_e32 v10, 1.0, v13
	v_rcp_f32_e32 v10, v10
	v_add_f32_e32 v11, 1.0, v14
	v_rcp_f32_e32 v11, v11
	v_and_b32_e32 v13, 0xffff0000, v4
	v_lshlrev_b32_e32 v14, 16, v4
	v_mul_f32_e64 v12, v14, v12
	v_mul_f32_e64 v13, v15, v13
	v_and_b32_e32 v15, 0xffff0000, v97
	v_mul_f32_e64 v10, v10, v12
	v_mul_f32_e64 v11, v11, v13
	v_lshlrev_b32_e32 v12, 16, v97
	v_mul_f32_e32 v4, 0xbfb8aa3b, v12
	v_exp_f32_e32 v13, v4
	v_mul_f32_e32 v4, 0xbfb8aa3b, v15
	v_exp_f32_e32 v14, v4
	v_cvt_pk_bf16_f32 v4, v10, v11
	v_add_f32_e32 v10, 1.0, v13
	v_rcp_f32_e32 v10, v10
	v_add_f32_e32 v11, 1.0, v14
	v_rcp_f32_e32 v11, v11
	v_and_b32_e32 v13, 0xffff0000, v5
	v_lshlrev_b32_e32 v14, 16, v5
	v_mul_f32_e64 v12, v14, v12
	v_mul_f32_e64 v13, v15, v13
	s_waitcnt vmcnt(6)
	v_and_b32_e32 v15, 0xffff0000, v90
	v_mul_f32_e64 v10, v10, v12
	v_mul_f32_e64 v11, v11, v13
	v_lshlrev_b32_e32 v12, 16, v90
	v_mul_f32_e32 v13, 0xbfb8aa3b, v12
	v_mul_f32_e32 v14, 0xbfb8aa3b, v15
	v_exp_f32_e32 v13, v13
	v_exp_f32_e32 v14, v14
	v_cvt_pk_bf16_f32 v5, v10, v11
	v_lshlrev_b64 v[10:11], 12, v[138:139]
	v_lshl_add_u64 v[10:11], s[0:1], 0, v[10:11]
	v_lshl_add_u64 v[10:11], v[10:11], 0, v[140:141]
	global_store_dwordx4 v[10:11], v[2:5], off
	v_and_b32_e32 v11, 0xffff0000, v91
	s_waitcnt lgkmcnt(0)
	v_lshlrev_b32_e32 v10, 16, v7
	v_add_f32_e32 v2, 1.0, v13
	v_add_f32_e32 v3, 1.0, v14
	v_rcp_f32_e32 v2, v2
	v_rcp_f32_e32 v3, v3
	v_and_b32_e32 v13, 0xffff0000, v6
	v_lshlrev_b32_e32 v14, 16, v6
	v_mul_f32_e64 v4, v14, v12
	v_mul_f32_e64 v5, v15, v13
	v_mul_f32_e32 v6, 0xbfb8aa3b, v11
	v_mul_f32_e64 v2, v2, v4
	v_mul_f32_e64 v3, v3, v5
	v_lshlrev_b32_e32 v4, 16, v91
	v_mul_f32_e32 v5, 0xbfb8aa3b, v4
	v_exp_f32_e32 v5, v5
	v_exp_f32_e32 v6, v6
	v_cvt_pk_bf16_f32 v2, v2, v3
	v_lshlrev_b32_e32 v0, 4, v0
	v_add_f32_e32 v3, 1.0, v5
	v_rcp_f32_e32 v12, v3
	v_add_f32_e32 v3, 1.0, v6
	v_and_b32_e32 v5, 0xffff0000, v7
	v_lshlrev_b32_e32 v6, 16, v92
	v_rcp_f32_e32 v13, v3
	v_mul_f32_e64 v4, v10, v4
	v_mul_f32_e64 v5, v11, v5
	v_and_b32_e32 v11, 0xffff0000, v92
	v_mul_f32_e32 v3, 0xbfb8aa3b, v6
	v_exp_f32_e32 v7, v3
	v_mul_f32_e32 v3, 0xbfb8aa3b, v11
	v_exp_f32_e32 v10, v3
	v_mul_f32_e64 v4, v12, v4
	v_mul_f32_e64 v5, v13, v5
	s_add_i32 s88, s88, s58
	v_cvt_pk_bf16_f32 v3, v4, v5
	v_add_f32_e32 v4, 1.0, v7
	v_add_f32_e32 v5, 1.0, v10
	v_rcp_f32_e32 v4, v4
	v_rcp_f32_e32 v5, v5
	v_and_b32_e32 v7, 0xffff0000, v8
	v_lshlrev_b32_e32 v10, 16, v8
	v_mul_f32_e64 v6, v10, v6
	v_mul_f32_e64 v7, v11, v7
	v_and_b32_e32 v11, 0xffff0000, v93
	v_mul_f32_e64 v4, v4, v6
	v_mul_f32_e64 v5, v5, v7
	v_lshlrev_b32_e32 v6, 16, v93
	v_mul_f32_e32 v7, 0xbfb8aa3b, v6
	v_exp_f32_e32 v7, v7
	v_mul_f32_e32 v8, 0xbfb8aa3b, v11
	v_exp_f32_e32 v8, v8
	v_cvt_pk_bf16_f32 v4, v4, v5
	v_add_f32_e32 v5, 1.0, v7
	v_rcp_f32_e32 v12, v5
	v_add_f32_e32 v5, 1.0, v8
	v_rcp_f32_e32 v13, v5
	v_and_b32_e32 v7, 0xffff0000, v9
	v_lshlrev_b32_e32 v10, 16, v9
	v_mul_f32_e64 v6, v10, v6
	v_mul_f32_e64 v7, v11, v7
	s_waitcnt vmcnt(6)
	v_lshlrev_b32_e32 v10, 16, v86
	v_mul_f32_e64 v6, v12, v6
	v_mul_f32_e64 v7, v13, v7
	v_and_b32_e32 v13, 0xffff0000, v86
	v_cvt_pk_bf16_f32 v5, v6, v7
	v_lshlrev_b64 v[6:7], 12, v[132:133]
	v_lshl_add_u64 v[6:7], s[0:1], 0, v[6:7]
	v_lshl_add_u64 v[6:7], v[6:7], 0, v[134:135]
	global_store_dwordx4 v[6:7], v[2:5], off
	s_add_i32 s49, s49, s58
	s_cmpk_lt_i32 s88, 0x200
	v_mul_lo_u32 v2, v136, s45
	v_lshlrev_b32_e32 v3, 4, v143
	v_add3_u32 v2, s4, v2, v3
	v_mul_f32_e32 v3, 0xbfb8aa3b, v10
	v_exp_f32_e32 v6, v3
	v_mul_f32_e32 v3, 0xbfb8aa3b, v13
	v_exp_f32_e32 v7, v3
	ds_read_b128 v[2:5], v2
	v_add_f32_e32 v6, 1.0, v6
	v_rcp_f32_e32 v14, v6
	v_add_f32_e32 v6, 1.0, v7
	v_rcp_f32_e32 v15, v6
	v_mul_lo_u32 v6, v130, s45
	v_lshlrev_b32_e32 v7, 4, v137
	v_add3_u32 v6, s4, v6, v7
	ds_read_b128 v[6:9], v6
	s_waitcnt lgkmcnt(1)
	v_and_b32_e32 v11, 0xffff0000, v2
	v_lshlrev_b32_e32 v12, 16, v2
	v_mul_f32_e64 v10, v12, v10
	v_mul_f32_e64 v11, v13, v11
	v_lshlrev_b32_e32 v12, 16, v87
	v_mul_f32_e64 v10, v14, v10
	v_mul_f32_e64 v11, v15, v11
	v_and_b32_e32 v15, 0xffff0000, v87
	v_mul_f32_e32 v2, 0xbfb8aa3b, v12
	v_exp_f32_e32 v13, v2
	v_mul_f32_e32 v2, 0xbfb8aa3b, v15
	v_exp_f32_e32 v14, v2
	v_cvt_pk_bf16_f32 v2, v10, v11
	v_add_f32_e32 v10, 1.0, v13
	v_rcp_f32_e32 v10, v10
	v_add_f32_e32 v11, 1.0, v14
	v_rcp_f32_e32 v11, v11
	v_and_b32_e32 v13, 0xffff0000, v3
	v_lshlrev_b32_e32 v14, 16, v3
	v_mul_f32_e64 v12, v14, v12
	v_mul_f32_e64 v13, v15, v13
	v_and_b32_e32 v15, 0xffff0000, v88
	v_mul_f32_e64 v10, v10, v12
	v_mul_f32_e64 v11, v11, v13
	v_lshlrev_b32_e32 v12, 16, v88
	v_mul_f32_e32 v3, 0xbfb8aa3b, v12
	v_exp_f32_e32 v13, v3
	v_mul_f32_e32 v3, 0xbfb8aa3b, v15
	v_exp_f32_e32 v14, v3
	v_cvt_pk_bf16_f32 v3, v10, v11
	v_add_f32_e32 v10, 1.0, v13
	v_rcp_f32_e32 v10, v10
	v_add_f32_e32 v11, 1.0, v14
	v_rcp_f32_e32 v11, v11
	v_and_b32_e32 v13, 0xffff0000, v4
	v_lshlrev_b32_e32 v14, 16, v4
	v_mul_f32_e64 v12, v14, v12
	v_mul_f32_e64 v13, v15, v13
	v_and_b32_e32 v15, 0xffff0000, v89
	v_mul_f32_e64 v10, v10, v12
	v_mul_f32_e64 v11, v11, v13
	v_lshlrev_b32_e32 v12, 16, v89
	v_mul_f32_e32 v4, 0xbfb8aa3b, v12
	v_exp_f32_e32 v13, v4
	v_mul_f32_e32 v4, 0xbfb8aa3b, v15
	v_exp_f32_e32 v14, v4
	v_cvt_pk_bf16_f32 v4, v10, v11
	v_add_f32_e32 v10, 1.0, v13
	v_rcp_f32_e32 v10, v10
	v_add_f32_e32 v11, 1.0, v14
	v_rcp_f32_e32 v11, v11
	v_and_b32_e32 v13, 0xffff0000, v5
	v_lshlrev_b32_e32 v14, 16, v5
	v_mul_f32_e64 v12, v14, v12
	v_mul_f32_e64 v13, v15, v13
	s_waitcnt vmcnt(6)
	v_and_b32_e32 v15, 0xffff0000, v82
	v_mul_f32_e64 v10, v10, v12
	v_mul_f32_e64 v11, v11, v13
	v_lshlrev_b32_e32 v12, 16, v82
	v_mul_f32_e32 v13, 0xbfb8aa3b, v12
	v_mul_f32_e32 v14, 0xbfb8aa3b, v15
	v_exp_f32_e32 v13, v13
	v_exp_f32_e32 v14, v14
	v_cvt_pk_bf16_f32 v5, v10, v11
	v_lshlrev_b64 v[10:11], 12, v[126:127]
	v_lshl_add_u64 v[10:11], s[0:1], 0, v[10:11]
	v_lshl_add_u64 v[10:11], v[10:11], 0, v[128:129]
	global_store_dwordx4 v[10:11], v[2:5], off
	v_and_b32_e32 v11, 0xffff0000, v83
	s_waitcnt lgkmcnt(0)
	v_lshlrev_b32_e32 v10, 16, v7
	v_add_f32_e32 v2, 1.0, v13
	v_add_f32_e32 v3, 1.0, v14
	v_rcp_f32_e32 v2, v2
	v_rcp_f32_e32 v3, v3
	v_and_b32_e32 v13, 0xffff0000, v6
	v_lshlrev_b32_e32 v14, 16, v6
	v_mul_f32_e64 v4, v14, v12
	v_mul_f32_e64 v5, v15, v13
	v_mul_f32_e32 v6, 0xbfb8aa3b, v11
	v_mul_f32_e64 v2, v2, v4
	v_mul_f32_e64 v3, v3, v5
	v_lshlrev_b32_e32 v4, 16, v83
	v_mul_f32_e32 v5, 0xbfb8aa3b, v4
	v_exp_f32_e32 v5, v5
	v_exp_f32_e32 v6, v6
	v_cvt_pk_bf16_f32 v2, v2, v3
	v_add_f32_e32 v3, 1.0, v5
	v_rcp_f32_e32 v12, v3
	v_add_f32_e32 v3, 1.0, v6
	v_and_b32_e32 v5, 0xffff0000, v7
	v_lshlrev_b32_e32 v6, 16, v84
	v_rcp_f32_e32 v13, v3
	v_mul_f32_e64 v4, v10, v4
	v_mul_f32_e64 v5, v11, v5
	v_and_b32_e32 v11, 0xffff0000, v84
	v_mul_f32_e32 v3, 0xbfb8aa3b, v6
	v_exp_f32_e32 v7, v3
	v_mul_f32_e32 v3, 0xbfb8aa3b, v11
	v_exp_f32_e32 v10, v3
	v_mul_f32_e64 v4, v12, v4
	v_mul_f32_e64 v5, v13, v5
	s_nop 0
	v_cvt_pk_bf16_f32 v3, v4, v5
	v_add_f32_e32 v4, 1.0, v7
	v_add_f32_e32 v5, 1.0, v10
	v_rcp_f32_e32 v4, v4
	v_rcp_f32_e32 v5, v5
	v_and_b32_e32 v7, 0xffff0000, v8
	v_lshlrev_b32_e32 v10, 16, v8
	v_mul_f32_e64 v6, v10, v6
	v_mul_f32_e64 v7, v11, v7
	v_and_b32_e32 v11, 0xffff0000, v85
	v_mul_f32_e64 v4, v4, v6
	v_mul_f32_e64 v5, v5, v7
	v_lshlrev_b32_e32 v6, 16, v85
	v_mul_f32_e32 v7, 0xbfb8aa3b, v6
	v_exp_f32_e32 v7, v7
	v_mul_f32_e32 v8, 0xbfb8aa3b, v11
	v_exp_f32_e32 v8, v8
	v_cvt_pk_bf16_f32 v4, v4, v5
	v_add_f32_e32 v5, 1.0, v7
	v_rcp_f32_e32 v12, v5
	v_add_f32_e32 v5, 1.0, v8
	v_rcp_f32_e32 v13, v5
	v_and_b32_e32 v7, 0xffff0000, v9
	v_lshlrev_b32_e32 v10, 16, v9
	v_mul_f32_e64 v6, v10, v6
	v_mul_f32_e64 v7, v11, v7
	s_waitcnt vmcnt(6)
	v_lshlrev_b32_e32 v10, 16, v78
	v_mul_f32_e64 v6, v12, v6
	v_mul_f32_e64 v7, v13, v7
	v_and_b32_e32 v13, 0xffff0000, v78
	v_cvt_pk_bf16_f32 v5, v6, v7
	v_lshlrev_b64 v[6:7], 12, v[120:121]
	v_lshl_add_u64 v[6:7], s[0:1], 0, v[6:7]
	v_lshl_add_u64 v[6:7], v[6:7], 0, v[122:123]
	global_store_dwordx4 v[6:7], v[2:5], off
	s_nop 1
	v_mul_lo_u32 v2, v124, s45
	v_lshlrev_b32_e32 v3, 4, v131
	v_add3_u32 v2, s4, v2, v3
	v_mul_f32_e32 v3, 0xbfb8aa3b, v10
	v_exp_f32_e32 v6, v3
	v_mul_f32_e32 v3, 0xbfb8aa3b, v13
	v_exp_f32_e32 v7, v3
	ds_read_b128 v[2:5], v2
	v_add_f32_e32 v6, 1.0, v6
	v_rcp_f32_e32 v14, v6
	v_add_f32_e32 v6, 1.0, v7
	v_rcp_f32_e32 v15, v6
	v_mul_lo_u32 v6, v118, s45
	v_lshlrev_b32_e32 v7, 4, v125
	v_add3_u32 v6, s4, v6, v7
	ds_read_b128 v[6:9], v6
	s_waitcnt lgkmcnt(1)
	v_and_b32_e32 v11, 0xffff0000, v2
	v_lshlrev_b32_e32 v12, 16, v2
	v_mul_f32_e64 v10, v12, v10
	v_mul_f32_e64 v11, v13, v11
	v_lshlrev_b32_e32 v12, 16, v79
	v_mul_f32_e64 v10, v14, v10
	v_mul_f32_e64 v11, v15, v11
	v_and_b32_e32 v15, 0xffff0000, v79
	v_mul_f32_e32 v2, 0xbfb8aa3b, v12
	v_exp_f32_e32 v13, v2
	v_mul_f32_e32 v2, 0xbfb8aa3b, v15
	v_exp_f32_e32 v14, v2
	v_cvt_pk_bf16_f32 v2, v10, v11
	v_add_f32_e32 v10, 1.0, v13
	v_rcp_f32_e32 v10, v10
	v_add_f32_e32 v11, 1.0, v14
	v_rcp_f32_e32 v11, v11
	v_and_b32_e32 v13, 0xffff0000, v3
	v_lshlrev_b32_e32 v14, 16, v3
	v_mul_f32_e64 v12, v14, v12
	v_mul_f32_e64 v13, v15, v13
	v_and_b32_e32 v15, 0xffff0000, v80
	v_mul_f32_e64 v10, v10, v12
	v_mul_f32_e64 v11, v11, v13
	v_lshlrev_b32_e32 v12, 16, v80
	v_mul_f32_e32 v3, 0xbfb8aa3b, v12
	v_exp_f32_e32 v13, v3
	v_mul_f32_e32 v3, 0xbfb8aa3b, v15
	v_exp_f32_e32 v14, v3
	v_cvt_pk_bf16_f32 v3, v10, v11
	v_add_f32_e32 v10, 1.0, v13
	v_rcp_f32_e32 v10, v10
	v_add_f32_e32 v11, 1.0, v14
	v_rcp_f32_e32 v11, v11
	v_and_b32_e32 v13, 0xffff0000, v4
	v_lshlrev_b32_e32 v14, 16, v4
	v_mul_f32_e64 v12, v14, v12
	v_mul_f32_e64 v13, v15, v13
	v_and_b32_e32 v15, 0xffff0000, v81
	v_mul_f32_e64 v10, v10, v12
	v_mul_f32_e64 v11, v11, v13
	v_lshlrev_b32_e32 v12, 16, v81
	v_mul_f32_e32 v4, 0xbfb8aa3b, v12
	v_exp_f32_e32 v13, v4
	v_mul_f32_e32 v4, 0xbfb8aa3b, v15
	v_exp_f32_e32 v14, v4
	v_cvt_pk_bf16_f32 v4, v10, v11
	v_add_f32_e32 v10, 1.0, v13
	v_rcp_f32_e32 v10, v10
	v_add_f32_e32 v11, 1.0, v14
	v_rcp_f32_e32 v11, v11
	v_and_b32_e32 v13, 0xffff0000, v5
	v_lshlrev_b32_e32 v14, 16, v5
	v_mul_f32_e64 v12, v14, v12
	v_mul_f32_e64 v13, v15, v13
	s_waitcnt vmcnt(6)
	v_and_b32_e32 v15, 0xffff0000, v74
	v_mul_f32_e64 v10, v10, v12
	v_mul_f32_e64 v11, v11, v13
	v_lshlrev_b32_e32 v12, 16, v74
	v_mul_f32_e32 v13, 0xbfb8aa3b, v12
	v_mul_f32_e32 v14, 0xbfb8aa3b, v15
	v_exp_f32_e32 v13, v13
	v_exp_f32_e32 v14, v14
	v_cvt_pk_bf16_f32 v5, v10, v11
	v_lshlrev_b64 v[10:11], 12, v[114:115]
	v_lshl_add_u64 v[10:11], s[0:1], 0, v[10:11]
	v_lshl_add_u64 v[10:11], v[10:11], 0, v[116:117]
	global_store_dwordx4 v[10:11], v[2:5], off
	v_and_b32_e32 v11, 0xffff0000, v75
	s_waitcnt lgkmcnt(0)
	v_lshlrev_b32_e32 v10, 16, v7
	v_add_f32_e32 v2, 1.0, v13
	v_add_f32_e32 v3, 1.0, v14
	v_rcp_f32_e32 v2, v2
	v_rcp_f32_e32 v3, v3
	v_and_b32_e32 v13, 0xffff0000, v6
	v_lshlrev_b32_e32 v14, 16, v6
	v_mul_f32_e64 v4, v14, v12
	v_mul_f32_e64 v5, v15, v13
	v_mul_f32_e32 v6, 0xbfb8aa3b, v11
	v_mul_f32_e64 v2, v2, v4
	v_mul_f32_e64 v3, v3, v5
	v_lshlrev_b32_e32 v4, 16, v75
	v_mul_f32_e32 v5, 0xbfb8aa3b, v4
	v_exp_f32_e32 v5, v5
	v_exp_f32_e32 v6, v6
	v_cvt_pk_bf16_f32 v2, v2, v3
	v_add_f32_e32 v3, 1.0, v5
	v_rcp_f32_e32 v12, v3
	v_add_f32_e32 v3, 1.0, v6
	v_and_b32_e32 v5, 0xffff0000, v7
	v_lshlrev_b32_e32 v6, 16, v76
	v_rcp_f32_e32 v13, v3
	v_mul_f32_e64 v4, v10, v4
	v_mul_f32_e64 v5, v11, v5
	v_and_b32_e32 v11, 0xffff0000, v76
	v_mul_f32_e32 v3, 0xbfb8aa3b, v6
	v_exp_f32_e32 v7, v3
	v_mul_f32_e32 v3, 0xbfb8aa3b, v11
	v_exp_f32_e32 v10, v3
	v_mul_f32_e64 v4, v12, v4
	v_mul_f32_e64 v5, v13, v5
	s_nop 0
	v_cvt_pk_bf16_f32 v3, v4, v5
	v_add_f32_e32 v4, 1.0, v7
	v_add_f32_e32 v5, 1.0, v10
	v_rcp_f32_e32 v4, v4
	v_rcp_f32_e32 v5, v5
	v_and_b32_e32 v7, 0xffff0000, v8
	v_lshlrev_b32_e32 v10, 16, v8
	v_mul_f32_e64 v6, v10, v6
	v_mul_f32_e64 v7, v11, v7
	v_and_b32_e32 v11, 0xffff0000, v77
	v_mul_f32_e64 v4, v4, v6
	v_mul_f32_e64 v5, v5, v7
	v_lshlrev_b32_e32 v6, 16, v77
	v_mul_f32_e32 v7, 0xbfb8aa3b, v6
	v_exp_f32_e32 v7, v7
	v_mul_f32_e32 v8, 0xbfb8aa3b, v11
	v_exp_f32_e32 v8, v8
	v_cvt_pk_bf16_f32 v4, v4, v5
	v_add_f32_e32 v5, 1.0, v7
	v_rcp_f32_e32 v12, v5
	v_add_f32_e32 v5, 1.0, v8
	v_rcp_f32_e32 v13, v5
	v_and_b32_e32 v7, 0xffff0000, v9
	v_lshlrev_b32_e32 v10, 16, v9
	v_mul_f32_e64 v6, v10, v6
	v_mul_f32_e64 v7, v11, v7
	s_waitcnt vmcnt(6)
	v_lshlrev_b32_e32 v10, 16, v70
	v_mul_f32_e64 v6, v12, v6
	v_mul_f32_e64 v7, v13, v7
	v_and_b32_e32 v13, 0xffff0000, v70
	v_cvt_pk_bf16_f32 v5, v6, v7
	v_lshlrev_b64 v[6:7], 12, v[108:109]
	v_lshl_add_u64 v[6:7], s[0:1], 0, v[6:7]
	v_lshl_add_u64 v[6:7], v[6:7], 0, v[110:111]
	global_store_dwordx4 v[6:7], v[2:5], off
	s_nop 1
	v_mul_lo_u32 v2, v112, s45
	v_lshlrev_b32_e32 v3, 4, v119
	v_add3_u32 v2, s4, v2, v3
	v_mul_f32_e32 v3, 0xbfb8aa3b, v10
	v_exp_f32_e32 v6, v3
	v_mul_f32_e32 v3, 0xbfb8aa3b, v13
	v_exp_f32_e32 v7, v3
	ds_read_b128 v[2:5], v2
	v_add_f32_e32 v6, 1.0, v6
	v_rcp_f32_e32 v14, v6
	v_add_f32_e32 v6, 1.0, v7
	v_rcp_f32_e32 v15, v6
	v_mul_lo_u32 v6, v106, s45
	v_add3_u32 v0, s4, v6, v0
	ds_read_b128 v[6:9], v0
	s_waitcnt lgkmcnt(1)
	v_and_b32_e32 v11, 0xffff0000, v2
	v_lshlrev_b32_e32 v12, 16, v2
	v_mul_f32_e64 v10, v12, v10
	v_mul_f32_e64 v11, v13, v11
	v_lshlrev_b32_e32 v12, 16, v71
	v_mul_f32_e64 v10, v14, v10
	v_mul_f32_e64 v11, v15, v11
	v_and_b32_e32 v15, 0xffff0000, v71
	v_mul_f32_e32 v0, 0xbfb8aa3b, v12
	v_exp_f32_e32 v0, v0
	v_mul_f32_e32 v2, 0xbfb8aa3b, v15
	v_exp_f32_e32 v13, v2
	v_cvt_pk_bf16_f32 v2, v10, v11
	v_add_f32_e32 v0, 1.0, v0
	v_rcp_f32_e32 v10, v0
	v_add_f32_e32 v0, 1.0, v13
	v_rcp_f32_e32 v11, v0
	v_and_b32_e32 v13, 0xffff0000, v3
	v_lshlrev_b32_e32 v14, 16, v3
	v_mul_f32_e64 v12, v14, v12
	v_mul_f32_e64 v13, v15, v13
	v_and_b32_e32 v15, 0xffff0000, v72
	v_mul_f32_e64 v10, v10, v12
	v_mul_f32_e64 v11, v11, v13
	v_lshlrev_b32_e32 v12, 16, v72
	v_mul_f32_e32 v0, 0xbfb8aa3b, v12
	v_exp_f32_e32 v0, v0
	v_mul_f32_e32 v3, 0xbfb8aa3b, v15
	v_exp_f32_e32 v13, v3
	v_cvt_pk_bf16_f32 v3, v10, v11
	v_add_f32_e32 v0, 1.0, v0
	v_rcp_f32_e32 v10, v0
	v_add_f32_e32 v0, 1.0, v13
	v_rcp_f32_e32 v11, v0
	v_and_b32_e32 v13, 0xffff0000, v4
	v_lshlrev_b32_e32 v14, 16, v4
	v_mul_f32_e64 v12, v14, v12
	v_mul_f32_e64 v13, v15, v13
	v_and_b32_e32 v15, 0xffff0000, v73
	v_mul_f32_e64 v10, v10, v12
	v_mul_f32_e64 v11, v11, v13
	v_lshlrev_b32_e32 v12, 16, v73
	v_mul_f32_e32 v0, 0xbfb8aa3b, v12
	v_exp_f32_e32 v0, v0
	v_mul_f32_e32 v4, 0xbfb8aa3b, v15
	v_exp_f32_e32 v13, v4
	v_cvt_pk_bf16_f32 v4, v10, v11
	v_add_f32_e32 v0, 1.0, v0
	v_rcp_f32_e32 v10, v0
	v_add_f32_e32 v0, 1.0, v13
	v_rcp_f32_e32 v11, v0
	v_and_b32_e32 v13, 0xffff0000, v5
	v_lshlrev_b32_e32 v14, 16, v5
	v_mul_f32_e64 v12, v14, v12
	v_mul_f32_e64 v13, v15, v13
	s_waitcnt vmcnt(6)
	v_and_b32_e32 v15, 0xffff0000, v66
	v_mul_f32_e64 v10, v10, v12
	v_mul_f32_e64 v11, v11, v13
	v_lshlrev_b32_e32 v12, 16, v66
	v_mul_f32_e32 v0, 0xbfb8aa3b, v12
	v_exp_f32_e32 v0, v0
	v_mul_f32_e32 v13, 0xbfb8aa3b, v15
	v_exp_f32_e32 v13, v13
	v_cvt_pk_bf16_f32 v5, v10, v11
	v_lshlrev_b64 v[10:11], 12, v[102:103]
	v_lshl_add_u64 v[10:11], s[0:1], 0, v[10:11]
	v_lshl_add_u64 v[10:11], v[10:11], 0, v[104:105]
	v_add_f32_e32 v0, 1.0, v0
	global_store_dwordx4 v[10:11], v[2:5], off
	s_waitcnt lgkmcnt(0)
	v_lshlrev_b32_e32 v14, 16, v6
	v_and_b32_e32 v11, 0xffff0000, v67
	v_rcp_f32_e32 v2, v0
	v_add_f32_e32 v0, 1.0, v13
	v_rcp_f32_e32 v3, v0
	v_and_b32_e32 v13, 0xffff0000, v6
	v_mul_f32_e64 v4, v14, v12
	v_mul_f32_e64 v5, v15, v13
	v_lshlrev_b32_e32 v10, 16, v7
	v_mul_f32_e64 v2, v2, v4
	v_mul_f32_e64 v3, v3, v5
	v_lshlrev_b32_e32 v4, 16, v67
	v_mul_f32_e32 v0, 0xbfb8aa3b, v4
	v_exp_f32_e32 v0, v0
	v_mul_f32_e32 v5, 0xbfb8aa3b, v11
	v_exp_f32_e32 v5, v5
	v_lshlrev_b32_e32 v6, 16, v68
	v_add_f32_e32 v0, 1.0, v0
	v_rcp_f32_e32 v12, v0
	v_add_f32_e32 v0, 1.0, v5
	v_and_b32_e32 v5, 0xffff0000, v7
	v_rcp_f32_e32 v13, v0
	v_mul_f32_e64 v4, v10, v4
	v_mul_f32_e64 v5, v11, v5
	v_and_b32_e32 v11, 0xffff0000, v68
	v_mul_f32_e32 v0, 0xbfb8aa3b, v6
	v_cvt_pk_bf16_f32 v2, v2, v3
	v_exp_f32_e32 v0, v0
	v_mul_f32_e32 v3, 0xbfb8aa3b, v11
	v_exp_f32_e32 v7, v3
	v_mul_f32_e64 v4, v12, v4
	v_mul_f32_e64 v5, v13, v5
	v_add_f32_e32 v0, 1.0, v0
	v_cvt_pk_bf16_f32 v3, v4, v5
	v_rcp_f32_e32 v4, v0
	v_add_f32_e32 v0, 1.0, v7
	v_rcp_f32_e32 v5, v0
	v_and_b32_e32 v7, 0xffff0000, v8
	v_lshlrev_b32_e32 v10, 16, v8
	v_mul_f32_e64 v6, v10, v6
	v_mul_f32_e64 v7, v11, v7
	v_and_b32_e32 v11, 0xffff0000, v69
	v_mul_f32_e64 v4, v4, v6
	v_mul_f32_e64 v5, v5, v7
	v_lshlrev_b32_e32 v6, 16, v69
	v_mul_f32_e32 v0, 0xbfb8aa3b, v6
	v_exp_f32_e32 v0, v0
	v_mul_f32_e32 v7, 0xbfb8aa3b, v11
	v_exp_f32_e32 v7, v7
	v_lshlrev_b32_e32 v10, 16, v9
	v_add_f32_e32 v0, 1.0, v0
	v_rcp_f32_e32 v12, v0
	v_add_f32_e32 v0, 1.0, v7
	v_rcp_f32_e32 v13, v0
	v_and_b32_e32 v7, 0xffff0000, v9
	v_mul_f32_e64 v6, v10, v6
	v_mul_f32_e64 v7, v11, v7
	v_cvt_pk_bf16_f32 v4, v4, v5
	v_mul_f32_e64 v6, v12, v6
	v_mul_f32_e64 v7, v13, v7
	s_nop 0
	v_cvt_pk_bf16_f32 v5, v6, v7
	v_lshlrev_b64 v[6:7], 12, v[98:99]
	v_lshl_add_u64 v[6:7], s[0:1], 0, v[6:7]
	v_lshl_add_u64 v[6:7], v[6:7], 0, v[100:101]
	global_store_dwordx4 v[6:7], v[2:5], off
	s_barrier
	s_cbranch_scc0 .LBB0_662

.LBB0_649:
	s_add_i32 s27, s0, -2
	s_and_b32 s27, s27, 1
	s_xor_b32 s34, s27, 1
	s_mul_i32 s35, s34, 0x4400
	s_add_i32 s35, s35, 0
	s_mulk_i32 s34, 0xc00
	s_add_i32 s34, s35, s34
	v_add3_u32 v0, s35, v157, v158
	s_waitcnt vmcnt(3)
	ds_write_b128 v0, v[130:133]
	v_add3_u32 v0, s68, v159, v158
	s_waitcnt vmcnt(2)
	ds_write_b128 v0, v[134:137] offset:34816
	v_add3_u32 v0, s35, v160, v161
	s_cmp_lt_u32 s0, s1
	s_waitcnt vmcnt(1)
	ds_write_b128 v0, v[138:141]
	v_add3_u32 v0, s68, v147, v161
	s_cselect_b32 s34, s0, s6
	s_lshl_b32 s34, s34, 20
	s_add_u32 s80, s78, s34
	s_addc_u32 s81, s79, 0
	s_add_u32 s80, s80, 0x1000
	s_addc_u32 s81, s81, 0
	s_add_u32 s82, s80, 0x1000
	s_addc_u32 s83, s81, 0
	s_waitcnt vmcnt(0)
	ds_write_b128 v0, v[142:145] offset:34816
	global_load_dwordx4 v[130:133], v150, s[80:81]
	global_load_dwordx4 v[134:137], v150, s[82:83]
	s_sub_i32 s34, s26, 63
	s_cmp_gt_i32 s34, s5
	global_load_dwordx4 v[138:141], v152, s[80:81]
	global_load_dwordx4 v[142:145], v152, s[82:83]
	s_sub_i32 s34, s26, 63
	s_cmp_gt_i32 s34, s5
	s_cbranch_scc1 .Lff1a_inact
	s_cmp_eq_u32 s72, 0
	s_cbranch_scc1 .Lff1a_first
	s_mul_i32 s34, s27, 0x4400
	v_add_u32_e32 v0, s34, v162
	ds_read_b128 v[198:201], v0
	ds_read_b128 v[202:205], v0 offset:32
	ds_read_b128 v[206:209], v0 offset:8704
	ds_read_b128 v[210:213], v0 offset:8736
	s_add_i32 s75, s4, 0x12800
	v_add_u32_e32 v246, s75, v149
	ds_read_b128 v[218:221], v246
	ds_read_b128 v[234:237], v246 offset:128
	ds_read_b128 v[222:225], v246 offset:32
	ds_read_b128 v[238:241], v246 offset:160
	ds_read_b128 v[226:229], v246 offset:64
	ds_read_b128 v[242:245], v246 offset:192
	ds_read_b128 v[230:233], v246 offset:96
	ds_read_b128 v[246:249], v246 offset:224
	s_waitcnt lgkmcnt(1)
	v_mfma_f32_32x32x16_bf16 v[218:233], v[198:201], v[98:101], v[218:233]
	v_sub_f32_e32 v82, v82, v197
	v_sub_f32_e32 v83, v83, v197
	v_sub_f32_e32 v84, v84, v197
	v_sub_f32_e32 v85, v85, v197
	v_exp_f32_e32 v82, v82
	v_exp_f32_e32 v83, v83
	v_exp_f32_e32 v84, v84
	v_exp_f32_e32 v85, v85
	s_waitcnt lgkmcnt(0)
	v_mfma_f32_32x32x16_bf16 v[234:249], v[206:209], v[98:101], v[234:249]
	v_sub_f32_e32 v86, v86, v197
	v_sub_f32_e32 v87, v87, v197
	v_sub_f32_e32 v88, v88, v197
	v_sub_f32_e32 v89, v89, v197
	v_exp_f32_e32 v86, v86
	v_exp_f32_e32 v87, v87
	v_exp_f32_e32 v88, v88
	v_exp_f32_e32 v89, v89
	v_mfma_f32_32x32x16_bf16 v[218:233], v[202:205], v[102:105], v[218:233]
	v_sub_f32_e32 v66, v66, v197
	v_sub_f32_e32 v67, v67, v197
	v_sub_f32_e32 v68, v68, v197
	v_sub_f32_e32 v69, v69, v197
	v_exp_f32_e32 v66, v66
	v_exp_f32_e32 v67, v67
	v_exp_f32_e32 v68, v68
	v_exp_f32_e32 v69, v69
	ds_read_b128 v[198:201], v0 offset:64
	ds_read_b128 v[202:205], v0 offset:96
	ds_read_b128 v[206:209], v0 offset:8768
	ds_read_b128 v[214:217], v0 offset:8800
	v_mfma_f32_32x32x16_bf16 v[234:249], v[210:213], v[102:105], v[234:249]
	v_add_f32_e32 v250, v82, v86
	v_add_f32_e32 v251, v83, v87
	v_add_f32_e32 v252, v84, v88
	v_add_f32_e32 v253, v85, v89
	v_sub_f32_e32 v70, v70, v197
	v_sub_f32_e32 v71, v71, v197
	v_sub_f32_e32 v72, v72, v197
	v_sub_f32_e32 v73, v73, v197
	s_waitcnt lgkmcnt(3)
	v_mfma_f32_32x32x16_bf16 v[218:233], v[198:201], v[106:109], v[218:233]
	v_exp_f32_e32 v70, v70
	v_exp_f32_e32 v71, v71
	v_exp_f32_e32 v72, v72
	v_exp_f32_e32 v73, v73
	v_add_f32_e32 v250, v250, v66
	v_add_f32_e32 v251, v251, v67
	v_add_f32_e32 v252, v252, v68
	v_add_f32_e32 v253, v253, v69
	s_waitcnt lgkmcnt(1)
	v_mfma_f32_32x32x16_bf16 v[234:249], v[206:209], v[106:109], v[234:249]
	v_sub_f32_e32 v90, v90, v197
	v_sub_f32_e32 v91, v91, v197
	v_sub_f32_e32 v92, v92, v197
	v_sub_f32_e32 v93, v93, v197
	v_exp_f32_e32 v90, v90
	v_exp_f32_e32 v91, v91
	v_exp_f32_e32 v92, v92
	v_exp_f32_e32 v93, v93
	v_mfma_f32_32x32x16_bf16 v[218:233], v[202:205], v[110:113], v[218:233]
	v_add_f32_e32 v250, v250, v70
	v_add_f32_e32 v251, v251, v71
	v_add_f32_e32 v252, v252, v72
	v_add_f32_e32 v253, v253, v73
	v_sub_f32_e32 v94, v94, v197
	v_sub_f32_e32 v95, v95, v197
	v_sub_f32_e32 v96, v96, v197
	v_sub_f32_e32 v97, v97, v197
	ds_read_b128 v[198:201], v0 offset:128
	ds_read_b128 v[202:205], v0 offset:160
	ds_read_b128 v[206:209], v0 offset:8832
	ds_read_b128 v[210:213], v0 offset:8864
	s_waitcnt lgkmcnt(4)
	v_mfma_f32_32x32x16_bf16 v[234:249], v[214:217], v[110:113], v[234:249]
	v_exp_f32_e32 v94, v94
	v_exp_f32_e32 v95, v95
	v_exp_f32_e32 v96, v96
	v_exp_f32_e32 v97, v97
	v_add_f32_e32 v250, v250, v90
	v_add_f32_e32 v251, v251, v91
	v_add_f32_e32 v252, v252, v92
	v_add_f32_e32 v253, v253, v93
	s_waitcnt lgkmcnt(3)
	v_mfma_f32_32x32x16_bf16 v[218:233], v[198:201], v[114:117], v[218:233]
	v_sub_f32_e32 v74, v74, v197
	v_sub_f32_e32 v75, v75, v197
	v_sub_f32_e32 v76, v76, v197
	v_sub_f32_e32 v77, v77, v197
	v_exp_f32_e32 v74, v74
	v_exp_f32_e32 v75, v75
	v_exp_f32_e32 v76, v76
	v_exp_f32_e32 v77, v77
	s_waitcnt lgkmcnt(1)
	v_mfma_f32_32x32x16_bf16 v[234:249], v[206:209], v[114:117], v[234:249]
	v_add_f32_e32 v250, v250, v94
	v_add_f32_e32 v251, v251, v95
	v_add_f32_e32 v252, v252, v96
	v_add_f32_e32 v253, v253, v97
	v_sub_f32_e32 v78, v78, v197
	v_sub_f32_e32 v79, v79, v197
	v_sub_f32_e32 v80, v80, v197
	v_sub_f32_e32 v81, v81, v197
	v_mfma_f32_32x32x16_bf16 v[218:233], v[202:205], v[118:121], v[218:233]
	v_exp_f32_e32 v78, v78
	v_exp_f32_e32 v79, v79
	v_exp_f32_e32 v80, v80
	v_exp_f32_e32 v81, v81
	v_add_f32_e32 v250, v250, v74
	v_add_f32_e32 v251, v251, v75
	v_add_f32_e32 v252, v252, v76
	v_add_f32_e32 v253, v253, v77
	ds_read_b128 v[198:201], v0 offset:192
	ds_read_b128 v[202:205], v0 offset:224
	ds_read_b128 v[206:209], v0 offset:8896
	ds_read_b128 v[214:217], v0 offset:8928
	s_waitcnt lgkmcnt(4)
	v_mfma_f32_32x32x16_bf16 v[234:249], v[210:213], v[118:121], v[234:249]
	v_add_f32_e32 v250, v250, v78
	v_add_f32_e32 v251, v251, v79
	v_add_f32_e32 v252, v252, v80
	v_add_f32_e32 v253, v253, v81
	v_add_f32_e32 v250, v250, v251
	v_add_f32_e32 v252, v252, v253
	v_add_f32_e32 v250, v250, v252
	v_add_f32_e32 v196, v196, v250
	s_waitcnt lgkmcnt(3)
	v_mfma_f32_32x32x16_bf16 v[218:233], v[198:201], v[122:125], v[218:233]
	v_cvt_pk_bf16_f32 v73, v72, v73
	v_cvt_pk_bf16_f32 v72, v70, v71
	v_cvt_pk_bf16_f32 v71, v68, v69
	v_cvt_pk_bf16_f32 v70, v66, v67
	v_cvt_pk_bf16_f32 v66, v82, v83
	v_cvt_pk_bf16_f32 v67, v84, v85
	v_cvt_pk_bf16_f32 v68, v86, v87
	v_cvt_pk_bf16_f32 v69, v88, v89
	s_waitcnt lgkmcnt(1)
	v_mfma_f32_32x32x16_bf16 v[234:249], v[206:209], v[122:125], v[234:249]
	v_cvt_pk_bf16_f32 v81, v80, v81
	v_cvt_pk_bf16_f32 v80, v78, v79
	v_cvt_pk_bf16_f32 v79, v76, v77
	v_cvt_pk_bf16_f32 v78, v74, v75
	v_cvt_pk_bf16_f32 v74, v90, v91
	v_cvt_pk_bf16_f32 v75, v92, v93
	v_cvt_pk_bf16_f32 v76, v94, v95
	v_cvt_pk_bf16_f32 v77, v96, v97
	v_mfma_f32_32x32x16_bf16 v[218:233], v[202:205], v[126:129], v[218:233]
	s_waitcnt lgkmcnt(0)
	v_mfma_f32_32x32x16_bf16 v[234:249], v[214:217], v[126:129], v[234:249]
	s_cmp_le_i32 s26, s5
	s_cbranch_scc1 .Lff1a_z2
	v_cmp_le_i32_e32 vcc, v165, v195
	s_nop 8
	v_cndmask_b32_e32 v234, v155, v234, vcc
	v_cmp_lt_i32_e32 vcc, v163, v195
	s_nop 1
	v_cndmask_b32_e32 v219, v155, v219, vcc
	v_cmp_le_i32_e32 vcc, v163, v195
	s_nop 1
	v_cndmask_b32_e32 v218, v155, v218, vcc
	v_cmp_le_i32_e32 vcc, v166, v195
	s_nop 1
	v_cndmask_b32_e32 v235, v155, v235, vcc
	v_cmp_le_i32_e32 vcc, v167, v195
	s_nop 1
	v_cndmask_b32_e32 v220, v155, v220, vcc
	v_cmp_le_i32_e32 vcc, v168, v195
	s_nop 1
	v_cndmask_b32_e32 v236, v155, v236, vcc
	v_cmp_le_i32_e32 vcc, v169, v195
	s_nop 1
	v_cndmask_b32_e32 v221, v155, v221, vcc
	v_cmp_le_i32_e32 vcc, v170, v195
	s_nop 1
	v_cndmask_b32_e32 v237, v155, v237, vcc
	v_cmp_le_i32_e32 vcc, v171, v195
	s_nop 1
	v_cndmask_b32_e32 v222, v155, v222, vcc
	v_cmp_le_i32_e32 vcc, v172, v195
	s_nop 1
	v_cndmask_b32_e32 v238, v155, v238, vcc
	v_cmp_le_i32_e32 vcc, v173, v195
	s_nop 1
	v_cndmask_b32_e32 v223, v155, v223, vcc
	v_cmp_le_i32_e32 vcc, v174, v195
	s_nop 1
	v_cndmask_b32_e32 v239, v155, v239, vcc
	v_cmp_le_i32_e32 vcc, v175, v195
	s_nop 1
	v_cndmask_b32_e32 v224, v155, v224, vcc
	v_cmp_le_i32_e32 vcc, v176, v195
	s_nop 1
	v_cndmask_b32_e32 v240, v155, v240, vcc
	v_cmp_le_i32_e32 vcc, v177, v195
	s_nop 1
	v_cndmask_b32_e32 v225, v155, v225, vcc
	v_cmp_le_i32_e32 vcc, v178, v195
	s_nop 1
	v_cndmask_b32_e32 v241, v155, v241, vcc
	v_cmp_le_i32_e32 vcc, v179, v195
	s_nop 1
	v_cndmask_b32_e32 v226, v155, v226, vcc
	v_cmp_le_i32_e32 vcc, v180, v195
	s_nop 1
	v_cndmask_b32_e32 v242, v155, v242, vcc
	v_cmp_le_i32_e32 vcc, v181, v195
	s_nop 1
	v_cndmask_b32_e32 v227, v155, v227, vcc
	v_cmp_le_i32_e32 vcc, v182, v195
	s_nop 1
	v_cndmask_b32_e32 v243, v155, v243, vcc
	v_cmp_le_i32_e32 vcc, v183, v195
	s_nop 1
	v_cndmask_b32_e32 v228, v155, v228, vcc
	v_cmp_le_i32_e32 vcc, v184, v195
	s_nop 1
	v_cndmask_b32_e32 v244, v155, v244, vcc
	v_cmp_le_i32_e32 vcc, v185, v195
	s_nop 1
	v_cndmask_b32_e32 v229, v155, v229, vcc
	v_cmp_le_i32_e32 vcc, v186, v195
	s_nop 1
	v_cndmask_b32_e32 v245, v155, v245, vcc
	v_cmp_le_i32_e32 vcc, v187, v195
	s_nop 1
	v_cndmask_b32_e32 v230, v155, v230, vcc
	v_cmp_le_i32_e32 vcc, v188, v195
	s_nop 1
	v_cndmask_b32_e32 v246, v155, v246, vcc
	v_cmp_le_i32_e32 vcc, v189, v195
	s_nop 1
	v_cndmask_b32_e32 v231, v155, v231, vcc
	v_cmp_le_i32_e32 vcc, v190, v195
	s_nop 1
	v_cndmask_b32_e32 v247, v155, v247, vcc
	v_cmp_le_i32_e32 vcc, v191, v195
	s_nop 1
	v_cndmask_b32_e32 v232, v155, v232, vcc
	v_cmp_le_i32_e32 vcc, v192, v195
	s_nop 1
	v_cndmask_b32_e32 v248, v155, v248, vcc
	v_cmp_le_i32_e32 vcc, v193, v195
	s_nop 1
	v_cndmask_b32_e32 v233, v155, v233, vcc
	v_cmp_le_i32_e32 vcc, v194, v195
	s_nop 1
	v_cndmask_b32_e32 v249, v155, v249, vcc
.Lff1a_z2:
	v_add_u32_e32 v250, s70, v164
	ds_read_b64_tr_b16 v[82:83], v250 offset:34816
	ds_read_b64_tr_b16 v[84:85], v250 offset:37376
	ds_read_b64_tr_b16 v[86:87], v250 offset:39936
	ds_read_b64_tr_b16 v[88:89], v250 offset:42496
	ds_read_b64_tr_b16 v[90:91], v250 offset:45056
	ds_read_b64_tr_b16 v[92:93], v250 offset:47616
	ds_read_b64_tr_b16 v[94:95], v250 offset:50176
	ds_read_b64_tr_b16 v[96:97], v250 offset:52736
	s_waitcnt lgkmcnt(6)
	v_mfma_f32_32x32x16_bf16 v[50:65], v[82:85], v[66:69], v[50:65]
	s_waitcnt lgkmcnt(4)
	v_mfma_f32_32x32x16_bf16 v[50:65], v[86:89], v[74:77], v[50:65]
	v_max3_f32 v0, v218, v234, v219
	v_max3_f32 v251, v222, v238, v223
	v_max3_f32 v252, v226, v242, v227
	s_waitcnt lgkmcnt(2)
	v_mfma_f32_32x32x16_bf16 v[50:65], v[90:93], v[70:73], v[50:65]
	v_max3_f32 v253, v230, v246, v231
	v_max3_f32 v0, v0, v235, v220
	v_max3_f32 v251, v251, v239, v224
	ds_read_b64_tr_b16 v[82:83], v250 offset:34880
	ds_read_b64_tr_b16 v[84:85], v250 offset:37440
	ds_read_b64_tr_b16 v[86:87], v250 offset:40000
	ds_read_b64_tr_b16 v[88:89], v250 offset:42560
	ds_read_b64_tr_b16 v[90:91], v250 offset:45120
	ds_read_b64_tr_b16 v[92:93], v250 offset:47680
	ds_read_b64_tr_b16 v[198:199], v250 offset:50240
	ds_read_b64_tr_b16 v[200:201], v250 offset:52800
	s_waitcnt lgkmcnt(8)
	v_mfma_f32_32x32x16_bf16 v[50:65], v[94:97], v[78:81], v[50:65]
	v_max3_f32 v252, v252, v243, v228
	v_max3_f32 v253, v253, v247, v232
	v_max3_f32 v0, v0, v236, v221
	s_waitcnt lgkmcnt(6)
	v_mfma_f32_32x32x16_bf16 v[34:49], v[82:85], v[66:69], v[34:49]
	v_max3_f32 v251, v251, v240, v225
	v_max3_f32 v252, v252, v244, v229
	v_max3_f32 v253, v253, v248, v233
	s_waitcnt lgkmcnt(4)
	v_mfma_f32_32x32x16_bf16 v[34:49], v[86:89], v[74:77], v[34:49]
	v_max_f32_e32 v0, v0, v237
	v_max_f32_e32 v251, v251, v241
	v_max_f32_e32 v252, v252, v245
	s_waitcnt lgkmcnt(2)
	v_mfma_f32_32x32x16_bf16 v[34:49], v[90:93], v[70:73], v[34:49]
	v_max_f32_e32 v253, v253, v249
	v_max3_f32 v0, v0, v251, v252
	v_max_f32_e32 v0, v0, v253
	ds_read_b64_tr_b16 v[82:83], v250 offset:34944
	ds_read_b64_tr_b16 v[84:85], v250 offset:37504
	ds_read_b64_tr_b16 v[86:87], v250 offset:40064
	ds_read_b64_tr_b16 v[88:89], v250 offset:42624
	ds_read_b64_tr_b16 v[90:91], v250 offset:45184
	ds_read_b64_tr_b16 v[92:93], v250 offset:47744
	ds_read_b64_tr_b16 v[94:95], v250 offset:50304
	ds_read_b64_tr_b16 v[96:97], v250 offset:52864
	s_waitcnt lgkmcnt(8)
	v_mfma_f32_32x32x16_bf16 v[34:49], v[198:201], v[78:81], v[34:49]
	s_nop 0
	v_mov_b32_e32 v251, v0
	v_nop
	s_waitcnt lgkmcnt(6)
	v_mfma_f32_32x32x16_bf16 v[18:33], v[82:85], v[66:69], v[18:33]
	v_nop
	v_permlane32_swap_b32 v0, v251
	s_nop 0
	s_waitcnt lgkmcnt(4)
	v_mfma_f32_32x32x16_bf16 v[18:33], v[86:89], v[74:77], v[18:33]
	v_max_f32_e32 v0, v0, v251
	v_add_f32_e32 v251, 0x42800000, v197
	v_cmp_gt_f32_e32 vcc, v0, v251
	s_waitcnt lgkmcnt(2)
	v_mfma_f32_32x32x16_bf16 v[18:33], v[90:93], v[70:73], v[18:33]
	ds_read_b64_tr_b16 v[82:83], v250 offset:35008
	ds_read_b64_tr_b16 v[84:85], v250 offset:37568
	ds_read_b64_tr_b16 v[86:87], v250 offset:40128
	ds_read_b64_tr_b16 v[88:89], v250 offset:42688
	ds_read_b64_tr_b16 v[90:91], v250 offset:45248
	ds_read_b64_tr_b16 v[92:93], v250 offset:47808
	ds_read_b64_tr_b16 v[198:199], v250 offset:50368
	ds_read_b64_tr_b16 v[200:201], v250 offset:52928
	s_waitcnt lgkmcnt(8)
	v_mfma_f32_32x32x16_bf16 v[18:33], v[94:97], v[78:81], v[18:33]
	s_waitcnt lgkmcnt(6)
	v_mfma_f32_32x32x16_bf16 v[2:17], v[82:85], v[66:69], v[2:17]
	s_waitcnt lgkmcnt(4)
	v_mfma_f32_32x32x16_bf16 v[2:17], v[86:89], v[74:77], v[2:17]
	s_waitcnt lgkmcnt(2)
	v_mfma_f32_32x32x16_bf16 v[2:17], v[90:93], v[70:73], v[2:17]
	s_waitcnt lgkmcnt(0)
	v_mfma_f32_32x32x16_bf16 v[2:17], v[198:201], v[78:81], v[2:17]
	s_branch .Lff1a_copy
.Lff1a_first:
	s_mul_i32 s34, s27, 0x4400
	v_add_u32_e32 v0, s34, v162
	ds_read_b128 v[198:201], v0
	ds_read_b128 v[202:205], v0 offset:32
	ds_read_b128 v[206:209], v0 offset:8704
	ds_read_b128 v[210:213], v0 offset:8736
	s_add_i32 s75, s4, 0x12800
	v_add_u32_e32 v246, s75, v149
	ds_read_b128 v[218:221], v246
	ds_read_b128 v[234:237], v246 offset:128
	ds_read_b128 v[222:225], v246 offset:32
	ds_read_b128 v[238:241], v246 offset:160
	ds_read_b128 v[226:229], v246 offset:64
	ds_read_b128 v[242:245], v246 offset:192
	ds_read_b128 v[230:233], v246 offset:96
	ds_read_b128 v[246:249], v246 offset:224
	s_waitcnt lgkmcnt(1)
	v_mfma_f32_32x32x16_bf16 v[218:233], v[198:201], v[98:101], v[218:233]
	s_waitcnt lgkmcnt(0)
	v_mfma_f32_32x32x16_bf16 v[234:249], v[206:209], v[98:101], v[234:249]
	v_mfma_f32_32x32x16_bf16 v[218:233], v[202:205], v[102:105], v[218:233]
	ds_read_b128 v[198:201], v0 offset:64
	ds_read_b128 v[202:205], v0 offset:96
	ds_read_b128 v[206:209], v0 offset:8768
	ds_read_b128 v[214:217], v0 offset:8800
	v_mfma_f32_32x32x16_bf16 v[234:249], v[210:213], v[102:105], v[234:249]
	s_waitcnt lgkmcnt(3)
	v_mfma_f32_32x32x16_bf16 v[218:233], v[198:201], v[106:109], v[218:233]
	s_waitcnt lgkmcnt(1)
	v_mfma_f32_32x32x16_bf16 v[234:249], v[206:209], v[106:109], v[234:249]
	v_mfma_f32_32x32x16_bf16 v[218:233], v[202:205], v[110:113], v[218:233]
	ds_read_b128 v[198:201], v0 offset:128
	ds_read_b128 v[202:205], v0 offset:160
	ds_read_b128 v[206:209], v0 offset:8832
	ds_read_b128 v[210:213], v0 offset:8864
	s_waitcnt lgkmcnt(4)
	v_mfma_f32_32x32x16_bf16 v[234:249], v[214:217], v[110:113], v[234:249]
	s_waitcnt lgkmcnt(3)
	v_mfma_f32_32x32x16_bf16 v[218:233], v[198:201], v[114:117], v[218:233]
	s_waitcnt lgkmcnt(1)
	v_mfma_f32_32x32x16_bf16 v[234:249], v[206:209], v[114:117], v[234:249]
	v_mfma_f32_32x32x16_bf16 v[218:233], v[202:205], v[118:121], v[218:233]
	ds_read_b128 v[198:201], v0 offset:192
	ds_read_b128 v[202:205], v0 offset:224
	ds_read_b128 v[206:209], v0 offset:8896
	ds_read_b128 v[214:217], v0 offset:8928
	s_waitcnt lgkmcnt(4)
	v_mfma_f32_32x32x16_bf16 v[234:249], v[210:213], v[118:121], v[234:249]
	s_waitcnt lgkmcnt(3)
	v_mfma_f32_32x32x16_bf16 v[218:233], v[198:201], v[122:125], v[218:233]
	s_waitcnt lgkmcnt(1)
	v_mfma_f32_32x32x16_bf16 v[234:249], v[206:209], v[122:125], v[234:249]
	v_mfma_f32_32x32x16_bf16 v[218:233], v[202:205], v[126:129], v[218:233]
	s_waitcnt lgkmcnt(0)
	v_mfma_f32_32x32x16_bf16 v[234:249], v[214:217], v[126:129], v[234:249]
	s_cmp_le_i32 s26, s5
	s_cbranch_scc1 .Lff1a_m1
	v_cmp_le_i32_e32 vcc, v165, v195
	s_nop 8
	v_cndmask_b32_e32 v234, v155, v234, vcc
	v_cmp_lt_i32_e32 vcc, v163, v195
	s_nop 1
	v_cndmask_b32_e32 v219, v155, v219, vcc
	v_cmp_le_i32_e32 vcc, v163, v195
	s_nop 1
	v_cndmask_b32_e32 v218, v155, v218, vcc
	v_cmp_le_i32_e32 vcc, v166, v195
	s_nop 1
	v_cndmask_b32_e32 v235, v155, v235, vcc
	v_cmp_le_i32_e32 vcc, v167, v195
	s_nop 1
	v_cndmask_b32_e32 v220, v155, v220, vcc
	v_cmp_le_i32_e32 vcc, v168, v195
	s_nop 1
	v_cndmask_b32_e32 v236, v155, v236, vcc
	v_cmp_le_i32_e32 vcc, v169, v195
	s_nop 1
	v_cndmask_b32_e32 v221, v155, v221, vcc
	v_cmp_le_i32_e32 vcc, v170, v195
	s_nop 1
	v_cndmask_b32_e32 v237, v155, v237, vcc
	v_cmp_le_i32_e32 vcc, v171, v195
	s_nop 1
	v_cndmask_b32_e32 v222, v155, v222, vcc
	v_cmp_le_i32_e32 vcc, v172, v195
	s_nop 1
	v_cndmask_b32_e32 v238, v155, v238, vcc
	v_cmp_le_i32_e32 vcc, v173, v195
	s_nop 1
	v_cndmask_b32_e32 v223, v155, v223, vcc
	v_cmp_le_i32_e32 vcc, v174, v195
	s_nop 1
	v_cndmask_b32_e32 v239, v155, v239, vcc
	v_cmp_le_i32_e32 vcc, v175, v195
	s_nop 1
	v_cndmask_b32_e32 v224, v155, v224, vcc
	v_cmp_le_i32_e32 vcc, v176, v195
	s_nop 1
	v_cndmask_b32_e32 v240, v155, v240, vcc
	v_cmp_le_i32_e32 vcc, v177, v195
	s_nop 1
	v_cndmask_b32_e32 v225, v155, v225, vcc
	v_cmp_le_i32_e32 vcc, v178, v195
	s_nop 1
	v_cndmask_b32_e32 v241, v155, v241, vcc
	v_cmp_le_i32_e32 vcc, v179, v195
	s_nop 1
	v_cndmask_b32_e32 v226, v155, v226, vcc
	v_cmp_le_i32_e32 vcc, v180, v195
	s_nop 1
	v_cndmask_b32_e32 v242, v155, v242, vcc
	v_cmp_le_i32_e32 vcc, v181, v195
	s_nop 1
	v_cndmask_b32_e32 v227, v155, v227, vcc
	v_cmp_le_i32_e32 vcc, v182, v195
	s_nop 1
	v_cndmask_b32_e32 v243, v155, v243, vcc
	v_cmp_le_i32_e32 vcc, v183, v195
	s_nop 1
	v_cndmask_b32_e32 v228, v155, v228, vcc
	v_cmp_le_i32_e32 vcc, v184, v195
	s_nop 1
	v_cndmask_b32_e32 v244, v155, v244, vcc
	v_cmp_le_i32_e32 vcc, v185, v195
	s_nop 1
	v_cndmask_b32_e32 v229, v155, v229, vcc
	v_cmp_le_i32_e32 vcc, v186, v195
	s_nop 1
	v_cndmask_b32_e32 v245, v155, v245, vcc
	v_cmp_le_i32_e32 vcc, v187, v195
	s_nop 1
	v_cndmask_b32_e32 v230, v155, v230, vcc
	v_cmp_le_i32_e32 vcc, v188, v195
	s_nop 1
	v_cndmask_b32_e32 v246, v155, v246, vcc
	v_cmp_le_i32_e32 vcc, v189, v195
	s_nop 1
	v_cndmask_b32_e32 v231, v155, v231, vcc
	v_cmp_le_i32_e32 vcc, v190, v195
	s_nop 1
	v_cndmask_b32_e32 v247, v155, v247, vcc
	v_cmp_le_i32_e32 vcc, v191, v195
	s_nop 1
	v_cndmask_b32_e32 v232, v155, v232, vcc
	v_cmp_le_i32_e32 vcc, v192, v195
	s_nop 1
	v_cndmask_b32_e32 v248, v155, v248, vcc
	v_cmp_le_i32_e32 vcc, v193, v195
	s_nop 1
	v_cndmask_b32_e32 v233, v155, v233, vcc
	v_cmp_le_i32_e32 vcc, v194, v195
	s_nop 1
	v_cndmask_b32_e32 v249, v155, v249, vcc
.Lff1a_m1:
	s_nop 11
	v_max3_f32 v0, v218, v234, v219
	v_max3_f32 v251, v222, v238, v223
	v_max3_f32 v252, v226, v242, v227
	v_max3_f32 v253, v230, v246, v231
	v_max3_f32 v0, v0, v235, v220
	v_max3_f32 v251, v251, v239, v224
	v_max3_f32 v252, v252, v243, v228
	v_max3_f32 v253, v253, v247, v232
	v_max3_f32 v0, v0, v236, v221
	v_max3_f32 v251, v251, v240, v225
	v_max3_f32 v252, v252, v244, v229
	v_max3_f32 v253, v253, v248, v233
	v_max_f32_e32 v0, v0, v237
	v_max_f32_e32 v251, v251, v241
	v_max_f32_e32 v252, v252, v245
	v_max_f32_e32 v253, v253, v249
	v_max3_f32 v0, v0, v251, v252
	v_max_f32_e32 v0, v0, v253
	s_nop 0
	v_mov_b32_e32 v251, v0
	v_nop
	v_nop
	v_permlane32_swap_b32 v0, v251
	s_nop 0
	v_max_f32_e32 v0, v0, v251
	v_add_f32_e32 v251, 0x42800000, v197
	v_cmp_gt_f32_e32 vcc, v0, v251
.Lff1a_copy:
	s_nop 7
	s_cbranch_vccz .Lff1a_norsc
	v_max_f32_e32 v0, v0, v0
	v_max_f32_e32 v251, v197, v197
	v_max_f32_e32 v251, v251, v0
	v_sub_f32_e32 v252, v197, v251
	v_exp_f32_e32 v252, v252
	v_mov_b32_e32 v197, v251
	s_nop 0
	v_mul_f32_e32 v196, v196, v252
	s_nop 1
	v_mul_f32_e64 v64, v64, v252
	v_mul_f32_e64 v65, v65, v252
	v_mul_f32_e64 v62, v62, v252
	v_mul_f32_e64 v63, v63, v252
	v_mul_f32_e64 v60, v60, v252
	v_mul_f32_e64 v61, v61, v252
	v_mul_f32_e64 v58, v58, v252
	v_mul_f32_e64 v59, v59, v252
	v_mul_f32_e64 v56, v56, v252
	v_mul_f32_e64 v57, v57, v252
	v_mul_f32_e64 v54, v54, v252
	v_mul_f32_e64 v55, v55, v252
	v_mul_f32_e64 v52, v52, v252
	v_mul_f32_e64 v53, v53, v252
	v_mul_f32_e64 v50, v50, v252
	v_mul_f32_e64 v51, v51, v252
	v_mul_f32_e64 v48, v48, v252
	v_mul_f32_e64 v49, v49, v252
	v_mul_f32_e64 v46, v46, v252
	v_mul_f32_e64 v47, v47, v252
	v_mul_f32_e64 v44, v44, v252
	v_mul_f32_e64 v45, v45, v252
	v_mul_f32_e64 v42, v42, v252
	v_mul_f32_e64 v43, v43, v252
	v_mul_f32_e64 v40, v40, v252
	v_mul_f32_e64 v41, v41, v252
	v_mul_f32_e64 v38, v38, v252
	v_mul_f32_e64 v39, v39, v252
	v_mul_f32_e64 v36, v36, v252
	v_mul_f32_e64 v37, v37, v252
	v_mul_f32_e64 v34, v34, v252
	v_mul_f32_e64 v35, v35, v252
	v_mul_f32_e64 v32, v32, v252
	v_mul_f32_e64 v33, v33, v252
	v_mul_f32_e64 v30, v30, v252
	v_mul_f32_e64 v31, v31, v252
	v_mul_f32_e64 v28, v28, v252
	v_mul_f32_e64 v29, v29, v252
	v_mul_f32_e64 v26, v26, v252
	v_mul_f32_e64 v27, v27, v252
	v_mul_f32_e64 v24, v24, v252
	v_mul_f32_e64 v25, v25, v252
	v_mul_f32_e64 v22, v22, v252
	v_mul_f32_e64 v23, v23, v252
	v_mul_f32_e64 v20, v20, v252
	v_mul_f32_e64 v21, v21, v252
	v_mul_f32_e64 v18, v18, v252
	v_mul_f32_e64 v19, v19, v252
	v_mul_f32_e64 v16, v16, v252
	v_mul_f32_e64 v17, v17, v252
	v_mul_f32_e64 v14, v14, v252
	v_mul_f32_e64 v15, v15, v252
	v_mul_f32_e64 v12, v12, v252
	v_mul_f32_e64 v13, v13, v252
	v_mul_f32_e64 v10, v10, v252
	v_mul_f32_e64 v11, v11, v252
	v_mul_f32_e64 v8, v8, v252
	v_mul_f32_e64 v9, v9, v252
	v_mul_f32_e64 v6, v6, v252
	v_mul_f32_e64 v7, v7, v252
	v_mul_f32_e64 v4, v4, v252
	v_mul_f32_e64 v5, v5, v252
	v_mul_f32_e64 v2, v2, v252
	v_mul_f32_e64 v3, v3, v252

.Lff1b_top:
	s_add_i32 s27, s0, -2
	s_and_b32 s27, s27, 1
	s_xor_b32 s34, s27, 1
	s_mul_i32 s35, s34, 0x4400
	s_add_i32 s35, s35, 0
	s_mulk_i32 s34, 0xc00
	s_add_i32 s34, s35, s34
	v_add3_u32 v0, s35, v157, v158
	s_waitcnt vmcnt(3)
	ds_write_b128 v0, v[130:133]
	v_add3_u32 v0, s68, v159, v158
	s_waitcnt vmcnt(2)
	ds_write_b128 v0, v[134:137] offset:34816
	v_add3_u32 v0, s35, v160, v161
	s_cmp_lt_u32 s0, s1
	s_waitcnt vmcnt(1)
	ds_write_b128 v0, v[138:141]
	v_add3_u32 v0, s68, v147, v161
	s_cselect_b32 s34, s0, s6
	s_lshl_b32 s34, s34, 20
	s_add_u32 s80, s78, s34
	s_addc_u32 s81, s79, 0
	s_add_u32 s80, s80, 0x1000
	s_addc_u32 s81, s81, 0
	s_add_u32 s82, s80, 0x1000
	s_addc_u32 s83, s81, 0
	s_waitcnt vmcnt(0)
	ds_write_b128 v0, v[142:145] offset:34816
	global_load_dwordx4 v[130:133], v150, s[80:81]
	global_load_dwordx4 v[134:137], v150, s[82:83]
	s_sub_i32 s34, s26, 63
	s_cmp_gt_i32 s34, s5
	global_load_dwordx4 v[138:141], v152, s[80:81]
	global_load_dwordx4 v[142:145], v152, s[82:83]
	s_sub_i32 s34, s26, 63
	s_cmp_gt_i32 s34, s5
	s_cbranch_scc1 .Lff1b_inact
	s_cmp_eq_u32 s72, 0
	s_cbranch_scc1 .Lff1b_first
	s_mul_i32 s34, s27, 0x4400
	v_add_u32_e32 v0, s34, v162
	ds_read_b128 v[198:201], v0
	ds_read_b128 v[202:205], v0 offset:32
	ds_read_b128 v[206:209], v0 offset:8704
	ds_read_b128 v[210:213], v0 offset:8736
	s_add_i32 s75, s4, 0x12800
	v_add_u32_e32 v78, s75, v149
	ds_read_b128 v[82:85], v78
	ds_read_b128 v[66:69], v78 offset:128
	ds_read_b128 v[86:89], v78 offset:32
	ds_read_b128 v[70:73], v78 offset:160
	ds_read_b128 v[90:93], v78 offset:64
	ds_read_b128 v[74:77], v78 offset:192
	ds_read_b128 v[94:97], v78 offset:96
	ds_read_b128 v[78:81], v78 offset:224
	s_waitcnt lgkmcnt(1)
	v_mfma_f32_32x32x16_bf16 v[82:97], v[198:201], v[98:101], v[82:97]
	v_sub_f32_e32 v218, v218, v197
	v_sub_f32_e32 v219, v219, v197
	v_sub_f32_e32 v220, v220, v197
	v_sub_f32_e32 v221, v221, v197
	v_exp_f32_e32 v218, v218
	v_exp_f32_e32 v219, v219
	v_exp_f32_e32 v220, v220
	v_exp_f32_e32 v221, v221
	s_waitcnt lgkmcnt(0)
	v_mfma_f32_32x32x16_bf16 v[66:81], v[206:209], v[98:101], v[66:81]
	v_sub_f32_e32 v222, v222, v197
	v_sub_f32_e32 v223, v223, v197
	v_sub_f32_e32 v224, v224, v197
	v_sub_f32_e32 v225, v225, v197
	v_exp_f32_e32 v222, v222
	v_exp_f32_e32 v223, v223
	v_exp_f32_e32 v224, v224
	v_exp_f32_e32 v225, v225
	v_mfma_f32_32x32x16_bf16 v[82:97], v[202:205], v[102:105], v[82:97]
	v_sub_f32_e32 v234, v234, v197
	v_sub_f32_e32 v235, v235, v197
	v_sub_f32_e32 v236, v236, v197
	v_sub_f32_e32 v237, v237, v197
	v_exp_f32_e32 v234, v234
	v_exp_f32_e32 v235, v235
	v_exp_f32_e32 v236, v236
	v_exp_f32_e32 v237, v237
	ds_read_b128 v[198:201], v0 offset:64
	ds_read_b128 v[202:205], v0 offset:96
	ds_read_b128 v[206:209], v0 offset:8768
	ds_read_b128 v[214:217], v0 offset:8800
	v_mfma_f32_32x32x16_bf16 v[66:81], v[210:213], v[102:105], v[66:81]
	v_add_f32_e32 v250, v218, v222
	v_add_f32_e32 v251, v219, v223
	v_add_f32_e32 v252, v220, v224
	v_add_f32_e32 v253, v221, v225
	v_sub_f32_e32 v238, v238, v197
	v_sub_f32_e32 v239, v239, v197
	v_sub_f32_e32 v240, v240, v197
	v_sub_f32_e32 v241, v241, v197
	s_waitcnt lgkmcnt(3)
	v_mfma_f32_32x32x16_bf16 v[82:97], v[198:201], v[106:109], v[82:97]
	v_exp_f32_e32 v238, v238
	v_exp_f32_e32 v239, v239
	v_exp_f32_e32 v240, v240
	v_exp_f32_e32 v241, v241
	v_add_f32_e32 v250, v250, v234
	v_add_f32_e32 v251, v251, v235
	v_add_f32_e32 v252, v252, v236
	v_add_f32_e32 v253, v253, v237
	s_waitcnt lgkmcnt(1)
	v_mfma_f32_32x32x16_bf16 v[66:81], v[206:209], v[106:109], v[66:81]
	v_sub_f32_e32 v226, v226, v197
	v_sub_f32_e32 v227, v227, v197
	v_sub_f32_e32 v228, v228, v197
	v_sub_f32_e32 v229, v229, v197
	v_exp_f32_e32 v226, v226
	v_exp_f32_e32 v227, v227
	v_exp_f32_e32 v228, v228
	v_exp_f32_e32 v229, v229
	v_mfma_f32_32x32x16_bf16 v[82:97], v[202:205], v[110:113], v[82:97]
	v_add_f32_e32 v250, v250, v238
	v_add_f32_e32 v251, v251, v239
	v_add_f32_e32 v252, v252, v240
	v_add_f32_e32 v253, v253, v241
	v_sub_f32_e32 v230, v230, v197
	v_sub_f32_e32 v231, v231, v197
	v_sub_f32_e32 v232, v232, v197
	v_sub_f32_e32 v233, v233, v197
	ds_read_b128 v[198:201], v0 offset:128
	ds_read_b128 v[202:205], v0 offset:160
	ds_read_b128 v[206:209], v0 offset:8832
	ds_read_b128 v[210:213], v0 offset:8864
	s_waitcnt lgkmcnt(4)
	v_mfma_f32_32x32x16_bf16 v[66:81], v[214:217], v[110:113], v[66:81]
	v_exp_f32_e32 v230, v230
	v_exp_f32_e32 v231, v231
	v_exp_f32_e32 v232, v232
	v_exp_f32_e32 v233, v233
	v_add_f32_e32 v250, v250, v226
	v_add_f32_e32 v251, v251, v227
	v_add_f32_e32 v252, v252, v228
	v_add_f32_e32 v253, v253, v229
	s_waitcnt lgkmcnt(3)
	v_mfma_f32_32x32x16_bf16 v[82:97], v[198:201], v[114:117], v[82:97]
	v_sub_f32_e32 v242, v242, v197
	v_sub_f32_e32 v243, v243, v197
	v_sub_f32_e32 v244, v244, v197
	v_sub_f32_e32 v245, v245, v197
	v_exp_f32_e32 v242, v242
	v_exp_f32_e32 v243, v243
	v_exp_f32_e32 v244, v244
	v_exp_f32_e32 v245, v245
	s_waitcnt lgkmcnt(1)
	v_mfma_f32_32x32x16_bf16 v[66:81], v[206:209], v[114:117], v[66:81]
	v_add_f32_e32 v250, v250, v230
	v_add_f32_e32 v251, v251, v231
	v_add_f32_e32 v252, v252, v232
	v_add_f32_e32 v253, v253, v233
	v_sub_f32_e32 v246, v246, v197
	v_sub_f32_e32 v247, v247, v197
	v_sub_f32_e32 v248, v248, v197
	v_sub_f32_e32 v249, v249, v197
	v_mfma_f32_32x32x16_bf16 v[82:97], v[202:205], v[118:121], v[82:97]
	v_exp_f32_e32 v246, v246
	v_exp_f32_e32 v247, v247
	v_exp_f32_e32 v248, v248
	v_exp_f32_e32 v249, v249
	v_add_f32_e32 v250, v250, v242
	v_add_f32_e32 v251, v251, v243
	v_add_f32_e32 v252, v252, v244
	v_add_f32_e32 v253, v253, v245
	ds_read_b128 v[198:201], v0 offset:192
	ds_read_b128 v[202:205], v0 offset:224
	ds_read_b128 v[206:209], v0 offset:8896
	ds_read_b128 v[214:217], v0 offset:8928
	s_waitcnt lgkmcnt(4)
	v_mfma_f32_32x32x16_bf16 v[66:81], v[210:213], v[118:121], v[66:81]
	v_add_f32_e32 v250, v250, v246
	v_add_f32_e32 v251, v251, v247
	v_add_f32_e32 v252, v252, v248
	v_add_f32_e32 v253, v253, v249
	v_add_f32_e32 v250, v250, v251
	v_add_f32_e32 v252, v252, v253
	v_add_f32_e32 v250, v250, v252
	v_add_f32_e32 v196, v196, v250
	s_waitcnt lgkmcnt(3)
	v_mfma_f32_32x32x16_bf16 v[82:97], v[198:201], v[122:125], v[82:97]
	v_cvt_pk_bf16_f32 v241, v240, v241
	v_cvt_pk_bf16_f32 v240, v238, v239
	v_cvt_pk_bf16_f32 v239, v236, v237
	v_cvt_pk_bf16_f32 v238, v234, v235
	v_cvt_pk_bf16_f32 v234, v218, v219
	v_cvt_pk_bf16_f32 v235, v220, v221
	v_cvt_pk_bf16_f32 v236, v222, v223
	v_cvt_pk_bf16_f32 v237, v224, v225
	s_waitcnt lgkmcnt(1)
	v_mfma_f32_32x32x16_bf16 v[66:81], v[206:209], v[122:125], v[66:81]
	v_cvt_pk_bf16_f32 v249, v248, v249
	v_cvt_pk_bf16_f32 v248, v246, v247
	v_cvt_pk_bf16_f32 v247, v244, v245
	v_cvt_pk_bf16_f32 v246, v242, v243
	v_cvt_pk_bf16_f32 v242, v226, v227
	v_cvt_pk_bf16_f32 v243, v228, v229
	v_cvt_pk_bf16_f32 v244, v230, v231
	v_cvt_pk_bf16_f32 v245, v232, v233
	v_mfma_f32_32x32x16_bf16 v[82:97], v[202:205], v[126:129], v[82:97]
	s_waitcnt lgkmcnt(0)
	v_mfma_f32_32x32x16_bf16 v[66:81], v[214:217], v[126:129], v[66:81]
	s_cmp_le_i32 s26, s5
	s_cbranch_scc1 .Lff1b_z2
	v_cmp_le_i32_e32 vcc, v165, v195
	s_nop 8
	v_cndmask_b32_e32 v66, v155, v66, vcc
	v_cmp_lt_i32_e32 vcc, v163, v195
	s_nop 1
	v_cndmask_b32_e32 v83, v155, v83, vcc
	v_cmp_le_i32_e32 vcc, v163, v195
	s_nop 1
	v_cndmask_b32_e32 v82, v155, v82, vcc
	v_cmp_le_i32_e32 vcc, v166, v195
	s_nop 1
	v_cndmask_b32_e32 v67, v155, v67, vcc
	v_cmp_le_i32_e32 vcc, v167, v195
	s_nop 1
	v_cndmask_b32_e32 v84, v155, v84, vcc
	v_cmp_le_i32_e32 vcc, v168, v195
	s_nop 1
	v_cndmask_b32_e32 v68, v155, v68, vcc
	v_cmp_le_i32_e32 vcc, v169, v195
	s_nop 1
	v_cndmask_b32_e32 v85, v155, v85, vcc
	v_cmp_le_i32_e32 vcc, v170, v195
	s_nop 1
	v_cndmask_b32_e32 v69, v155, v69, vcc
	v_cmp_le_i32_e32 vcc, v171, v195
	s_nop 1
	v_cndmask_b32_e32 v86, v155, v86, vcc
	v_cmp_le_i32_e32 vcc, v172, v195
	s_nop 1
	v_cndmask_b32_e32 v70, v155, v70, vcc
	v_cmp_le_i32_e32 vcc, v173, v195
	s_nop 1
	v_cndmask_b32_e32 v87, v155, v87, vcc
	v_cmp_le_i32_e32 vcc, v174, v195
	s_nop 1
	v_cndmask_b32_e32 v71, v155, v71, vcc
	v_cmp_le_i32_e32 vcc, v175, v195
	s_nop 1
	v_cndmask_b32_e32 v88, v155, v88, vcc
	v_cmp_le_i32_e32 vcc, v176, v195
	s_nop 1
	v_cndmask_b32_e32 v72, v155, v72, vcc
	v_cmp_le_i32_e32 vcc, v177, v195
	s_nop 1
	v_cndmask_b32_e32 v89, v155, v89, vcc
	v_cmp_le_i32_e32 vcc, v178, v195
	s_nop 1
	v_cndmask_b32_e32 v73, v155, v73, vcc
	v_cmp_le_i32_e32 vcc, v179, v195
	s_nop 1
	v_cndmask_b32_e32 v90, v155, v90, vcc
	v_cmp_le_i32_e32 vcc, v180, v195
	s_nop 1
	v_cndmask_b32_e32 v74, v155, v74, vcc
	v_cmp_le_i32_e32 vcc, v181, v195
	s_nop 1
	v_cndmask_b32_e32 v91, v155, v91, vcc
	v_cmp_le_i32_e32 vcc, v182, v195
	s_nop 1
	v_cndmask_b32_e32 v75, v155, v75, vcc
	v_cmp_le_i32_e32 vcc, v183, v195
	s_nop 1
	v_cndmask_b32_e32 v92, v155, v92, vcc
	v_cmp_le_i32_e32 vcc, v184, v195
	s_nop 1
	v_cndmask_b32_e32 v76, v155, v76, vcc
	v_cmp_le_i32_e32 vcc, v185, v195
	s_nop 1
	v_cndmask_b32_e32 v93, v155, v93, vcc
	v_cmp_le_i32_e32 vcc, v186, v195
	s_nop 1
	v_cndmask_b32_e32 v77, v155, v77, vcc
	v_cmp_le_i32_e32 vcc, v187, v195
	s_nop 1
	v_cndmask_b32_e32 v94, v155, v94, vcc
	v_cmp_le_i32_e32 vcc, v188, v195
	s_nop 1
	v_cndmask_b32_e32 v78, v155, v78, vcc
	v_cmp_le_i32_e32 vcc, v189, v195
	s_nop 1
	v_cndmask_b32_e32 v95, v155, v95, vcc
	v_cmp_le_i32_e32 vcc, v190, v195
	s_nop 1
	v_cndmask_b32_e32 v79, v155, v79, vcc
	v_cmp_le_i32_e32 vcc, v191, v195
	s_nop 1
	v_cndmask_b32_e32 v96, v155, v96, vcc
	v_cmp_le_i32_e32 vcc, v192, v195
	s_nop 1
	v_cndmask_b32_e32 v80, v155, v80, vcc
	v_cmp_le_i32_e32 vcc, v193, v195
	s_nop 1
	v_cndmask_b32_e32 v97, v155, v97, vcc
	v_cmp_le_i32_e32 vcc, v194, v195
	s_nop 1
	v_cndmask_b32_e32 v81, v155, v81, vcc
.Lff1b_z2:
	v_add_u32_e32 v250, s70, v164
	ds_read_b64_tr_b16 v[218:219], v250 offset:34816
	ds_read_b64_tr_b16 v[220:221], v250 offset:37376
	ds_read_b64_tr_b16 v[222:223], v250 offset:39936
	ds_read_b64_tr_b16 v[224:225], v250 offset:42496
	ds_read_b64_tr_b16 v[226:227], v250 offset:45056
	ds_read_b64_tr_b16 v[228:229], v250 offset:47616
	ds_read_b64_tr_b16 v[230:231], v250 offset:50176
	ds_read_b64_tr_b16 v[232:233], v250 offset:52736
	s_waitcnt lgkmcnt(6)
	v_mfma_f32_32x32x16_bf16 v[50:65], v[218:221], v[234:237], v[50:65]
	s_waitcnt lgkmcnt(4)
	v_mfma_f32_32x32x16_bf16 v[50:65], v[222:225], v[242:245], v[50:65]
	v_max3_f32 v0, v82, v66, v83
	v_max3_f32 v251, v86, v70, v87
	v_max3_f32 v252, v90, v74, v91
	s_waitcnt lgkmcnt(2)
	v_mfma_f32_32x32x16_bf16 v[50:65], v[226:229], v[238:241], v[50:65]
	v_max3_f32 v253, v94, v78, v95
	v_max3_f32 v0, v0, v67, v84
	v_max3_f32 v251, v251, v71, v88
	ds_read_b64_tr_b16 v[218:219], v250 offset:34880
	ds_read_b64_tr_b16 v[220:221], v250 offset:37440
	ds_read_b64_tr_b16 v[222:223], v250 offset:40000
	ds_read_b64_tr_b16 v[224:225], v250 offset:42560
	ds_read_b64_tr_b16 v[226:227], v250 offset:45120
	ds_read_b64_tr_b16 v[228:229], v250 offset:47680
	ds_read_b64_tr_b16 v[198:199], v250 offset:50240
	ds_read_b64_tr_b16 v[200:201], v250 offset:52800
	s_waitcnt lgkmcnt(8)
	v_mfma_f32_32x32x16_bf16 v[50:65], v[230:233], v[246:249], v[50:65]
	v_max3_f32 v252, v252, v75, v92
	v_max3_f32 v253, v253, v79, v96
	v_max3_f32 v0, v0, v68, v85
	s_waitcnt lgkmcnt(6)
	v_mfma_f32_32x32x16_bf16 v[34:49], v[218:221], v[234:237], v[34:49]
	v_max3_f32 v251, v251, v72, v89
	v_max3_f32 v252, v252, v76, v93
	v_max3_f32 v253, v253, v80, v97
	s_waitcnt lgkmcnt(4)
	v_mfma_f32_32x32x16_bf16 v[34:49], v[222:225], v[242:245], v[34:49]
	v_max_f32_e32 v0, v0, v69
	v_max_f32_e32 v251, v251, v73
	v_max_f32_e32 v252, v252, v77
	s_waitcnt lgkmcnt(2)
	v_mfma_f32_32x32x16_bf16 v[34:49], v[226:229], v[238:241], v[34:49]
	v_max_f32_e32 v253, v253, v81
	v_max3_f32 v0, v0, v251, v252
	v_max_f32_e32 v0, v0, v253
	ds_read_b64_tr_b16 v[218:219], v250 offset:34944
	ds_read_b64_tr_b16 v[220:221], v250 offset:37504
	ds_read_b64_tr_b16 v[222:223], v250 offset:40064
	ds_read_b64_tr_b16 v[224:225], v250 offset:42624
	ds_read_b64_tr_b16 v[226:227], v250 offset:45184
	ds_read_b64_tr_b16 v[228:229], v250 offset:47744
	ds_read_b64_tr_b16 v[230:231], v250 offset:50304
	ds_read_b64_tr_b16 v[232:233], v250 offset:52864
	s_waitcnt lgkmcnt(8)
	v_mfma_f32_32x32x16_bf16 v[34:49], v[198:201], v[246:249], v[34:49]
	s_nop 0
	v_mov_b32_e32 v251, v0
	v_nop
	s_waitcnt lgkmcnt(6)
	v_mfma_f32_32x32x16_bf16 v[18:33], v[218:221], v[234:237], v[18:33]
	v_nop
	v_permlane32_swap_b32 v0, v251
	s_nop 0
	s_waitcnt lgkmcnt(4)
	v_mfma_f32_32x32x16_bf16 v[18:33], v[222:225], v[242:245], v[18:33]
	v_max_f32_e32 v0, v0, v251
	v_add_f32_e32 v251, 0x42800000, v197
	v_cmp_gt_f32_e32 vcc, v0, v251
	s_waitcnt lgkmcnt(2)
	v_mfma_f32_32x32x16_bf16 v[18:33], v[226:229], v[238:241], v[18:33]
	ds_read_b64_tr_b16 v[218:219], v250 offset:35008
	ds_read_b64_tr_b16 v[220:221], v250 offset:37568
	ds_read_b64_tr_b16 v[222:223], v250 offset:40128
	ds_read_b64_tr_b16 v[224:225], v250 offset:42688
	ds_read_b64_tr_b16 v[226:227], v250 offset:45248
	ds_read_b64_tr_b16 v[228:229], v250 offset:47808
	ds_read_b64_tr_b16 v[198:199], v250 offset:50368
	ds_read_b64_tr_b16 v[200:201], v250 offset:52928
	s_waitcnt lgkmcnt(8)
	v_mfma_f32_32x32x16_bf16 v[18:33], v[230:233], v[246:249], v[18:33]
	s_waitcnt lgkmcnt(6)
	v_mfma_f32_32x32x16_bf16 v[2:17], v[218:221], v[234:237], v[2:17]
	s_waitcnt lgkmcnt(4)
	v_mfma_f32_32x32x16_bf16 v[2:17], v[222:225], v[242:245], v[2:17]
	s_waitcnt lgkmcnt(2)
	v_mfma_f32_32x32x16_bf16 v[2:17], v[226:229], v[238:241], v[2:17]
	s_waitcnt lgkmcnt(0)
	v_mfma_f32_32x32x16_bf16 v[2:17], v[198:201], v[246:249], v[2:17]
	s_branch .Lff1b_copy
.Lff1b_first:
	s_mul_i32 s34, s27, 0x4400
	v_add_u32_e32 v0, s34, v162
	ds_read_b128 v[198:201], v0
	ds_read_b128 v[202:205], v0 offset:32
	ds_read_b128 v[206:209], v0 offset:8704
	ds_read_b128 v[210:213], v0 offset:8736
	s_add_i32 s75, s4, 0x12800
	v_add_u32_e32 v78, s75, v149
	ds_read_b128 v[82:85], v78
	ds_read_b128 v[66:69], v78 offset:128
	ds_read_b128 v[86:89], v78 offset:32
	ds_read_b128 v[70:73], v78 offset:160
	ds_read_b128 v[90:93], v78 offset:64
	ds_read_b128 v[74:77], v78 offset:192
	ds_read_b128 v[94:97], v78 offset:96
	ds_read_b128 v[78:81], v78 offset:224
	s_waitcnt lgkmcnt(1)
	v_mfma_f32_32x32x16_bf16 v[82:97], v[198:201], v[98:101], v[82:97]
	s_waitcnt lgkmcnt(0)
	v_mfma_f32_32x32x16_bf16 v[66:81], v[206:209], v[98:101], v[66:81]
	v_mfma_f32_32x32x16_bf16 v[82:97], v[202:205], v[102:105], v[82:97]
	ds_read_b128 v[198:201], v0 offset:64
	ds_read_b128 v[202:205], v0 offset:96
	ds_read_b128 v[206:209], v0 offset:8768
	ds_read_b128 v[214:217], v0 offset:8800
	v_mfma_f32_32x32x16_bf16 v[66:81], v[210:213], v[102:105], v[66:81]
	s_waitcnt lgkmcnt(3)
	v_mfma_f32_32x32x16_bf16 v[82:97], v[198:201], v[106:109], v[82:97]
	s_waitcnt lgkmcnt(1)
	v_mfma_f32_32x32x16_bf16 v[66:81], v[206:209], v[106:109], v[66:81]
	v_mfma_f32_32x32x16_bf16 v[82:97], v[202:205], v[110:113], v[82:97]
	ds_read_b128 v[198:201], v0 offset:128
	ds_read_b128 v[202:205], v0 offset:160
	ds_read_b128 v[206:209], v0 offset:8832
	ds_read_b128 v[210:213], v0 offset:8864
	s_waitcnt lgkmcnt(4)
	v_mfma_f32_32x32x16_bf16 v[66:81], v[214:217], v[110:113], v[66:81]
	s_waitcnt lgkmcnt(3)
	v_mfma_f32_32x32x16_bf16 v[82:97], v[198:201], v[114:117], v[82:97]
	s_waitcnt lgkmcnt(1)
	v_mfma_f32_32x32x16_bf16 v[66:81], v[206:209], v[114:117], v[66:81]
	v_mfma_f32_32x32x16_bf16 v[82:97], v[202:205], v[118:121], v[82:97]
	ds_read_b128 v[198:201], v0 offset:192
	ds_read_b128 v[202:205], v0 offset:224
	ds_read_b128 v[206:209], v0 offset:8896
	ds_read_b128 v[214:217], v0 offset:8928
	s_waitcnt lgkmcnt(4)
	v_mfma_f32_32x32x16_bf16 v[66:81], v[210:213], v[118:121], v[66:81]
	s_waitcnt lgkmcnt(3)
	v_mfma_f32_32x32x16_bf16 v[82:97], v[198:201], v[122:125], v[82:97]
	s_waitcnt lgkmcnt(1)
	v_mfma_f32_32x32x16_bf16 v[66:81], v[206:209], v[122:125], v[66:81]
	v_mfma_f32_32x32x16_bf16 v[82:97], v[202:205], v[126:129], v[82:97]
	s_waitcnt lgkmcnt(0)
	v_mfma_f32_32x32x16_bf16 v[66:81], v[214:217], v[126:129], v[66:81]
	s_cmp_le_i32 s26, s5
	s_cbranch_scc1 .Lff1b_m1
	v_cmp_le_i32_e32 vcc, v165, v195
	s_nop 8
	v_cndmask_b32_e32 v66, v155, v66, vcc
	v_cmp_lt_i32_e32 vcc, v163, v195
	s_nop 1
	v_cndmask_b32_e32 v83, v155, v83, vcc
	v_cmp_le_i32_e32 vcc, v163, v195
	s_nop 1
	v_cndmask_b32_e32 v82, v155, v82, vcc
	v_cmp_le_i32_e32 vcc, v166, v195
	s_nop 1
	v_cndmask_b32_e32 v67, v155, v67, vcc
	v_cmp_le_i32_e32 vcc, v167, v195
	s_nop 1
	v_cndmask_b32_e32 v84, v155, v84, vcc
	v_cmp_le_i32_e32 vcc, v168, v195
	s_nop 1
	v_cndmask_b32_e32 v68, v155, v68, vcc
	v_cmp_le_i32_e32 vcc, v169, v195
	s_nop 1
	v_cndmask_b32_e32 v85, v155, v85, vcc
	v_cmp_le_i32_e32 vcc, v170, v195
	s_nop 1
	v_cndmask_b32_e32 v69, v155, v69, vcc
	v_cmp_le_i32_e32 vcc, v171, v195
	s_nop 1
	v_cndmask_b32_e32 v86, v155, v86, vcc
	v_cmp_le_i32_e32 vcc, v172, v195
	s_nop 1
	v_cndmask_b32_e32 v70, v155, v70, vcc
	v_cmp_le_i32_e32 vcc, v173, v195
	s_nop 1
	v_cndmask_b32_e32 v87, v155, v87, vcc
	v_cmp_le_i32_e32 vcc, v174, v195
	s_nop 1
	v_cndmask_b32_e32 v71, v155, v71, vcc
	v_cmp_le_i32_e32 vcc, v175, v195
	s_nop 1
	v_cndmask_b32_e32 v88, v155, v88, vcc
	v_cmp_le_i32_e32 vcc, v176, v195
	s_nop 1
	v_cndmask_b32_e32 v72, v155, v72, vcc
	v_cmp_le_i32_e32 vcc, v177, v195
	s_nop 1
	v_cndmask_b32_e32 v89, v155, v89, vcc
	v_cmp_le_i32_e32 vcc, v178, v195
	s_nop 1
	v_cndmask_b32_e32 v73, v155, v73, vcc
	v_cmp_le_i32_e32 vcc, v179, v195
	s_nop 1
	v_cndmask_b32_e32 v90, v155, v90, vcc
	v_cmp_le_i32_e32 vcc, v180, v195
	s_nop 1
	v_cndmask_b32_e32 v74, v155, v74, vcc
	v_cmp_le_i32_e32 vcc, v181, v195
	s_nop 1
	v_cndmask_b32_e32 v91, v155, v91, vcc
	v_cmp_le_i32_e32 vcc, v182, v195
	s_nop 1
	v_cndmask_b32_e32 v75, v155, v75, vcc
	v_cmp_le_i32_e32 vcc, v183, v195
	s_nop 1
	v_cndmask_b32_e32 v92, v155, v92, vcc
	v_cmp_le_i32_e32 vcc, v184, v195
	s_nop 1
	v_cndmask_b32_e32 v76, v155, v76, vcc
	v_cmp_le_i32_e32 vcc, v185, v195
	s_nop 1
	v_cndmask_b32_e32 v93, v155, v93, vcc
	v_cmp_le_i32_e32 vcc, v186, v195
	s_nop 1
	v_cndmask_b32_e32 v77, v155, v77, vcc
	v_cmp_le_i32_e32 vcc, v187, v195
	s_nop 1
	v_cndmask_b32_e32 v94, v155, v94, vcc
	v_cmp_le_i32_e32 vcc, v188, v195
	s_nop 1
	v_cndmask_b32_e32 v78, v155, v78, vcc
	v_cmp_le_i32_e32 vcc, v189, v195
	s_nop 1
	v_cndmask_b32_e32 v95, v155, v95, vcc
	v_cmp_le_i32_e32 vcc, v190, v195
	s_nop 1
	v_cndmask_b32_e32 v79, v155, v79, vcc
	v_cmp_le_i32_e32 vcc, v191, v195
	s_nop 1
	v_cndmask_b32_e32 v96, v155, v96, vcc
	v_cmp_le_i32_e32 vcc, v192, v195
	s_nop 1
	v_cndmask_b32_e32 v80, v155, v80, vcc
	v_cmp_le_i32_e32 vcc, v193, v195
	s_nop 1
	v_cndmask_b32_e32 v97, v155, v97, vcc
	v_cmp_le_i32_e32 vcc, v194, v195
	s_nop 1
	v_cndmask_b32_e32 v81, v155, v81, vcc
.Lff1b_m1:
	s_nop 11
	v_max3_f32 v0, v82, v66, v83
	v_max3_f32 v251, v86, v70, v87
	v_max3_f32 v252, v90, v74, v91
	v_max3_f32 v253, v94, v78, v95
	v_max3_f32 v0, v0, v67, v84
	v_max3_f32 v251, v251, v71, v88
	v_max3_f32 v252, v252, v75, v92
	v_max3_f32 v253, v253, v79, v96
	v_max3_f32 v0, v0, v68, v85
	v_max3_f32 v251, v251, v72, v89
	v_max3_f32 v252, v252, v76, v93
	v_max3_f32 v253, v253, v80, v97
	v_max_f32_e32 v0, v0, v69
	v_max_f32_e32 v251, v251, v73
	v_max_f32_e32 v252, v252, v77
	v_max_f32_e32 v253, v253, v81
	v_max3_f32 v0, v0, v251, v252
	v_max_f32_e32 v0, v0, v253
	s_nop 0
	v_mov_b32_e32 v251, v0
	v_nop
	v_nop
	v_permlane32_swap_b32 v0, v251
	s_nop 0
	v_max_f32_e32 v0, v0, v251
	v_add_f32_e32 v251, 0x42800000, v197
	v_cmp_gt_f32_e32 vcc, v0, v251

.LBB0_654:
	s_setprio 0
	v_mov_b32_e32 v0, v196
	v_nop
	v_nop
	v_permlane32_swap_b32 v196, v0
	s_lshl_b32 s16, s16, 1
	v_add_f32_e32 v146, v196, v0
	v_ashrrev_i32_e32 v0, 31, v156
	v_lshrrev_b32_e32 v0, 28, v0
	v_add_u32_e32 v0, v156, v0
	s_waitcnt vmcnt(0)
	v_ashrrev_i32_e32 v144, 4, v0
	v_and_b32_e32 v0, -16, v0
	v_sub_u32_e32 v147, v156, v0
	v_lshlrev_b32_e32 v68, 3, v147
	v_ashrrev_i32_e32 v69, 31, v68
	v_add_u32_e32 v0, 64, v156
	v_lshlrev_b64 v[140:141], 1, v[68:69]
	v_ashrrev_i32_e32 v68, 31, v0
	v_lshrrev_b32_e32 v68, 28, v68
	v_ashrrev_i32_e32 v145, 31, v144
	v_add_u32_e32 v68, v0, v68
	v_lshl_add_u64 v[138:139], s[24:25], 0, v[144:145]
	v_ashrrev_i32_e32 v142, 4, v68
	v_lshlrev_b64 v[66:67], 14, v[138:139]
	v_and_b32_e32 v68, -16, v68
	v_ashrrev_i32_e32 v143, 31, v142
	v_lshl_add_u64 v[66:67], s[12:13], 0, v[66:67]
	v_sub_u32_e32 v145, v0, v68
	v_lshl_add_u64 v[132:133], s[24:25], 0, v[142:143]
	v_lshl_add_u64 v[66:67], v[66:67], 0, s[16:17]
	v_lshlrev_b64 v[68:69], 14, v[132:133]
	v_lshlrev_b32_e32 v70, 3, v145
	v_lshl_add_u64 v[66:67], v[66:67], 0, v[140:141]
	v_lshl_add_u64 v[68:69], s[12:13], 0, v[68:69]
	v_ashrrev_i32_e32 v71, 31, v70
	v_add_co_u32_e32 v66, vcc, s48, v66
	v_lshl_add_u64 v[68:69], v[68:69], 0, s[16:17]
	v_lshlrev_b64 v[134:135], 1, v[70:71]
	v_addc_co_u32_e32 v67, vcc, 0, v67, vcc
	v_lshl_add_u64 v[68:69], v[68:69], 0, v[134:135]
	v_add_co_u32_e32 v68, vcc, s48, v68
	v_add_u32_e32 v0, 0x80, v156
	s_nop 0
	v_addc_co_u32_e32 v69, vcc, 0, v69, vcc
	global_load_dwordx4 v[94:97], v[66:67], off
	global_load_dwordx4 v[90:93], v[68:69], off
	v_ashrrev_i32_e32 v66, 31, v0
	v_lshrrev_b32_e32 v66, 28, v66
	v_add_u32_e32 v66, v0, v66
	v_ashrrev_i32_e32 v136, 4, v66
	v_and_b32_e32 v66, -16, v66
	v_sub_u32_e32 v143, v0, v66
	v_lshlrev_b32_e32 v68, 3, v143
	v_ashrrev_i32_e32 v69, 31, v68
	v_add_u32_e32 v0, 0xc0, v156
	v_lshlrev_b64 v[128:129], 1, v[68:69]
	v_ashrrev_i32_e32 v68, 31, v0
	v_lshrrev_b32_e32 v68, 28, v68
	v_ashrrev_i32_e32 v137, 31, v136
	v_add_u32_e32 v68, v0, v68
	v_lshl_add_u64 v[126:127], s[24:25], 0, v[136:137]
	v_ashrrev_i32_e32 v130, 4, v68
	v_lshlrev_b64 v[66:67], 14, v[126:127]
	v_and_b32_e32 v68, -16, v68
	v_ashrrev_i32_e32 v131, 31, v130
	v_lshl_add_u64 v[66:67], s[12:13], 0, v[66:67]
	v_sub_u32_e32 v137, v0, v68
	v_lshl_add_u64 v[120:121], s[24:25], 0, v[130:131]
	v_lshl_add_u64 v[66:67], v[66:67], 0, s[16:17]
	v_lshlrev_b64 v[68:69], 14, v[120:121]
	v_lshlrev_b32_e32 v70, 3, v137
	v_lshl_add_u64 v[66:67], v[66:67], 0, v[128:129]
	v_lshl_add_u64 v[68:69], s[12:13], 0, v[68:69]
	v_ashrrev_i32_e32 v71, 31, v70
	v_add_co_u32_e32 v66, vcc, s48, v66
	v_lshl_add_u64 v[68:69], v[68:69], 0, s[16:17]
	v_lshlrev_b64 v[122:123], 1, v[70:71]
	v_addc_co_u32_e32 v67, vcc, 0, v67, vcc
	v_lshl_add_u64 v[68:69], v[68:69], 0, v[122:123]
	v_add_co_u32_e32 v68, vcc, s48, v68
	v_add_u32_e32 v0, 0x100, v156
	s_nop 0
	v_addc_co_u32_e32 v69, vcc, 0, v69, vcc
	global_load_dwordx4 v[86:89], v[66:67], off
	global_load_dwordx4 v[82:85], v[68:69], off
	v_ashrrev_i32_e32 v66, 31, v0
	v_lshrrev_b32_e32 v66, 28, v66
	v_add_u32_e32 v66, v0, v66
	v_ashrrev_i32_e32 v124, 4, v66
	v_and_b32_e32 v66, -16, v66
	v_sub_u32_e32 v131, v0, v66
	v_lshlrev_b32_e32 v68, 3, v131
	v_ashrrev_i32_e32 v69, 31, v68
	v_add_u32_e32 v0, 0x140, v156
	v_lshlrev_b64 v[116:117], 1, v[68:69]
	v_ashrrev_i32_e32 v68, 31, v0
	v_lshrrev_b32_e32 v68, 28, v68
	v_ashrrev_i32_e32 v125, 31, v124
	v_add_u32_e32 v68, v0, v68
	v_lshl_add_u64 v[114:115], s[24:25], 0, v[124:125]
	v_ashrrev_i32_e32 v118, 4, v68
	v_lshlrev_b64 v[66:67], 14, v[114:115]
	v_and_b32_e32 v68, -16, v68
	v_ashrrev_i32_e32 v119, 31, v118
	v_lshl_add_u64 v[66:67], s[12:13], 0, v[66:67]
	v_sub_u32_e32 v125, v0, v68
	v_lshl_add_u64 v[108:109], s[24:25], 0, v[118:119]
	v_lshl_add_u64 v[66:67], v[66:67], 0, s[16:17]
	v_lshlrev_b64 v[68:69], 14, v[108:109]
	v_lshlrev_b32_e32 v70, 3, v125
	v_lshl_add_u64 v[66:67], v[66:67], 0, v[116:117]
	v_lshl_add_u64 v[68:69], s[12:13], 0, v[68:69]
	v_ashrrev_i32_e32 v71, 31, v70
	v_add_co_u32_e32 v66, vcc, s48, v66
	v_lshl_add_u64 v[68:69], v[68:69], 0, s[16:17]
	v_lshlrev_b64 v[110:111], 1, v[70:71]
	v_addc_co_u32_e32 v67, vcc, 0, v67, vcc
	v_lshl_add_u64 v[68:69], v[68:69], 0, v[110:111]
	v_add_co_u32_e32 v68, vcc, s48, v68
	v_add_u32_e32 v0, 0x180, v156
	s_nop 0
	v_addc_co_u32_e32 v69, vcc, 0, v69, vcc
	global_load_dwordx4 v[78:81], v[66:67], off
	global_load_dwordx4 v[74:77], v[68:69], off
	v_ashrrev_i32_e32 v66, 31, v0
	v_lshrrev_b32_e32 v66, 28, v66
	v_add_u32_e32 v66, v0, v66
	v_ashrrev_i32_e32 v112, 4, v66
	v_and_b32_e32 v66, -16, v66
	v_sub_u32_e32 v119, v0, v66
	v_lshlrev_b32_e32 v68, 3, v119
	v_ashrrev_i32_e32 v69, 31, v68
	v_add_u32_e32 v0, 0x1c0, v156
	v_lshlrev_b64 v[104:105], 1, v[68:69]
	v_ashrrev_i32_e32 v68, 31, v0
	v_lshrrev_b32_e32 v68, 28, v68
	v_ashrrev_i32_e32 v113, 31, v112
	v_add_u32_e32 v68, v0, v68
	v_lshl_add_u64 v[102:103], s[24:25], 0, v[112:113]
	v_ashrrev_i32_e32 v106, 4, v68
	v_lshlrev_b64 v[66:67], 14, v[102:103]
	v_and_b32_e32 v68, -16, v68
	v_ashrrev_i32_e32 v107, 31, v106
	s_and_b32 s0, s49, 7
	v_lshl_add_u64 v[66:67], s[12:13], 0, v[66:67]
	v_sub_u32_e32 v0, v0, v68
	v_lshl_add_u64 v[98:99], s[24:25], 0, v[106:107]
	s_lshl_b32 s7, s0, 8
	s_lshl_b32 s6, s0, 10
	v_lshl_add_u64 v[66:67], v[66:67], 0, s[16:17]
	v_lshlrev_b64 v[68:69], 14, v[98:99]
	v_lshlrev_b32_e32 v70, 3, v0
	v_div_scale_f32 v107, s[0:1], v146, v146, 1.0
	v_lshl_add_u64 v[66:67], v[66:67], 0, v[104:105]
	v_lshl_add_u64 v[68:69], s[12:13], 0, v[68:69]
	v_ashrrev_i32_e32 v71, 31, v70
	v_rcp_f32_e32 v113, v107
	v_add_co_u32_e32 v66, vcc, s48, v66
	v_lshl_add_u64 v[68:69], v[68:69], 0, s[16:17]
	v_lshlrev_b64 v[100:101], 1, v[70:71]
	v_addc_co_u32_e32 v67, vcc, 0, v67, vcc
	v_lshl_add_u64 v[68:69], v[68:69], 0, v[100:101]
	v_add_co_u32_e32 v68, vcc, s48, v68
	v_fma_f32 v148, -v107, v113, 1.0
	s_nop 0
	v_addc_co_u32_e32 v69, vcc, 0, v69, vcc
	v_fmac_f32_e32 v113, v148, v113
	v_div_scale_f32 v148, vcc, 1.0, v146, 1.0
	v_mul_f32_e32 v149, v148, v113
	v_fma_f32 v150, -v107, v149, v148
	v_fmac_f32_e32 v149, v150, v113
	v_fma_f32 v107, -v107, v149, v148
	v_div_fmas_f32 v107, v107, v113, v149
	v_div_fixup_f32 v146, v107, v146, 1.0
	v_mul_f32_e64 v50, v50, v146
	v_mul_f32_e64 v51, v51, v146
	v_mul_f32_e64 v52, v52, v146
	v_mul_f32_e64 v53, v53, v146
	s_mulk_i32 s33, 0x110
	v_and_b32_e32 v107, 31, v156
	v_cvt_pk_bf16_f32 v50, v50, v51
	v_cvt_pk_bf16_f32 v51, v52, v53
	v_ashrrev_i32_e32 v52, 2, v156
	v_mul_f32_e64 v2, v2, v146
	v_mul_f32_e64 v3, v3, v146
	v_mul_f32_e64 v4, v4, v146
	v_mul_f32_e64 v5, v5, v146
	s_add_i32 s4, s33, 0
	v_mul_u32_u24_e32 v107, 0x110, v107
	v_and_b32_e32 v52, -8, v52
	v_cvt_pk_bf16_f32 v2, v2, v3
	v_cvt_pk_bf16_f32 v3, v4, v5
	v_mul_f32_e64 v4, v6, v146
	v_mul_f32_e64 v5, v7, v146
	v_mul_f32_e64 v6, v8, v146
	v_mul_f32_e64 v7, v9, v146
	v_add3_u32 v107, s4, v107, v52
	v_cvt_pk_bf16_f32 v4, v4, v5
	v_cvt_pk_bf16_f32 v5, v6, v7
	global_load_dwordx4 v[70:73], v[66:67], off
	s_nop 0
	global_load_dwordx4 v[66:69], v[68:69], off
	v_mul_f32_e64 v34, v34, v146
	v_mul_f32_e64 v35, v35, v146
	v_mul_f32_e64 v36, v36, v146
	v_mul_f32_e64 v37, v37, v146
	v_mul_f32_e64 v18, v18, v146
	v_mul_f32_e64 v19, v19, v146
	v_mul_f32_e64 v20, v20, v146
	v_mul_f32_e64 v21, v21, v146
	ds_write2_b64 v107, v[2:3], v[4:5] offset0:24 offset1:26
	v_mul_f32_e64 v2, v10, v146
	v_mul_f32_e64 v3, v11, v146
	v_mul_f32_e64 v4, v12, v146
	v_mul_f32_e64 v5, v13, v146
	v_mul_f32_e64 v52, v54, v146
	v_mul_f32_e64 v53, v55, v146
	v_mul_f32_e64 v54, v56, v146
	v_mul_f32_e64 v55, v57, v146
	v_cvt_pk_bf16_f32 v34, v34, v35
	v_cvt_pk_bf16_f32 v35, v36, v37
	v_mul_f32_e64 v36, v38, v146
	v_mul_f32_e64 v37, v39, v146
	v_mul_f32_e64 v38, v40, v146
	v_mul_f32_e64 v39, v41, v146
	v_cvt_pk_bf16_f32 v18, v18, v19
	v_cvt_pk_bf16_f32 v19, v20, v21
	v_mul_f32_e64 v20, v22, v146
	v_mul_f32_e64 v21, v23, v146
	v_mul_f32_e64 v22, v24, v146
	v_mul_f32_e64 v23, v25, v146
	v_cvt_pk_bf16_f32 v2, v2, v3
	v_cvt_pk_bf16_f32 v3, v4, v5
	v_mul_f32_e64 v4, v14, v146
	v_mul_f32_e64 v5, v15, v146
	v_mul_f32_e64 v6, v16, v146
	v_mul_f32_e64 v7, v17, v146
	v_cvt_pk_bf16_f32 v52, v52, v53
	v_cvt_pk_bf16_f32 v53, v54, v55
	v_cvt_pk_bf16_f32 v36, v36, v37
	v_cvt_pk_bf16_f32 v37, v38, v39
	v_cvt_pk_bf16_f32 v20, v20, v21
	v_cvt_pk_bf16_f32 v21, v22, v23
	v_cvt_pk_bf16_f32 v4, v4, v5
	v_cvt_pk_bf16_f32 v5, v6, v7
	ds_write2_b64 v107, v[50:51], v[52:53] offset1:2
	v_mul_f32_e64 v50, v58, v146
	v_mul_f32_e64 v51, v59, v146
	v_mul_f32_e64 v52, v60, v146
	v_mul_f32_e64 v53, v61, v146
	ds_write2_b64 v107, v[34:35], v[36:37] offset0:8 offset1:10
	v_mul_f32_e64 v34, v42, v146
	v_mul_f32_e64 v35, v43, v146
	v_mul_f32_e64 v36, v44, v146
	v_mul_f32_e64 v37, v45, v146
	ds_write2_b64 v107, v[18:19], v[20:21] offset0:16 offset1:18
	v_mul_f32_e64 v18, v26, v146
	v_mul_f32_e64 v19, v27, v146
	v_mul_f32_e64 v20, v28, v146
	v_mul_f32_e64 v21, v29, v146
	ds_write2_b64 v107, v[2:3], v[4:5] offset0:28 offset1:30
	v_mul_lo_u32 v2, v144, s45
	v_lshlrev_b32_e32 v3, 4, v147
	s_waitcnt vmcnt(7)
	v_lshlrev_b32_e32 v10, 16, v94
	v_cvt_pk_bf16_f32 v50, v50, v51
	v_cvt_pk_bf16_f32 v51, v52, v53
	v_mul_f32_e64 v52, v62, v146
	v_mul_f32_e64 v53, v63, v146
	v_mul_f32_e64 v54, v64, v146
	v_mul_f32_e64 v55, v65, v146
	v_cvt_pk_bf16_f32 v34, v34, v35
	v_cvt_pk_bf16_f32 v35, v36, v37
	v_mul_f32_e64 v36, v46, v146
	v_mul_f32_e64 v37, v47, v146
	v_mul_f32_e64 v38, v48, v146
	v_mul_f32_e64 v39, v49, v146
	v_cvt_pk_bf16_f32 v18, v18, v19
	v_cvt_pk_bf16_f32 v19, v20, v21
	v_mul_f32_e64 v20, v30, v146
	v_mul_f32_e64 v21, v31, v146
	v_mul_f32_e64 v22, v32, v146
	v_mul_f32_e64 v23, v33, v146
	v_add3_u32 v2, s4, v2, v3
	v_and_b32_e32 v13, 0xffff0000, v94
	v_mul_f32_e32 v3, 0xbfb8aa3b, v10
	v_cvt_pk_bf16_f32 v52, v52, v53
	v_cvt_pk_bf16_f32 v53, v54, v55
	v_cvt_pk_bf16_f32 v36, v36, v37
	v_cvt_pk_bf16_f32 v37, v38, v39
	v_cvt_pk_bf16_f32 v20, v20, v21
	v_cvt_pk_bf16_f32 v21, v22, v23
	v_exp_f32_e32 v6, v3
	v_mul_f32_e32 v3, 0xbfb8aa3b, v13
	ds_write2_b64 v107, v[50:51], v[52:53] offset0:4 offset1:6
	ds_write2_b64 v107, v[34:35], v[36:37] offset0:12 offset1:14
	ds_write2_b64 v107, v[18:19], v[20:21] offset0:20 offset1:22
	v_exp_f32_e32 v7, v3
	s_waitcnt lgkmcnt(0)
	ds_read_b128 v[2:5], v2
	v_add_f32_e32 v6, 1.0, v6
	v_rcp_f32_e32 v14, v6
	v_add_f32_e32 v6, 1.0, v7
	v_rcp_f32_e32 v15, v6
	v_mul_lo_u32 v6, v142, s45
	v_lshlrev_b32_e32 v7, 4, v145
	v_add3_u32 v6, s4, v6, v7
	ds_read_b128 v[6:9], v6
	s_waitcnt lgkmcnt(1)
	v_and_b32_e32 v11, 0xffff0000, v2
	v_lshlrev_b32_e32 v12, 16, v2
	v_mul_f32_e64 v10, v12, v10
	v_mul_f32_e64 v11, v13, v11
	v_lshlrev_b32_e32 v12, 16, v95
	v_mul_f32_e64 v10, v14, v10
	v_mul_f32_e64 v11, v15, v11
	v_and_b32_e32 v15, 0xffff0000, v95
	v_mul_f32_e32 v2, 0xbfb8aa3b, v12
	v_exp_f32_e32 v13, v2
	v_mul_f32_e32 v2, 0xbfb8aa3b, v15
	v_exp_f32_e32 v14, v2
	v_cvt_pk_bf16_f32 v2, v10, v11
	v_add_f32_e32 v10, 1.0, v13
	v_rcp_f32_e32 v10, v10
	v_add_f32_e32 v11, 1.0, v14
	v_rcp_f32_e32 v11, v11
	v_and_b32_e32 v13, 0xffff0000, v3
	v_lshlrev_b32_e32 v14, 16, v3
	v_mul_f32_e64 v12, v14, v12
	v_mul_f32_e64 v13, v15, v13
	v_and_b32_e32 v15, 0xffff0000, v96
	v_mul_f32_e64 v10, v10, v12
	v_mul_f32_e64 v11, v11, v13
	v_lshlrev_b32_e32 v12, 16, v96
	v_mul_f32_e32 v3, 0xbfb8aa3b, v12
	v_exp_f32_e32 v13, v3
	v_mul_f32_e32 v3, 0xbfb8aa3b, v15
	v_exp_f32_e32 v14, v3
	v_cvt_pk_bf16_f32 v3, v10, v11
	v_add_f32_e32 v10, 1.0, v13
	v_rcp_f32_e32 v10, v10
	v_add_f32_e32 v11, 1.0, v14
	v_rcp_f32_e32 v11, v11
	v_and_b32_e32 v13, 0xffff0000, v4
	v_lshlrev_b32_e32 v14, 16, v4
	v_mul_f32_e64 v12, v14, v12
	v_mul_f32_e64 v13, v15, v13
	v_and_b32_e32 v15, 0xffff0000, v97
	v_mul_f32_e64 v10, v10, v12
	v_mul_f32_e64 v11, v11, v13
	v_lshlrev_b32_e32 v12, 16, v97
	v_mul_f32_e32 v4, 0xbfb8aa3b, v12
	v_exp_f32_e32 v13, v4
	v_mul_f32_e32 v4, 0xbfb8aa3b, v15
	v_exp_f32_e32 v14, v4
	v_cvt_pk_bf16_f32 v4, v10, v11
	v_add_f32_e32 v10, 1.0, v13
	v_rcp_f32_e32 v10, v10
	v_add_f32_e32 v11, 1.0, v14
	v_rcp_f32_e32 v11, v11
	v_and_b32_e32 v13, 0xffff0000, v5
	v_lshlrev_b32_e32 v14, 16, v5
	v_mul_f32_e64 v12, v14, v12
	v_mul_f32_e64 v13, v15, v13
	s_waitcnt vmcnt(6)
	v_and_b32_e32 v15, 0xffff0000, v90
	v_mul_f32_e64 v10, v10, v12
	v_mul_f32_e64 v11, v11, v13
	v_lshlrev_b32_e32 v12, 16, v90
	s_addk_i32 s6, 0x400
	v_mul_f32_e32 v13, 0xbfb8aa3b, v12
	v_mul_f32_e32 v14, 0xbfb8aa3b, v15
	s_add_u32 s0, s36, s16
	v_exp_f32_e32 v13, v13
	v_exp_f32_e32 v14, v14
	s_addc_u32 s1, s37, 0
	v_cvt_pk_bf16_f32 v5, v10, v11
	v_lshlrev_b64 v[10:11], 12, v[138:139]
	v_lshl_add_u64 v[10:11], s[0:1], 0, v[10:11]
	v_lshl_add_u64 v[10:11], v[10:11], 0, v[140:141]
	global_store_dwordx4 v[10:11], v[2:5], off
	v_and_b32_e32 v11, 0xffff0000, v91
	s_waitcnt lgkmcnt(0)
	v_lshlrev_b32_e32 v10, 16, v7
	v_add_f32_e32 v2, 1.0, v13
	v_add_f32_e32 v3, 1.0, v14
	v_rcp_f32_e32 v2, v2
	v_rcp_f32_e32 v3, v3
	v_and_b32_e32 v13, 0xffff0000, v6
	v_lshlrev_b32_e32 v14, 16, v6
	v_mul_f32_e64 v4, v14, v12
	v_mul_f32_e64 v5, v15, v13
	v_mul_f32_e32 v6, 0xbfb8aa3b, v11
	v_mul_f32_e64 v2, v2, v4
	v_mul_f32_e64 v3, v3, v5
	v_lshlrev_b32_e32 v4, 16, v91
	v_mul_f32_e32 v5, 0xbfb8aa3b, v4
	v_exp_f32_e32 v5, v5
	v_exp_f32_e32 v6, v6
	v_cvt_pk_bf16_f32 v2, v2, v3
	v_lshlrev_b32_e32 v0, 4, v0
	v_add_f32_e32 v3, 1.0, v5
	v_rcp_f32_e32 v12, v3
	v_add_f32_e32 v3, 1.0, v6
	v_and_b32_e32 v5, 0xffff0000, v7
	v_lshlrev_b32_e32 v6, 16, v92
	v_rcp_f32_e32 v13, v3
	v_mul_f32_e64 v4, v10, v4
	v_mul_f32_e64 v5, v11, v5
	v_and_b32_e32 v11, 0xffff0000, v92
	v_mul_f32_e32 v3, 0xbfb8aa3b, v6
	v_exp_f32_e32 v7, v3
	v_mul_f32_e32 v3, 0xbfb8aa3b, v11
	v_exp_f32_e32 v10, v3
	v_mul_f32_e64 v4, v12, v4
	v_mul_f32_e64 v5, v13, v5
	v_mov_b32_e32 v28, v255
	v_cvt_pk_bf16_f32 v3, v4, v5
	v_add_f32_e32 v4, 1.0, v7
	v_add_f32_e32 v5, 1.0, v10
	v_rcp_f32_e32 v4, v4
	v_rcp_f32_e32 v5, v5
	v_and_b32_e32 v7, 0xffff0000, v8
	v_lshlrev_b32_e32 v10, 16, v8
	v_mul_f32_e64 v6, v10, v6
	v_mul_f32_e64 v7, v11, v7
	v_and_b32_e32 v11, 0xffff0000, v93
	v_mul_f32_e64 v4, v4, v6
	v_mul_f32_e64 v5, v5, v7
	v_lshlrev_b32_e32 v6, 16, v93
	v_mul_f32_e32 v7, 0xbfb8aa3b, v6
	v_exp_f32_e32 v7, v7
	v_mul_f32_e32 v8, 0xbfb8aa3b, v11
	v_exp_f32_e32 v8, v8
	v_cvt_pk_bf16_f32 v4, v4, v5
	v_add_f32_e32 v5, 1.0, v7
	v_rcp_f32_e32 v12, v5
	v_add_f32_e32 v5, 1.0, v8
	v_rcp_f32_e32 v13, v5
	v_and_b32_e32 v7, 0xffff0000, v9
	v_lshlrev_b32_e32 v10, 16, v9
	v_mul_f32_e64 v6, v10, v6
	v_mul_f32_e64 v7, v11, v7
	s_waitcnt vmcnt(6)
	v_lshlrev_b32_e32 v10, 16, v86
	v_mul_f32_e64 v6, v12, v6
	v_mul_f32_e64 v7, v13, v7
	v_and_b32_e32 v13, 0xffff0000, v86
	v_cvt_pk_bf16_f32 v5, v6, v7
	v_lshlrev_b64 v[6:7], 12, v[132:133]
	v_lshl_add_u64 v[6:7], s[0:1], 0, v[6:7]
	v_lshl_add_u64 v[6:7], v[6:7], 0, v[134:135]
	global_store_dwordx4 v[6:7], v[2:5], off
	s_lshl_b32 s27, s50, 8
	s_or_b32 s5, s22, s27
	v_mul_lo_u32 v2, v136, s45
	v_lshlrev_b32_e32 v3, 4, v143
	v_add3_u32 v2, s4, v2, v3
	v_mul_f32_e32 v3, 0xbfb8aa3b, v10
	v_exp_f32_e32 v6, v3
	v_mul_f32_e32 v3, 0xbfb8aa3b, v13
	v_exp_f32_e32 v7, v3
	ds_read_b128 v[2:5], v2
	v_add_f32_e32 v6, 1.0, v6
	v_rcp_f32_e32 v14, v6
	v_add_f32_e32 v6, 1.0, v7
	v_rcp_f32_e32 v15, v6
	v_mul_lo_u32 v6, v130, s45
	v_lshlrev_b32_e32 v7, 4, v137
	v_add3_u32 v6, s4, v6, v7
	ds_read_b128 v[6:9], v6
	s_waitcnt lgkmcnt(1)
	v_and_b32_e32 v11, 0xffff0000, v2
	v_lshlrev_b32_e32 v12, 16, v2
	v_mul_f32_e64 v10, v12, v10
	v_mul_f32_e64 v11, v13, v11
	v_lshlrev_b32_e32 v12, 16, v87
	v_mul_f32_e64 v10, v14, v10
	v_mul_f32_e64 v11, v15, v11
	v_and_b32_e32 v15, 0xffff0000, v87
	v_mul_f32_e32 v2, 0xbfb8aa3b, v12
	v_exp_f32_e32 v13, v2
	v_mul_f32_e32 v2, 0xbfb8aa3b, v15
	v_exp_f32_e32 v14, v2
	v_cvt_pk_bf16_f32 v2, v10, v11
	v_add_f32_e32 v10, 1.0, v13
	v_rcp_f32_e32 v10, v10
	v_add_f32_e32 v11, 1.0, v14
	v_rcp_f32_e32 v11, v11
	v_and_b32_e32 v13, 0xffff0000, v3
	v_lshlrev_b32_e32 v14, 16, v3
	v_mul_f32_e64 v12, v14, v12
	v_mul_f32_e64 v13, v15, v13
	v_and_b32_e32 v15, 0xffff0000, v88
	v_mul_f32_e64 v10, v10, v12
	v_mul_f32_e64 v11, v11, v13
	v_lshlrev_b32_e32 v12, 16, v88
	v_mul_f32_e32 v3, 0xbfb8aa3b, v12
	v_exp_f32_e32 v13, v3
	v_mul_f32_e32 v3, 0xbfb8aa3b, v15
	v_exp_f32_e32 v14, v3
	v_cvt_pk_bf16_f32 v3, v10, v11
	v_add_f32_e32 v10, 1.0, v13
	v_rcp_f32_e32 v10, v10
	v_add_f32_e32 v11, 1.0, v14
	v_rcp_f32_e32 v11, v11
	v_and_b32_e32 v13, 0xffff0000, v4
	v_lshlrev_b32_e32 v14, 16, v4
	v_mul_f32_e64 v12, v14, v12
	v_mul_f32_e64 v13, v15, v13
	v_and_b32_e32 v15, 0xffff0000, v89
	v_mul_f32_e64 v10, v10, v12
	v_mul_f32_e64 v11, v11, v13
	v_lshlrev_b32_e32 v12, 16, v89
	v_mul_f32_e32 v4, 0xbfb8aa3b, v12
	v_exp_f32_e32 v13, v4
	v_mul_f32_e32 v4, 0xbfb8aa3b, v15
	v_exp_f32_e32 v14, v4
	v_cvt_pk_bf16_f32 v4, v10, v11
	v_add_f32_e32 v10, 1.0, v13
	v_rcp_f32_e32 v10, v10
	v_add_f32_e32 v11, 1.0, v14
	v_rcp_f32_e32 v11, v11
	v_and_b32_e32 v13, 0xffff0000, v5
	v_lshlrev_b32_e32 v14, 16, v5
	v_mul_f32_e64 v12, v14, v12
	v_mul_f32_e64 v13, v15, v13
	s_waitcnt vmcnt(6)
	v_and_b32_e32 v15, 0xffff0000, v82
	v_mul_f32_e64 v10, v10, v12
	v_mul_f32_e64 v11, v11, v13
	v_lshlrev_b32_e32 v12, 16, v82
	v_mul_f32_e32 v13, 0xbfb8aa3b, v12
	v_mul_f32_e32 v14, 0xbfb8aa3b, v15
	v_exp_f32_e32 v13, v13
	v_exp_f32_e32 v14, v14
	v_cvt_pk_bf16_f32 v5, v10, v11
	v_lshlrev_b64 v[10:11], 12, v[126:127]
	v_lshl_add_u64 v[10:11], s[0:1], 0, v[10:11]
	v_lshl_add_u64 v[10:11], v[10:11], 0, v[128:129]
	global_store_dwordx4 v[10:11], v[2:5], off
	v_and_b32_e32 v11, 0xffff0000, v83
	s_waitcnt lgkmcnt(0)
	v_lshlrev_b32_e32 v10, 16, v7
	v_add_f32_e32 v2, 1.0, v13
	v_add_f32_e32 v3, 1.0, v14
	v_rcp_f32_e32 v2, v2
	v_rcp_f32_e32 v3, v3
	v_and_b32_e32 v13, 0xffff0000, v6
	v_lshlrev_b32_e32 v14, 16, v6
	v_mul_f32_e64 v4, v14, v12
	v_mul_f32_e64 v5, v15, v13
	v_mul_f32_e32 v6, 0xbfb8aa3b, v11
	v_mul_f32_e64 v2, v2, v4
	v_mul_f32_e64 v3, v3, v5
	v_lshlrev_b32_e32 v4, 16, v83
	v_mul_f32_e32 v5, 0xbfb8aa3b, v4
	v_exp_f32_e32 v5, v5
	v_exp_f32_e32 v6, v6
	v_cvt_pk_bf16_f32 v2, v2, v3
	s_lshl_b32 s33, s50, 2
	v_add_f32_e32 v3, 1.0, v5
	v_rcp_f32_e32 v12, v3
	v_add_f32_e32 v3, 1.0, v6
	v_and_b32_e32 v5, 0xffff0000, v7
	v_lshlrev_b32_e32 v6, 16, v84
	v_rcp_f32_e32 v13, v3
	v_mul_f32_e64 v4, v10, v4
	v_mul_f32_e64 v5, v11, v5
	v_and_b32_e32 v11, 0xffff0000, v84
	v_mul_f32_e32 v3, 0xbfb8aa3b, v6
	v_exp_f32_e32 v7, v3
	v_mul_f32_e32 v3, 0xbfb8aa3b, v11
	v_exp_f32_e32 v10, v3
	v_mul_f32_e64 v4, v12, v4
	v_mul_f32_e64 v5, v13, v5
	s_mov_b32 s24, 0
	v_cvt_pk_bf16_f32 v3, v4, v5
	v_add_f32_e32 v4, 1.0, v7
	v_add_f32_e32 v5, 1.0, v10
	v_rcp_f32_e32 v4, v4
	v_rcp_f32_e32 v5, v5
	v_and_b32_e32 v7, 0xffff0000, v8
	v_lshlrev_b32_e32 v10, 16, v8
	v_mul_f32_e64 v6, v10, v6
	v_mul_f32_e64 v7, v11, v7
	v_and_b32_e32 v11, 0xffff0000, v85
	v_mul_f32_e64 v4, v4, v6
	v_mul_f32_e64 v5, v5, v7
	v_lshlrev_b32_e32 v6, 16, v85
	v_mul_f32_e32 v7, 0xbfb8aa3b, v6
	v_exp_f32_e32 v7, v7
	v_mul_f32_e32 v8, 0xbfb8aa3b, v11
	v_exp_f32_e32 v8, v8
	v_cvt_pk_bf16_f32 v4, v4, v5
	v_add_f32_e32 v5, 1.0, v7
	v_rcp_f32_e32 v12, v5
	v_add_f32_e32 v5, 1.0, v8
	v_rcp_f32_e32 v13, v5
	v_and_b32_e32 v7, 0xffff0000, v9
	v_lshlrev_b32_e32 v10, 16, v9
	v_mul_f32_e64 v6, v10, v6
	v_mul_f32_e64 v7, v11, v7
	s_waitcnt vmcnt(6)
	v_lshlrev_b32_e32 v10, 16, v78
	v_mul_f32_e64 v6, v12, v6
	v_mul_f32_e64 v7, v13, v7
	v_and_b32_e32 v13, 0xffff0000, v78
	v_cvt_pk_bf16_f32 v5, v6, v7
	v_lshlrev_b64 v[6:7], 12, v[120:121]
	v_lshl_add_u64 v[6:7], s[0:1], 0, v[6:7]
	v_lshl_add_u64 v[6:7], v[6:7], 0, v[122:123]
	global_store_dwordx4 v[6:7], v[2:5], off
	s_mov_b32 s25, 2
	s_mov_b32 s26, 63
	v_mul_lo_u32 v2, v124, s45
	v_lshlrev_b32_e32 v3, 4, v131
	v_add3_u32 v2, s4, v2, v3
	v_mul_f32_e32 v3, 0xbfb8aa3b, v10
	v_exp_f32_e32 v6, v3
	v_mul_f32_e32 v3, 0xbfb8aa3b, v13
	v_exp_f32_e32 v7, v3
	ds_read_b128 v[2:5], v2
	v_add_f32_e32 v6, 1.0, v6
	v_rcp_f32_e32 v14, v6
	v_add_f32_e32 v6, 1.0, v7
	v_rcp_f32_e32 v15, v6
	v_mul_lo_u32 v6, v118, s45
	v_lshlrev_b32_e32 v7, 4, v125
	v_add3_u32 v6, s4, v6, v7
	ds_read_b128 v[6:9], v6
	s_waitcnt lgkmcnt(1)
	v_and_b32_e32 v11, 0xffff0000, v2
	v_lshlrev_b32_e32 v12, 16, v2
	v_mul_f32_e64 v10, v12, v10
	v_mul_f32_e64 v11, v13, v11
	v_lshlrev_b32_e32 v12, 16, v79
	v_mul_f32_e64 v10, v14, v10
	v_mul_f32_e64 v11, v15, v11
	v_and_b32_e32 v15, 0xffff0000, v79
	v_mul_f32_e32 v2, 0xbfb8aa3b, v12
	v_exp_f32_e32 v13, v2
	v_mul_f32_e32 v2, 0xbfb8aa3b, v15
	v_exp_f32_e32 v14, v2
	v_cvt_pk_bf16_f32 v2, v10, v11
	v_add_f32_e32 v10, 1.0, v13
	v_rcp_f32_e32 v10, v10
	v_add_f32_e32 v11, 1.0, v14
	v_rcp_f32_e32 v11, v11
	v_and_b32_e32 v13, 0xffff0000, v3
	v_lshlrev_b32_e32 v14, 16, v3
	v_mul_f32_e64 v12, v14, v12
	v_mul_f32_e64 v13, v15, v13
	v_and_b32_e32 v15, 0xffff0000, v80
	v_mul_f32_e64 v10, v10, v12
	v_mul_f32_e64 v11, v11, v13
	v_lshlrev_b32_e32 v12, 16, v80
	v_mul_f32_e32 v3, 0xbfb8aa3b, v12
	v_exp_f32_e32 v13, v3
	v_mul_f32_e32 v3, 0xbfb8aa3b, v15
	v_exp_f32_e32 v14, v3
	v_cvt_pk_bf16_f32 v3, v10, v11
	v_add_f32_e32 v10, 1.0, v13
	v_rcp_f32_e32 v10, v10
	v_add_f32_e32 v11, 1.0, v14
	v_rcp_f32_e32 v11, v11
	v_and_b32_e32 v13, 0xffff0000, v4
	v_lshlrev_b32_e32 v14, 16, v4
	v_mul_f32_e64 v12, v14, v12
	v_mul_f32_e64 v13, v15, v13
	v_and_b32_e32 v15, 0xffff0000, v81
	v_mul_f32_e64 v10, v10, v12
	v_mul_f32_e64 v11, v11, v13
	v_lshlrev_b32_e32 v12, 16, v81
	v_mul_f32_e32 v4, 0xbfb8aa3b, v12
	v_exp_f32_e32 v13, v4
	v_mul_f32_e32 v4, 0xbfb8aa3b, v15
	v_exp_f32_e32 v14, v4
	v_cvt_pk_bf16_f32 v4, v10, v11
	v_add_f32_e32 v10, 1.0, v13
	v_rcp_f32_e32 v10, v10
	v_add_f32_e32 v11, 1.0, v14
	v_rcp_f32_e32 v11, v11
	v_and_b32_e32 v13, 0xffff0000, v5
	v_lshlrev_b32_e32 v14, 16, v5
	v_mul_f32_e64 v12, v14, v12
	v_mul_f32_e64 v13, v15, v13
	s_waitcnt vmcnt(6)
	v_and_b32_e32 v15, 0xffff0000, v74
	v_mul_f32_e64 v10, v10, v12
	v_mul_f32_e64 v11, v11, v13
	v_lshlrev_b32_e32 v12, 16, v74
	v_mul_f32_e32 v13, 0xbfb8aa3b, v12
	v_mul_f32_e32 v14, 0xbfb8aa3b, v15
	v_exp_f32_e32 v13, v13
	v_exp_f32_e32 v14, v14
	v_cvt_pk_bf16_f32 v5, v10, v11
	v_lshlrev_b64 v[10:11], 12, v[114:115]
	v_lshl_add_u64 v[10:11], s[0:1], 0, v[10:11]
	v_lshl_add_u64 v[10:11], v[10:11], 0, v[116:117]
	global_store_dwordx4 v[10:11], v[2:5], off
	v_and_b32_e32 v11, 0xffff0000, v75
	s_waitcnt lgkmcnt(0)
	v_lshlrev_b32_e32 v10, 16, v7
	v_add_f32_e32 v2, 1.0, v13
	v_add_f32_e32 v3, 1.0, v14
	v_rcp_f32_e32 v2, v2
	v_rcp_f32_e32 v3, v3
	v_and_b32_e32 v13, 0xffff0000, v6
	v_lshlrev_b32_e32 v14, 16, v6
	v_mul_f32_e64 v4, v14, v12
	v_mul_f32_e64 v5, v15, v13
	v_mul_f32_e32 v6, 0xbfb8aa3b, v11
	v_mul_f32_e64 v2, v2, v4
	v_mul_f32_e64 v3, v3, v5
	v_lshlrev_b32_e32 v4, 16, v75
	v_mul_f32_e32 v5, 0xbfb8aa3b, v4
	v_exp_f32_e32 v5, v5
	v_exp_f32_e32 v6, v6
	v_cvt_pk_bf16_f32 v2, v2, v3
	v_mov_b32_e32 v196, 0
	v_add_f32_e32 v3, 1.0, v5
	v_rcp_f32_e32 v12, v3
	v_add_f32_e32 v3, 1.0, v6
	v_and_b32_e32 v5, 0xffff0000, v7
	v_lshlrev_b32_e32 v6, 16, v76
	v_rcp_f32_e32 v13, v3
	v_mul_f32_e64 v4, v10, v4
	v_mul_f32_e64 v5, v11, v5
	v_and_b32_e32 v11, 0xffff0000, v76
	v_mul_f32_e32 v3, 0xbfb8aa3b, v6
	v_exp_f32_e32 v7, v3
	v_mul_f32_e32 v3, 0xbfb8aa3b, v11
	v_exp_f32_e32 v10, v3
	v_mul_f32_e64 v4, v12, v4
	v_mul_f32_e64 v5, v13, v5
	v_mov_b32_e32 v197, 0xf149f2ca
	v_cvt_pk_bf16_f32 v3, v4, v5
	v_add_f32_e32 v4, 1.0, v7
	v_add_f32_e32 v5, 1.0, v10
	v_rcp_f32_e32 v4, v4
	v_rcp_f32_e32 v5, v5
	v_and_b32_e32 v7, 0xffff0000, v8
	v_lshlrev_b32_e32 v10, 16, v8
	v_mul_f32_e64 v6, v10, v6
	v_mul_f32_e64 v7, v11, v7
	v_and_b32_e32 v11, 0xffff0000, v77
	v_mul_f32_e64 v4, v4, v6
	v_mul_f32_e64 v5, v5, v7
	v_lshlrev_b32_e32 v6, 16, v77
	v_mul_f32_e32 v7, 0xbfb8aa3b, v6
	v_exp_f32_e32 v7, v7
	v_mul_f32_e32 v8, 0xbfb8aa3b, v11
	v_exp_f32_e32 v8, v8
	v_cvt_pk_bf16_f32 v4, v4, v5
	v_add_f32_e32 v5, 1.0, v7
	v_rcp_f32_e32 v12, v5
	v_add_f32_e32 v5, 1.0, v8
	v_rcp_f32_e32 v13, v5
	v_and_b32_e32 v7, 0xffff0000, v9
	v_lshlrev_b32_e32 v10, 16, v9
	v_mul_f32_e64 v6, v10, v6
	v_mul_f32_e64 v7, v11, v7
	s_waitcnt vmcnt(6)
	v_lshlrev_b32_e32 v10, 16, v70
	v_mul_f32_e64 v6, v12, v6
	v_mul_f32_e64 v7, v13, v7
	v_and_b32_e32 v13, 0xffff0000, v70
	v_cvt_pk_bf16_f32 v5, v6, v7
	v_lshlrev_b64 v[6:7], 12, v[108:109]
	v_lshl_add_u64 v[6:7], s[0:1], 0, v[6:7]
	v_lshl_add_u64 v[6:7], v[6:7], 0, v[110:111]
	global_store_dwordx4 v[6:7], v[2:5], off
	s_nop 1
	v_mul_lo_u32 v2, v112, s45
	v_lshlrev_b32_e32 v3, 4, v119
	v_add3_u32 v2, s4, v2, v3
	v_mul_f32_e32 v3, 0xbfb8aa3b, v10
	v_exp_f32_e32 v6, v3
	v_mul_f32_e32 v3, 0xbfb8aa3b, v13
	v_exp_f32_e32 v7, v3
	ds_read_b128 v[2:5], v2
	v_add_f32_e32 v6, 1.0, v6
	v_rcp_f32_e32 v14, v6
	v_add_f32_e32 v6, 1.0, v7
	v_rcp_f32_e32 v15, v6
	v_mul_lo_u32 v6, v106, s45
	v_add3_u32 v0, s4, v6, v0
	ds_read_b128 v[6:9], v0
	s_waitcnt lgkmcnt(1)
	v_and_b32_e32 v11, 0xffff0000, v2
	v_lshlrev_b32_e32 v12, 16, v2
	v_mul_f32_e64 v10, v12, v10
	v_mul_f32_e64 v11, v13, v11
	v_lshlrev_b32_e32 v12, 16, v71
	v_mul_f32_e64 v10, v14, v10
	v_mul_f32_e64 v11, v15, v11
	v_and_b32_e32 v15, 0xffff0000, v71
	v_mul_f32_e32 v0, 0xbfb8aa3b, v12
	v_exp_f32_e32 v0, v0
	v_mul_f32_e32 v2, 0xbfb8aa3b, v15
	v_exp_f32_e32 v13, v2
	v_cvt_pk_bf16_f32 v2, v10, v11
	v_add_f32_e32 v0, 1.0, v0
	v_rcp_f32_e32 v10, v0
	v_add_f32_e32 v0, 1.0, v13
	v_rcp_f32_e32 v11, v0
	v_and_b32_e32 v13, 0xffff0000, v3
	v_lshlrev_b32_e32 v14, 16, v3
	v_mul_f32_e64 v12, v14, v12
	v_mul_f32_e64 v13, v15, v13
	v_and_b32_e32 v15, 0xffff0000, v72
	v_mul_f32_e64 v10, v10, v12
	v_mul_f32_e64 v11, v11, v13
	v_lshlrev_b32_e32 v12, 16, v72
	v_mul_f32_e32 v0, 0xbfb8aa3b, v12
	v_exp_f32_e32 v0, v0
	v_mul_f32_e32 v3, 0xbfb8aa3b, v15
	v_exp_f32_e32 v13, v3
	v_cvt_pk_bf16_f32 v3, v10, v11
	v_add_f32_e32 v0, 1.0, v0
	v_rcp_f32_e32 v10, v0
	v_add_f32_e32 v0, 1.0, v13
	v_rcp_f32_e32 v11, v0
	v_and_b32_e32 v13, 0xffff0000, v4
	v_lshlrev_b32_e32 v14, 16, v4
	v_mul_f32_e64 v12, v14, v12
	v_mul_f32_e64 v13, v15, v13
	v_and_b32_e32 v15, 0xffff0000, v73
	v_mul_f32_e64 v10, v10, v12
	v_mul_f32_e64 v11, v11, v13
	v_lshlrev_b32_e32 v12, 16, v73
	v_mul_f32_e32 v0, 0xbfb8aa3b, v12
	v_exp_f32_e32 v0, v0
	v_mul_f32_e32 v4, 0xbfb8aa3b, v15
	v_exp_f32_e32 v13, v4
	v_cvt_pk_bf16_f32 v4, v10, v11
	v_add_f32_e32 v0, 1.0, v0
	v_rcp_f32_e32 v10, v0
	v_add_f32_e32 v0, 1.0, v13
	v_rcp_f32_e32 v11, v0
	v_and_b32_e32 v13, 0xffff0000, v5
	v_lshlrev_b32_e32 v14, 16, v5
	v_mul_f32_e64 v12, v14, v12
	v_mul_f32_e64 v13, v15, v13
	s_waitcnt vmcnt(6)
	v_and_b32_e32 v15, 0xffff0000, v66
	v_mul_f32_e64 v10, v10, v12
	v_mul_f32_e64 v11, v11, v13
	v_lshlrev_b32_e32 v12, 16, v66
	v_mul_f32_e32 v0, 0xbfb8aa3b, v12
	v_exp_f32_e32 v0, v0
	v_mul_f32_e32 v13, 0xbfb8aa3b, v15
	v_exp_f32_e32 v13, v13
	v_cvt_pk_bf16_f32 v5, v10, v11
	v_lshlrev_b64 v[10:11], 12, v[102:103]
	v_lshl_add_u64 v[10:11], s[0:1], 0, v[10:11]
	v_lshl_add_u64 v[10:11], v[10:11], 0, v[104:105]
	v_add_f32_e32 v0, 1.0, v0
	global_store_dwordx4 v[10:11], v[2:5], off
	s_waitcnt lgkmcnt(0)
	v_lshlrev_b32_e32 v14, 16, v6
	v_and_b32_e32 v11, 0xffff0000, v67
	v_rcp_f32_e32 v2, v0
	v_add_f32_e32 v0, 1.0, v13
	v_rcp_f32_e32 v3, v0
	v_and_b32_e32 v13, 0xffff0000, v6
	v_mul_f32_e64 v4, v14, v12
	v_mul_f32_e64 v5, v15, v13
	v_lshlrev_b32_e32 v10, 16, v7
	v_mul_f32_e64 v2, v2, v4
	v_mul_f32_e64 v3, v3, v5
	v_lshlrev_b32_e32 v4, 16, v67
	v_mul_f32_e32 v0, 0xbfb8aa3b, v4
	v_exp_f32_e32 v0, v0
	v_mul_f32_e32 v5, 0xbfb8aa3b, v11
	v_exp_f32_e32 v5, v5
	v_lshlrev_b32_e32 v6, 16, v68
	v_add_f32_e32 v0, 1.0, v0
	v_rcp_f32_e32 v12, v0
	v_add_f32_e32 v0, 1.0, v5
	v_and_b32_e32 v5, 0xffff0000, v7
	v_rcp_f32_e32 v13, v0
	v_mul_f32_e64 v4, v10, v4
	v_mul_f32_e64 v5, v11, v5
	v_and_b32_e32 v11, 0xffff0000, v68
	v_mul_f32_e32 v0, 0xbfb8aa3b, v6
	v_cvt_pk_bf16_f32 v2, v2, v3
	v_exp_f32_e32 v0, v0
	v_mul_f32_e32 v3, 0xbfb8aa3b, v11
	v_exp_f32_e32 v7, v3
	v_mul_f32_e64 v4, v12, v4
	v_mul_f32_e64 v5, v13, v5
	v_add_f32_e32 v0, 1.0, v0
	v_cvt_pk_bf16_f32 v3, v4, v5
	v_rcp_f32_e32 v4, v0
	v_add_f32_e32 v0, 1.0, v7
	v_rcp_f32_e32 v5, v0
	v_and_b32_e32 v7, 0xffff0000, v8
	v_lshlrev_b32_e32 v10, 16, v8
	v_mul_f32_e64 v6, v10, v6
	v_mul_f32_e64 v7, v11, v7
	v_and_b32_e32 v11, 0xffff0000, v69
	v_mul_f32_e64 v4, v4, v6
	v_mul_f32_e64 v5, v5, v7
	v_lshlrev_b32_e32 v6, 16, v69
	v_mul_f32_e32 v0, 0xbfb8aa3b, v6
	v_exp_f32_e32 v0, v0
	v_mul_f32_e32 v7, 0xbfb8aa3b, v11
	v_exp_f32_e32 v7, v7
	v_lshlrev_b32_e32 v10, 16, v9
	v_add_f32_e32 v0, 1.0, v0
	v_rcp_f32_e32 v12, v0
	v_add_f32_e32 v0, 1.0, v7
	v_rcp_f32_e32 v13, v0
	v_and_b32_e32 v7, 0xffff0000, v9
	v_mul_f32_e64 v6, v10, v6
	v_mul_f32_e64 v7, v11, v7
	v_cvt_pk_bf16_f32 v4, v4, v5
	v_mul_f32_e64 v6, v12, v6
	v_mul_f32_e64 v7, v13, v7
	s_nop 0
	v_cvt_pk_bf16_f32 v5, v6, v7
	v_lshlrev_b64 v[6:7], 12, v[98:99]
	v_lshl_add_u64 v[6:7], s[0:1], 0, v[6:7]
	v_lshl_add_u64 v[6:7], v[6:7], 0, v[100:101]
	global_store_dwordx4 v[6:7], v[2:5], off
	s_barrier
	s_nop 0
	v_ashrrev_i32_e32 v0, 31, v28
	v_lshrrev_b32_e32 v0, 28, v0
	v_add_u32_e32 v0, v28, v0
	v_ashrrev_i32_e32 v146, 4, v0
	v_and_b32_e32 v0, -16, v0
	v_sub_u32_e32 v29, v28, v0
	v_ashrrev_i32_e32 v147, 31, v146
	v_lshlrev_b32_e32 v4, 3, v29
	v_lshlrev_b64 v[2:3], 14, v[146:147]
	v_ashrrev_i32_e32 v5, 31, v4
	v_lshl_add_u64 v[2:3], s[20:21], 0, v[2:3]
	v_lshlrev_b64 v[18:19], 1, v[4:5]
	v_lshl_add_u64 v[20:21], v[2:3], 0, v[18:19]
	v_add_co_u32_e32 v6, vcc, s43, v20
	v_add_u32_e32 v0, 0x200, v28
	s_nop 0
	v_addc_co_u32_e32 v7, vcc, 0, v21, vcc
	global_load_dwordx4 v[2:5], v[6:7], off offset:-4096
	s_nop 0
	global_load_dwordx4 v[6:9], v[6:7], off
	v_ashrrev_i32_e32 v10, 31, v0
	v_readfirstlane_b32 s4, v28
	v_lshrrev_b32_e32 v10, 28, v10
	s_ashr_i32 s22, s4, 1
	v_add_u32_e32 v10, v0, v10
	s_andn2_b32 s22, s22, 31
	v_ashrrev_i32_e32 v148, 4, v10
	v_and_b32_e32 v10, -16, v10
	s_ashr_i32 s34, s22, 31
	v_sub_u32_e32 v30, v0, v10
	s_add_u32 s4, s5, s22
	v_ashrrev_i32_e32 v149, 31, v148
	v_lshlrev_b32_e32 v12, 3, v30
	v_and_b32_e32 v31, 31, v28
	s_addc_u32 s5, s23, s34
	v_lshlrev_b64 v[10:11], 14, v[148:149]
	v_ashrrev_i32_e32 v13, 31, v12
	v_or_b32_e32 v26, s4, v31
	v_mov_b32_e32 v27, s5
	v_lshl_add_u64 v[10:11], s[20:21], 0, v[10:11]
	v_lshlrev_b64 v[22:23], 1, v[12:13]
	v_lshlrev_b64 v[26:27], 14, v[26:27]
	v_lshl_add_u64 v[24:25], v[10:11], 0, v[22:23]
	v_bfe_u32 v32, v28, 5, 1
	v_lshl_add_u64 v[26:27], s[12:13], 0, v[26:27]
	v_add_co_u32_e32 v14, vcc, s43, v24
	v_lshl_add_u64 v[26:27], v[26:27], 0, s[16:17]
	v_lshlrev_b32_e32 v0, 4, v32
	v_addc_co_u32_e32 v15, vcc, 0, v25, vcc
	v_lshl_add_u64 v[26:27], v[26:27], 0, v[0:1]
	v_mul_lo_u32 v149, v146, s45
	v_lshlrev_b32_e32 v156, 4, v29
	global_load_dwordx4 v[10:13], v[14:15], off offset:-4096
	s_nop 0
	global_load_dwordx4 v[14:17], v[14:15], off
	s_nop 0
	global_load_dwordx4 v[98:101], v[26:27], off
	global_load_dwordx4 v[102:105], v[26:27], off offset:32
	global_load_dwordx4 v[106:109], v[26:27], off offset:64
	global_load_dwordx4 v[110:113], v[26:27], off offset:96
	global_load_dwordx4 v[114:117], v[26:27], off offset:128
	global_load_dwordx4 v[118:121], v[26:27], off offset:160
	global_load_dwordx4 v[122:125], v[26:27], off offset:192
	global_load_dwordx4 v[126:129], v[26:27], off offset:224
	v_add3_u32 v26, 0, v149, v156
	s_waitcnt vmcnt(0)
	v_mul_lo_u32 v158, v148, s45
	v_lshlrev_b32_e32 v159, 4, v30
	v_lshlrev_b32_e32 v163, 2, v32
	v_add_u32_e32 v161, 0, v0
	s_add_i32 s7, s7, s22
	v_and_b32_e32 v147, 63, v28
	v_mad_u32_u24 v162, v31, s45, v161
	v_lshl_add_u32 v150, v146, 14, v18
	s_mov_b64 s[78:79], s[20:21]
	v_lshl_add_u32 v152, v148, 14, v22
	v_or_b32_e32 v195, s7, v31
	s_add_i32 s23, s33, 4
	v_mul_lo_u32 v157, v146, s46
	v_mul_lo_u32 v160, v148, s46
	s_add_i32 s27, s22, s27
	s_or_b32 s33, s33, 3
	v_or_b32_e32 v165, 32, v163
	v_or_b32_e32 v166, 33, v163
	v_or_b32_e32 v167, 2, v163
	v_or_b32_e32 v168, 34, v163
	v_or_b32_e32 v169, 3, v163
	v_or_b32_e32 v170, 35, v163
	v_or_b32_e32 v171, 8, v163
	v_or_b32_e32 v172, 40, v163
	v_or_b32_e32 v173, 9, v163
	v_or_b32_e32 v174, 41, v163
	v_or_b32_e32 v175, 10, v163
	v_or_b32_e32 v176, 42, v163
	v_or_b32_e32 v177, 11, v163
	v_or_b32_e32 v178, 43, v163
	v_or_b32_e32 v179, 16, v163
	v_or_b32_e32 v180, 48, v163
	v_or_b32_e32 v181, 17, v163
	v_or_b32_e32 v182, 49, v163
	v_or_b32_e32 v183, 18, v163
	v_or_b32_e32 v184, 50, v163
	v_or_b32_e32 v185, 19, v163
	v_or_b32_e32 v186, 51, v163
	v_or_b32_e32 v187, 24, v163
	v_or_b32_e32 v188, 56, v163
	ds_write_b128 v26, v[2:5]
	v_mad_u64_u32 v[2:3], s[34:35], v146, 48, v[26:27]
	ds_write_b128 v2, v[6:9] offset:34816
	v_add_co_u32_e32 v2, vcc, s47, v20
	v_mov_b32_e32 v4, v1
	s_nop 0
	v_addc_co_u32_e32 v3, vcc, 0, v21, vcc
	global_load_dwordx4 v[130:133], v[2:3], off offset:-4096
	global_load_dwordx4 v[134:137], v[2:3], off
	v_add_co_u32_e32 v2, vcc, s47, v24
	v_mov_b32_e32 v5, v1
	s_nop 0
	v_addc_co_u32_e32 v3, vcc, 0, v25, vcc
	global_load_dwordx4 v[138:141], v[2:3], off offset:-4096
	global_load_dwordx4 v[142:145], v[2:3], off
	v_add3_u32 v2, 0, v158, v159
	v_mov_b32_e32 v6, v1
	v_mov_b32_e32 v7, v1
	v_mov_b32_e32 v8, v1
	v_mov_b32_e32 v9, v1
	v_or_b32_e32 v189, 25, v163
	v_or_b32_e32 v190, 57, v163
	v_or_b32_e32 v191, 26, v163
	v_or_b32_e32 v192, 58, v163
	v_or_b32_e32 v193, 27, v163
	v_or_b32_e32 v194, 59, v163
	ds_write_b128 v2, v[10:13]
	v_mad_u64_u32 v[2:3], s[34:35], v148, 48, v[2:3]
	ds_write_b128 v2, v[14:17] offset:34816
	v_lshrrev_b32_e32 v2, 2, v28
	v_and_or_b32 v0, v2, 3, v163
	v_lshlrev_b32_e32 v2, 1, v28
	v_lshlrev_b32_e32 v3, 3, v28
	v_mad_u32_u24 v0, v0, s46, 0
	v_and_b32_e32 v2, 32, v2
	v_and_b32_e32 v3, 24, v3
	v_mov_b32_e32 v14, v1
	v_mov_b32_e32 v15, v1
	v_add3_u32 v164, v0, v2, v3
	v_mov_b32_e32 v0, v1
	v_mov_b32_e32 v2, v1
	v_mov_b32_e32 v3, v1
	v_mov_b32_e32 v10, v1
	v_mov_b32_e32 v11, v1
	v_mov_b32_e32 v12, v1
	v_mov_b32_e32 v13, v1
	v_mov_b64_e32 v[64:65], v[14:15]
	v_mov_b64_e32 v[48:49], v[14:15]
	v_mov_b64_e32 v[32:33], v[14:15]
	v_mov_b64_e32 v[62:63], v[12:13]
	v_mov_b64_e32 v[60:61], v[10:11]
	v_mov_b64_e32 v[58:59], v[8:9]
	v_mov_b64_e32 v[56:57], v[6:7]
	v_mov_b64_e32 v[54:55], v[4:5]
	v_mov_b64_e32 v[52:53], v[2:3]
	v_mov_b64_e32 v[50:51], v[0:1]
	v_mov_b64_e32 v[46:47], v[12:13]
	v_mov_b64_e32 v[44:45], v[10:11]
	v_mov_b64_e32 v[42:43], v[8:9]
	v_mov_b64_e32 v[40:41], v[6:7]
	v_mov_b64_e32 v[38:39], v[4:5]
	v_mov_b64_e32 v[36:37], v[2:3]
	v_mov_b64_e32 v[34:35], v[0:1]
	v_mov_b64_e32 v[30:31], v[12:13]
	v_mov_b64_e32 v[28:29], v[10:11]
	v_mov_b64_e32 v[26:27], v[8:9]
	v_mov_b64_e32 v[24:25], v[6:7]
	v_mov_b64_e32 v[22:23], v[4:5]
	v_mov_b64_e32 v[20:21], v[2:3]
	v_mov_b64_e32 v[18:19], v[0:1]
	v_mov_b64_e32 v[16:17], v[14:15]
	v_mov_b64_e32 v[14:15], v[12:13]
	v_mov_b64_e32 v[12:13], v[10:11]
	v_mov_b64_e32 v[10:11], v[8:9]
	v_mov_b64_e32 v[8:9], v[6:7]
	v_mov_b64_e32 v[6:7], v[4:5]
	v_mov_b64_e32 v[4:5], v[2:3]
	v_mov_b64_e32 v[2:3], v[0:1]
	s_waitcnt lgkmcnt(0)
	s_movk_i32 s68, 0x5000
	s_mov_b32 s69, 0
	s_mov_b32 s70, 0xe800
	s_mov_b32 s72, 0
	s_barrier
	v_readfirstlane_b32 s73, v255
	s_cmp_lt_u32 s73, 0x100
	s_cbranch_scc1 .Lyp657
	s_setprio 1

.LBB0_657:
	s_add_i32 s7, s25, -2
	s_and_b32 s7, s7, 1
	s_xor_b32 s20, s7, 1
	s_mul_i32 s21, s20, 0x4400
	s_add_i32 s21, s21, 0
	s_mulk_i32 s20, 0xc00
	s_add_i32 s20, s21, s20
	v_add3_u32 v0, s21, v149, v156
	s_waitcnt vmcnt(3)
	ds_write_b128 v0, v[130:133]
	v_add3_u32 v0, s68, v157, v156
	s_waitcnt vmcnt(2)
	ds_write_b128 v0, v[134:137] offset:34816
	v_add3_u32 v0, s21, v158, v159
	s_cmp_lt_u32 s25, s23
	s_waitcnt vmcnt(1)
	ds_write_b128 v0, v[138:141]
	v_add3_u32 v0, s68, v160, v159
	s_cselect_b32 s20, s25, s33
	s_lshl_b32 s20, s20, 20
	s_add_u32 s80, s78, s20
	s_addc_u32 s81, s79, 0
	s_add_u32 s80, s80, 0x1000
	s_addc_u32 s81, s81, 0
	s_add_u32 s82, s80, 0x1000
	s_addc_u32 s83, s81, 0
	s_waitcnt vmcnt(0)
	ds_write_b128 v0, v[142:145] offset:34816
	global_load_dwordx4 v[130:133], v150, s[80:81]
	global_load_dwordx4 v[134:137], v150, s[82:83]
	s_sub_i32 s20, s26, 63
	s_cmp_gt_i32 s20, s27
	global_load_dwordx4 v[138:141], v152, s[80:81]
	global_load_dwordx4 v[142:145], v152, s[82:83]
	s_sub_i32 s20, s26, 63
	s_cmp_gt_i32 s20, s27
	s_cbranch_scc1 .Lff2a_inact
	s_cmp_eq_u32 s72, 0
	s_cbranch_scc1 .Lff2a_first
	s_mul_i32 s20, s7, 0x4400
	v_add_u32_e32 v0, s20, v162
	ds_read_b128 v[198:201], v0
	ds_read_b128 v[202:205], v0 offset:32
	ds_read_b128 v[206:209], v0 offset:8704
	ds_read_b128 v[210:213], v0 offset:8736
	s_add_i32 s75, s24, 0x12800
	v_add_u32_e32 v246, s75, v161
	ds_read_b128 v[218:221], v246
	ds_read_b128 v[234:237], v246 offset:128
	ds_read_b128 v[222:225], v246 offset:32
	ds_read_b128 v[238:241], v246 offset:160
	ds_read_b128 v[226:229], v246 offset:64
	ds_read_b128 v[242:245], v246 offset:192
	ds_read_b128 v[230:233], v246 offset:96
	ds_read_b128 v[246:249], v246 offset:224
	s_waitcnt lgkmcnt(1)
	v_mfma_f32_32x32x16_bf16 v[218:233], v[198:201], v[98:101], v[218:233]
	v_sub_f32_e32 v82, v82, v197
	v_sub_f32_e32 v83, v83, v197
	v_sub_f32_e32 v84, v84, v197
	v_sub_f32_e32 v85, v85, v197
	v_exp_f32_e32 v82, v82
	v_exp_f32_e32 v83, v83
	v_exp_f32_e32 v84, v84
	v_exp_f32_e32 v85, v85
	s_waitcnt lgkmcnt(0)
	v_mfma_f32_32x32x16_bf16 v[234:249], v[206:209], v[98:101], v[234:249]
	v_sub_f32_e32 v86, v86, v197
	v_sub_f32_e32 v87, v87, v197
	v_sub_f32_e32 v88, v88, v197
	v_sub_f32_e32 v89, v89, v197
	v_exp_f32_e32 v86, v86
	v_exp_f32_e32 v87, v87
	v_exp_f32_e32 v88, v88
	v_exp_f32_e32 v89, v89
	v_mfma_f32_32x32x16_bf16 v[218:233], v[202:205], v[102:105], v[218:233]
	v_sub_f32_e32 v66, v66, v197
	v_sub_f32_e32 v67, v67, v197
	v_sub_f32_e32 v68, v68, v197
	v_sub_f32_e32 v69, v69, v197
	v_exp_f32_e32 v66, v66
	v_exp_f32_e32 v67, v67
	v_exp_f32_e32 v68, v68
	v_exp_f32_e32 v69, v69
	ds_read_b128 v[198:201], v0 offset:64
	ds_read_b128 v[202:205], v0 offset:96
	ds_read_b128 v[206:209], v0 offset:8768
	ds_read_b128 v[214:217], v0 offset:8800
	v_mfma_f32_32x32x16_bf16 v[234:249], v[210:213], v[102:105], v[234:249]
	v_add_f32_e32 v250, v82, v86
	v_add_f32_e32 v251, v83, v87
	v_add_f32_e32 v252, v84, v88
	v_add_f32_e32 v253, v85, v89
	v_sub_f32_e32 v70, v70, v197
	v_sub_f32_e32 v71, v71, v197
	v_sub_f32_e32 v72, v72, v197
	v_sub_f32_e32 v73, v73, v197
	s_waitcnt lgkmcnt(3)
	v_mfma_f32_32x32x16_bf16 v[218:233], v[198:201], v[106:109], v[218:233]
	v_exp_f32_e32 v70, v70
	v_exp_f32_e32 v71, v71
	v_exp_f32_e32 v72, v72
	v_exp_f32_e32 v73, v73
	v_add_f32_e32 v250, v250, v66
	v_add_f32_e32 v251, v251, v67
	v_add_f32_e32 v252, v252, v68
	v_add_f32_e32 v253, v253, v69
	s_waitcnt lgkmcnt(1)
	v_mfma_f32_32x32x16_bf16 v[234:249], v[206:209], v[106:109], v[234:249]
	v_sub_f32_e32 v90, v90, v197
	v_sub_f32_e32 v91, v91, v197
	v_sub_f32_e32 v92, v92, v197
	v_sub_f32_e32 v93, v93, v197
	v_exp_f32_e32 v90, v90
	v_exp_f32_e32 v91, v91
	v_exp_f32_e32 v92, v92
	v_exp_f32_e32 v93, v93
	v_mfma_f32_32x32x16_bf16 v[218:233], v[202:205], v[110:113], v[218:233]
	v_add_f32_e32 v250, v250, v70
	v_add_f32_e32 v251, v251, v71
	v_add_f32_e32 v252, v252, v72
	v_add_f32_e32 v253, v253, v73
	v_sub_f32_e32 v94, v94, v197
	v_sub_f32_e32 v95, v95, v197
	v_sub_f32_e32 v96, v96, v197
	v_sub_f32_e32 v97, v97, v197
	ds_read_b128 v[198:201], v0 offset:128
	ds_read_b128 v[202:205], v0 offset:160
	ds_read_b128 v[206:209], v0 offset:8832
	ds_read_b128 v[210:213], v0 offset:8864
	s_waitcnt lgkmcnt(4)
	v_mfma_f32_32x32x16_bf16 v[234:249], v[214:217], v[110:113], v[234:249]
	v_exp_f32_e32 v94, v94
	v_exp_f32_e32 v95, v95
	v_exp_f32_e32 v96, v96
	v_exp_f32_e32 v97, v97
	v_add_f32_e32 v250, v250, v90
	v_add_f32_e32 v251, v251, v91
	v_add_f32_e32 v252, v252, v92
	v_add_f32_e32 v253, v253, v93
	s_waitcnt lgkmcnt(3)
	v_mfma_f32_32x32x16_bf16 v[218:233], v[198:201], v[114:117], v[218:233]
	v_sub_f32_e32 v74, v74, v197
	v_sub_f32_e32 v75, v75, v197
	v_sub_f32_e32 v76, v76, v197
	v_sub_f32_e32 v77, v77, v197
	v_exp_f32_e32 v74, v74
	v_exp_f32_e32 v75, v75
	v_exp_f32_e32 v76, v76
	v_exp_f32_e32 v77, v77
	s_waitcnt lgkmcnt(1)
	v_mfma_f32_32x32x16_bf16 v[234:249], v[206:209], v[114:117], v[234:249]
	v_add_f32_e32 v250, v250, v94
	v_add_f32_e32 v251, v251, v95
	v_add_f32_e32 v252, v252, v96
	v_add_f32_e32 v253, v253, v97
	v_sub_f32_e32 v78, v78, v197
	v_sub_f32_e32 v79, v79, v197
	v_sub_f32_e32 v80, v80, v197
	v_sub_f32_e32 v81, v81, v197
	v_mfma_f32_32x32x16_bf16 v[218:233], v[202:205], v[118:121], v[218:233]
	v_exp_f32_e32 v78, v78
	v_exp_f32_e32 v79, v79
	v_exp_f32_e32 v80, v80
	v_exp_f32_e32 v81, v81
	v_add_f32_e32 v250, v250, v74
	v_add_f32_e32 v251, v251, v75
	v_add_f32_e32 v252, v252, v76
	v_add_f32_e32 v253, v253, v77
	ds_read_b128 v[198:201], v0 offset:192
	ds_read_b128 v[202:205], v0 offset:224
	ds_read_b128 v[206:209], v0 offset:8896
	ds_read_b128 v[214:217], v0 offset:8928
	s_waitcnt lgkmcnt(4)
	v_mfma_f32_32x32x16_bf16 v[234:249], v[210:213], v[118:121], v[234:249]
	v_add_f32_e32 v250, v250, v78
	v_add_f32_e32 v251, v251, v79
	v_add_f32_e32 v252, v252, v80
	v_add_f32_e32 v253, v253, v81
	v_add_f32_e32 v250, v250, v251
	v_add_f32_e32 v252, v252, v253
	v_add_f32_e32 v250, v250, v252
	v_add_f32_e32 v196, v196, v250
	s_waitcnt lgkmcnt(3)
	v_mfma_f32_32x32x16_bf16 v[218:233], v[198:201], v[122:125], v[218:233]
	v_cvt_pk_bf16_f32 v73, v72, v73
	v_cvt_pk_bf16_f32 v72, v70, v71
	v_cvt_pk_bf16_f32 v71, v68, v69
	v_cvt_pk_bf16_f32 v70, v66, v67
	v_cvt_pk_bf16_f32 v66, v82, v83
	v_cvt_pk_bf16_f32 v67, v84, v85
	v_cvt_pk_bf16_f32 v68, v86, v87
	v_cvt_pk_bf16_f32 v69, v88, v89
	s_waitcnt lgkmcnt(1)
	v_mfma_f32_32x32x16_bf16 v[234:249], v[206:209], v[122:125], v[234:249]
	v_cvt_pk_bf16_f32 v81, v80, v81
	v_cvt_pk_bf16_f32 v80, v78, v79
	v_cvt_pk_bf16_f32 v79, v76, v77
	v_cvt_pk_bf16_f32 v78, v74, v75
	v_cvt_pk_bf16_f32 v74, v90, v91
	v_cvt_pk_bf16_f32 v75, v92, v93
	v_cvt_pk_bf16_f32 v76, v94, v95
	v_cvt_pk_bf16_f32 v77, v96, v97
	v_mfma_f32_32x32x16_bf16 v[218:233], v[202:205], v[126:129], v[218:233]
	s_waitcnt lgkmcnt(0)
	v_mfma_f32_32x32x16_bf16 v[234:249], v[214:217], v[126:129], v[234:249]
	s_cmp_le_i32 s26, s27
	s_cbranch_scc1 .Lff2a_z2
	v_cmp_le_i32_e32 vcc, v165, v195
	s_nop 8
	v_cndmask_b32_e32 v234, v155, v234, vcc
	v_cmp_lt_i32_e32 vcc, v163, v195
	s_nop 1
	v_cndmask_b32_e32 v219, v155, v219, vcc
	v_cmp_le_i32_e32 vcc, v163, v195
	s_nop 1
	v_cndmask_b32_e32 v218, v155, v218, vcc
	v_cmp_le_i32_e32 vcc, v166, v195
	s_nop 1
	v_cndmask_b32_e32 v235, v155, v235, vcc
	v_cmp_le_i32_e32 vcc, v167, v195
	s_nop 1
	v_cndmask_b32_e32 v220, v155, v220, vcc
	v_cmp_le_i32_e32 vcc, v168, v195
	s_nop 1
	v_cndmask_b32_e32 v236, v155, v236, vcc
	v_cmp_le_i32_e32 vcc, v169, v195
	s_nop 1
	v_cndmask_b32_e32 v221, v155, v221, vcc
	v_cmp_le_i32_e32 vcc, v170, v195
	s_nop 1
	v_cndmask_b32_e32 v237, v155, v237, vcc
	v_cmp_le_i32_e32 vcc, v171, v195
	s_nop 1
	v_cndmask_b32_e32 v222, v155, v222, vcc
	v_cmp_le_i32_e32 vcc, v172, v195
	s_nop 1
	v_cndmask_b32_e32 v238, v155, v238, vcc
	v_cmp_le_i32_e32 vcc, v173, v195
	s_nop 1
	v_cndmask_b32_e32 v223, v155, v223, vcc
	v_cmp_le_i32_e32 vcc, v174, v195
	s_nop 1
	v_cndmask_b32_e32 v239, v155, v239, vcc
	v_cmp_le_i32_e32 vcc, v175, v195
	s_nop 1
	v_cndmask_b32_e32 v224, v155, v224, vcc
	v_cmp_le_i32_e32 vcc, v176, v195
	s_nop 1
	v_cndmask_b32_e32 v240, v155, v240, vcc
	v_cmp_le_i32_e32 vcc, v177, v195
	s_nop 1
	v_cndmask_b32_e32 v225, v155, v225, vcc
	v_cmp_le_i32_e32 vcc, v178, v195
	s_nop 1
	v_cndmask_b32_e32 v241, v155, v241, vcc
	v_cmp_le_i32_e32 vcc, v179, v195
	s_nop 1
	v_cndmask_b32_e32 v226, v155, v226, vcc
	v_cmp_le_i32_e32 vcc, v180, v195
	s_nop 1
	v_cndmask_b32_e32 v242, v155, v242, vcc
	v_cmp_le_i32_e32 vcc, v181, v195
	s_nop 1
	v_cndmask_b32_e32 v227, v155, v227, vcc
	v_cmp_le_i32_e32 vcc, v182, v195
	s_nop 1
	v_cndmask_b32_e32 v243, v155, v243, vcc
	v_cmp_le_i32_e32 vcc, v183, v195
	s_nop 1
	v_cndmask_b32_e32 v228, v155, v228, vcc
	v_cmp_le_i32_e32 vcc, v184, v195
	s_nop 1
	v_cndmask_b32_e32 v244, v155, v244, vcc
	v_cmp_le_i32_e32 vcc, v185, v195
	s_nop 1
	v_cndmask_b32_e32 v229, v155, v229, vcc
	v_cmp_le_i32_e32 vcc, v186, v195
	s_nop 1
	v_cndmask_b32_e32 v245, v155, v245, vcc
	v_cmp_le_i32_e32 vcc, v187, v195
	s_nop 1
	v_cndmask_b32_e32 v230, v155, v230, vcc
	v_cmp_le_i32_e32 vcc, v188, v195
	s_nop 1
	v_cndmask_b32_e32 v246, v155, v246, vcc
	v_cmp_le_i32_e32 vcc, v189, v195
	s_nop 1
	v_cndmask_b32_e32 v231, v155, v231, vcc
	v_cmp_le_i32_e32 vcc, v190, v195
	s_nop 1
	v_cndmask_b32_e32 v247, v155, v247, vcc
	v_cmp_le_i32_e32 vcc, v191, v195
	s_nop 1
	v_cndmask_b32_e32 v232, v155, v232, vcc
	v_cmp_le_i32_e32 vcc, v192, v195
	s_nop 1
	v_cndmask_b32_e32 v248, v155, v248, vcc
	v_cmp_le_i32_e32 vcc, v193, v195
	s_nop 1
	v_cndmask_b32_e32 v233, v155, v233, vcc
	v_cmp_le_i32_e32 vcc, v194, v195
	s_nop 1
	v_cndmask_b32_e32 v249, v155, v249, vcc

.Lff2a_first:
	s_mul_i32 s20, s7, 0x4400
	v_add_u32_e32 v0, s20, v162
	ds_read_b128 v[198:201], v0
	ds_read_b128 v[202:205], v0 offset:32
	ds_read_b128 v[206:209], v0 offset:8704
	ds_read_b128 v[210:213], v0 offset:8736
	s_add_i32 s75, s24, 0x12800
	v_add_u32_e32 v246, s75, v161
	ds_read_b128 v[218:221], v246
	ds_read_b128 v[234:237], v246 offset:128
	ds_read_b128 v[222:225], v246 offset:32
	ds_read_b128 v[238:241], v246 offset:160
	ds_read_b128 v[226:229], v246 offset:64
	ds_read_b128 v[242:245], v246 offset:192
	ds_read_b128 v[230:233], v246 offset:96
	ds_read_b128 v[246:249], v246 offset:224
	s_waitcnt lgkmcnt(1)
	v_mfma_f32_32x32x16_bf16 v[218:233], v[198:201], v[98:101], v[218:233]
	s_waitcnt lgkmcnt(0)
	v_mfma_f32_32x32x16_bf16 v[234:249], v[206:209], v[98:101], v[234:249]
	v_mfma_f32_32x32x16_bf16 v[218:233], v[202:205], v[102:105], v[218:233]
	ds_read_b128 v[198:201], v0 offset:64
	ds_read_b128 v[202:205], v0 offset:96
	ds_read_b128 v[206:209], v0 offset:8768
	ds_read_b128 v[214:217], v0 offset:8800
	v_mfma_f32_32x32x16_bf16 v[234:249], v[210:213], v[102:105], v[234:249]
	s_waitcnt lgkmcnt(3)
	v_mfma_f32_32x32x16_bf16 v[218:233], v[198:201], v[106:109], v[218:233]
	s_waitcnt lgkmcnt(1)
	v_mfma_f32_32x32x16_bf16 v[234:249], v[206:209], v[106:109], v[234:249]
	v_mfma_f32_32x32x16_bf16 v[218:233], v[202:205], v[110:113], v[218:233]
	ds_read_b128 v[198:201], v0 offset:128
	ds_read_b128 v[202:205], v0 offset:160
	ds_read_b128 v[206:209], v0 offset:8832
	ds_read_b128 v[210:213], v0 offset:8864
	s_waitcnt lgkmcnt(4)
	v_mfma_f32_32x32x16_bf16 v[234:249], v[214:217], v[110:113], v[234:249]
	s_waitcnt lgkmcnt(3)
	v_mfma_f32_32x32x16_bf16 v[218:233], v[198:201], v[114:117], v[218:233]
	s_waitcnt lgkmcnt(1)
	v_mfma_f32_32x32x16_bf16 v[234:249], v[206:209], v[114:117], v[234:249]
	v_mfma_f32_32x32x16_bf16 v[218:233], v[202:205], v[118:121], v[218:233]
	ds_read_b128 v[198:201], v0 offset:192
	ds_read_b128 v[202:205], v0 offset:224
	ds_read_b128 v[206:209], v0 offset:8896
	ds_read_b128 v[214:217], v0 offset:8928
	s_waitcnt lgkmcnt(4)
	v_mfma_f32_32x32x16_bf16 v[234:249], v[210:213], v[118:121], v[234:249]
	s_waitcnt lgkmcnt(3)
	v_mfma_f32_32x32x16_bf16 v[218:233], v[198:201], v[122:125], v[218:233]
	s_waitcnt lgkmcnt(1)
	v_mfma_f32_32x32x16_bf16 v[234:249], v[206:209], v[122:125], v[234:249]
	v_mfma_f32_32x32x16_bf16 v[218:233], v[202:205], v[126:129], v[218:233]
	s_waitcnt lgkmcnt(0)
	v_mfma_f32_32x32x16_bf16 v[234:249], v[214:217], v[126:129], v[234:249]
	s_cmp_le_i32 s26, s27
	s_cbranch_scc1 .Lff2a_m1
	v_cmp_le_i32_e32 vcc, v165, v195
	s_nop 8
	v_cndmask_b32_e32 v234, v155, v234, vcc
	v_cmp_lt_i32_e32 vcc, v163, v195
	s_nop 1
	v_cndmask_b32_e32 v219, v155, v219, vcc
	v_cmp_le_i32_e32 vcc, v163, v195
	s_nop 1
	v_cndmask_b32_e32 v218, v155, v218, vcc
	v_cmp_le_i32_e32 vcc, v166, v195
	s_nop 1
	v_cndmask_b32_e32 v235, v155, v235, vcc
	v_cmp_le_i32_e32 vcc, v167, v195
	s_nop 1
	v_cndmask_b32_e32 v220, v155, v220, vcc
	v_cmp_le_i32_e32 vcc, v168, v195
	s_nop 1
	v_cndmask_b32_e32 v236, v155, v236, vcc
	v_cmp_le_i32_e32 vcc, v169, v195
	s_nop 1
	v_cndmask_b32_e32 v221, v155, v221, vcc
	v_cmp_le_i32_e32 vcc, v170, v195
	s_nop 1
	v_cndmask_b32_e32 v237, v155, v237, vcc
	v_cmp_le_i32_e32 vcc, v171, v195
	s_nop 1
	v_cndmask_b32_e32 v222, v155, v222, vcc
	v_cmp_le_i32_e32 vcc, v172, v195
	s_nop 1
	v_cndmask_b32_e32 v238, v155, v238, vcc
	v_cmp_le_i32_e32 vcc, v173, v195
	s_nop 1
	v_cndmask_b32_e32 v223, v155, v223, vcc
	v_cmp_le_i32_e32 vcc, v174, v195
	s_nop 1
	v_cndmask_b32_e32 v239, v155, v239, vcc
	v_cmp_le_i32_e32 vcc, v175, v195
	s_nop 1
	v_cndmask_b32_e32 v224, v155, v224, vcc
	v_cmp_le_i32_e32 vcc, v176, v195
	s_nop 1
	v_cndmask_b32_e32 v240, v155, v240, vcc
	v_cmp_le_i32_e32 vcc, v177, v195
	s_nop 1
	v_cndmask_b32_e32 v225, v155, v225, vcc
	v_cmp_le_i32_e32 vcc, v178, v195
	s_nop 1
	v_cndmask_b32_e32 v241, v155, v241, vcc
	v_cmp_le_i32_e32 vcc, v179, v195
	s_nop 1
	v_cndmask_b32_e32 v226, v155, v226, vcc
	v_cmp_le_i32_e32 vcc, v180, v195
	s_nop 1
	v_cndmask_b32_e32 v242, v155, v242, vcc
	v_cmp_le_i32_e32 vcc, v181, v195
	s_nop 1
	v_cndmask_b32_e32 v227, v155, v227, vcc
	v_cmp_le_i32_e32 vcc, v182, v195
	s_nop 1
	v_cndmask_b32_e32 v243, v155, v243, vcc
	v_cmp_le_i32_e32 vcc, v183, v195
	s_nop 1
	v_cndmask_b32_e32 v228, v155, v228, vcc
	v_cmp_le_i32_e32 vcc, v184, v195
	s_nop 1
	v_cndmask_b32_e32 v244, v155, v244, vcc
	v_cmp_le_i32_e32 vcc, v185, v195
	s_nop 1
	v_cndmask_b32_e32 v229, v155, v229, vcc
	v_cmp_le_i32_e32 vcc, v186, v195
	s_nop 1
	v_cndmask_b32_e32 v245, v155, v245, vcc
	v_cmp_le_i32_e32 vcc, v187, v195
	s_nop 1
	v_cndmask_b32_e32 v230, v155, v230, vcc
	v_cmp_le_i32_e32 vcc, v188, v195
	s_nop 1
	v_cndmask_b32_e32 v246, v155, v246, vcc
	v_cmp_le_i32_e32 vcc, v189, v195
	s_nop 1
	v_cndmask_b32_e32 v231, v155, v231, vcc
	v_cmp_le_i32_e32 vcc, v190, v195
	s_nop 1
	v_cndmask_b32_e32 v247, v155, v247, vcc
	v_cmp_le_i32_e32 vcc, v191, v195
	s_nop 1
	v_cndmask_b32_e32 v232, v155, v232, vcc
	v_cmp_le_i32_e32 vcc, v192, v195
	s_nop 1
	v_cndmask_b32_e32 v248, v155, v248, vcc
	v_cmp_le_i32_e32 vcc, v193, v195
	s_nop 1
	v_cndmask_b32_e32 v233, v155, v233, vcc
	v_cmp_le_i32_e32 vcc, v194, v195
	s_nop 1
	v_cndmask_b32_e32 v249, v155, v249, vcc

.Lff2b_top:
	s_add_i32 s7, s25, -2
	s_and_b32 s7, s7, 1
	s_xor_b32 s20, s7, 1
	s_mul_i32 s21, s20, 0x4400
	s_add_i32 s21, s21, 0
	s_mulk_i32 s20, 0xc00
	s_add_i32 s20, s21, s20
	v_add3_u32 v0, s21, v149, v156
	s_waitcnt vmcnt(3)
	ds_write_b128 v0, v[130:133]
	v_add3_u32 v0, s68, v157, v156
	s_waitcnt vmcnt(2)
	ds_write_b128 v0, v[134:137] offset:34816
	v_add3_u32 v0, s21, v158, v159
	s_cmp_lt_u32 s25, s23
	s_waitcnt vmcnt(1)
	ds_write_b128 v0, v[138:141]
	v_add3_u32 v0, s68, v160, v159
	s_cselect_b32 s20, s25, s33
	s_lshl_b32 s20, s20, 20
	s_add_u32 s80, s78, s20
	s_addc_u32 s81, s79, 0
	s_add_u32 s80, s80, 0x1000
	s_addc_u32 s81, s81, 0
	s_add_u32 s82, s80, 0x1000
	s_addc_u32 s83, s81, 0
	s_waitcnt vmcnt(0)
	ds_write_b128 v0, v[142:145] offset:34816
	global_load_dwordx4 v[130:133], v150, s[80:81]
	global_load_dwordx4 v[134:137], v150, s[82:83]
	s_sub_i32 s20, s26, 63
	s_cmp_gt_i32 s20, s27
	global_load_dwordx4 v[138:141], v152, s[80:81]
	global_load_dwordx4 v[142:145], v152, s[82:83]
	s_sub_i32 s20, s26, 63
	s_cmp_gt_i32 s20, s27
	s_cbranch_scc1 .Lff2b_inact
	s_cmp_eq_u32 s72, 0
	s_cbranch_scc1 .Lff2b_first
	s_mul_i32 s20, s7, 0x4400
	v_add_u32_e32 v0, s20, v162
	ds_read_b128 v[198:201], v0
	ds_read_b128 v[202:205], v0 offset:32
	ds_read_b128 v[206:209], v0 offset:8704
	ds_read_b128 v[210:213], v0 offset:8736
	s_add_i32 s75, s24, 0x12800
	v_add_u32_e32 v78, s75, v161
	ds_read_b128 v[82:85], v78
	ds_read_b128 v[66:69], v78 offset:128
	ds_read_b128 v[86:89], v78 offset:32
	ds_read_b128 v[70:73], v78 offset:160
	ds_read_b128 v[90:93], v78 offset:64
	ds_read_b128 v[74:77], v78 offset:192
	ds_read_b128 v[94:97], v78 offset:96
	ds_read_b128 v[78:81], v78 offset:224
	s_waitcnt lgkmcnt(1)
	v_mfma_f32_32x32x16_bf16 v[82:97], v[198:201], v[98:101], v[82:97]
	v_sub_f32_e32 v218, v218, v197
	v_sub_f32_e32 v219, v219, v197
	v_sub_f32_e32 v220, v220, v197
	v_sub_f32_e32 v221, v221, v197
	v_exp_f32_e32 v218, v218
	v_exp_f32_e32 v219, v219
	v_exp_f32_e32 v220, v220
	v_exp_f32_e32 v221, v221
	s_waitcnt lgkmcnt(0)
	v_mfma_f32_32x32x16_bf16 v[66:81], v[206:209], v[98:101], v[66:81]
	v_sub_f32_e32 v222, v222, v197
	v_sub_f32_e32 v223, v223, v197
	v_sub_f32_e32 v224, v224, v197
	v_sub_f32_e32 v225, v225, v197
	v_exp_f32_e32 v222, v222
	v_exp_f32_e32 v223, v223
	v_exp_f32_e32 v224, v224
	v_exp_f32_e32 v225, v225
	v_mfma_f32_32x32x16_bf16 v[82:97], v[202:205], v[102:105], v[82:97]
	v_sub_f32_e32 v234, v234, v197
	v_sub_f32_e32 v235, v235, v197
	v_sub_f32_e32 v236, v236, v197
	v_sub_f32_e32 v237, v237, v197
	v_exp_f32_e32 v234, v234
	v_exp_f32_e32 v235, v235
	v_exp_f32_e32 v236, v236
	v_exp_f32_e32 v237, v237
	ds_read_b128 v[198:201], v0 offset:64
	ds_read_b128 v[202:205], v0 offset:96
	ds_read_b128 v[206:209], v0 offset:8768
	ds_read_b128 v[214:217], v0 offset:8800
	v_mfma_f32_32x32x16_bf16 v[66:81], v[210:213], v[102:105], v[66:81]
	v_add_f32_e32 v250, v218, v222
	v_add_f32_e32 v251, v219, v223
	v_add_f32_e32 v252, v220, v224
	v_add_f32_e32 v253, v221, v225
	v_sub_f32_e32 v238, v238, v197
	v_sub_f32_e32 v239, v239, v197
	v_sub_f32_e32 v240, v240, v197
	v_sub_f32_e32 v241, v241, v197
	s_waitcnt lgkmcnt(3)
	v_mfma_f32_32x32x16_bf16 v[82:97], v[198:201], v[106:109], v[82:97]
	v_exp_f32_e32 v238, v238
	v_exp_f32_e32 v239, v239
	v_exp_f32_e32 v240, v240
	v_exp_f32_e32 v241, v241
	v_add_f32_e32 v250, v250, v234
	v_add_f32_e32 v251, v251, v235
	v_add_f32_e32 v252, v252, v236
	v_add_f32_e32 v253, v253, v237
	s_waitcnt lgkmcnt(1)
	v_mfma_f32_32x32x16_bf16 v[66:81], v[206:209], v[106:109], v[66:81]
	v_sub_f32_e32 v226, v226, v197
	v_sub_f32_e32 v227, v227, v197
	v_sub_f32_e32 v228, v228, v197
	v_sub_f32_e32 v229, v229, v197
	v_exp_f32_e32 v226, v226
	v_exp_f32_e32 v227, v227
	v_exp_f32_e32 v228, v228
	v_exp_f32_e32 v229, v229
	v_mfma_f32_32x32x16_bf16 v[82:97], v[202:205], v[110:113], v[82:97]
	v_add_f32_e32 v250, v250, v238
	v_add_f32_e32 v251, v251, v239
	v_add_f32_e32 v252, v252, v240
	v_add_f32_e32 v253, v253, v241
	v_sub_f32_e32 v230, v230, v197
	v_sub_f32_e32 v231, v231, v197
	v_sub_f32_e32 v232, v232, v197
	v_sub_f32_e32 v233, v233, v197
	ds_read_b128 v[198:201], v0 offset:128
	ds_read_b128 v[202:205], v0 offset:160
	ds_read_b128 v[206:209], v0 offset:8832
	ds_read_b128 v[210:213], v0 offset:8864
	s_waitcnt lgkmcnt(4)
	v_mfma_f32_32x32x16_bf16 v[66:81], v[214:217], v[110:113], v[66:81]
	v_exp_f32_e32 v230, v230
	v_exp_f32_e32 v231, v231
	v_exp_f32_e32 v232, v232
	v_exp_f32_e32 v233, v233
	v_add_f32_e32 v250, v250, v226
	v_add_f32_e32 v251, v251, v227
	v_add_f32_e32 v252, v252, v228
	v_add_f32_e32 v253, v253, v229
	s_waitcnt lgkmcnt(3)
	v_mfma_f32_32x32x16_bf16 v[82:97], v[198:201], v[114:117], v[82:97]
	v_sub_f32_e32 v242, v242, v197
	v_sub_f32_e32 v243, v243, v197
	v_sub_f32_e32 v244, v244, v197
	v_sub_f32_e32 v245, v245, v197
	v_exp_f32_e32 v242, v242
	v_exp_f32_e32 v243, v243
	v_exp_f32_e32 v244, v244
	v_exp_f32_e32 v245, v245
	s_waitcnt lgkmcnt(1)
	v_mfma_f32_32x32x16_bf16 v[66:81], v[206:209], v[114:117], v[66:81]
	v_add_f32_e32 v250, v250, v230
	v_add_f32_e32 v251, v251, v231
	v_add_f32_e32 v252, v252, v232
	v_add_f32_e32 v253, v253, v233
	v_sub_f32_e32 v246, v246, v197
	v_sub_f32_e32 v247, v247, v197
	v_sub_f32_e32 v248, v248, v197
	v_sub_f32_e32 v249, v249, v197
	v_mfma_f32_32x32x16_bf16 v[82:97], v[202:205], v[118:121], v[82:97]
	v_exp_f32_e32 v246, v246
	v_exp_f32_e32 v247, v247
	v_exp_f32_e32 v248, v248
	v_exp_f32_e32 v249, v249
	v_add_f32_e32 v250, v250, v242
	v_add_f32_e32 v251, v251, v243
	v_add_f32_e32 v252, v252, v244
	v_add_f32_e32 v253, v253, v245
	ds_read_b128 v[198:201], v0 offset:192
	ds_read_b128 v[202:205], v0 offset:224
	ds_read_b128 v[206:209], v0 offset:8896
	ds_read_b128 v[214:217], v0 offset:8928
	s_waitcnt lgkmcnt(4)
	v_mfma_f32_32x32x16_bf16 v[66:81], v[210:213], v[118:121], v[66:81]
	v_add_f32_e32 v250, v250, v246
	v_add_f32_e32 v251, v251, v247
	v_add_f32_e32 v252, v252, v248
	v_add_f32_e32 v253, v253, v249
	v_add_f32_e32 v250, v250, v251
	v_add_f32_e32 v252, v252, v253
	v_add_f32_e32 v250, v250, v252
	v_add_f32_e32 v196, v196, v250
	s_waitcnt lgkmcnt(3)
	v_mfma_f32_32x32x16_bf16 v[82:97], v[198:201], v[122:125], v[82:97]
	v_cvt_pk_bf16_f32 v241, v240, v241
	v_cvt_pk_bf16_f32 v240, v238, v239
	v_cvt_pk_bf16_f32 v239, v236, v237
	v_cvt_pk_bf16_f32 v238, v234, v235
	v_cvt_pk_bf16_f32 v234, v218, v219
	v_cvt_pk_bf16_f32 v235, v220, v221
	v_cvt_pk_bf16_f32 v236, v222, v223
	v_cvt_pk_bf16_f32 v237, v224, v225
	s_waitcnt lgkmcnt(1)
	v_mfma_f32_32x32x16_bf16 v[66:81], v[206:209], v[122:125], v[66:81]
	v_cvt_pk_bf16_f32 v249, v248, v249
	v_cvt_pk_bf16_f32 v248, v246, v247
	v_cvt_pk_bf16_f32 v247, v244, v245
	v_cvt_pk_bf16_f32 v246, v242, v243
	v_cvt_pk_bf16_f32 v242, v226, v227
	v_cvt_pk_bf16_f32 v243, v228, v229
	v_cvt_pk_bf16_f32 v244, v230, v231
	v_cvt_pk_bf16_f32 v245, v232, v233
	v_mfma_f32_32x32x16_bf16 v[82:97], v[202:205], v[126:129], v[82:97]
	s_waitcnt lgkmcnt(0)
	v_mfma_f32_32x32x16_bf16 v[66:81], v[214:217], v[126:129], v[66:81]
	s_cmp_le_i32 s26, s27
	s_cbranch_scc1 .Lff2b_z2
	v_cmp_le_i32_e32 vcc, v165, v195
	s_nop 8
	v_cndmask_b32_e32 v66, v155, v66, vcc
	v_cmp_lt_i32_e32 vcc, v163, v195
	s_nop 1
	v_cndmask_b32_e32 v83, v155, v83, vcc
	v_cmp_le_i32_e32 vcc, v163, v195
	s_nop 1
	v_cndmask_b32_e32 v82, v155, v82, vcc
	v_cmp_le_i32_e32 vcc, v166, v195
	s_nop 1
	v_cndmask_b32_e32 v67, v155, v67, vcc
	v_cmp_le_i32_e32 vcc, v167, v195
	s_nop 1
	v_cndmask_b32_e32 v84, v155, v84, vcc
	v_cmp_le_i32_e32 vcc, v168, v195
	s_nop 1
	v_cndmask_b32_e32 v68, v155, v68, vcc
	v_cmp_le_i32_e32 vcc, v169, v195
	s_nop 1
	v_cndmask_b32_e32 v85, v155, v85, vcc
	v_cmp_le_i32_e32 vcc, v170, v195
	s_nop 1
	v_cndmask_b32_e32 v69, v155, v69, vcc
	v_cmp_le_i32_e32 vcc, v171, v195
	s_nop 1
	v_cndmask_b32_e32 v86, v155, v86, vcc
	v_cmp_le_i32_e32 vcc, v172, v195
	s_nop 1
	v_cndmask_b32_e32 v70, v155, v70, vcc
	v_cmp_le_i32_e32 vcc, v173, v195
	s_nop 1
	v_cndmask_b32_e32 v87, v155, v87, vcc
	v_cmp_le_i32_e32 vcc, v174, v195
	s_nop 1
	v_cndmask_b32_e32 v71, v155, v71, vcc
	v_cmp_le_i32_e32 vcc, v175, v195
	s_nop 1
	v_cndmask_b32_e32 v88, v155, v88, vcc
	v_cmp_le_i32_e32 vcc, v176, v195
	s_nop 1
	v_cndmask_b32_e32 v72, v155, v72, vcc
	v_cmp_le_i32_e32 vcc, v177, v195
	s_nop 1
	v_cndmask_b32_e32 v89, v155, v89, vcc
	v_cmp_le_i32_e32 vcc, v178, v195
	s_nop 1
	v_cndmask_b32_e32 v73, v155, v73, vcc
	v_cmp_le_i32_e32 vcc, v179, v195
	s_nop 1
	v_cndmask_b32_e32 v90, v155, v90, vcc
	v_cmp_le_i32_e32 vcc, v180, v195
	s_nop 1
	v_cndmask_b32_e32 v74, v155, v74, vcc
	v_cmp_le_i32_e32 vcc, v181, v195
	s_nop 1
	v_cndmask_b32_e32 v91, v155, v91, vcc
	v_cmp_le_i32_e32 vcc, v182, v195
	s_nop 1
	v_cndmask_b32_e32 v75, v155, v75, vcc
	v_cmp_le_i32_e32 vcc, v183, v195
	s_nop 1
	v_cndmask_b32_e32 v92, v155, v92, vcc
	v_cmp_le_i32_e32 vcc, v184, v195
	s_nop 1
	v_cndmask_b32_e32 v76, v155, v76, vcc
	v_cmp_le_i32_e32 vcc, v185, v195
	s_nop 1
	v_cndmask_b32_e32 v93, v155, v93, vcc
	v_cmp_le_i32_e32 vcc, v186, v195
	s_nop 1
	v_cndmask_b32_e32 v77, v155, v77, vcc
	v_cmp_le_i32_e32 vcc, v187, v195
	s_nop 1
	v_cndmask_b32_e32 v94, v155, v94, vcc
	v_cmp_le_i32_e32 vcc, v188, v195
	s_nop 1
	v_cndmask_b32_e32 v78, v155, v78, vcc
	v_cmp_le_i32_e32 vcc, v189, v195
	s_nop 1
	v_cndmask_b32_e32 v95, v155, v95, vcc
	v_cmp_le_i32_e32 vcc, v190, v195
	s_nop 1
	v_cndmask_b32_e32 v79, v155, v79, vcc
	v_cmp_le_i32_e32 vcc, v191, v195
	s_nop 1
	v_cndmask_b32_e32 v96, v155, v96, vcc
	v_cmp_le_i32_e32 vcc, v192, v195
	s_nop 1
	v_cndmask_b32_e32 v80, v155, v80, vcc
	v_cmp_le_i32_e32 vcc, v193, v195
	s_nop 1
	v_cndmask_b32_e32 v97, v155, v97, vcc
	v_cmp_le_i32_e32 vcc, v194, v195
	s_nop 1
	v_cndmask_b32_e32 v81, v155, v81, vcc

.Lff2b_first:
	s_mul_i32 s20, s7, 0x4400
	v_add_u32_e32 v0, s20, v162
	ds_read_b128 v[198:201], v0
	ds_read_b128 v[202:205], v0 offset:32
	ds_read_b128 v[206:209], v0 offset:8704
	ds_read_b128 v[210:213], v0 offset:8736
	s_add_i32 s75, s24, 0x12800
	v_add_u32_e32 v78, s75, v161
	ds_read_b128 v[82:85], v78
	ds_read_b128 v[66:69], v78 offset:128
	ds_read_b128 v[86:89], v78 offset:32
	ds_read_b128 v[70:73], v78 offset:160
	ds_read_b128 v[90:93], v78 offset:64
	ds_read_b128 v[74:77], v78 offset:192
	ds_read_b128 v[94:97], v78 offset:96
	ds_read_b128 v[78:81], v78 offset:224
	s_waitcnt lgkmcnt(1)
	v_mfma_f32_32x32x16_bf16 v[82:97], v[198:201], v[98:101], v[82:97]
	s_waitcnt lgkmcnt(0)
	v_mfma_f32_32x32x16_bf16 v[66:81], v[206:209], v[98:101], v[66:81]
	v_mfma_f32_32x32x16_bf16 v[82:97], v[202:205], v[102:105], v[82:97]
	ds_read_b128 v[198:201], v0 offset:64
	ds_read_b128 v[202:205], v0 offset:96
	ds_read_b128 v[206:209], v0 offset:8768
	ds_read_b128 v[214:217], v0 offset:8800
	v_mfma_f32_32x32x16_bf16 v[66:81], v[210:213], v[102:105], v[66:81]
	s_waitcnt lgkmcnt(3)
	v_mfma_f32_32x32x16_bf16 v[82:97], v[198:201], v[106:109], v[82:97]
	s_waitcnt lgkmcnt(1)
	v_mfma_f32_32x32x16_bf16 v[66:81], v[206:209], v[106:109], v[66:81]
	v_mfma_f32_32x32x16_bf16 v[82:97], v[202:205], v[110:113], v[82:97]
	ds_read_b128 v[198:201], v0 offset:128
	ds_read_b128 v[202:205], v0 offset:160
	ds_read_b128 v[206:209], v0 offset:8832
	ds_read_b128 v[210:213], v0 offset:8864
	s_waitcnt lgkmcnt(4)
	v_mfma_f32_32x32x16_bf16 v[66:81], v[214:217], v[110:113], v[66:81]
	s_waitcnt lgkmcnt(3)
	v_mfma_f32_32x32x16_bf16 v[82:97], v[198:201], v[114:117], v[82:97]
	s_waitcnt lgkmcnt(1)
	v_mfma_f32_32x32x16_bf16 v[66:81], v[206:209], v[114:117], v[66:81]
	v_mfma_f32_32x32x16_bf16 v[82:97], v[202:205], v[118:121], v[82:97]
	ds_read_b128 v[198:201], v0 offset:192
	ds_read_b128 v[202:205], v0 offset:224
	ds_read_b128 v[206:209], v0 offset:8896
	ds_read_b128 v[214:217], v0 offset:8928
	s_waitcnt lgkmcnt(4)
	v_mfma_f32_32x32x16_bf16 v[66:81], v[210:213], v[118:121], v[66:81]
	s_waitcnt lgkmcnt(3)
	v_mfma_f32_32x32x16_bf16 v[82:97], v[198:201], v[122:125], v[82:97]
	s_waitcnt lgkmcnt(1)
	v_mfma_f32_32x32x16_bf16 v[66:81], v[206:209], v[122:125], v[66:81]
	v_mfma_f32_32x32x16_bf16 v[82:97], v[202:205], v[126:129], v[82:97]
	s_waitcnt lgkmcnt(0)
	v_mfma_f32_32x32x16_bf16 v[66:81], v[214:217], v[126:129], v[66:81]
	s_cmp_le_i32 s26, s27
	s_cbranch_scc1 .Lff2b_m1
	v_cmp_le_i32_e32 vcc, v165, v195
	s_nop 8
	v_cndmask_b32_e32 v66, v155, v66, vcc
	v_cmp_lt_i32_e32 vcc, v163, v195
	s_nop 1
	v_cndmask_b32_e32 v83, v155, v83, vcc
	v_cmp_le_i32_e32 vcc, v163, v195
	s_nop 1
	v_cndmask_b32_e32 v82, v155, v82, vcc
	v_cmp_le_i32_e32 vcc, v166, v195
	s_nop 1
	v_cndmask_b32_e32 v67, v155, v67, vcc
	v_cmp_le_i32_e32 vcc, v167, v195
	s_nop 1
	v_cndmask_b32_e32 v84, v155, v84, vcc
	v_cmp_le_i32_e32 vcc, v168, v195
	s_nop 1
	v_cndmask_b32_e32 v68, v155, v68, vcc
	v_cmp_le_i32_e32 vcc, v169, v195
	s_nop 1
	v_cndmask_b32_e32 v85, v155, v85, vcc
	v_cmp_le_i32_e32 vcc, v170, v195
	s_nop 1
	v_cndmask_b32_e32 v69, v155, v69, vcc
	v_cmp_le_i32_e32 vcc, v171, v195
	s_nop 1
	v_cndmask_b32_e32 v86, v155, v86, vcc
	v_cmp_le_i32_e32 vcc, v172, v195
	s_nop 1
	v_cndmask_b32_e32 v70, v155, v70, vcc
	v_cmp_le_i32_e32 vcc, v173, v195
	s_nop 1
	v_cndmask_b32_e32 v87, v155, v87, vcc
	v_cmp_le_i32_e32 vcc, v174, v195
	s_nop 1
	v_cndmask_b32_e32 v71, v155, v71, vcc
	v_cmp_le_i32_e32 vcc, v175, v195
	s_nop 1
	v_cndmask_b32_e32 v88, v155, v88, vcc
	v_cmp_le_i32_e32 vcc, v176, v195
	s_nop 1
	v_cndmask_b32_e32 v72, v155, v72, vcc
	v_cmp_le_i32_e32 vcc, v177, v195
	s_nop 1
	v_cndmask_b32_e32 v89, v155, v89, vcc
	v_cmp_le_i32_e32 vcc, v178, v195
	s_nop 1
	v_cndmask_b32_e32 v73, v155, v73, vcc
	v_cmp_le_i32_e32 vcc, v179, v195
	s_nop 1
	v_cndmask_b32_e32 v90, v155, v90, vcc
	v_cmp_le_i32_e32 vcc, v180, v195
	s_nop 1
	v_cndmask_b32_e32 v74, v155, v74, vcc
	v_cmp_le_i32_e32 vcc, v181, v195
	s_nop 1
	v_cndmask_b32_e32 v91, v155, v91, vcc
	v_cmp_le_i32_e32 vcc, v182, v195
	s_nop 1
	v_cndmask_b32_e32 v75, v155, v75, vcc
	v_cmp_le_i32_e32 vcc, v183, v195
	s_nop 1
	v_cndmask_b32_e32 v92, v155, v92, vcc
	v_cmp_le_i32_e32 vcc, v184, v195
	s_nop 1
	v_cndmask_b32_e32 v76, v155, v76, vcc
	v_cmp_le_i32_e32 vcc, v185, v195
	s_nop 1
	v_cndmask_b32_e32 v93, v155, v93, vcc
	v_cmp_le_i32_e32 vcc, v186, v195
	s_nop 1
	v_cndmask_b32_e32 v77, v155, v77, vcc
	v_cmp_le_i32_e32 vcc, v187, v195
	s_nop 1
	v_cndmask_b32_e32 v94, v155, v94, vcc
	v_cmp_le_i32_e32 vcc, v188, v195
	s_nop 1
	v_cndmask_b32_e32 v78, v155, v78, vcc
	v_cmp_le_i32_e32 vcc, v189, v195
	s_nop 1
	v_cndmask_b32_e32 v95, v155, v95, vcc
	v_cmp_le_i32_e32 vcc, v190, v195
	s_nop 1
	v_cndmask_b32_e32 v79, v155, v79, vcc
	v_cmp_le_i32_e32 vcc, v191, v195
	s_nop 1
	v_cndmask_b32_e32 v96, v155, v96, vcc
	v_cmp_le_i32_e32 vcc, v192, v195
	s_nop 1
	v_cndmask_b32_e32 v80, v155, v80, vcc
	v_cmp_le_i32_e32 vcc, v193, v195
	s_nop 1
	v_cndmask_b32_e32 v97, v155, v97, vcc
	v_cmp_le_i32_e32 vcc, v194, v195
	s_nop 1
	v_cndmask_b32_e32 v81, v155, v81, vcc

.LBB0_732:
	v_lshl_add_u32 v174, s34, 8, v190
	v_lshl_or_b32 v172, s6, 8, v192
	v_ashrrev_i32_e32 v175, 31, v174
	v_ashrrev_i32_e32 v173, 31, v172
	v_lshlrev_b64 v[128:129], 11, v[174:175]
	v_lshl_add_u64 v[188:189], v[128:129], 0, v[172:173]
	v_lshlrev_b64 v[128:129], 1, v[188:189]
	v_lshl_add_u64 v[130:131], s[10:11], 0, v[128:129]
	v_or_b32_e32 v128, 0x100, v128
	v_or_b32_e32 v184, 16, v174
	v_lshl_add_u64 v[128:129], s[10:11], 0, v[128:129]
	v_ashrrev_i32_e32 v185, 31, v184
	global_load_dwordx4 v[198:201], v[130:131], off
	global_load_dwordx4 v[152:155], v[128:129], off
	v_lshlrev_b64 v[128:129], 11, v[184:185]
	v_lshl_add_u64 v[186:187], v[128:129], 0, v[172:173]
	v_lshlrev_b64 v[128:129], 1, v[186:187]
	v_lshl_add_u64 v[130:131], s[10:11], 0, v[128:129]
	v_or_b32_e32 v128, 0x100, v128
	v_or_b32_e32 v180, 32, v174
	v_lshl_add_u64 v[128:129], s[10:11], 0, v[128:129]
	v_ashrrev_i32_e32 v181, 31, v180
	global_load_dwordx4 v[148:151], v[130:131], off
	global_load_dwordx4 v[144:147], v[128:129], off
	v_lshlrev_b64 v[128:129], 11, v[180:181]
	v_lshl_add_u64 v[182:183], v[128:129], 0, v[172:173]
	v_lshlrev_b64 v[128:129], 1, v[182:183]
	v_lshl_add_u64 v[130:131], s[10:11], 0, v[128:129]
	v_or_b32_e32 v128, 0x100, v128
	v_or_b32_e32 v176, 48, v174
	v_lshl_add_u64 v[128:129], s[10:11], 0, v[128:129]
	v_ashrrev_i32_e32 v177, 31, v176
	global_load_dwordx4 v[140:143], v[130:131], off
	global_load_dwordx4 v[136:139], v[128:129], off
	v_lshlrev_b64 v[128:129], 11, v[176:177]
	v_lshl_add_u64 v[178:179], v[128:129], 0, v[172:173]
	v_lshlrev_b64 v[128:129], 1, v[178:179]
	v_lshl_add_u64 v[130:131], s[10:11], 0, v[128:129]
	v_or_b32_e32 v128, 0x100, v128
	v_lshl_add_u64 v[128:129], s[10:11], 0, v[128:129]
	global_load_dwordx4 v[132:135], v[130:131], off
	s_nop 0
	global_load_dwordx4 v[128:131], v[128:129], off
	s_waitcnt vmcnt(0)
	v_lshlrev_b32_e32 v202, 16, v198
	v_and_b32_e32 v203, 0xffff0000, v198
	v_lshlrev_b32_e32 v198, 16, v199
	v_and_b32_e32 v199, 0xffff0000, v199
	v_lshlrev_b32_e32 v204, 16, v200
	v_and_b32_e32 v205, 0xffff0000, v200
	v_lshlrev_b32_e32 v200, 16, v201
	v_and_b32_e32 v201, 0xffff0000, v201
	v_cndmask_b32_e64 v197, 0, 1, s[20:21]
	v_add_f32_e64 v126, v126, v198
	v_add_f32_e64 v127, v127, v199
	v_add_f32_e64 v124, v124, v202
	v_add_f32_e64 v125, v125, v203
	v_add_f32_e64 v122, v122, v200
	v_add_f32_e64 v123, v123, v201
	v_add_f32_e64 v120, v120, v204
	v_add_f32_e64 v121, v121, v205
	v_cmp_ne_u32_e64 s[6:7], 1, v197
	s_andn2_b64 vcc, exec, s[20:21]
	v_lshl_add_u64 v[188:189], v[188:189], 2, s[52:53]
	s_cbranch_vccnz .LBB0_734
	global_store_dwordx4 v[188:189], v[124:127], off
	global_store_dwordx4 v[188:189], v[120:123], off offset:16
.LBB0_734:
	v_lshlrev_b32_e32 v198, 16, v152
	v_and_b32_e32 v199, 0xffff0000, v152
	v_lshlrev_b32_e32 v152, 16, v153
	v_and_b32_e32 v153, 0xffff0000, v153
	v_lshlrev_b32_e32 v200, 16, v154
	v_and_b32_e32 v201, 0xffff0000, v154
	v_lshlrev_b32_e32 v154, 16, v155
	v_and_b32_e32 v155, 0xffff0000, v155
	v_add_f32_e64 v118, v118, v152
	v_add_f32_e64 v119, v119, v153
	v_add_f32_e64 v116, v116, v198
	v_add_f32_e64 v117, v117, v199
	v_add_f32_e64 v114, v114, v154
	v_add_f32_e64 v115, v115, v155
	s_and_b64 vcc, exec, s[6:7]
	v_add_f32_e64 v112, v112, v200
	v_add_f32_e64 v113, v113, v201
	s_cbranch_vccnz .LBB0_736
	global_store_dwordx4 v[188:189], v[116:119], off offset:512
	global_store_dwordx4 v[188:189], v[112:115], off offset:528

.LBB0_738:
	s_or_b64 exec, exec, s[34:35]
	v_lshlrev_b32_e32 v112, 16, v148
	s_waitcnt lgkmcnt(0)
	v_and_b32_e32 v113, 0xffff0000, v148
	v_lshlrev_b32_e32 v116, 16, v149
	v_and_b32_e32 v117, 0xffff0000, v149
	v_lshlrev_b32_e32 v118, 16, v150
	v_and_b32_e32 v119, 0xffff0000, v150
	v_lshlrev_b32_e32 v122, 16, v151
	v_and_b32_e32 v123, 0xffff0000, v151
	v_add_f32_e64 v110, v110, v116
	v_add_f32_e64 v111, v111, v117
	v_add_f32_e64 v108, v108, v112
	v_add_f32_e64 v109, v109, v113
	v_add_f32_e64 v106, v106, v122
	v_add_f32_e64 v107, v107, v123
	v_add_f32_e64 v104, v104, v118
	v_add_f32_e64 v105, v105, v119
	s_and_b64 vcc, exec, s[6:7]
	v_lshl_add_u64 v[112:113], v[186:187], 2, s[52:53]
	s_cbranch_vccnz .LBB0_740
	global_store_dwordx4 v[112:113], v[108:111], off
	global_store_dwordx4 v[112:113], v[104:107], off offset:16
.LBB0_740:
	v_lshlrev_b32_e32 v116, 16, v144
	v_and_b32_e32 v117, 0xffff0000, v144
	v_lshlrev_b32_e32 v118, 16, v145
	v_and_b32_e32 v119, 0xffff0000, v145
	v_lshlrev_b32_e32 v122, 16, v146
	v_and_b32_e32 v123, 0xffff0000, v146
	v_lshlrev_b32_e32 v124, 16, v147
	v_and_b32_e32 v125, 0xffff0000, v147
	v_add_f32_e64 v102, v102, v118
	v_add_f32_e64 v103, v103, v119
	v_add_f32_e64 v100, v100, v116
	v_add_f32_e64 v101, v101, v117
	v_add_f32_e64 v98, v98, v124
	v_add_f32_e64 v99, v99, v125
	s_and_b64 vcc, exec, s[6:7]
	v_add_f32_e64 v96, v96, v122
	v_add_f32_e64 v97, v97, v123
	s_cbranch_vccnz .LBB0_742
	global_store_dwordx4 v[112:113], v[100:103], off offset:512
	global_store_dwordx4 v[112:113], v[96:99], off offset:528

.LBB0_744:
	s_or_b64 exec, exec, s[34:35]
	v_lshlrev_b32_e32 v96, 16, v140
	s_waitcnt lgkmcnt(0)
	v_and_b32_e32 v97, 0xffff0000, v140
	v_lshlrev_b32_e32 v98, 16, v141
	v_and_b32_e32 v99, 0xffff0000, v141
	v_lshlrev_b32_e32 v100, 16, v142
	v_and_b32_e32 v101, 0xffff0000, v142
	v_lshlrev_b32_e32 v102, 16, v143
	v_and_b32_e32 v103, 0xffff0000, v143
	v_add_f32_e64 v94, v94, v98
	v_add_f32_e64 v95, v95, v99
	v_add_f32_e64 v92, v92, v96
	v_add_f32_e64 v93, v93, v97
	v_add_f32_e64 v90, v90, v102
	v_add_f32_e64 v91, v91, v103
	v_add_f32_e64 v88, v88, v100
	v_add_f32_e64 v89, v89, v101
	s_and_b64 vcc, exec, s[6:7]
	v_lshl_add_u64 v[96:97], v[182:183], 2, s[52:53]
	s_cbranch_vccnz .LBB0_746
	global_store_dwordx4 v[96:97], v[92:95], off
	global_store_dwordx4 v[96:97], v[88:91], off offset:16
.LBB0_746:
	v_lshlrev_b32_e32 v98, 16, v136
	v_and_b32_e32 v99, 0xffff0000, v136
	v_lshlrev_b32_e32 v100, 16, v137
	v_and_b32_e32 v101, 0xffff0000, v137
	v_lshlrev_b32_e32 v102, 16, v138
	v_and_b32_e32 v103, 0xffff0000, v138
	v_lshlrev_b32_e32 v104, 16, v139
	v_and_b32_e32 v105, 0xffff0000, v139
	v_add_f32_e64 v86, v86, v100
	v_add_f32_e64 v87, v87, v101
	v_add_f32_e64 v84, v84, v98
	v_add_f32_e64 v85, v85, v99
	v_add_f32_e64 v82, v82, v104
	v_add_f32_e64 v83, v83, v105
	s_and_b64 vcc, exec, s[6:7]
	v_add_f32_e64 v80, v80, v102
	v_add_f32_e64 v81, v81, v103
	s_cbranch_vccnz .LBB0_748
	global_store_dwordx4 v[96:97], v[84:87], off offset:512
	global_store_dwordx4 v[96:97], v[80:83], off offset:528

.LBB0_750:
	s_or_b64 exec, exec, s[34:35]
	v_lshlrev_b32_e32 v80, 16, v132
	s_waitcnt lgkmcnt(0)
	v_and_b32_e32 v81, 0xffff0000, v132
	v_lshlrev_b32_e32 v82, 16, v133
	v_and_b32_e32 v83, 0xffff0000, v133
	v_lshlrev_b32_e32 v84, 16, v134
	v_and_b32_e32 v85, 0xffff0000, v134
	v_lshlrev_b32_e32 v86, 16, v135
	v_and_b32_e32 v87, 0xffff0000, v135
	v_add_f32_e64 v78, v78, v82
	v_add_f32_e64 v79, v79, v83
	v_add_f32_e64 v76, v76, v80
	v_add_f32_e64 v77, v77, v81
	v_add_f32_e64 v74, v74, v86
	v_add_f32_e64 v75, v75, v87
	v_add_f32_e64 v72, v72, v84
	v_add_f32_e64 v73, v73, v85
	s_and_b64 vcc, exec, s[6:7]
	v_lshl_add_u64 v[80:81], v[178:179], 2, s[52:53]
	s_cbranch_vccnz .LBB0_752
	global_store_dwordx4 v[80:81], v[76:79], off
	global_store_dwordx4 v[80:81], v[72:75], off offset:16
.LBB0_752:
	v_lshlrev_b32_e32 v82, 16, v128
	v_and_b32_e32 v83, 0xffff0000, v128
	v_lshlrev_b32_e32 v84, 16, v129
	v_and_b32_e32 v85, 0xffff0000, v129
	v_lshlrev_b32_e32 v86, 16, v130
	v_and_b32_e32 v87, 0xffff0000, v130
	v_lshlrev_b32_e32 v88, 16, v131
	v_and_b32_e32 v89, 0xffff0000, v131
	v_add_f32_e64 v70, v70, v84
	v_add_f32_e64 v71, v71, v85
	v_add_f32_e64 v68, v68, v82
	v_add_f32_e64 v69, v69, v83
	v_add_f32_e64 v66, v66, v88
	v_add_f32_e64 v67, v67, v89
	s_and_b64 vcc, exec, s[6:7]
	v_add_f32_e64 v64, v64, v86
	v_add_f32_e64 v65, v65, v87
	s_cbranch_vccnz .LBB0_754
	global_store_dwordx4 v[80:81], v[68:71], off offset:512
	global_store_dwordx4 v[80:81], v[64:67], off offset:528

.LBB0_756:
	s_or_b64 exec, exec, s[34:35]
	v_add_u32_e32 v104, 0x80, v174
	v_ashrrev_i32_e32 v105, 31, v104
	s_waitcnt lgkmcnt(0)
	v_lshlrev_b64 v[64:65], 11, v[104:105]
	v_lshl_add_u64 v[110:111], v[64:65], 0, v[172:173]
	v_lshlrev_b64 v[64:65], 1, v[110:111]
	v_lshl_add_u64 v[66:67], s[10:11], 0, v[64:65]
	v_or_b32_e32 v64, 0x100, v64
	v_add_u32_e32 v100, 0x90, v174
	v_lshl_add_u64 v[64:65], s[10:11], 0, v[64:65]
	v_ashrrev_i32_e32 v101, 31, v100
	global_load_dwordx4 v[106:109], v[66:67], off
	global_load_dwordx4 v[88:91], v[64:65], off
	v_lshlrev_b64 v[64:65], 11, v[100:101]
	v_lshl_add_u64 v[102:103], v[64:65], 0, v[172:173]
	v_lshlrev_b64 v[64:65], 1, v[102:103]
	v_lshl_add_u64 v[66:67], s[10:11], 0, v[64:65]
	v_or_b32_e32 v64, 0x100, v64
	v_add_u32_e32 v96, 0xa0, v174
	v_lshl_add_u64 v[64:65], s[10:11], 0, v[64:65]
	v_ashrrev_i32_e32 v97, 31, v96
	global_load_dwordx4 v[84:87], v[66:67], off
	global_load_dwordx4 v[80:83], v[64:65], off
	v_lshlrev_b64 v[64:65], 11, v[96:97]
	v_lshl_add_u64 v[98:99], v[64:65], 0, v[172:173]
	v_lshlrev_b64 v[64:65], 1, v[98:99]
	v_lshl_add_u64 v[66:67], s[10:11], 0, v[64:65]
	v_or_b32_e32 v64, 0x100, v64
	v_add_u32_e32 v92, 0xb0, v174
	v_lshl_add_u64 v[64:65], s[10:11], 0, v[64:65]
	v_ashrrev_i32_e32 v93, 31, v92
	global_load_dwordx4 v[76:79], v[66:67], off
	global_load_dwordx4 v[72:75], v[64:65], off
	v_lshlrev_b64 v[64:65], 11, v[92:93]
	v_lshl_add_u64 v[94:95], v[64:65], 0, v[172:173]
	v_lshlrev_b64 v[64:65], 1, v[94:95]
	v_lshl_add_u64 v[66:67], s[10:11], 0, v[64:65]
	v_or_b32_e32 v64, 0x100, v64
	v_lshl_add_u64 v[64:65], s[10:11], 0, v[64:65]
	global_load_dwordx4 v[68:71], v[66:67], off
	s_nop 0
	global_load_dwordx4 v[64:67], v[64:65], off
	s_waitcnt vmcnt(7)
	v_lshlrev_b32_e32 v112, 16, v106
	v_and_b32_e32 v113, 0xffff0000, v106
	v_lshlrev_b32_e32 v106, 16, v107
	v_and_b32_e32 v107, 0xffff0000, v107
	v_lshlrev_b32_e32 v116, 16, v108
	v_and_b32_e32 v117, 0xffff0000, v108
	v_lshlrev_b32_e32 v108, 16, v109
	v_and_b32_e32 v109, 0xffff0000, v109
	v_add_f32_e64 v62, v62, v106
	v_add_f32_e64 v63, v63, v107
	v_add_f32_e64 v60, v60, v112
	v_add_f32_e64 v61, v61, v113
	v_add_f32_e64 v58, v58, v108
	v_add_f32_e64 v59, v59, v109
	v_add_f32_e64 v56, v56, v116
	v_add_f32_e64 v57, v57, v117
	s_and_b64 vcc, exec, s[6:7]
	v_lshl_add_u64 v[106:107], v[110:111], 2, s[52:53]
	s_cbranch_vccnz .LBB0_758
	global_store_dwordx4 v[106:107], v[60:63], off
	global_store_dwordx4 v[106:107], v[56:59], off offset:16
.LBB0_758:
	s_waitcnt vmcnt(6)
	v_lshlrev_b32_e32 v108, 16, v88
	v_and_b32_e32 v109, 0xffff0000, v88
	v_lshlrev_b32_e32 v88, 16, v89
	v_and_b32_e32 v89, 0xffff0000, v89
	v_lshlrev_b32_e32 v110, 16, v90
	v_and_b32_e32 v111, 0xffff0000, v90
	v_lshlrev_b32_e32 v90, 16, v91
	v_and_b32_e32 v91, 0xffff0000, v91
	v_add_f32_e64 v54, v54, v88
	v_add_f32_e64 v55, v55, v89
	v_add_f32_e64 v52, v52, v108
	v_add_f32_e64 v53, v53, v109
	v_add_f32_e64 v50, v50, v90
	v_add_f32_e64 v51, v51, v91
	s_and_b64 vcc, exec, s[6:7]
	v_add_f32_e64 v48, v48, v110
	v_add_f32_e64 v49, v49, v111
	s_cbranch_vccnz .LBB0_760
	global_store_dwordx4 v[106:107], v[52:55], off offset:512
	global_store_dwordx4 v[106:107], v[48:51], off offset:528

.LBB0_762:
	s_or_b64 exec, exec, s[34:35]
	s_waitcnt vmcnt(5)
	v_lshlrev_b32_e32 v48, 16, v84
	s_waitcnt lgkmcnt(0)
	v_and_b32_e32 v49, 0xffff0000, v84
	v_lshlrev_b32_e32 v50, 16, v85
	v_and_b32_e32 v51, 0xffff0000, v85
	v_lshlrev_b32_e32 v52, 16, v86
	v_and_b32_e32 v53, 0xffff0000, v86
	v_lshlrev_b32_e32 v54, 16, v87
	v_and_b32_e32 v55, 0xffff0000, v87
	v_add_f32_e64 v46, v46, v50
	v_add_f32_e64 v47, v47, v51
	v_add_f32_e64 v44, v44, v48
	v_add_f32_e64 v45, v45, v49
	v_add_f32_e64 v42, v42, v54
	v_add_f32_e64 v43, v43, v55
	v_add_f32_e64 v40, v40, v52
	v_add_f32_e64 v41, v41, v53
	s_and_b64 vcc, exec, s[6:7]
	v_lshl_add_u64 v[48:49], v[102:103], 2, s[52:53]
	s_cbranch_vccnz .LBB0_764
	global_store_dwordx4 v[48:49], v[44:47], off
	global_store_dwordx4 v[48:49], v[40:43], off offset:16
.LBB0_764:
	s_waitcnt vmcnt(4)
	v_lshlrev_b32_e32 v50, 16, v80
	v_and_b32_e32 v51, 0xffff0000, v80
	v_lshlrev_b32_e32 v52, 16, v81
	v_and_b32_e32 v53, 0xffff0000, v81
	v_lshlrev_b32_e32 v54, 16, v82
	v_and_b32_e32 v55, 0xffff0000, v82
	v_lshlrev_b32_e32 v56, 16, v83
	v_and_b32_e32 v57, 0xffff0000, v83
	v_add_f32_e64 v38, v38, v52
	v_add_f32_e64 v39, v39, v53
	v_add_f32_e64 v36, v36, v50
	v_add_f32_e64 v37, v37, v51
	v_add_f32_e64 v34, v34, v56
	v_add_f32_e64 v35, v35, v57
	s_and_b64 vcc, exec, s[6:7]
	v_add_f32_e64 v32, v32, v54
	v_add_f32_e64 v33, v33, v55
	s_cbranch_vccnz .LBB0_766
	global_store_dwordx4 v[48:49], v[36:39], off offset:512
	global_store_dwordx4 v[48:49], v[32:35], off offset:528

.LBB0_768:
	s_or_b64 exec, exec, s[34:35]
	s_waitcnt vmcnt(3)
	v_lshlrev_b32_e32 v32, 16, v76
	s_waitcnt lgkmcnt(0)
	v_and_b32_e32 v33, 0xffff0000, v76
	v_lshlrev_b32_e32 v34, 16, v77
	v_and_b32_e32 v35, 0xffff0000, v77
	v_lshlrev_b32_e32 v36, 16, v78
	v_and_b32_e32 v37, 0xffff0000, v78
	v_lshlrev_b32_e32 v38, 16, v79
	v_and_b32_e32 v39, 0xffff0000, v79
	v_add_f32_e64 v30, v30, v34
	v_add_f32_e64 v31, v31, v35
	v_add_f32_e64 v28, v28, v32
	v_add_f32_e64 v29, v29, v33
	v_add_f32_e64 v26, v26, v38
	v_add_f32_e64 v27, v27, v39
	v_add_f32_e64 v24, v24, v36
	v_add_f32_e64 v25, v25, v37
	s_and_b64 vcc, exec, s[6:7]
	v_lshl_add_u64 v[32:33], v[98:99], 2, s[52:53]
	s_cbranch_vccnz .LBB0_770
	global_store_dwordx4 v[32:33], v[28:31], off
	global_store_dwordx4 v[32:33], v[24:27], off offset:16
.LBB0_770:
	s_waitcnt vmcnt(2)
	v_lshlrev_b32_e32 v34, 16, v72
	v_and_b32_e32 v35, 0xffff0000, v72
	v_lshlrev_b32_e32 v36, 16, v73
	v_and_b32_e32 v37, 0xffff0000, v73
	v_lshlrev_b32_e32 v38, 16, v74
	v_and_b32_e32 v39, 0xffff0000, v74
	v_lshlrev_b32_e32 v40, 16, v75
	v_and_b32_e32 v41, 0xffff0000, v75
	v_add_f32_e64 v22, v22, v36
	v_add_f32_e64 v23, v23, v37
	v_add_f32_e64 v20, v20, v34
	v_add_f32_e64 v21, v21, v35
	v_add_f32_e64 v18, v18, v40
	v_add_f32_e64 v19, v19, v41
	s_and_b64 vcc, exec, s[6:7]
	v_add_f32_e64 v16, v16, v38
	v_add_f32_e64 v17, v17, v39
	s_cbranch_vccnz .LBB0_772
	global_store_dwordx4 v[32:33], v[20:23], off offset:512
	global_store_dwordx4 v[32:33], v[16:19], off offset:528

.LBB0_774:
	s_or_b64 exec, exec, s[34:35]
	s_waitcnt vmcnt(1)
	v_lshlrev_b32_e32 v16, 16, v68
	s_waitcnt lgkmcnt(0)
	v_and_b32_e32 v17, 0xffff0000, v68
	v_lshlrev_b32_e32 v18, 16, v69
	v_and_b32_e32 v19, 0xffff0000, v69
	v_lshlrev_b32_e32 v20, 16, v70
	v_and_b32_e32 v21, 0xffff0000, v70
	v_lshlrev_b32_e32 v22, 16, v71
	v_and_b32_e32 v23, 0xffff0000, v71
	v_add_f32_e64 v14, v14, v18
	v_add_f32_e64 v15, v15, v19
	v_add_f32_e64 v12, v12, v16
	v_add_f32_e64 v13, v13, v17
	v_add_f32_e64 v10, v10, v22
	v_add_f32_e64 v11, v11, v23
	v_add_f32_e64 v8, v8, v20
	v_add_f32_e64 v9, v9, v21
	s_and_b64 vcc, exec, s[6:7]
	v_lshl_add_u64 v[16:17], v[94:95], 2, s[52:53]
	s_cbranch_vccnz .LBB0_776
	global_store_dwordx4 v[16:17], v[12:15], off
	global_store_dwordx4 v[16:17], v[8:11], off offset:16
.LBB0_776:
	s_waitcnt vmcnt(0)
	v_lshlrev_b32_e32 v18, 16, v64
	v_and_b32_e32 v19, 0xffff0000, v64
	v_lshlrev_b32_e32 v20, 16, v65
	v_and_b32_e32 v21, 0xffff0000, v65
	v_lshlrev_b32_e32 v22, 16, v66
	v_and_b32_e32 v23, 0xffff0000, v66
	v_lshlrev_b32_e32 v24, 16, v67
	v_and_b32_e32 v25, 0xffff0000, v67
	v_add_f32_e64 v6, v6, v20
	v_add_f32_e64 v7, v7, v21
	v_add_f32_e64 v4, v4, v18
	v_add_f32_e64 v5, v5, v19
	v_add_f32_e64 v2, v2, v24
	v_add_f32_e64 v3, v3, v25
	s_and_b64 vcc, exec, s[6:7]
	v_add_f32_e64 v0, v0, v22
	v_add_f32_e64 v1, v1, v23
	s_cbranch_vccnz .LBB0_778
	global_store_dwordx4 v[16:17], v[4:7], off offset:512
	global_store_dwordx4 v[16:17], v[0:3], off offset:528

.LBB0_838:
	global_load_dword v17, v[12:13], off
	global_load_dwordx4 v[18:21], v[14:15], off offset:-4096
	global_load_dwordx4 v[22:25], v[2:3], off
	global_load_dwordx4 v[26:29], v[14:15], off offset:-3072
	v_add_u32_e32 v0, s6, v0
	v_lshl_add_u64 v[12:13], v[12:13], 0, s[14:15]
	s_waitcnt vmcnt(3)
	v_fmamk_f32 v17, v17, 0x3a000000, v1
	v_mul_f32_e32 v30, 0x4f800000, v17
	v_cmp_gt_f32_e32 vcc, s3, v17
	s_nop 1
	v_cndmask_b32_e32 v17, v17, v30, vcc
	v_sqrt_f32_e32 v30, v17
	s_nop 0
	v_add_u32_e32 v31, -1, v30
	v_add_u32_e32 v32, 1, v30
	v_fma_f32 v33, -v31, v30, v17
	v_fma_f32 v34, -v32, v30, v17
	v_cmp_ge_f32_e64 s[0:1], 0, v33
	s_nop 1
	v_cndmask_b32_e64 v30, v30, v31, s[0:1]
	v_cmp_lt_f32_e64 s[0:1], 0, v34
	s_nop 1
	v_cndmask_b32_e64 v30, v30, v32, s[0:1]
	v_mul_f32_e32 v31, 0x37800000, v30
	v_cndmask_b32_e32 v30, v30, v31, vcc
	v_cmp_class_f32_e32 vcc, v17, v16
	s_nop 1
	v_cndmask_b32_e32 v17, v30, v17, vcc
	v_div_scale_f32 v30, s[0:1], v17, v17, 1.0
	v_rcp_f32_e32 v32, v30
	v_div_scale_f32 v31, vcc, 1.0, v17, 1.0
	v_fma_f32 v33, -v30, v32, 1.0
	v_fmac_f32_e32 v32, v33, v32
	v_mul_f32_e32 v33, v31, v32
	v_fma_f32 v34, -v30, v33, v31
	v_fmac_f32_e32 v33, v34, v32
	v_fma_f32 v30, -v30, v33, v31
	v_div_fmas_f32 v30, v30, v32, v33
	v_div_fixup_f32 v30, v30, v17, 1.0
	s_waitcnt vmcnt(2)
	v_mul_f32_e64 v18, v18, v30
	v_mul_f32_e64 v19, v19, v30
	v_mul_f32_e64 v20, v20, v30
	v_mul_f32_e64 v21, v21, v30
	s_waitcnt vmcnt(1)
	v_mul_f32_e64 v18, v22, v18
	v_mul_f32_e64 v19, v23, v19
	v_mul_f32_e64 v20, v24, v20
	v_mul_f32_e64 v21, v25, v21
	global_store_dwordx4 v[14:15], v[18:21], off offset:-4096
	global_load_dwordx4 v[18:21], v[2:3], off offset:1024
	s_nop 0
	global_load_dwordx4 v[22:25], v[14:15], off offset:-2048
	s_waitcnt vmcnt(3)
	v_mul_f32_e64 v28, v28, v30
	v_mul_f32_e64 v29, v29, v30
	v_mul_f32_e64 v26, v26, v30
	v_mul_f32_e64 v27, v27, v30
	v_cmp_lt_i32_e32 vcc, s7, v0
	s_or_b64 s[18:19], vcc, s[18:19]
	s_waitcnt vmcnt(1)
	v_mul_f32_e64 v18, v18, v26
	v_mul_f32_e64 v19, v19, v27
	v_mul_f32_e64 v20, v20, v28
	v_mul_f32_e64 v21, v21, v29
	global_store_dwordx4 v[14:15], v[18:21], off offset:-3072
	global_load_dwordx4 v[18:21], v[2:3], off offset:2048
	s_nop 0
	global_load_dwordx4 v[26:29], v[14:15], off offset:-1024
	s_waitcnt vmcnt(3)
	v_mul_f32_e64 v24, v30, v24
	v_mul_f32_e64 v25, v30, v25
	v_mul_f32_e64 v22, v30, v22
	v_mul_f32_e64 v23, v30, v23
	s_waitcnt vmcnt(1)
	v_mul_f32_e64 v18, v22, v18
	v_mul_f32_e64 v19, v23, v19
	v_mul_f32_e64 v20, v24, v20
	v_mul_f32_e64 v21, v25, v21
	global_store_dwordx4 v[14:15], v[18:21], off offset:-2048
	global_load_dwordx4 v[18:21], v[2:3], off offset:3072
	s_nop 0
	global_load_dwordx4 v[22:25], v[14:15], off
	s_waitcnt vmcnt(3)
	v_mul_f32_e64 v28, v30, v28
	v_mul_f32_e64 v29, v30, v29
	v_mul_f32_e64 v26, v30, v26
	v_mul_f32_e64 v27, v30, v27
	s_waitcnt vmcnt(1)
	v_mul_f32_e64 v18, v26, v18
	v_mul_f32_e64 v19, v27, v19
	v_mul_f32_e64 v20, v28, v20
	v_mul_f32_e64 v21, v29, v21
	global_store_dwordx4 v[14:15], v[18:21], off offset:-1024
	global_load_dwordx4 v[18:21], v[4:5], off
	s_nop 0
	global_load_dwordx4 v[26:29], v[14:15], off offset:1024
	s_waitcnt vmcnt(3)
	v_mul_f32_e64 v24, v30, v24
	v_mul_f32_e64 v25, v30, v25
	v_mul_f32_e64 v22, v30, v22
	v_mul_f32_e64 v23, v30, v23
	s_waitcnt vmcnt(1)
	v_mul_f32_e64 v18, v22, v18
	v_mul_f32_e64 v19, v23, v19
	v_mul_f32_e64 v20, v24, v20
	v_mul_f32_e64 v21, v25, v21
	global_store_dwordx4 v[14:15], v[18:21], off
	global_load_dwordx4 v[18:21], v[6:7], off
	s_nop 0
	global_load_dwordx4 v[22:25], v[14:15], off offset:2048
	s_waitcnt vmcnt(3)
	v_mul_f32_e64 v28, v30, v28
	v_mul_f32_e64 v29, v30, v29
	v_mul_f32_e64 v26, v30, v26
	v_mul_f32_e64 v27, v30, v27
	s_waitcnt vmcnt(1)
	v_mul_f32_e64 v18, v26, v18
	v_mul_f32_e64 v19, v27, v19
	v_mul_f32_e64 v20, v28, v20
	v_mul_f32_e64 v21, v29, v21
	global_store_dwordx4 v[14:15], v[18:21], off offset:1024
	global_load_dwordx4 v[18:21], v[8:9], off
	s_nop 0
	global_load_dwordx4 v[26:29], v[14:15], off offset:3072
	s_waitcnt vmcnt(3)
	v_mul_f32_e64 v24, v30, v24
	v_mul_f32_e64 v25, v30, v25
	v_mul_f32_e64 v22, v30, v22
	v_mul_f32_e64 v23, v30, v23
	s_waitcnt vmcnt(1)
	v_mul_f32_e64 v18, v22, v18
	v_mul_f32_e64 v19, v23, v19
	v_mul_f32_e64 v20, v24, v20
	v_mul_f32_e64 v21, v25, v21
	global_store_dwordx4 v[14:15], v[18:21], off offset:2048
	global_load_dwordx4 v[18:21], v[10:11], off
	s_waitcnt vmcnt(2)
	v_mul_f32_e64 v22, v30, v28
	v_mul_f32_e64 v23, v30, v29
	v_mul_f32_e64 v24, v30, v26
	v_mul_f32_e64 v25, v30, v27
	s_waitcnt vmcnt(0)
	v_mul_f32_e64 v18, v24, v18
	v_mul_f32_e64 v19, v25, v19
	v_mul_f32_e64 v20, v22, v20
	v_mul_f32_e64 v21, v23, v21
	global_store_dwordx4 v[14:15], v[18:21], off offset:3072
	v_lshl_add_u64 v[14:15], v[14:15], 0, s[16:17]
	s_andn2_b64 exec, exec, s[18:19]
	s_cbranch_execnz .LBB0_838

.LBB0_855:
	v_lshl_add_u32 v174, s6, 8, v206
	v_lshl_or_b32 v176, s28, 8, v208
	v_ashrrev_i32_e32 v177, 31, v176
	v_ashrrev_i32_e32 v175, 31, v174
	v_lshl_add_u64 v[204:205], v[176:177], 1, s[10:11]
	v_lshlrev_b64 v[128:129], 12, v[174:175]
	v_or_b32_e32 v172, 16, v174
	v_lshl_add_u64 v[128:129], v[204:205], 0, v[128:129]
	v_ashrrev_i32_e32 v173, 31, v172
	global_load_dwordx4 v[178:181], v[128:129], off
	global_load_dwordx4 v[182:185], v[128:129], off offset:256
	v_lshlrev_b64 v[128:129], 12, v[172:173]
	v_or_b32_e32 v170, 32, v174
	v_lshl_add_u64 v[128:129], v[204:205], 0, v[128:129]
	v_ashrrev_i32_e32 v171, 31, v170
	global_load_dwordx4 v[148:151], v[128:129], off
	global_load_dwordx4 v[144:147], v[128:129], off offset:256
	v_lshlrev_b64 v[128:129], 12, v[170:171]
	v_or_b32_e32 v168, 48, v174
	v_lshl_add_u64 v[128:129], v[204:205], 0, v[128:129]
	v_ashrrev_i32_e32 v169, 31, v168
	global_load_dwordx4 v[140:143], v[128:129], off
	global_load_dwordx4 v[136:139], v[128:129], off offset:256
	v_lshlrev_b64 v[128:129], 12, v[168:169]
	v_lshl_add_u64 v[128:129], v[204:205], 0, v[128:129]
	global_load_dwordx4 v[132:135], v[128:129], off
	s_nop 0
	global_load_dwordx4 v[128:131], v[128:129], off offset:256
	v_and_b32_e32 v187, 64, v212
	v_xor_b32_e32 v186, 16, v212
	v_add_u32_e32 v187, 64, v187
	v_xor_b32_e32 v188, 32, v212
	v_cmp_lt_i32_e32 vcc, v186, v187
	s_waitcnt vmcnt(0)
	v_lshlrev_b32_e32 v192, 16, v180
	v_cndmask_b32_e32 v186, v212, v186, vcc
	v_cmp_lt_i32_e32 vcc, v188, v187
	v_lshlrev_b32_e32 v216, 2, v186
	v_lshlrev_b32_e32 v186, 16, v178
	v_cndmask_b32_e32 v187, v212, v188, vcc
	v_lshlrev_b32_e32 v215, 2, v187
	v_and_b32_e32 v187, 0xffff0000, v178
	v_and_b32_e32 v193, 0xffff0000, v180
	v_lshlrev_b32_e32 v200, 16, v182
	v_and_b32_e32 v201, 0xffff0000, v182
	v_lshlrev_b32_e32 v178, 16, v179
	v_and_b32_e32 v179, 0xffff0000, v179
	v_lshlrev_b32_e32 v180, 16, v181
	v_and_b32_e32 v181, 0xffff0000, v181
	v_lshlrev_b32_e32 v182, 16, v183
	v_and_b32_e32 v183, 0xffff0000, v183
	v_lshlrev_b32_e32 v202, 16, v184
	v_and_b32_e32 v203, 0xffff0000, v184
	v_lshlrev_b32_e32 v184, 16, v185
	v_and_b32_e32 v185, 0xffff0000, v185
	v_add_f32_e64 v190, v126, v178
	v_add_f32_e64 v191, v127, v179
	v_add_f32_e64 v196, v124, v186
	v_add_f32_e64 v197, v125, v187
	v_add_f32_e64 v194, v118, v182
	v_add_f32_e64 v195, v119, v183
	v_add_f32_e64 v200, v116, v200
	v_add_f32_e64 v201, v117, v201
	v_add_f32_e64 v198, v120, v192
	v_add_f32_e64 v199, v121, v193
	v_mul_f32_e32 v120, v197, v197
	v_mul_f32_e32 v121, v191, v191
	v_add_f32_e64 v192, v112, v202
	v_add_f32_e64 v193, v113, v203
	v_mul_f32_e32 v112, v201, v201
	v_mul_f32_e32 v113, v195, v195
	v_fmac_f32_e32 v120, v196, v196
	v_fmac_f32_e32 v121, v190, v190
	v_fmac_f32_e32 v112, v200, v200
	v_fmac_f32_e32 v113, v194, v194
	v_add_f32_e32 v120, v120, v121
	v_mul_f32_e32 v121, v199, v199
	v_add_f32_e32 v112, v112, v113
	v_mul_f32_e32 v113, v193, v193
	v_add_f32_e64 v188, v122, v180
	v_add_f32_e64 v189, v123, v181
	v_fmac_f32_e32 v121, v198, v198
	v_add_f32_e64 v186, v114, v184
	v_add_f32_e64 v187, v115, v185
	v_fmac_f32_e32 v113, v192, v192
	v_add_f32_e32 v120, v121, v120
	v_mul_f32_e32 v121, v189, v189
	v_add_f32_e32 v112, v113, v112
	v_mul_f32_e32 v113, v187, v187
	v_fmac_f32_e32 v121, v188, v188
	v_fmac_f32_e32 v113, v186, v186
	v_add_f32_e32 v120, v121, v120
	v_add_f32_e32 v112, v113, v112
	v_add_f32_e32 v112, v120, v112
	ds_bpermute_b32 v113, v216, v112
	s_waitcnt lgkmcnt(0)
	v_add_f32_e32 v114, v112, v113
	ds_bpermute_b32 v115, v215, v114
	v_lshl_add_u64 v[112:113], v[174:175], 2, s[12:13]
	s_and_saveexec_b64 s[28:29], s[0:1]
	s_cbranch_execz .LBB0_857
	s_waitcnt lgkmcnt(0)
	v_add_f32_e32 v114, v114, v115
	global_atomic_add_f32 v[112:113], v114, off
.LBB0_857:
	s_or_b64 exec, exec, s[28:29]
	v_lshlrev_b32_e32 v114, 16, v148
	s_waitcnt lgkmcnt(0)
	v_and_b32_e32 v115, 0xffff0000, v148
	v_lshlrev_b32_e32 v116, 16, v149
	v_and_b32_e32 v117, 0xffff0000, v149
	v_lshlrev_b32_e32 v122, 16, v144
	v_and_b32_e32 v123, 0xffff0000, v144
	v_lshlrev_b32_e32 v124, 16, v145
	v_and_b32_e32 v125, 0xffff0000, v145
	v_lshlrev_b32_e32 v118, 16, v150
	v_and_b32_e32 v119, 0xffff0000, v150
	v_lshlrev_b32_e32 v126, 16, v146
	v_and_b32_e32 v127, 0xffff0000, v146
	v_add_f32_e64 v148, v110, v116
	v_add_f32_e64 v149, v111, v117
	v_add_f32_e64 v180, v108, v114
	v_add_f32_e64 v181, v109, v115
	v_add_f32_e64 v178, v102, v124
	v_add_f32_e64 v179, v103, v125
	v_add_f32_e64 v184, v100, v122
	v_add_f32_e64 v185, v101, v123
	v_lshlrev_b32_e32 v120, 16, v151
	v_and_b32_e32 v121, 0xffff0000, v151
	v_add_f32_e64 v182, v104, v118
	v_add_f32_e64 v183, v105, v119
	v_mul_f32_e32 v104, v181, v181
	v_mul_f32_e32 v105, v149, v149
	v_add_f32_e64 v150, v96, v126
	v_add_f32_e64 v151, v97, v127
	v_mul_f32_e32 v96, v185, v185
	v_mul_f32_e32 v97, v179, v179
	v_fmac_f32_e32 v104, v180, v180
	v_fmac_f32_e32 v105, v148, v148
	v_fmac_f32_e32 v96, v184, v184
	v_fmac_f32_e32 v97, v178, v178
	v_lshlrev_b32_e32 v144, 16, v147
	v_and_b32_e32 v145, 0xffff0000, v147
	v_add_f32_e32 v104, v104, v105
	v_mul_f32_e32 v105, v183, v183
	v_add_f32_e32 v96, v96, v97
	v_mul_f32_e32 v97, v151, v151
	v_add_f32_e64 v146, v106, v120
	v_add_f32_e64 v147, v107, v121
	v_fmac_f32_e32 v105, v182, v182
	v_add_f32_e64 v144, v98, v144
	v_add_f32_e64 v145, v99, v145
	v_fmac_f32_e32 v97, v150, v150
	v_add_f32_e32 v104, v105, v104
	v_mul_f32_e32 v105, v147, v147
	v_add_f32_e32 v96, v97, v96
	v_mul_f32_e32 v97, v145, v145
	v_fmac_f32_e32 v105, v146, v146
	v_fmac_f32_e32 v97, v144, v144
	v_add_f32_e32 v104, v105, v104
	v_add_f32_e32 v96, v97, v96
	v_add_f32_e32 v96, v104, v96
	ds_bpermute_b32 v97, v216, v96
	v_lshl_add_u64 v[202:203], v[172:173], 2, s[12:13]
	s_waitcnt lgkmcnt(0)
	v_add_f32_e32 v96, v96, v97
	ds_bpermute_b32 v97, v215, v96
	s_and_saveexec_b64 s[28:29], s[0:1]
	s_cbranch_execz .LBB0_859
	s_waitcnt lgkmcnt(0)
	v_add_f32_e32 v96, v96, v97
	global_atomic_add_f32 v[202:203], v96, off
.LBB0_859:
	s_or_b64 exec, exec, s[28:29]
	v_lshlrev_b32_e32 v96, 16, v140
	s_waitcnt lgkmcnt(0)
	v_and_b32_e32 v97, 0xffff0000, v140
	v_lshlrev_b32_e32 v98, 16, v141
	v_and_b32_e32 v99, 0xffff0000, v141
	v_lshlrev_b32_e32 v104, 16, v136
	v_and_b32_e32 v105, 0xffff0000, v136
	v_lshlrev_b32_e32 v106, 16, v137
	v_and_b32_e32 v107, 0xffff0000, v137
	v_lshlrev_b32_e32 v100, 16, v142
	v_and_b32_e32 v101, 0xffff0000, v142
	v_lshlrev_b32_e32 v108, 16, v138
	v_and_b32_e32 v109, 0xffff0000, v138
	v_add_f32_e64 v118, v94, v98
	v_add_f32_e64 v119, v95, v99
	v_add_f32_e64 v124, v92, v96
	v_add_f32_e64 v125, v93, v97
	v_add_f32_e64 v122, v86, v106
	v_add_f32_e64 v123, v87, v107
	v_add_f32_e64 v136, v84, v104
	v_add_f32_e64 v137, v85, v105
	v_add_f32_e64 v126, v88, v100
	v_add_f32_e64 v127, v89, v101
	v_mul_f32_e32 v88, v125, v125
	v_mul_f32_e32 v89, v119, v119
	v_add_f32_e64 v120, v80, v108
	v_add_f32_e64 v121, v81, v109
	v_mul_f32_e32 v80, v137, v137
	v_mul_f32_e32 v81, v123, v123
	v_fmac_f32_e32 v88, v124, v124
	v_fmac_f32_e32 v89, v118, v118
	v_fmac_f32_e32 v80, v136, v136
	v_fmac_f32_e32 v81, v122, v122
	v_lshlrev_b32_e32 v102, 16, v143
	v_and_b32_e32 v103, 0xffff0000, v143
	v_lshlrev_b32_e32 v110, 16, v139
	v_and_b32_e32 v111, 0xffff0000, v139
	v_add_f32_e32 v88, v88, v89
	v_mul_f32_e32 v89, v127, v127
	v_add_f32_e32 v80, v80, v81
	v_mul_f32_e32 v81, v121, v121
	v_add_f32_e64 v116, v90, v102
	v_add_f32_e64 v117, v91, v103
	v_fmac_f32_e32 v89, v126, v126
	v_add_f32_e64 v114, v82, v110
	v_add_f32_e64 v115, v83, v111
	v_fmac_f32_e32 v81, v120, v120
	v_add_f32_e32 v88, v89, v88
	v_mul_f32_e32 v89, v117, v117
	v_add_f32_e32 v80, v81, v80
	v_mul_f32_e32 v81, v115, v115
	v_fmac_f32_e32 v89, v116, v116
	v_fmac_f32_e32 v81, v114, v114
	v_add_f32_e32 v88, v89, v88
	v_add_f32_e32 v80, v81, v80
	v_add_f32_e32 v80, v88, v80
	ds_bpermute_b32 v81, v216, v80
	v_lshl_add_u64 v[138:139], v[170:171], 2, s[12:13]
	s_waitcnt lgkmcnt(0)
	v_add_f32_e32 v80, v80, v81
	ds_bpermute_b32 v81, v215, v80
	s_and_saveexec_b64 s[28:29], s[0:1]
	s_cbranch_execz .LBB0_861
	s_waitcnt lgkmcnt(0)
	v_add_f32_e32 v80, v80, v81
	global_atomic_add_f32 v[138:139], v80, off
.LBB0_861:
	s_or_b64 exec, exec, s[28:29]
	v_lshlrev_b32_e32 v80, 16, v132
	s_waitcnt lgkmcnt(0)
	v_and_b32_e32 v81, 0xffff0000, v132
	v_lshlrev_b32_e32 v82, 16, v133
	v_and_b32_e32 v83, 0xffff0000, v133
	v_lshlrev_b32_e32 v88, 16, v128
	v_and_b32_e32 v89, 0xffff0000, v128
	v_lshlrev_b32_e32 v90, 16, v129
	v_and_b32_e32 v91, 0xffff0000, v129
	v_lshlrev_b32_e32 v84, 16, v134
	v_and_b32_e32 v85, 0xffff0000, v134
	v_lshlrev_b32_e32 v92, 16, v130
	v_and_b32_e32 v93, 0xffff0000, v130
	v_add_f32_e64 v100, v78, v82
	v_add_f32_e64 v101, v79, v83
	v_add_f32_e64 v106, v76, v80
	v_add_f32_e64 v107, v77, v81
	v_add_f32_e64 v104, v70, v90
	v_add_f32_e64 v105, v71, v91
	v_add_f32_e64 v110, v68, v88
	v_add_f32_e64 v111, v69, v89
	v_add_f32_e64 v108, v72, v84
	v_add_f32_e64 v109, v73, v85
	v_mul_f32_e32 v72, v107, v107
	v_mul_f32_e32 v73, v101, v101
	v_add_f32_e64 v102, v64, v92
	v_add_f32_e64 v103, v65, v93
	v_mul_f32_e32 v64, v111, v111
	v_mul_f32_e32 v65, v105, v105
	v_fmac_f32_e32 v72, v106, v106
	v_fmac_f32_e32 v73, v100, v100
	v_fmac_f32_e32 v64, v110, v110
	v_fmac_f32_e32 v65, v104, v104
	v_lshlrev_b32_e32 v86, 16, v135
	v_and_b32_e32 v87, 0xffff0000, v135
	v_lshlrev_b32_e32 v94, 16, v131
	v_and_b32_e32 v95, 0xffff0000, v131
	v_add_f32_e32 v72, v72, v73
	v_mul_f32_e32 v73, v109, v109
	v_add_f32_e32 v64, v64, v65
	v_mul_f32_e32 v65, v103, v103
	v_add_f32_e64 v98, v74, v86
	v_add_f32_e64 v99, v75, v87
	v_fmac_f32_e32 v73, v108, v108
	v_add_f32_e64 v96, v66, v94
	v_add_f32_e64 v97, v67, v95
	v_fmac_f32_e32 v65, v102, v102
	v_add_f32_e32 v72, v73, v72
	v_mul_f32_e32 v73, v99, v99
	v_add_f32_e32 v64, v65, v64
	v_mul_f32_e32 v65, v97, v97
	v_fmac_f32_e32 v73, v98, v98
	v_fmac_f32_e32 v65, v96, v96
	v_add_f32_e32 v72, v73, v72
	v_add_f32_e32 v64, v65, v64
	v_add_f32_e32 v64, v72, v64
	ds_bpermute_b32 v65, v216, v64
	v_lshl_add_u64 v[128:129], v[168:169], 2, s[12:13]
	s_waitcnt lgkmcnt(0)
	v_add_f32_e32 v64, v64, v65
	ds_bpermute_b32 v65, v215, v64
	s_and_saveexec_b64 s[28:29], s[0:1]
	s_cbranch_execz .LBB0_863
	s_waitcnt lgkmcnt(0)
	v_add_f32_e32 v64, v64, v65
	global_atomic_add_f32 v[128:129], v64, off
.LBB0_863:
	s_or_b64 exec, exec, s[28:29]
	v_add_u32_e32 v94, 0x80, v174
	v_ashrrev_i32_e32 v95, 31, v94
	s_waitcnt lgkmcnt(0)
	v_lshlrev_b64 v[64:65], 12, v[94:95]
	v_add_u32_e32 v92, 0x90, v174
	v_lshl_add_u64 v[64:65], v[204:205], 0, v[64:65]
	v_ashrrev_i32_e32 v93, 31, v92
	global_load_dwordx4 v[130:133], v[64:65], off
	global_load_dwordx4 v[140:143], v[64:65], off offset:256
	v_lshlrev_b64 v[64:65], 12, v[92:93]
	v_add_u32_e32 v90, 0xa0, v174
	v_lshl_add_u64 v[64:65], v[204:205], 0, v[64:65]
	v_ashrrev_i32_e32 v91, 31, v90
	global_load_dwordx4 v[84:87], v[64:65], off
	global_load_dwordx4 v[80:83], v[64:65], off offset:256
	v_lshlrev_b64 v[64:65], 12, v[90:91]
	v_add_u32_e32 v88, 0xb0, v174
	v_lshl_add_u64 v[64:65], v[204:205], 0, v[64:65]
	v_ashrrev_i32_e32 v89, 31, v88
	global_load_dwordx4 v[76:79], v[64:65], off
	global_load_dwordx4 v[72:75], v[64:65], off offset:256
	v_lshlrev_b64 v[64:65], 12, v[88:89]
	v_lshl_add_u64 v[64:65], v[204:205], 0, v[64:65]
	global_load_dwordx4 v[68:71], v[64:65], off
	s_nop 0
	global_load_dwordx4 v[64:67], v[64:65], off offset:256
	s_waitcnt vmcnt(7)
	v_lshlrev_b32_e32 v134, 16, v130
	v_and_b32_e32 v135, 0xffff0000, v130
	v_lshlrev_b32_e32 v130, 16, v131
	v_and_b32_e32 v131, 0xffff0000, v131
	v_lshlrev_b32_e32 v204, 16, v132
	v_and_b32_e32 v205, 0xffff0000, v132
	v_lshlrev_b32_e32 v132, 16, v133
	v_and_b32_e32 v133, 0xffff0000, v133
	s_waitcnt vmcnt(6)
	v_lshlrev_b32_e32 v218, 16, v140
	v_and_b32_e32 v219, 0xffff0000, v140
	v_lshlrev_b32_e32 v140, 16, v141
	v_and_b32_e32 v141, 0xffff0000, v141
	v_lshlrev_b32_e32 v220, 16, v142
	v_and_b32_e32 v221, 0xffff0000, v142
	v_lshlrev_b32_e32 v142, 16, v143
	v_and_b32_e32 v143, 0xffff0000, v143
	v_add_f32_e64 v62, v62, v130
	v_add_f32_e64 v63, v63, v131
	v_add_f32_e64 v60, v60, v134
	v_add_f32_e64 v61, v61, v135
	v_mul_f32_e32 v131, v63, v63
	v_mul_f32_e32 v130, v61, v61
	v_add_f32_e64 v56, v56, v204
	v_add_f32_e64 v57, v57, v205
	v_fmac_f32_e32 v130, v60, v60
	v_fmac_f32_e32 v131, v62, v62
	v_add_f32_e32 v130, v130, v131
	v_mul_f32_e32 v131, v57, v57
	v_add_f32_e64 v58, v58, v132
	v_add_f32_e64 v59, v59, v133
	v_fmac_f32_e32 v131, v56, v56
	v_add_f32_e32 v130, v131, v130
	v_mul_f32_e32 v131, v59, v59
	v_fmac_f32_e32 v131, v58, v58
	v_add_f32_e64 v54, v54, v140
	v_add_f32_e64 v55, v55, v141
	v_add_f32_e64 v52, v52, v218
	v_add_f32_e64 v53, v53, v219
	v_add_f32_e32 v130, v131, v130
	v_mul_f32_e32 v131, v53, v53
	v_mul_f32_e32 v132, v55, v55
	v_add_f32_e64 v48, v48, v220
	v_add_f32_e64 v49, v49, v221
	v_fmac_f32_e32 v131, v52, v52
	v_fmac_f32_e32 v132, v54, v54
	v_add_f32_e32 v131, v131, v132
	v_mul_f32_e32 v132, v49, v49
	v_add_f32_e64 v50, v50, v142
	v_add_f32_e64 v51, v51, v143
	v_fmac_f32_e32 v132, v48, v48
	v_add_f32_e32 v131, v132, v131
	v_mul_f32_e32 v132, v51, v51
	v_fmac_f32_e32 v132, v50, v50
	v_add_f32_e32 v131, v132, v131
	v_add_f32_e32 v130, v130, v131
	ds_bpermute_b32 v131, v216, v130
	s_waitcnt lgkmcnt(0)
	v_add_f32_e32 v130, v130, v131
	ds_bpermute_b32 v131, v215, v130
	s_and_saveexec_b64 s[28:29], s[0:1]
	s_cbranch_execz .LBB0_865
	v_lshl_add_u64 v[132:133], v[94:95], 2, s[12:13]
	s_waitcnt lgkmcnt(0)
	v_add_f32_e32 v130, v130, v131
	global_atomic_add_f32 v[132:133], v130, off
.LBB0_865:
	s_or_b64 exec, exec, s[28:29]
	s_waitcnt vmcnt(5)
	v_lshlrev_b32_e32 v130, 16, v84
	s_waitcnt lgkmcnt(0)
	v_and_b32_e32 v131, 0xffff0000, v84
	v_lshlrev_b32_e32 v84, 16, v85
	v_and_b32_e32 v85, 0xffff0000, v85
	s_waitcnt vmcnt(4)
	v_lshlrev_b32_e32 v134, 16, v80
	v_and_b32_e32 v135, 0xffff0000, v80
	v_lshlrev_b32_e32 v80, 16, v81
	v_and_b32_e32 v81, 0xffff0000, v81
	v_add_f32_e64 v46, v46, v84
	v_add_f32_e64 v47, v47, v85
	v_add_f32_e64 v44, v44, v130
	v_add_f32_e64 v45, v45, v131
	v_add_f32_e64 v38, v38, v80
	v_add_f32_e64 v39, v39, v81
	v_add_f32_e64 v36, v36, v134
	v_add_f32_e64 v37, v37, v135
	v_lshlrev_b32_e32 v132, 16, v86
	v_and_b32_e32 v133, 0xffff0000, v86
	v_lshlrev_b32_e32 v140, 16, v82
	v_and_b32_e32 v141, 0xffff0000, v82
	v_mul_f32_e32 v84, v45, v45
	v_mul_f32_e32 v85, v47, v47
	v_mul_f32_e32 v80, v37, v37
	v_mul_f32_e32 v81, v39, v39
	v_add_f32_e64 v40, v40, v132
	v_add_f32_e64 v41, v41, v133
	v_fmac_f32_e32 v84, v44, v44
	v_fmac_f32_e32 v85, v46, v46
	v_add_f32_e64 v32, v32, v140
	v_add_f32_e64 v33, v33, v141
	v_fmac_f32_e32 v80, v36, v36
	v_fmac_f32_e32 v81, v38, v38
	v_lshlrev_b32_e32 v86, 16, v87
	v_and_b32_e32 v87, 0xffff0000, v87
	v_lshlrev_b32_e32 v82, 16, v83
	v_and_b32_e32 v83, 0xffff0000, v83
	v_add_f32_e32 v84, v84, v85
	v_mul_f32_e32 v85, v41, v41
	v_add_f32_e32 v80, v80, v81
	v_mul_f32_e32 v81, v33, v33
	v_add_f32_e64 v42, v42, v86
	v_add_f32_e64 v43, v43, v87
	v_fmac_f32_e32 v85, v40, v40
	v_add_f32_e64 v34, v34, v82
	v_add_f32_e64 v35, v35, v83
	v_fmac_f32_e32 v81, v32, v32
	v_add_f32_e32 v84, v85, v84
	v_mul_f32_e32 v85, v43, v43
	v_add_f32_e32 v80, v81, v80
	v_mul_f32_e32 v81, v35, v35
	v_fmac_f32_e32 v85, v42, v42
	v_fmac_f32_e32 v81, v34, v34
	v_add_f32_e32 v84, v85, v84
	v_add_f32_e32 v80, v81, v80
	v_add_f32_e32 v80, v84, v80
	ds_bpermute_b32 v81, v216, v80
	s_waitcnt lgkmcnt(0)
	v_add_f32_e32 v80, v80, v81
	ds_bpermute_b32 v81, v215, v80
	s_and_saveexec_b64 s[28:29], s[0:1]
	s_cbranch_execz .LBB0_867
	v_lshl_add_u64 v[82:83], v[92:93], 2, s[12:13]
	s_waitcnt lgkmcnt(0)
	v_add_f32_e32 v80, v80, v81
	global_atomic_add_f32 v[82:83], v80, off
.LBB0_867:
	s_or_b64 exec, exec, s[28:29]
	s_waitcnt vmcnt(3)
	v_lshlrev_b32_e32 v80, 16, v76
	s_waitcnt lgkmcnt(0)
	v_and_b32_e32 v81, 0xffff0000, v76
	v_lshlrev_b32_e32 v76, 16, v77
	v_and_b32_e32 v77, 0xffff0000, v77
	s_waitcnt vmcnt(2)
	v_lshlrev_b32_e32 v84, 16, v72
	v_and_b32_e32 v85, 0xffff0000, v72
	v_lshlrev_b32_e32 v72, 16, v73
	v_and_b32_e32 v73, 0xffff0000, v73
	v_add_f32_e64 v30, v30, v76
	v_add_f32_e64 v31, v31, v77
	v_add_f32_e64 v28, v28, v80
	v_add_f32_e64 v29, v29, v81
	v_add_f32_e64 v22, v22, v72
	v_add_f32_e64 v23, v23, v73
	v_add_f32_e64 v20, v20, v84
	v_add_f32_e64 v21, v21, v85
	v_lshlrev_b32_e32 v82, 16, v78
	v_and_b32_e32 v83, 0xffff0000, v78
	v_lshlrev_b32_e32 v86, 16, v74
	v_and_b32_e32 v87, 0xffff0000, v74
	v_mul_f32_e32 v76, v29, v29
	v_mul_f32_e32 v77, v31, v31
	v_mul_f32_e32 v72, v21, v21
	v_mul_f32_e32 v73, v23, v23
	v_add_f32_e64 v24, v24, v82
	v_add_f32_e64 v25, v25, v83
	v_fmac_f32_e32 v76, v28, v28
	v_fmac_f32_e32 v77, v30, v30
	v_add_f32_e64 v16, v16, v86
	v_add_f32_e64 v17, v17, v87
	v_fmac_f32_e32 v72, v20, v20
	v_fmac_f32_e32 v73, v22, v22
	v_lshlrev_b32_e32 v78, 16, v79
	v_and_b32_e32 v79, 0xffff0000, v79
	v_lshlrev_b32_e32 v74, 16, v75
	v_and_b32_e32 v75, 0xffff0000, v75
	v_add_f32_e32 v76, v76, v77
	v_mul_f32_e32 v77, v25, v25
	v_add_f32_e32 v72, v72, v73
	v_mul_f32_e32 v73, v17, v17
	v_add_f32_e64 v26, v26, v78
	v_add_f32_e64 v27, v27, v79
	v_fmac_f32_e32 v77, v24, v24
	v_add_f32_e64 v18, v18, v74
	v_add_f32_e64 v19, v19, v75
	v_fmac_f32_e32 v73, v16, v16
	v_add_f32_e32 v76, v77, v76
	v_mul_f32_e32 v77, v27, v27
	v_add_f32_e32 v72, v73, v72
	v_mul_f32_e32 v73, v19, v19
	v_fmac_f32_e32 v77, v26, v26
	v_fmac_f32_e32 v73, v18, v18
	v_add_f32_e32 v76, v77, v76
	v_add_f32_e32 v72, v73, v72
	v_add_f32_e32 v72, v76, v72
	ds_bpermute_b32 v73, v216, v72
	s_waitcnt lgkmcnt(0)
	v_add_f32_e32 v72, v72, v73
	ds_bpermute_b32 v73, v215, v72
	s_and_saveexec_b64 s[28:29], s[0:1]
	s_cbranch_execz .LBB0_869
	v_lshl_add_u64 v[74:75], v[90:91], 2, s[12:13]
	s_waitcnt lgkmcnt(0)
	v_add_f32_e32 v72, v72, v73
	global_atomic_add_f32 v[74:75], v72, off
.LBB0_869:
	s_or_b64 exec, exec, s[28:29]
	s_waitcnt vmcnt(1)
	v_lshlrev_b32_e32 v72, 16, v68
	s_waitcnt lgkmcnt(0)
	v_and_b32_e32 v73, 0xffff0000, v68
	v_lshlrev_b32_e32 v68, 16, v69
	v_and_b32_e32 v69, 0xffff0000, v69
	s_waitcnt vmcnt(0)
	v_lshlrev_b32_e32 v76, 16, v64
	v_and_b32_e32 v77, 0xffff0000, v64
	v_lshlrev_b32_e32 v64, 16, v65
	v_and_b32_e32 v65, 0xffff0000, v65
	v_add_f32_e64 v14, v14, v68
	v_add_f32_e64 v15, v15, v69
	v_add_f32_e64 v12, v12, v72
	v_add_f32_e64 v13, v13, v73
	v_add_f32_e64 v6, v6, v64
	v_add_f32_e64 v7, v7, v65
	v_add_f32_e64 v4, v4, v76
	v_add_f32_e64 v5, v5, v77
	v_lshlrev_b32_e32 v74, 16, v70
	v_and_b32_e32 v75, 0xffff0000, v70
	v_lshlrev_b32_e32 v78, 16, v66
	v_and_b32_e32 v79, 0xffff0000, v66
	v_mul_f32_e32 v68, v13, v13
	v_mul_f32_e32 v69, v15, v15
	v_mul_f32_e32 v64, v5, v5
	v_mul_f32_e32 v65, v7, v7
	v_add_f32_e64 v8, v8, v74
	v_add_f32_e64 v9, v9, v75
	v_fmac_f32_e32 v68, v12, v12
	v_fmac_f32_e32 v69, v14, v14
	v_add_f32_e64 v0, v0, v78
	v_add_f32_e64 v1, v1, v79
	v_fmac_f32_e32 v64, v4, v4
	v_fmac_f32_e32 v65, v6, v6
	v_lshlrev_b32_e32 v70, 16, v71
	v_and_b32_e32 v71, 0xffff0000, v71
	v_lshlrev_b32_e32 v66, 16, v67
	v_and_b32_e32 v67, 0xffff0000, v67
	v_add_f32_e32 v68, v68, v69
	v_mul_f32_e32 v69, v9, v9
	v_add_f32_e32 v64, v64, v65
	v_mul_f32_e32 v65, v1, v1
	v_add_f32_e64 v10, v10, v70
	v_add_f32_e64 v11, v11, v71
	v_fmac_f32_e32 v69, v8, v8
	v_add_f32_e64 v2, v2, v66
	v_add_f32_e64 v3, v3, v67
	v_fmac_f32_e32 v65, v0, v0
	v_add_f32_e32 v68, v69, v68
	v_mul_f32_e32 v69, v11, v11
	v_add_f32_e32 v64, v65, v64
	v_mul_f32_e32 v65, v3, v3
	v_fmac_f32_e32 v69, v10, v10
	v_fmac_f32_e32 v65, v2, v2
	v_add_f32_e32 v68, v69, v68
	v_add_f32_e32 v64, v65, v64
	v_add_f32_e32 v64, v68, v64
	ds_bpermute_b32 v65, v216, v64
	s_waitcnt lgkmcnt(0)
	v_add_f32_e32 v64, v64, v65
	ds_bpermute_b32 v65, v215, v64
	s_and_saveexec_b64 s[28:29], s[0:1]
	s_cbranch_execz .LBB0_871
	v_lshl_add_u64 v[66:67], v[88:89], 2, s[12:13]
	s_waitcnt lgkmcnt(0)
	v_add_f32_e32 v64, v64, v65
	global_atomic_add_f32 v[66:67], v64, off

.LBB0_882:
	s_or_b64 exec, exec, s[28:29]
	s_barrier
	global_load_dword v76, v[112:113], off sc1
	v_lshlrev_b64 v[66:67], 2, v[176:177]
	v_lshl_add_u64 v[64:65], s[66:67], 0, v[66:67]
	global_load_dwordx4 v[68:71], v[64:65], off
	global_load_dwordx4 v[72:75], v[64:65], off offset:16
	s_waitcnt vmcnt(2)
	v_fmamk_f32 v76, v76, 0x3a000000, v213
	v_mul_f32_e32 v77, 0x4f800000, v76
	v_cmp_gt_f32_e32 vcc, s50, v76
	s_nop 1
	v_cndmask_b32_e32 v78, v76, v77, vcc
	v_sqrt_f32_e32 v79, v78
	v_lshlrev_b64 v[76:77], 13, v[174:175]
	v_lshl_add_u64 v[76:77], s[52:53], 0, v[76:77]
	v_lshl_add_u64 v[76:77], v[76:77], 0, v[66:67]
	v_add_u32_e32 v80, -1, v79
	v_add_u32_e32 v81, 1, v79
	v_fma_f32 v82, -v80, v79, v78
	v_fma_f32 v83, -v81, v79, v78
	v_cmp_ge_f32_e64 s[6:7], 0, v82
	s_nop 1
	v_cndmask_b32_e64 v79, v79, v80, s[6:7]
	v_cmp_lt_f32_e64 s[6:7], 0, v83
	s_nop 1
	v_cndmask_b32_e64 v79, v79, v81, s[6:7]
	v_mul_f32_e32 v80, 0x37800000, v79
	v_cndmask_b32_e32 v79, v79, v80, vcc
	v_cmp_class_f32_e32 vcc, v78, v214
	s_nop 1
	v_cndmask_b32_e32 v78, v79, v78, vcc
	v_div_scale_f32 v79, s[6:7], v78, v78, 1.0
	v_rcp_f32_e32 v80, v79
	v_div_scale_f32 v81, vcc, 1.0, v78, 1.0
	v_fma_f32 v82, -v79, v80, 1.0
	v_fmac_f32_e32 v80, v82, v80
	v_mul_f32_e32 v82, v81, v80
	v_fma_f32 v83, -v79, v82, v81
	v_fmac_f32_e32 v82, v83, v80
	v_fma_f32 v79, -v79, v82, v81
	v_div_fmas_f32 v79, v79, v80, v82
	v_div_fixup_f32 v78, v79, v78, 1.0
	v_mul_f32_e64 v80, v196, v78
	v_mul_f32_e64 v81, v197, v78
	v_mul_f32_e64 v82, v190, v78
	v_mul_f32_e64 v83, v191, v78
	v_mul_f32_e64 v84, v198, v78
	v_mul_f32_e64 v85, v199, v78
	v_mul_f32_e64 v86, v188, v78
	v_mul_f32_e64 v87, v189, v78
	s_waitcnt vmcnt(1)
	v_mul_f32_e64 v70, v70, v82
	v_mul_f32_e64 v71, v71, v83
	v_mul_f32_e64 v68, v68, v80
	v_mul_f32_e64 v69, v69, v81
	s_waitcnt vmcnt(0)
	v_mul_f32_e64 v74, v74, v86
	v_mul_f32_e64 v75, v75, v87
	v_mul_f32_e64 v72, v72, v84
	v_mul_f32_e64 v73, v73, v85
	global_store_dwordx4 v[76:77], v[68:71], off
	global_store_dwordx4 v[76:77], v[72:75], off offset:16
	global_load_dwordx4 v[68:71], v[64:65], off offset:512
	s_nop 0
	global_load_dwordx4 v[72:75], v[64:65], off offset:528
	v_mul_f32_e64 v80, v194, v78
	v_mul_f32_e64 v81, v195, v78
	v_mul_f32_e64 v82, v200, v78
	v_mul_f32_e64 v83, v201, v78
	v_mul_f32_e64 v84, v186, v78
	v_mul_f32_e64 v85, v187, v78
	v_mul_f32_e64 v79, v193, v78
	v_mul_f32_e64 v78, v192, v78
	s_waitcnt vmcnt(1)
	v_mul_f32_e64 v68, v68, v82
	v_mul_f32_e64 v69, v69, v83
	v_mul_f32_e64 v70, v70, v80
	v_mul_f32_e64 v71, v71, v81
	s_waitcnt vmcnt(0)
	v_mul_f32_e64 v72, v72, v78
	v_mul_f32_e64 v73, v73, v79
	v_mul_f32_e64 v74, v74, v84
	v_mul_f32_e64 v75, v75, v85
	global_store_dwordx4 v[76:77], v[68:71], off offset:512
	global_store_dwordx4 v[76:77], v[72:75], off offset:528
	global_load_dword v76, v[202:203], off sc1
	s_nop 0
	global_load_dwordx4 v[68:71], v[64:65], off
	global_load_dwordx4 v[72:75], v[64:65], off offset:16
	s_waitcnt vmcnt(2)
	v_fmamk_f32 v76, v76, 0x3a000000, v213
	v_mul_f32_e32 v77, 0x4f800000, v76
	v_cmp_gt_f32_e32 vcc, s50, v76
	s_nop 1
	v_cndmask_b32_e32 v78, v76, v77, vcc
	v_sqrt_f32_e32 v79, v78
	v_lshlrev_b64 v[76:77], 13, v[172:173]
	v_lshl_add_u64 v[76:77], s[52:53], 0, v[76:77]
	v_lshl_add_u64 v[76:77], v[76:77], 0, v[66:67]
	v_add_u32_e32 v80, -1, v79
	v_add_u32_e32 v81, 1, v79
	v_fma_f32 v82, -v80, v79, v78
	v_fma_f32 v83, -v81, v79, v78
	v_cmp_ge_f32_e64 s[6:7], 0, v82
	s_nop 1
	v_cndmask_b32_e64 v79, v79, v80, s[6:7]
	v_cmp_lt_f32_e64 s[6:7], 0, v83
	s_nop 1
	v_cndmask_b32_e64 v79, v79, v81, s[6:7]
	v_mul_f32_e32 v80, 0x37800000, v79
	v_cndmask_b32_e32 v79, v79, v80, vcc
	v_cmp_class_f32_e32 vcc, v78, v214
	s_nop 1
	v_cndmask_b32_e32 v78, v79, v78, vcc
	v_div_scale_f32 v79, s[6:7], v78, v78, 1.0
	v_rcp_f32_e32 v80, v79
	v_div_scale_f32 v81, vcc, 1.0, v78, 1.0
	v_fma_f32 v82, -v79, v80, 1.0
	v_fmac_f32_e32 v80, v82, v80
	v_mul_f32_e32 v82, v81, v80
	v_fma_f32 v83, -v79, v82, v81
	v_fmac_f32_e32 v82, v83, v80
	v_fma_f32 v79, -v79, v82, v81
	v_div_fmas_f32 v79, v79, v80, v82
	v_div_fixup_f32 v78, v79, v78, 1.0
	v_mul_f32_e64 v80, v180, v78
	v_mul_f32_e64 v81, v181, v78
	v_mul_f32_e64 v82, v148, v78
	v_mul_f32_e64 v83, v149, v78
	v_mul_f32_e64 v84, v182, v78
	v_mul_f32_e64 v85, v183, v78
	v_mul_f32_e64 v86, v146, v78
	v_mul_f32_e64 v87, v147, v78
	s_waitcnt vmcnt(1)
	v_mul_f32_e64 v70, v70, v82
	v_mul_f32_e64 v71, v71, v83
	v_mul_f32_e64 v68, v68, v80
	v_mul_f32_e64 v69, v69, v81
	s_waitcnt vmcnt(0)
	v_mul_f32_e64 v74, v74, v86
	v_mul_f32_e64 v75, v75, v87
	v_mul_f32_e64 v72, v72, v84
	v_mul_f32_e64 v73, v73, v85
	global_store_dwordx4 v[76:77], v[68:71], off
	global_store_dwordx4 v[76:77], v[72:75], off offset:16
	global_load_dwordx4 v[68:71], v[64:65], off offset:512
	s_nop 0
	global_load_dwordx4 v[72:75], v[64:65], off offset:528
	v_mul_f32_e64 v80, v178, v78
	v_mul_f32_e64 v81, v179, v78
	v_mul_f32_e64 v82, v184, v78
	v_mul_f32_e64 v83, v185, v78
	v_mul_f32_e64 v84, v144, v78
	v_mul_f32_e64 v85, v145, v78
	v_mul_f32_e64 v79, v151, v78
	v_mul_f32_e64 v78, v150, v78
	s_waitcnt vmcnt(1)
	v_mul_f32_e64 v68, v68, v82
	v_mul_f32_e64 v69, v69, v83
	v_mul_f32_e64 v70, v70, v80
	v_mul_f32_e64 v71, v71, v81
	s_waitcnt vmcnt(0)
	v_mul_f32_e64 v72, v72, v78
	v_mul_f32_e64 v73, v73, v79
	v_mul_f32_e64 v74, v74, v84
	v_mul_f32_e64 v75, v75, v85
	global_store_dwordx4 v[76:77], v[68:71], off offset:512
	global_store_dwordx4 v[76:77], v[72:75], off offset:528
	global_load_dword v76, v[138:139], off sc1
	s_nop 0
	global_load_dwordx4 v[68:71], v[64:65], off
	global_load_dwordx4 v[72:75], v[64:65], off offset:16
	s_waitcnt vmcnt(2)
	v_fmamk_f32 v76, v76, 0x3a000000, v213
	v_mul_f32_e32 v77, 0x4f800000, v76
	v_cmp_gt_f32_e32 vcc, s50, v76
	s_nop 1
	v_cndmask_b32_e32 v78, v76, v77, vcc
	v_sqrt_f32_e32 v79, v78
	v_lshlrev_b64 v[76:77], 13, v[170:171]
	v_lshl_add_u64 v[76:77], s[52:53], 0, v[76:77]
	v_lshl_add_u64 v[76:77], v[76:77], 0, v[66:67]
	v_add_u32_e32 v80, -1, v79
	v_add_u32_e32 v81, 1, v79
	v_fma_f32 v82, -v80, v79, v78
	v_fma_f32 v83, -v81, v79, v78
	v_cmp_ge_f32_e64 s[6:7], 0, v82
	s_nop 1
	v_cndmask_b32_e64 v79, v79, v80, s[6:7]
	v_cmp_lt_f32_e64 s[6:7], 0, v83
	s_nop 1
	v_cndmask_b32_e64 v79, v79, v81, s[6:7]
	v_mul_f32_e32 v80, 0x37800000, v79
	v_cndmask_b32_e32 v79, v79, v80, vcc
	v_cmp_class_f32_e32 vcc, v78, v214
	s_nop 1
	v_cndmask_b32_e32 v78, v79, v78, vcc
	v_div_scale_f32 v79, s[6:7], v78, v78, 1.0
	v_rcp_f32_e32 v80, v79
	v_div_scale_f32 v81, vcc, 1.0, v78, 1.0
	v_fma_f32 v82, -v79, v80, 1.0
	v_fmac_f32_e32 v80, v82, v80
	v_mul_f32_e32 v82, v81, v80
	v_fma_f32 v83, -v79, v82, v81
	v_fmac_f32_e32 v82, v83, v80
	v_fma_f32 v79, -v79, v82, v81
	v_div_fmas_f32 v79, v79, v80, v82
	v_div_fixup_f32 v78, v79, v78, 1.0
	v_mul_f32_e64 v80, v124, v78
	v_mul_f32_e64 v81, v125, v78
	v_mul_f32_e64 v82, v118, v78
	v_mul_f32_e64 v83, v119, v78
	v_mul_f32_e64 v84, v126, v78
	v_mul_f32_e64 v85, v127, v78
	v_mul_f32_e64 v86, v116, v78
	v_mul_f32_e64 v87, v117, v78
	s_waitcnt vmcnt(1)
	v_mul_f32_e64 v70, v70, v82
	v_mul_f32_e64 v71, v71, v83
	v_mul_f32_e64 v68, v68, v80
	v_mul_f32_e64 v69, v69, v81
	s_waitcnt vmcnt(0)
	v_mul_f32_e64 v74, v74, v86
	v_mul_f32_e64 v75, v75, v87
	v_mul_f32_e64 v72, v72, v84
	v_mul_f32_e64 v73, v73, v85
	global_store_dwordx4 v[76:77], v[68:71], off
	global_store_dwordx4 v[76:77], v[72:75], off offset:16
	global_load_dwordx4 v[68:71], v[64:65], off offset:512
	s_nop 0
	global_load_dwordx4 v[72:75], v[64:65], off offset:528
	v_mul_f32_e64 v80, v122, v78
	v_mul_f32_e64 v81, v123, v78
	v_mul_f32_e64 v82, v136, v78
	v_mul_f32_e64 v83, v137, v78
	v_mul_f32_e64 v84, v114, v78
	v_mul_f32_e64 v85, v115, v78
	v_mul_f32_e64 v79, v121, v78
	v_mul_f32_e64 v78, v120, v78
	s_waitcnt vmcnt(1)
	v_mul_f32_e64 v68, v68, v82
	v_mul_f32_e64 v69, v69, v83
	v_mul_f32_e64 v70, v70, v80
	v_mul_f32_e64 v71, v71, v81
	s_waitcnt vmcnt(0)
	v_mul_f32_e64 v72, v72, v78
	v_mul_f32_e64 v73, v73, v79
	v_mul_f32_e64 v74, v74, v84
	v_mul_f32_e64 v75, v75, v85
	global_store_dwordx4 v[76:77], v[68:71], off offset:512
	global_store_dwordx4 v[76:77], v[72:75], off offset:528
	global_load_dword v76, v[128:129], off sc1
	s_nop 0
	global_load_dwordx4 v[68:71], v[64:65], off
	global_load_dwordx4 v[72:75], v[64:65], off offset:16
	s_waitcnt vmcnt(2)
	v_fmamk_f32 v76, v76, 0x3a000000, v213
	v_mul_f32_e32 v77, 0x4f800000, v76
	v_cmp_gt_f32_e32 vcc, s50, v76
	s_nop 1
	v_cndmask_b32_e32 v78, v76, v77, vcc
	v_sqrt_f32_e32 v79, v78
	v_lshlrev_b64 v[76:77], 13, v[168:169]
	v_lshl_add_u64 v[76:77], s[52:53], 0, v[76:77]
	v_lshl_add_u64 v[76:77], v[76:77], 0, v[66:67]
	v_add_u32_e32 v80, -1, v79
	v_add_u32_e32 v81, 1, v79
	v_fma_f32 v82, -v80, v79, v78
	v_fma_f32 v83, -v81, v79, v78
	v_cmp_ge_f32_e64 s[6:7], 0, v82
	s_nop 1
	v_cndmask_b32_e64 v79, v79, v80, s[6:7]
	v_cmp_lt_f32_e64 s[6:7], 0, v83
	s_nop 1
	v_cndmask_b32_e64 v79, v79, v81, s[6:7]
	v_mul_f32_e32 v80, 0x37800000, v79
	v_cndmask_b32_e32 v79, v79, v80, vcc
	v_cmp_class_f32_e32 vcc, v78, v214
	s_nop 1
	v_cndmask_b32_e32 v78, v79, v78, vcc
	v_div_scale_f32 v79, s[6:7], v78, v78, 1.0
	v_rcp_f32_e32 v80, v79
	v_div_scale_f32 v81, vcc, 1.0, v78, 1.0
	v_fma_f32 v82, -v79, v80, 1.0
	v_fmac_f32_e32 v80, v82, v80
	v_mul_f32_e32 v82, v81, v80
	v_fma_f32 v83, -v79, v82, v81
	v_fmac_f32_e32 v82, v83, v80
	v_fma_f32 v79, -v79, v82, v81
	v_div_fmas_f32 v79, v79, v80, v82
	v_div_fixup_f32 v78, v79, v78, 1.0
	v_mul_f32_e64 v80, v106, v78
	v_mul_f32_e64 v81, v107, v78
	v_mul_f32_e64 v82, v100, v78
	v_mul_f32_e64 v83, v101, v78
	v_mul_f32_e64 v84, v108, v78
	v_mul_f32_e64 v85, v109, v78
	v_mul_f32_e64 v86, v98, v78
	v_mul_f32_e64 v87, v99, v78
	s_waitcnt vmcnt(1)
	v_mul_f32_e64 v70, v70, v82
	v_mul_f32_e64 v71, v71, v83
	v_mul_f32_e64 v68, v68, v80
	v_mul_f32_e64 v69, v69, v81
	s_waitcnt vmcnt(0)
	v_mul_f32_e64 v74, v74, v86
	v_mul_f32_e64 v75, v75, v87
	v_mul_f32_e64 v72, v72, v84
	v_mul_f32_e64 v73, v73, v85
	global_store_dwordx4 v[76:77], v[68:71], off
	global_store_dwordx4 v[76:77], v[72:75], off offset:16
	global_load_dwordx4 v[68:71], v[64:65], off offset:512
	s_nop 0
	global_load_dwordx4 v[72:75], v[64:65], off offset:528
	v_mul_f32_e64 v80, v104, v78
	v_mul_f32_e64 v81, v105, v78
	v_mul_f32_e64 v82, v110, v78
	v_mul_f32_e64 v83, v111, v78
	v_mul_f32_e64 v84, v96, v78
	v_mul_f32_e64 v85, v97, v78
	v_mul_f32_e64 v79, v103, v78
	v_mul_f32_e64 v78, v102, v78
	s_waitcnt vmcnt(1)
	v_mul_f32_e64 v68, v68, v82
	v_mul_f32_e64 v69, v69, v83
	v_mul_f32_e64 v70, v70, v80
	v_mul_f32_e64 v71, v71, v81
	s_waitcnt vmcnt(0)
	v_mul_f32_e64 v72, v72, v78
	v_mul_f32_e64 v73, v73, v79
	v_mul_f32_e64 v74, v74, v84
	v_mul_f32_e64 v75, v75, v85
	global_store_dwordx4 v[76:77], v[68:71], off offset:512
	global_store_dwordx4 v[76:77], v[72:75], off offset:528
	global_load_dword v76, v[112:113], off offset:512 sc1
	s_nop 0
	global_load_dwordx4 v[68:71], v[64:65], off
	global_load_dwordx4 v[72:75], v[64:65], off offset:16
	s_waitcnt vmcnt(2)
	v_fmamk_f32 v76, v76, 0x3a000000, v213
	v_mul_f32_e32 v77, 0x4f800000, v76
	v_cmp_gt_f32_e32 vcc, s50, v76
	s_nop 1
	v_cndmask_b32_e32 v78, v76, v77, vcc
	v_sqrt_f32_e32 v79, v78
	v_lshlrev_b64 v[76:77], 13, v[94:95]
	v_lshl_add_u64 v[76:77], s[52:53], 0, v[76:77]
	v_lshl_add_u64 v[76:77], v[76:77], 0, v[66:67]
	v_add_u32_e32 v80, -1, v79
	v_add_u32_e32 v81, 1, v79
	v_fma_f32 v82, -v80, v79, v78
	v_fma_f32 v83, -v81, v79, v78
	v_cmp_ge_f32_e64 s[6:7], 0, v82
	s_nop 1
	v_cndmask_b32_e64 v79, v79, v80, s[6:7]
	v_cmp_lt_f32_e64 s[6:7], 0, v83
	s_nop 1
	v_cndmask_b32_e64 v79, v79, v81, s[6:7]
	v_mul_f32_e32 v80, 0x37800000, v79
	v_cndmask_b32_e32 v79, v79, v80, vcc
	v_cmp_class_f32_e32 vcc, v78, v214
	s_nop 1
	v_cndmask_b32_e32 v78, v79, v78, vcc
	v_div_scale_f32 v79, s[6:7], v78, v78, 1.0
	v_rcp_f32_e32 v80, v79
	v_div_scale_f32 v81, vcc, 1.0, v78, 1.0
	v_fma_f32 v82, -v79, v80, 1.0
	v_fmac_f32_e32 v80, v82, v80
	v_mul_f32_e32 v82, v81, v80
	v_fma_f32 v83, -v79, v82, v81
	v_fmac_f32_e32 v82, v83, v80
	v_fma_f32 v79, -v79, v82, v81
	v_div_fmas_f32 v79, v79, v80, v82
	v_div_fixup_f32 v78, v79, v78, 1.0
	v_mul_f32_e64 v60, v60, v78
	v_mul_f32_e64 v61, v61, v78
	v_mul_f32_e64 v62, v62, v78
	v_mul_f32_e64 v63, v63, v78
	v_mul_f32_e64 v80, v56, v78
	v_mul_f32_e64 v81, v57, v78
	v_mul_f32_e64 v82, v58, v78
	v_mul_f32_e64 v83, v59, v78
	s_waitcnt vmcnt(1)
	v_mul_f32_e64 v58, v70, v62
	v_mul_f32_e64 v59, v71, v63
	v_mul_f32_e64 v56, v68, v60
	v_mul_f32_e64 v57, v69, v61
	s_waitcnt vmcnt(0)
	v_mul_f32_e64 v62, v74, v82
	v_mul_f32_e64 v63, v75, v83
	v_mul_f32_e64 v60, v72, v80
	v_mul_f32_e64 v61, v73, v81
	global_store_dwordx4 v[76:77], v[56:59], off
	global_store_dwordx4 v[76:77], v[60:63], off offset:16
	global_load_dwordx4 v[56:59], v[64:65], off offset:512
	s_nop 0
	global_load_dwordx4 v[60:63], v[64:65], off offset:528
	v_mul_f32_e64 v54, v54, v78
	v_mul_f32_e64 v55, v55, v78
	v_mul_f32_e64 v52, v52, v78
	v_mul_f32_e64 v53, v53, v78
	v_mul_f32_e64 v68, v50, v78
	v_mul_f32_e64 v69, v51, v78
	v_mul_f32_e64 v70, v48, v78
	v_mul_f32_e64 v71, v49, v78
	s_waitcnt vmcnt(1)
	v_mul_f32_e64 v48, v56, v52
	v_mul_f32_e64 v49, v57, v53
	v_mul_f32_e64 v50, v58, v54
	v_mul_f32_e64 v51, v59, v55
	s_waitcnt vmcnt(0)
	v_mul_f32_e64 v52, v60, v70
	v_mul_f32_e64 v53, v61, v71
	v_mul_f32_e64 v54, v62, v68
	v_mul_f32_e64 v55, v63, v69
	global_store_dwordx4 v[76:77], v[48:51], off offset:512
	global_store_dwordx4 v[76:77], v[52:55], off offset:528
	global_load_dword v56, v[112:113], off offset:576 sc1
	s_nop 0
	global_load_dwordx4 v[48:51], v[64:65], off
	global_load_dwordx4 v[52:55], v[64:65], off offset:16
	s_waitcnt vmcnt(2)
	v_fmamk_f32 v56, v56, 0x3a000000, v213
	v_mul_f32_e32 v57, 0x4f800000, v56
	v_cmp_gt_f32_e32 vcc, s50, v56
	s_nop 1
	v_cndmask_b32_e32 v58, v56, v57, vcc
	v_sqrt_f32_e32 v59, v58
	v_lshlrev_b64 v[56:57], 13, v[92:93]
	v_lshl_add_u64 v[56:57], s[52:53], 0, v[56:57]
	v_lshl_add_u64 v[56:57], v[56:57], 0, v[66:67]
	v_add_u32_e32 v60, -1, v59
	v_add_u32_e32 v61, 1, v59
	v_fma_f32 v62, -v60, v59, v58
	v_fma_f32 v63, -v61, v59, v58
	v_cmp_ge_f32_e64 s[6:7], 0, v62
	s_nop 1
	v_cndmask_b32_e64 v59, v59, v60, s[6:7]
	v_cmp_lt_f32_e64 s[6:7], 0, v63
	s_nop 1
	v_cndmask_b32_e64 v59, v59, v61, s[6:7]
	v_mul_f32_e32 v60, 0x37800000, v59
	v_cndmask_b32_e32 v59, v59, v60, vcc
	v_cmp_class_f32_e32 vcc, v58, v214
	s_nop 1
	v_cndmask_b32_e32 v58, v59, v58, vcc
	v_div_scale_f32 v59, s[6:7], v58, v58, 1.0
	v_rcp_f32_e32 v60, v59
	v_div_scale_f32 v61, vcc, 1.0, v58, 1.0
	v_fma_f32 v62, -v59, v60, 1.0
	v_fmac_f32_e32 v60, v62, v60
	v_mul_f32_e32 v62, v61, v60
	v_fma_f32 v63, -v59, v62, v61
	v_fmac_f32_e32 v62, v63, v60
	v_fma_f32 v59, -v59, v62, v61
	v_div_fmas_f32 v59, v59, v60, v62
	v_div_fixup_f32 v58, v59, v58, 1.0
	v_mul_f32_e64 v44, v44, v58
	v_mul_f32_e64 v45, v45, v58
	v_mul_f32_e64 v46, v46, v58
	v_mul_f32_e64 v47, v47, v58
	v_mul_f32_e64 v60, v40, v58
	v_mul_f32_e64 v61, v41, v58
	v_mul_f32_e64 v62, v42, v58
	v_mul_f32_e64 v63, v43, v58
	s_waitcnt vmcnt(1)
	v_mul_f32_e64 v42, v50, v46
	v_mul_f32_e64 v43, v51, v47
	v_mul_f32_e64 v40, v48, v44
	v_mul_f32_e64 v41, v49, v45
	s_waitcnt vmcnt(0)
	v_mul_f32_e64 v46, v54, v62
	v_mul_f32_e64 v47, v55, v63
	v_mul_f32_e64 v44, v52, v60
	v_mul_f32_e64 v45, v53, v61
	global_store_dwordx4 v[56:57], v[40:43], off
	global_store_dwordx4 v[56:57], v[44:47], off offset:16
	global_load_dwordx4 v[40:43], v[64:65], off offset:512
	s_nop 0
	global_load_dwordx4 v[44:47], v[64:65], off offset:528
	v_mul_f32_e64 v38, v38, v58
	v_mul_f32_e64 v39, v39, v58
	v_mul_f32_e64 v36, v36, v58
	v_mul_f32_e64 v37, v37, v58
	v_mul_f32_e64 v48, v34, v58
	v_mul_f32_e64 v49, v35, v58
	v_mul_f32_e64 v50, v32, v58
	v_mul_f32_e64 v51, v33, v58
	s_waitcnt vmcnt(1)
	v_mul_f32_e64 v32, v40, v36
	v_mul_f32_e64 v33, v41, v37
	v_mul_f32_e64 v34, v42, v38
	v_mul_f32_e64 v35, v43, v39
	s_waitcnt vmcnt(0)
	v_mul_f32_e64 v36, v44, v50
	v_mul_f32_e64 v37, v45, v51
	v_mul_f32_e64 v38, v46, v48
	v_mul_f32_e64 v39, v47, v49
	global_store_dwordx4 v[56:57], v[32:35], off offset:512
	global_store_dwordx4 v[56:57], v[36:39], off offset:528
	global_load_dword v40, v[112:113], off offset:640 sc1
	s_nop 0
	global_load_dwordx4 v[32:35], v[64:65], off
	global_load_dwordx4 v[36:39], v[64:65], off offset:16
	s_waitcnt vmcnt(2)
	v_fmamk_f32 v40, v40, 0x3a000000, v213
	v_mul_f32_e32 v41, 0x4f800000, v40
	v_cmp_gt_f32_e32 vcc, s50, v40
	s_nop 1
	v_cndmask_b32_e32 v42, v40, v41, vcc
	v_sqrt_f32_e32 v43, v42
	v_lshlrev_b64 v[40:41], 13, v[90:91]
	v_lshl_add_u64 v[40:41], s[52:53], 0, v[40:41]
	v_lshl_add_u64 v[40:41], v[40:41], 0, v[66:67]
	v_add_u32_e32 v44, -1, v43
	v_add_u32_e32 v45, 1, v43
	v_fma_f32 v46, -v44, v43, v42
	v_fma_f32 v47, -v45, v43, v42
	v_cmp_ge_f32_e64 s[6:7], 0, v46
	s_nop 1
	v_cndmask_b32_e64 v43, v43, v44, s[6:7]
	v_cmp_lt_f32_e64 s[6:7], 0, v47
	s_nop 1
	v_cndmask_b32_e64 v43, v43, v45, s[6:7]
	v_mul_f32_e32 v44, 0x37800000, v43
	v_cndmask_b32_e32 v43, v43, v44, vcc
	v_cmp_class_f32_e32 vcc, v42, v214
	s_nop 1
	v_cndmask_b32_e32 v42, v43, v42, vcc
	v_div_scale_f32 v43, s[6:7], v42, v42, 1.0
	v_rcp_f32_e32 v44, v43
	v_div_scale_f32 v45, vcc, 1.0, v42, 1.0
	v_fma_f32 v46, -v43, v44, 1.0
	v_fmac_f32_e32 v44, v46, v44
	v_mul_f32_e32 v46, v45, v44
	v_fma_f32 v47, -v43, v46, v45
	v_fmac_f32_e32 v46, v47, v44
	v_fma_f32 v43, -v43, v46, v45
	v_div_fmas_f32 v43, v43, v44, v46
	v_div_fixup_f32 v42, v43, v42, 1.0
	v_mul_f32_e64 v28, v28, v42
	v_mul_f32_e64 v29, v29, v42
	v_mul_f32_e64 v30, v30, v42
	v_mul_f32_e64 v31, v31, v42
	v_mul_f32_e64 v44, v24, v42
	v_mul_f32_e64 v45, v25, v42
	v_mul_f32_e64 v46, v26, v42
	v_mul_f32_e64 v47, v27, v42
	s_waitcnt vmcnt(1)
	v_mul_f32_e64 v26, v34, v30
	v_mul_f32_e64 v27, v35, v31
	v_mul_f32_e64 v24, v32, v28
	v_mul_f32_e64 v25, v33, v29
	s_waitcnt vmcnt(0)
	v_mul_f32_e64 v30, v38, v46
	v_mul_f32_e64 v31, v39, v47
	v_mul_f32_e64 v28, v36, v44
	v_mul_f32_e64 v29, v37, v45
	global_store_dwordx4 v[40:41], v[24:27], off
	global_store_dwordx4 v[40:41], v[28:31], off offset:16
	global_load_dwordx4 v[24:27], v[64:65], off offset:512
	s_nop 0
	global_load_dwordx4 v[28:31], v[64:65], off offset:528
	v_mul_f32_e64 v22, v22, v42
	v_mul_f32_e64 v23, v23, v42
	v_mul_f32_e64 v20, v20, v42
	v_mul_f32_e64 v21, v21, v42
	v_mul_f32_e64 v32, v18, v42
	v_mul_f32_e64 v33, v19, v42
	v_mul_f32_e64 v34, v16, v42
	v_mul_f32_e64 v35, v17, v42
	s_waitcnt vmcnt(1)
	v_mul_f32_e64 v16, v24, v20
	v_mul_f32_e64 v17, v25, v21
	v_mul_f32_e64 v18, v26, v22
	v_mul_f32_e64 v19, v27, v23
	s_waitcnt vmcnt(0)
	v_mul_f32_e64 v20, v28, v34
	v_mul_f32_e64 v21, v29, v35
	v_mul_f32_e64 v22, v30, v32
	v_mul_f32_e64 v23, v31, v33
	global_store_dwordx4 v[40:41], v[16:19], off offset:512
	global_store_dwordx4 v[40:41], v[20:23], off offset:528
	global_load_dword v24, v[112:113], off offset:704 sc1
	s_nop 0
	global_load_dwordx4 v[16:19], v[64:65], off
	global_load_dwordx4 v[20:23], v[64:65], off offset:16
	s_waitcnt vmcnt(2)
	v_fmamk_f32 v24, v24, 0x3a000000, v213
	v_mul_f32_e32 v25, 0x4f800000, v24
	v_cmp_gt_f32_e32 vcc, s50, v24
	s_nop 1
	v_cndmask_b32_e32 v26, v24, v25, vcc
	v_sqrt_f32_e32 v27, v26
	v_lshlrev_b64 v[24:25], 13, v[88:89]
	v_lshl_add_u64 v[24:25], s[52:53], 0, v[24:25]
	v_lshl_add_u64 v[24:25], v[24:25], 0, v[66:67]
	v_add_u32_e32 v28, -1, v27
	v_add_u32_e32 v29, 1, v27
	v_fma_f32 v30, -v28, v27, v26
	v_fma_f32 v31, -v29, v27, v26
	v_cmp_ge_f32_e64 s[6:7], 0, v30
	s_nop 1
	v_cndmask_b32_e64 v27, v27, v28, s[6:7]
	v_cmp_lt_f32_e64 s[6:7], 0, v31
	s_nop 1
	v_cndmask_b32_e64 v27, v27, v29, s[6:7]
	v_mul_f32_e32 v28, 0x37800000, v27
	v_cndmask_b32_e32 v27, v27, v28, vcc
	v_cmp_class_f32_e32 vcc, v26, v214
	s_nop 1
	v_cndmask_b32_e32 v26, v27, v26, vcc
	v_div_scale_f32 v27, s[6:7], v26, v26, 1.0
	v_rcp_f32_e32 v28, v27
	v_div_scale_f32 v29, vcc, 1.0, v26, 1.0
	v_fma_f32 v30, -v27, v28, 1.0
	v_fmac_f32_e32 v28, v30, v28
	v_mul_f32_e32 v30, v29, v28
	v_fma_f32 v31, -v27, v30, v29
	v_fmac_f32_e32 v30, v31, v28
	v_fma_f32 v27, -v27, v30, v29
	v_div_fmas_f32 v27, v27, v28, v30
	v_div_fixup_f32 v26, v27, v26, 1.0
	v_mul_f32_e64 v12, v12, v26
	v_mul_f32_e64 v13, v13, v26
	v_mul_f32_e64 v14, v14, v26
	v_mul_f32_e64 v15, v15, v26
	v_mul_f32_e64 v28, v8, v26
	v_mul_f32_e64 v29, v9, v26
	v_mul_f32_e64 v30, v10, v26
	v_mul_f32_e64 v31, v11, v26
	s_waitcnt vmcnt(1)
	v_mul_f32_e64 v10, v18, v14
	v_mul_f32_e64 v11, v19, v15
	v_mul_f32_e64 v8, v16, v12
	v_mul_f32_e64 v9, v17, v13
	s_waitcnt vmcnt(0)
	v_mul_f32_e64 v14, v22, v30
	v_mul_f32_e64 v15, v23, v31
	v_mul_f32_e64 v12, v20, v28
	v_mul_f32_e64 v13, v21, v29
	global_store_dwordx4 v[24:25], v[8:11], off
	global_store_dwordx4 v[24:25], v[12:15], off offset:16
	global_load_dwordx4 v[8:11], v[64:65], off offset:512
	s_nop 0
	global_load_dwordx4 v[12:15], v[64:65], off offset:528
	v_mul_f32_e64 v6, v6, v26
	v_mul_f32_e64 v7, v7, v26
	v_mul_f32_e64 v4, v4, v26
	v_mul_f32_e64 v5, v5, v26
	s_andn2_b64 vcc, exec, s[4:5]
	v_mul_f32_e64 v16, v2, v26
	v_mul_f32_e64 v17, v3, v26
	v_mul_f32_e64 v18, v0, v26
	v_mul_f32_e64 v19, v1, v26
	s_mov_b64 s[4:5], -1
	s_waitcnt vmcnt(1)
	v_mul_f32_e64 v0, v8, v4
	v_mul_f32_e64 v1, v9, v5
	v_mul_f32_e64 v2, v10, v6
	v_mul_f32_e64 v3, v11, v7
	s_waitcnt vmcnt(0)
	v_mul_f32_e64 v4, v12, v18
	v_mul_f32_e64 v5, v13, v19
	v_mul_f32_e64 v6, v14, v16
	v_mul_f32_e64 v7, v15, v17
	global_store_dwordx4 v[24:25], v[0:3], off offset:512
	global_store_dwordx4 v[24:25], v[4:7], off offset:528
	s_cbranch_vccnz .LBB0_848
	s_andn2_b64 vcc, exec, s[14:15]
	s_cbranch_vccnz .LBB0_847
	s_barrier
	s_branch .LBB0_847
